# residual-add GEMM epilogues (out-proj, MLP down): tiles with no masked rows use two batched passes (8 loads + 8 LDS reads, one wait, 8 adds + stores) instead of a 16-step load/wait/store ladder
# speedup vs baseline: 1.0481x; 1.0024x over previous
; #define GLOADQ(RA, RB, KT, q) do { const int k0_ = (KT) << 6; \
;     RA[q] = ldg16(ap.ptr(m0 + lrow + 32 * (q), k0_) + lkc); RB[q] = ldg16(W + (size_t)(n0 + lrow + 32 * (q)) * ldw + k0_ + lkc); } while (0)
; #define GLOAD(RA, RB, KT) do { GLOADQ(RA, RB, KT, 0); GLOADQ(RA, RB, KT, 1); GLOADQ(RA, RB, KT, 2); GLOADQ(RA, RB, KT, 3); } while (0)
; #define SSTOREQ(RA, RB, ST, q) do { \
;     *(u32x4*)(sA + (ST) * SBUF + (lrow + 32 * (q)) * GP + lkc) = RA[q]; *(u32x4*)(sB + (ST) * SBUF + (lrow + 32 * (q)) * GP + lkc) = RB[q]; } while (0)
; #define SSTORE(RA, RB, ST) do { SSTOREQ(RA, RB, ST, 0); SSTOREQ(RA, RB, ST, 1); SSTOREQ(RA, RB, ST, 2); SSTOREQ(RA, RB, ST, 3); } while (0)
; #define FLOAD(F, ST, ks) do { _Pragma("unroll") for (int a = 0; a < 2; ++a) { \
;     F[a] = *(const bf16x8*)(sB + (ST) * SBUF + (wn * 64 + a * 32 + r) * GP + (ks) * 16 + h * 8); \
;     F[2 + a] = *(const bf16x8*)(sA + (ST) * SBUF + (wm * 64 + a * 32 + r) * GP + (ks) * 16 + h * 8); } } while (0)
; template <bool MIDK, class AP, class EPI>
; DI void gemm_tile(const AP& ap, const u16* __restrict__ W, int ldw, int K, int m0, int n0, const EPI& epi, char* smem, float r0, float r1, int tid, bool dry) {
;     ...
;   bf16x8 f0[4], f1[4];
;   GLOAD(ra0, rb0, 0);
;   GLOAD(ra1, rb1, 1);
;   __syncthreads();
;   SSTORE(ra0, rb0, 0);
;   if (nk > 2) GLOAD(ra0, rb0, 2);
;   __syncthreads();
;   for (int kt = 0; kt < nk; kt += 2) {
;     const bool l3 = kt + 3 < nk, s2 = kt + 2 < nk, l4 = kt + 4 < nk;
;     FLOAD(f0, 0, 0); FLOAD(f1, 0, 1);
;     FMMA(f0); SSTOREQ(ra1, rb1, 1, 0); if (l3) GLOADQ(ra1, rb1, kt + 3, 0);
;     FLOAD(f0, 0, 2);
;     FMMA(f1); SSTOREQ(ra1, rb1, 1, 1); if (l3) GLOADQ(ra1, rb1, kt + 3, 1);
;     FLOAD(f1, 0, 3);
;     FMMA(f0); SSTOREQ(ra1, rb1, 1, 2); if (l3) GLOADQ(ra1, rb1, kt + 3, 2);
;     FMMA(f1); SSTOREQ(ra1, rb1, 1, 3); if (l3) GLOADQ(ra1, rb1, kt + 3, 3);
; __global__ void __launch_bounds__(256, 2) mega(Params pin) {
;     ...
;         const int g0 = mt * 128 + (wave >> 1) * 64 + r;
;         const float ra0 = rsqrtf(ldgf(ssq + 2 * (size_t)MPAD + g0) * (1.0f / 512.0f) + EPS), rg0 = rsqrtf(ldgf(ssq + 3 * (size_t)MPAD + g0) * (1.0f / 512.0f) + EPS);
;         const float ra1 = rsqrtf(ldgf(ssq + 2 * (size_t)MPAD + g0 + 32) * (1.0f / 512.0f) + EPS), rg1 = rsqrtf(ldgf(ssq + 3 * (size_t)MPAD + g0 + 32) * (1.0f / 512.0f) + EPS);
.LBB0_171:
	s_and_b32 s4, s26, 0x380
	v_add_u32_e32 v4, s4, v163
	v_ashrrev_i32_e32 v5, 31, v4
	v_add_u32_e32 v130, s10, v163
	v_lshlrev_b64 v[4:5], 11, v[4:5]
	v_lshl_add_u64 v[142:143], v[138:139], 0, v[4:5]
	v_add_u32_e32 v132, 32, v130
	v_add_u32_e32 v150, 64, v130
	v_mad_i64_i32 v[154:155], s[0:1], v130, s67, v[136:137]
	v_mad_i64_i32 v[156:157], s[0:1], v132, s67, v[136:137]
	v_add_co_u32_e32 v12, vcc, s77, v142
	v_mad_i64_i32 v[158:159], s[0:1], v150, s67, v[136:137]
	s_nop 0
	v_addc_co_u32_e32 v13, vcc, 0, v143, vcc
	s_mov_b32 s0, 0x20000
	v_add_u32_e32 v152, 0x60, v130
	global_load_dwordx4 v[0:3], v[154:155], off
	global_load_dwordx4 v[4:7], v[142:143], off
	v_add_co_u32_e32 v20, vcc, s0, v142
	v_mad_i64_i32 v[160:161], s[0:1], v152, s67, v[136:137]
	global_load_dwordx4 v[8:11], v[156:157], off
	global_load_dwordx4 v[16:19], v[158:159], off
	v_addc_co_u32_e32 v21, vcc, 0, v143, vcc
	s_mov_b32 s0, 0x30000
	v_add_co_u32_e32 v28, vcc, s0, v142
	global_load_dwordx4 v[24:27], v[160:161], off
	s_nop 0
	v_addc_co_u32_e32 v29, vcc, 0, v143, vcc
	global_load_dwordx4 v[12:15], v[12:13], off
	s_mov_b64 s[0:1], 0x10000
	global_load_dwordx4 v[20:23], v[20:21], off
	s_nop 0
	global_load_dwordx4 v[28:31], v[28:29], off
	s_nop 0
	global_load_dwordx4 v[80:83], v[154:155], off offset:192
	global_load_dwordx4 v[84:87], v[156:157], off offset:192
	global_load_dwordx4 v[88:91], v[158:159], off offset:192
	global_load_dwordx4 v[92:95], v[160:161], off offset:192
	v_lshl_add_u64 v[148:149], v[142:143], 0, s[0:1]
	s_mov_b64 s[0:1], 0x20000
	v_lshl_add_u64 v[144:145], v[142:143], 0, s[0:1]
	s_mov_b64 s[0:1], 0x30000
	v_lshl_add_u64 v[146:147], v[142:143], 0, s[0:1]
	global_load_dwordx4 v[104:107], v[142:143], off offset:128
	global_load_dwordx4 v[108:111], v[148:149], off offset:128
	global_load_dwordx4 v[112:115], v[144:145], off offset:128
	global_load_dwordx4 v[116:119], v[146:147], off offset:128
	s_waitcnt lgkmcnt(0)
	s_barrier
	global_load_dwordx4 v[120:123], v[154:155], off offset:384
	global_load_dwordx4 v[124:127], v[142:143], off offset:256
	global_load_dwordx4 v[96:99], v[156:157], off offset:384
	global_load_dwordx4 v[100:103], v[148:149], off offset:256
	global_load_dwordx4 v[72:75], v[158:159], off offset:384
	global_load_dwordx4 v[76:79], v[144:145], off offset:256
	global_load_dwordx4 v[64:67], v[160:161], off offset:384
	global_load_dwordx4 v[68:71], v[146:147], off offset:256
	v_ashrrev_i32_e32 v131, 31, v130
	v_ashrrev_i32_e32 v133, 31, v132
	v_ashrrev_i32_e32 v151, 31, v150
	v_ashrrev_i32_e32 v153, 31, v152
	s_mov_b32 s5, 0x800000
	s_waitcnt vmcnt(0)
	v_fmamk_f32 v187, v187, 0x3b000000, v224
	v_fmamk_f32 v189, v189, 0x3b000000, v224
	v_cmp_gt_f32_e64 s[2:3], s5, v187
	v_mul_f32_e32 v190, 0x4b800000, v189
	v_cmp_gt_f32_e32 vcc, s5, v189
	ds_write_b128 v134, v[0:3]
	ds_write_b128 v134, v[8:11] offset:4608
	ds_write_b128 v134, v[16:19] offset:9216
	ds_write_b128 v134, v[24:27] offset:13824
	ds_write_b128 v134, v[4:7] offset:18432
	ds_write_b128 v134, v[12:15] offset:23040
	ds_write_b128 v134, v[20:23] offset:27648
	ds_write_b128 v134, v[28:31] offset:32256
	s_waitcnt lgkmcnt(0)
	s_barrier
	ds_read_b128 v[0:3], v128 offset:18432
	ds_read_b128 v[4:7], v165
	ds_read_b128 v[8:11], v165 offset:4608
	s_waitcnt lgkmcnt(1)
	v_mfma_f32_32x32x16_bf16 v[48:63], v[0:3], v[4:7], 0
	v_cndmask_b32_e32 v189, v189, v190, vcc
	v_rsq_f32_e32 v192, v189
	s_nop 0
	v_mul_f32_e32 v198, 0x45800000, v192
	s_waitcnt lgkmcnt(0)
	v_mfma_f32_32x32x16_bf16 v[32:47], v[0:3], v[8:11], 0
	ds_read_b128 v[0:3], v128 offset:23040
	ds_read_b128 v[194:197], v164 offset:18464
	ds_read_b128 v[200:203], v165 offset:32
	ds_read_b128 v[204:207], v165 offset:4640
	s_waitcnt lgkmcnt(1)
	v_mfma_f32_32x32x16_bf16 v[48:63], v[194:197], v[200:203], v[48:63]
	s_waitcnt lgkmcnt(0)
	v_mfma_f32_32x32x16_bf16 v[32:47], v[194:197], v[204:207], v[32:47]
	ds_read_b128 v[194:197], v164 offset:23072
	ds_write_b128 v134, v[80:83] offset:36864
	ds_write_b128 v134, v[104:107] offset:55296
	ds_read_b128 v[80:83], v164 offset:18496
	ds_read_b128 v[104:107], v165 offset:64
	v_mfma_f32_32x32x16_bf16 v[16:31], v[0:3], v[4:7], 0
	v_mfma_f32_32x32x16_bf16 v[0:15], v[0:3], v[8:11], 0
	s_waitcnt lgkmcnt(4)
	v_mfma_f32_32x32x16_bf16 v[16:31], v[194:197], v[200:203], v[16:31]
	v_mfma_f32_32x32x16_bf16 v[0:15], v[194:197], v[204:207], v[0:15]
	ds_read_b128 v[194:197], v165 offset:4672
	s_waitcnt lgkmcnt(1)
	v_mfma_f32_32x32x16_bf16 v[48:63], v[80:83], v[104:107], v[48:63]
	s_waitcnt lgkmcnt(0)
	v_mfma_f32_32x32x16_bf16 v[32:47], v[80:83], v[194:197], v[32:47]
	ds_read_b128 v[80:83], v164 offset:23104
	ds_write_b128 v134, v[84:87] offset:41472
	ds_write_b128 v134, v[108:111] offset:59904
	s_waitcnt lgkmcnt(2)
	v_mfma_f32_32x32x16_bf16 v[16:31], v[80:83], v[104:107], v[16:31]
	v_mfma_f32_32x32x16_bf16 v[0:15], v[80:83], v[194:197], v[0:15]
	ds_read_b128 v[80:83], v164 offset:18528
	ds_read_b128 v[84:87], v165 offset:96
	ds_read_b128 v[194:197], v165 offset:4704
	ds_read_b128 v[200:203], v164 offset:23136
	global_load_dwordx4 v[204:207], v[154:155], off offset:576
	s_waitcnt lgkmcnt(2)
	v_mfma_f32_32x32x16_bf16 v[48:63], v[80:83], v[84:87], v[48:63]
	s_waitcnt lgkmcnt(1)
	v_mfma_f32_32x32x16_bf16 v[32:47], v[80:83], v[194:197], v[32:47]
	s_waitcnt lgkmcnt(0)
	v_mfma_f32_32x32x16_bf16 v[16:31], v[200:203], v[84:87], v[16:31]
	global_load_dwordx4 v[208:211], v[142:143], off offset:384
	global_load_dwordx4 v[104:107], v[156:157], off offset:576
	global_load_dwordx4 v[108:111], v[148:149], off offset:384
	global_load_dwordx4 v[80:83], v[158:159], off offset:576
	global_load_dwordx4 v[84:87], v[144:145], off offset:384
	ds_write_b128 v134, v[88:91] offset:46080
	ds_write_b128 v134, v[112:115] offset:64512
	ds_write_b128 v134, v[92:95] offset:50688
	ds_write_b128 v135, v[116:119] offset:13824
	global_load_dwordx4 v[88:91], v[160:161], off offset:576
	global_load_dwordx4 v[92:95], v[146:147], off offset:384
	s_waitcnt lgkmcnt(0)
	s_barrier
; #define GLOADQ(RA, RB, KT, q) do { const int k0_ = (KT) << 6; \
;     RA[q] = ldg16(ap.ptr(m0 + lrow + 32 * (q), k0_) + lkc); RB[q] = ldg16(W + (size_t)(n0 + lrow + 32 * (q)) * ldw + k0_ + lkc); } while (0)
; #define SSTOREQ(RA, RB, ST, q) do { \
;     *(u32x4*)(sA + (ST) * SBUF + (lrow + 32 * (q)) * GP + lkc) = RA[q]; *(u32x4*)(sB + (ST) * SBUF + (lrow + 32 * (q)) * GP + lkc) = RB[q]; } while (0)
; #define FLOAD(F, ST, ks) do { _Pragma("unroll") for (int a = 0; a < 2; ++a) { \
;     F[a] = *(const bf16x8*)(sB + (ST) * SBUF + (wn * 64 + a * 32 + r) * GP + (ks) * 16 + h * 8); \
;     F[2 + a] = *(const bf16x8*)(sA + (ST) * SBUF + (wm * 64 + a * 32 + r) * GP + (ks) * 16 + h * 8); } } while (0)
; #define FMMA(F) do { _Pragma("unroll") for (int a = 0; a < 2; ++a) _Pragma("unroll") for (int b = 0; b < 2; ++b) acc[a][b] = MFMA(F[a], F[2 + b], acc[a][b]); } while (0)
; template <bool MIDK, class AP, class EPI>
; DI void gemm_tile(const AP& ap, const u16* __restrict__ W, int ldw, int K, int m0, int n0, const EPI& epi, char* smem, float r0, float r1, int tid, bool dry) {
;     ...
;   for (int kt = 0; kt < nk; kt += 2) {
;     const bool l3 = kt + 3 < nk, s2 = kt + 2 < nk, l4 = kt + 4 < nk;
;     FLOAD(f0, 0, 0); FLOAD(f1, 0, 1);
;     FMMA(f0); SSTOREQ(ra1, rb1, 1, 0); if (l3) GLOADQ(ra1, rb1, kt + 3, 0);
;     FLOAD(f0, 0, 2);
;     FMMA(f1); SSTOREQ(ra1, rb1, 1, 1); if (l3) GLOADQ(ra1, rb1, kt + 3, 1);
;     FLOAD(f1, 0, 3);
;     FMMA(f0); SSTOREQ(ra1, rb1, 1, 2); if (l3) GLOADQ(ra1, rb1, kt + 3, 2);
;     FMMA(f1); SSTOREQ(ra1, rb1, 1, 3); if (l3) GLOADQ(ra1, rb1, kt + 3, 3);
;     __syncthreads();
;     FLOAD(f0, 1, 0); FLOAD(f1, 1, 1);
;     FMMA(f0); if (s2) SSTOREQ(ra0, rb0, 0, 0); if (l4) GLOADQ(ra0, rb0, kt + 4, 0);
;     FLOAD(f0, 1, 2);
;     FMMA(f1); if (s2) SSTOREQ(ra0, rb0, 0, 1); if (l4) GLOADQ(ra0, rb0, kt + 4, 1);
;     FLOAD(f1, 1, 3);
;     FMMA(f0); if (s2) SSTOREQ(ra0, rb0, 0, 2); if (l4) GLOADQ(ra0, rb0, kt + 4, 2);
;     FMMA(f1); if (s2) SSTOREQ(ra0, rb0, 0, 3); if (l4) GLOADQ(ra0, rb0, kt + 4, 3);
	v_mfma_f32_32x32x16_bf16 v[0:15], v[200:203], v[194:197], v[0:15]
	ds_read_b128 v[112:115], v128 offset:55296
	ds_read_b128 v[116:119], v165 offset:36864
	ds_read_b128 v[194:197], v165 offset:41472
	s_waitcnt lgkmcnt(1)
	v_mfma_f32_32x32x16_bf16 v[48:63], v[112:115], v[116:119], v[48:63]
	s_waitcnt lgkmcnt(0)
	v_mfma_f32_32x32x16_bf16 v[32:47], v[112:115], v[194:197], v[32:47]
	ds_read_b128 v[112:115], v128 offset:59904
	s_waitcnt lgkmcnt(0)
	v_mfma_f32_32x32x16_bf16 v[16:31], v[112:115], v[116:119], v[16:31]
	v_mfma_f32_32x32x16_bf16 v[0:15], v[112:115], v[194:197], v[0:15]
	ds_read_b128 v[112:115], v164 offset:55328
	ds_read_b128 v[116:119], v165 offset:36896
	ds_read_b128 v[194:197], v165 offset:41504
	s_waitcnt lgkmcnt(1)
	v_mfma_f32_32x32x16_bf16 v[48:63], v[112:115], v[116:119], v[48:63]
	s_waitcnt lgkmcnt(0)
	v_mfma_f32_32x32x16_bf16 v[32:47], v[112:115], v[194:197], v[32:47]
	ds_read_b128 v[112:115], v164 offset:59936
	ds_write_b128 v134, v[120:123]
	ds_write_b128 v134, v[124:127] offset:18432
	s_waitcnt lgkmcnt(2)
	v_mfma_f32_32x32x16_bf16 v[16:31], v[112:115], v[116:119], v[16:31]
	v_mfma_f32_32x32x16_bf16 v[0:15], v[112:115], v[194:197], v[0:15]
	ds_read_b128 v[112:115], v164 offset:55360
	ds_read_b128 v[116:119], v165 offset:36928
	ds_read_b128 v[120:123], v165 offset:41536
	s_waitcnt lgkmcnt(1)
	v_mfma_f32_32x32x16_bf16 v[48:63], v[112:115], v[116:119], v[48:63]
	s_waitcnt lgkmcnt(0)
	v_mfma_f32_32x32x16_bf16 v[32:47], v[112:115], v[120:123], v[32:47]
	ds_read_b128 v[112:115], v164 offset:59968
	ds_write_b128 v134, v[96:99] offset:4608
	ds_write_b128 v134, v[100:103] offset:23040
	ds_read_b128 v[96:99], v164 offset:55392
	ds_read_b128 v[100:103], v165 offset:36960
	s_waitcnt lgkmcnt(4)
	v_mfma_f32_32x32x16_bf16 v[0:15], v[112:115], v[120:123], v[0:15]
	ds_read_b128 v[120:123], v165 offset:41568
	s_waitcnt lgkmcnt(1)
	v_mfma_f32_32x32x16_bf16 v[48:63], v[96:99], v[100:103], v[48:63]
	s_waitcnt lgkmcnt(0)
	v_mfma_f32_32x32x16_bf16 v[32:47], v[96:99], v[120:123], v[32:47]
	ds_read_b128 v[96:99], v164 offset:60000
	v_mfma_f32_32x32x16_bf16 v[16:31], v[112:115], v[116:119], v[16:31]
	global_load_dwordx4 v[124:127], v[154:155], off offset:768
	global_load_dwordx4 v[194:197], v[142:143], off offset:512
	global_load_dwordx4 v[112:115], v[156:157], off offset:768
	global_load_dwordx4 v[116:119], v[148:149], off offset:512
	ds_write_b128 v134, v[72:75] offset:9216
	ds_write_b128 v134, v[76:79] offset:27648
	global_load_dwordx4 v[72:75], v[158:159], off offset:768
	global_load_dwordx4 v[76:79], v[144:145], off offset:512
	ds_write_b128 v134, v[64:67] offset:13824
	ds_write_b128 v134, v[68:71] offset:32256
	global_load_dwordx4 v[64:67], v[160:161], off offset:768
	global_load_dwordx4 v[68:71], v[146:147], off offset:512
	s_waitcnt lgkmcnt(0)
	s_barrier
	v_mfma_f32_32x32x16_bf16 v[16:31], v[96:99], v[100:103], v[16:31]
	v_mfma_f32_32x32x16_bf16 v[0:15], v[96:99], v[120:123], v[0:15]
	ds_read_b128 v[96:99], v128 offset:18432
	ds_read_b128 v[100:103], v165
	ds_read_b128 v[120:123], v165 offset:4608
	s_waitcnt lgkmcnt(1)
	v_mfma_f32_32x32x16_bf16 v[48:63], v[96:99], v[100:103], v[48:63]
	s_waitcnt lgkmcnt(0)
	v_mfma_f32_32x32x16_bf16 v[32:47], v[96:99], v[120:123], v[32:47]
	ds_read_b128 v[96:99], v128 offset:23040
	s_waitcnt lgkmcnt(0)
	v_mfma_f32_32x32x16_bf16 v[16:31], v[96:99], v[100:103], v[16:31]
	v_mfma_f32_32x32x16_bf16 v[0:15], v[96:99], v[120:123], v[0:15]
	ds_read_b128 v[96:99], v164 offset:18464
	ds_read_b128 v[100:103], v165 offset:32
	ds_read_b128 v[120:123], v165 offset:4640
	s_waitcnt lgkmcnt(1)
	v_mfma_f32_32x32x16_bf16 v[48:63], v[96:99], v[100:103], v[48:63]
	s_waitcnt lgkmcnt(0)
	v_mfma_f32_32x32x16_bf16 v[32:47], v[96:99], v[120:123], v[32:47]
	ds_read_b128 v[96:99], v164 offset:23072
	s_waitcnt vmcnt(15)
	ds_write_b128 v134, v[204:207] offset:36864
	s_waitcnt vmcnt(14)
	ds_write_b128 v134, v[208:211] offset:55296
	s_waitcnt lgkmcnt(2)
	v_mfma_f32_32x32x16_bf16 v[16:31], v[96:99], v[100:103], v[16:31]
	v_mfma_f32_32x32x16_bf16 v[0:15], v[96:99], v[120:123], v[0:15]
	ds_read_b128 v[96:99], v164 offset:18496
	ds_read_b128 v[100:103], v165 offset:64
	ds_read_b128 v[120:123], v165 offset:4672
	s_waitcnt lgkmcnt(1)
	v_mfma_f32_32x32x16_bf16 v[48:63], v[96:99], v[100:103], v[48:63]
	s_waitcnt lgkmcnt(0)
	v_mfma_f32_32x32x16_bf16 v[32:47], v[96:99], v[120:123], v[32:47]
	ds_read_b128 v[96:99], v164 offset:23104
	s_waitcnt vmcnt(13)
	ds_write_b128 v134, v[104:107] offset:41472
	s_waitcnt vmcnt(12)
	ds_write_b128 v134, v[108:111] offset:59904
	s_waitcnt lgkmcnt(2)
	v_mfma_f32_32x32x16_bf16 v[16:31], v[96:99], v[100:103], v[16:31]
	v_mfma_f32_32x32x16_bf16 v[0:15], v[96:99], v[120:123], v[0:15]
	ds_read_b128 v[96:99], v164 offset:18528
	ds_read_b128 v[100:103], v165 offset:96
	ds_read_b128 v[120:123], v165 offset:4704
	ds_read_b128 v[200:203], v164 offset:23136
	global_load_dwordx4 v[204:207], v[154:155], off offset:960
	global_load_dwordx4 v[208:211], v[142:143], off offset:640
	global_load_dwordx4 v[104:107], v[156:157], off offset:960
	global_load_dwordx4 v[108:111], v[148:149], off offset:640
	s_waitcnt vmcnt(15)
	ds_write_b128 v134, v[80:83] offset:46080
	s_waitcnt vmcnt(14)
	ds_write_b128 v134, v[84:87] offset:64512
	s_waitcnt lgkmcnt(4)
	v_mfma_f32_32x32x16_bf16 v[48:63], v[96:99], v[100:103], v[48:63]
	s_waitcnt lgkmcnt(3)
	v_mfma_f32_32x32x16_bf16 v[32:47], v[96:99], v[120:123], v[32:47]
	s_waitcnt lgkmcnt(2)
	v_mfma_f32_32x32x16_bf16 v[16:31], v[200:203], v[100:103], v[16:31]
	global_load_dwordx4 v[96:99], v[158:159], off offset:960
	global_load_dwordx4 v[100:103], v[144:145], off offset:640
	s_waitcnt vmcnt(15)
	ds_write_b128 v134, v[88:91] offset:50688
	s_waitcnt vmcnt(14)
	ds_write_b128 v135, v[92:95] offset:13824
	global_load_dwordx4 v[88:91], v[160:161], off offset:960
	global_load_dwordx4 v[92:95], v[146:147], off offset:640
	s_waitcnt lgkmcnt(0)
	s_barrier
; #define GLOADQ(RA, RB, KT, q) do { const int k0_ = (KT) << 6; \
;     RA[q] = ldg16(ap.ptr(m0 + lrow + 32 * (q), k0_) + lkc); RB[q] = ldg16(W + (size_t)(n0 + lrow + 32 * (q)) * ldw + k0_ + lkc); } while (0)
; #define SSTOREQ(RA, RB, ST, q) do { \
;     *(u32x4*)(sA + (ST) * SBUF + (lrow + 32 * (q)) * GP + lkc) = RA[q]; *(u32x4*)(sB + (ST) * SBUF + (lrow + 32 * (q)) * GP + lkc) = RB[q]; } while (0)
; #define FLOAD(F, ST, ks) do { _Pragma("unroll") for (int a = 0; a < 2; ++a) { \
;     F[a] = *(const bf16x8*)(sB + (ST) * SBUF + (wn * 64 + a * 32 + r) * GP + (ks) * 16 + h * 8); \
;     F[2 + a] = *(const bf16x8*)(sA + (ST) * SBUF + (wm * 64 + a * 32 + r) * GP + (ks) * 16 + h * 8); } } while (0)
; #define FMMA(F) do { _Pragma("unroll") for (int a = 0; a < 2; ++a) _Pragma("unroll") for (int b = 0; b < 2; ++b) acc[a][b] = MFMA(F[a], F[2 + b], acc[a][b]); } while (0)
; template <bool MIDK, class AP, class EPI>
; DI void gemm_tile(const AP& ap, const u16* __restrict__ W, int ldw, int K, int m0, int n0, const EPI& epi, char* smem, float r0, float r1, int tid, bool dry) {
;     ...
;   for (int kt = 0; kt < nk; kt += 2) {
;     const bool l3 = kt + 3 < nk, s2 = kt + 2 < nk, l4 = kt + 4 < nk;
;     FLOAD(f0, 0, 0); FLOAD(f1, 0, 1);
;     FMMA(f0); SSTOREQ(ra1, rb1, 1, 0); if (l3) GLOADQ(ra1, rb1, kt + 3, 0);
;     FLOAD(f0, 0, 2);
;     FMMA(f1); SSTOREQ(ra1, rb1, 1, 1); if (l3) GLOADQ(ra1, rb1, kt + 3, 1);
;     FLOAD(f1, 0, 3);
;     FMMA(f0); SSTOREQ(ra1, rb1, 1, 2); if (l3) GLOADQ(ra1, rb1, kt + 3, 2);
;     FMMA(f1); SSTOREQ(ra1, rb1, 1, 3); if (l3) GLOADQ(ra1, rb1, kt + 3, 3);
;     __syncthreads();
;     FLOAD(f0, 1, 0); FLOAD(f1, 1, 1);
;     FMMA(f0); if (s2) SSTOREQ(ra0, rb0, 0, 0); if (l4) GLOADQ(ra0, rb0, kt + 4, 0);
;     FLOAD(f0, 1, 2);
;     FMMA(f1); if (s2) SSTOREQ(ra0, rb0, 0, 1); if (l4) GLOADQ(ra0, rb0, kt + 4, 1);
;     FLOAD(f1, 1, 3);
;     FMMA(f0); if (s2) SSTOREQ(ra0, rb0, 0, 2); if (l4) GLOADQ(ra0, rb0, kt + 4, 2);
;     FMMA(f1); if (s2) SSTOREQ(ra0, rb0, 0, 3); if (l4) GLOADQ(ra0, rb0, kt + 4, 3);
	ds_read_b128 v[80:83], v128 offset:55296
	ds_read_b128 v[84:87], v165 offset:36864
	v_mfma_f32_32x32x16_bf16 v[0:15], v[200:203], v[120:123], v[0:15]
	ds_read_b128 v[120:123], v165 offset:41472
	s_waitcnt lgkmcnt(1)
	v_mfma_f32_32x32x16_bf16 v[48:63], v[80:83], v[84:87], v[48:63]
	s_waitcnt lgkmcnt(0)
	v_mfma_f32_32x32x16_bf16 v[32:47], v[80:83], v[120:123], v[32:47]
	ds_read_b128 v[80:83], v128 offset:59904
	s_waitcnt lgkmcnt(0)
	v_mfma_f32_32x32x16_bf16 v[16:31], v[80:83], v[84:87], v[16:31]
	v_mfma_f32_32x32x16_bf16 v[0:15], v[80:83], v[120:123], v[0:15]
	ds_read_b128 v[80:83], v164 offset:55328
	ds_read_b128 v[84:87], v165 offset:36896
	ds_read_b128 v[120:123], v165 offset:41504
	s_waitcnt lgkmcnt(1)
	v_mfma_f32_32x32x16_bf16 v[48:63], v[80:83], v[84:87], v[48:63]
	s_waitcnt lgkmcnt(0)
	v_mfma_f32_32x32x16_bf16 v[32:47], v[80:83], v[120:123], v[32:47]
	ds_read_b128 v[80:83], v164 offset:59936
	s_waitcnt vmcnt(15)
	ds_write_b128 v134, v[124:127]
	s_waitcnt vmcnt(14)
	ds_write_b128 v134, v[194:197] offset:18432
	s_waitcnt lgkmcnt(2)
	v_mfma_f32_32x32x16_bf16 v[16:31], v[80:83], v[84:87], v[16:31]
	v_mfma_f32_32x32x16_bf16 v[0:15], v[80:83], v[120:123], v[0:15]
	ds_read_b128 v[80:83], v164 offset:55360
	ds_read_b128 v[84:87], v165 offset:36928
	ds_read_b128 v[120:123], v165 offset:41536
	s_waitcnt lgkmcnt(1)
	v_mfma_f32_32x32x16_bf16 v[48:63], v[80:83], v[84:87], v[48:63]
	s_waitcnt lgkmcnt(0)
	v_mfma_f32_32x32x16_bf16 v[32:47], v[80:83], v[120:123], v[32:47]
	ds_read_b128 v[80:83], v164 offset:59968
	s_waitcnt vmcnt(13)
	ds_write_b128 v134, v[112:115] offset:4608
	s_waitcnt vmcnt(12)
	ds_write_b128 v134, v[116:119] offset:23040
	s_waitcnt lgkmcnt(2)
	v_mfma_f32_32x32x16_bf16 v[16:31], v[80:83], v[84:87], v[16:31]
	v_mfma_f32_32x32x16_bf16 v[0:15], v[80:83], v[120:123], v[0:15]
	ds_read_b128 v[80:83], v164 offset:55392
	ds_read_b128 v[84:87], v165 offset:36960
	ds_read_b128 v[112:115], v165 offset:41568
	s_waitcnt lgkmcnt(1)
	v_mfma_f32_32x32x16_bf16 v[48:63], v[80:83], v[84:87], v[48:63]
	s_waitcnt lgkmcnt(0)
	v_mfma_f32_32x32x16_bf16 v[32:47], v[80:83], v[112:115], v[32:47]
	ds_read_b128 v[80:83], v164 offset:60000
	global_load_dwordx4 v[194:197], v[154:155], off offset:1152
	global_load_dwordx4 v[200:203], v[142:143], off offset:768
	global_load_dwordx4 v[120:123], v[156:157], off offset:1152
	global_load_dwordx4 v[124:127], v[148:149], off offset:768
	s_waitcnt vmcnt(15)
	ds_write_b128 v134, v[72:75] offset:9216
	s_waitcnt vmcnt(14)
	ds_write_b128 v134, v[76:79] offset:27648
	global_load_dwordx4 v[72:75], v[158:159], off offset:1152
	global_load_dwordx4 v[76:79], v[144:145], off offset:768
	s_waitcnt vmcnt(15)
	ds_write_b128 v134, v[64:67] offset:13824
	s_waitcnt vmcnt(14)
	ds_write_b128 v134, v[68:71] offset:32256
	s_waitcnt lgkmcnt(4)
	v_mfma_f32_32x32x16_bf16 v[16:31], v[80:83], v[84:87], v[16:31]
	v_mfma_f32_32x32x16_bf16 v[0:15], v[80:83], v[112:115], v[0:15]
	global_load_dwordx4 v[80:83], v[160:161], off offset:1152
	global_load_dwordx4 v[84:87], v[146:147], off offset:768
	s_waitcnt lgkmcnt(0)
	s_barrier
	ds_read_b128 v[64:67], v128 offset:18432
	ds_read_b128 v[68:71], v165
	ds_read_b128 v[112:115], v165 offset:4608
	s_waitcnt lgkmcnt(1)
	v_mfma_f32_32x32x16_bf16 v[48:63], v[64:67], v[68:71], v[48:63]
	s_waitcnt lgkmcnt(0)
	v_mfma_f32_32x32x16_bf16 v[32:47], v[64:67], v[112:115], v[32:47]
	ds_read_b128 v[64:67], v128 offset:23040
	s_waitcnt lgkmcnt(0)
	v_mfma_f32_32x32x16_bf16 v[16:31], v[64:67], v[68:71], v[16:31]
	v_mfma_f32_32x32x16_bf16 v[0:15], v[64:67], v[112:115], v[0:15]
	ds_read_b128 v[64:67], v164 offset:18464
	ds_read_b128 v[68:71], v165 offset:32
	ds_read_b128 v[112:115], v165 offset:4640
	s_waitcnt lgkmcnt(1)
	v_mfma_f32_32x32x16_bf16 v[48:63], v[64:67], v[68:71], v[48:63]
	s_waitcnt lgkmcnt(0)
	v_mfma_f32_32x32x16_bf16 v[32:47], v[64:67], v[112:115], v[32:47]
	ds_read_b128 v[64:67], v164 offset:23072
	s_waitcnt vmcnt(15)
	ds_write_b128 v134, v[204:207] offset:36864
	s_waitcnt vmcnt(14)
	ds_write_b128 v134, v[208:211] offset:55296
	s_waitcnt lgkmcnt(2)
	v_mfma_f32_32x32x16_bf16 v[16:31], v[64:67], v[68:71], v[16:31]
	v_mfma_f32_32x32x16_bf16 v[0:15], v[64:67], v[112:115], v[0:15]
	ds_read_b128 v[64:67], v164 offset:18496
	ds_read_b128 v[68:71], v165 offset:64
	ds_read_b128 v[112:115], v165 offset:4672
	s_waitcnt lgkmcnt(1)
	v_mfma_f32_32x32x16_bf16 v[48:63], v[64:67], v[68:71], v[48:63]
	s_waitcnt lgkmcnt(0)
	v_mfma_f32_32x32x16_bf16 v[32:47], v[64:67], v[112:115], v[32:47]
	ds_read_b128 v[64:67], v164 offset:23104
	s_waitcnt vmcnt(13)
	ds_write_b128 v134, v[104:107] offset:41472
	s_waitcnt vmcnt(12)
	ds_write_b128 v134, v[108:111] offset:59904
	s_waitcnt lgkmcnt(2)
	v_mfma_f32_32x32x16_bf16 v[16:31], v[64:67], v[68:71], v[16:31]
	v_mfma_f32_32x32x16_bf16 v[0:15], v[64:67], v[112:115], v[0:15]
	ds_read_b128 v[64:67], v164 offset:18528
	ds_read_b128 v[68:71], v165 offset:96
	ds_read_b128 v[104:107], v165 offset:4704
	ds_read_b128 v[112:115], v164 offset:23136
	global_load_dwordx4 v[204:207], v[154:155], off offset:1344
	global_load_dwordx4 v[208:211], v[142:143], off offset:896
	global_load_dwordx4 v[108:111], v[156:157], off offset:1344
	global_load_dwordx4 v[116:119], v[148:149], off offset:896
	s_waitcnt vmcnt(15)
	ds_write_b128 v134, v[96:99] offset:46080
	s_waitcnt vmcnt(14)
	ds_write_b128 v134, v[100:103] offset:64512
	s_waitcnt lgkmcnt(4)
	v_mfma_f32_32x32x16_bf16 v[48:63], v[64:67], v[68:71], v[48:63]
	s_waitcnt lgkmcnt(3)
	v_mfma_f32_32x32x16_bf16 v[32:47], v[64:67], v[104:107], v[32:47]
	s_waitcnt lgkmcnt(2)
	v_mfma_f32_32x32x16_bf16 v[16:31], v[112:115], v[68:71], v[16:31]
	global_load_dwordx4 v[64:67], v[158:159], off offset:1344
	global_load_dwordx4 v[68:71], v[144:145], off offset:896
	s_waitcnt vmcnt(15)
	ds_write_b128 v134, v[88:91] offset:50688
	s_waitcnt vmcnt(14)
	ds_write_b128 v135, v[92:95] offset:13824
	v_lshlrev_b64 v[158:159], 10, v[150:151]
	v_lshl_add_u64 v[158:159], v[140:141], 0, v[158:159]
	v_mfma_f32_32x32x16_bf16 v[0:15], v[112:115], v[104:107], v[0:15]
	global_load_dwordx4 v[104:107], v[160:161], off offset:1344
	global_load_dwordx4 v[112:115], v[146:147], off offset:896
	s_waitcnt lgkmcnt(0)
	s_barrier
; #define GLOADQ(RA, RB, KT, q) do { const int k0_ = (KT) << 6; \
;     RA[q] = ldg16(ap.ptr(m0 + lrow + 32 * (q), k0_) + lkc); RB[q] = ldg16(W + (size_t)(n0 + lrow + 32 * (q)) * ldw + k0_ + lkc); } while (0)
; #define SSTOREQ(RA, RB, ST, q) do { \
;     *(u32x4*)(sA + (ST) * SBUF + (lrow + 32 * (q)) * GP + lkc) = RA[q]; *(u32x4*)(sB + (ST) * SBUF + (lrow + 32 * (q)) * GP + lkc) = RB[q]; } while (0)
; #define FLOAD(F, ST, ks) do { _Pragma("unroll") for (int a = 0; a < 2; ++a) { \
;     F[a] = *(const bf16x8*)(sB + (ST) * SBUF + (wn * 64 + a * 32 + r) * GP + (ks) * 16 + h * 8); \
;     F[2 + a] = *(const bf16x8*)(sA + (ST) * SBUF + (wm * 64 + a * 32 + r) * GP + (ks) * 16 + h * 8); } } while (0)
; #define FMMA(F) do { _Pragma("unroll") for (int a = 0; a < 2; ++a) _Pragma("unroll") for (int b = 0; b < 2; ++b) acc[a][b] = MFMA(F[a], F[2 + b], acc[a][b]); } while (0)
; template <bool MIDK, class AP, class EPI>
; DI void gemm_tile(const AP& ap, const u16* __restrict__ W, int ldw, int K, int m0, int n0, const EPI& epi, char* smem, float r0, float r1, int tid, bool dry) {
;     ...
;   for (int kt = 0; kt < nk; kt += 2) {
;     const bool l3 = kt + 3 < nk, s2 = kt + 2 < nk, l4 = kt + 4 < nk;
;     FLOAD(f0, 0, 0); FLOAD(f1, 0, 1);
;     FMMA(f0); SSTOREQ(ra1, rb1, 1, 0); if (l3) GLOADQ(ra1, rb1, kt + 3, 0);
;     FLOAD(f0, 0, 2);
;     FMMA(f1); SSTOREQ(ra1, rb1, 1, 1); if (l3) GLOADQ(ra1, rb1, kt + 3, 1);
;     FLOAD(f1, 0, 3);
;     FMMA(f0); SSTOREQ(ra1, rb1, 1, 2); if (l3) GLOADQ(ra1, rb1, kt + 3, 2);
;     FMMA(f1); SSTOREQ(ra1, rb1, 1, 3); if (l3) GLOADQ(ra1, rb1, kt + 3, 3);
;     __syncthreads();
;     FLOAD(f0, 1, 0); FLOAD(f1, 1, 1);
;     FMMA(f0); if (s2) SSTOREQ(ra0, rb0, 0, 0); if (l4) GLOADQ(ra0, rb0, kt + 4, 0);
;     FLOAD(f0, 1, 2);
;     FMMA(f1); if (s2) SSTOREQ(ra0, rb0, 0, 1); if (l4) GLOADQ(ra0, rb0, kt + 4, 1);
;     FLOAD(f1, 1, 3);
;     FMMA(f0); if (s2) SSTOREQ(ra0, rb0, 0, 2); if (l4) GLOADQ(ra0, rb0, kt + 4, 2);
;     FMMA(f1); if (s2) SSTOREQ(ra0, rb0, 0, 3); if (l4) GLOADQ(ra0, rb0, kt + 4, 3);
	ds_read_b128 v[88:91], v128 offset:55296
	ds_read_b128 v[92:95], v165 offset:36864
	ds_read_b128 v[96:99], v165 offset:41472
	v_lshlrev_b64 v[160:161], 10, v[152:153]
	s_waitcnt lgkmcnt(1)
	v_mfma_f32_32x32x16_bf16 v[48:63], v[88:91], v[92:95], v[48:63]
	v_lshl_add_u64 v[160:161], v[140:141], 0, v[160:161]
	s_waitcnt lgkmcnt(0)
	v_mfma_f32_32x32x16_bf16 v[32:47], v[88:91], v[96:99], v[32:47]
	ds_read_b128 v[88:91], v128 offset:59904
	s_waitcnt lgkmcnt(0)
	v_mfma_f32_32x32x16_bf16 v[16:31], v[88:91], v[92:95], v[16:31]
	v_mfma_f32_32x32x16_bf16 v[0:15], v[88:91], v[96:99], v[0:15]
	ds_read_b128 v[88:91], v164 offset:55328
	ds_read_b128 v[92:95], v165 offset:36896
	ds_read_b128 v[96:99], v165 offset:41504
	s_waitcnt lgkmcnt(1)
	v_mfma_f32_32x32x16_bf16 v[48:63], v[88:91], v[92:95], v[48:63]
	s_waitcnt lgkmcnt(0)
	v_mfma_f32_32x32x16_bf16 v[32:47], v[88:91], v[96:99], v[32:47]
	ds_read_b128 v[88:91], v164 offset:59936
	s_waitcnt vmcnt(15)
	ds_write_b128 v134, v[194:197]
	s_waitcnt vmcnt(14)
	ds_write_b128 v134, v[200:203] offset:18432
	s_waitcnt lgkmcnt(2)
	v_mfma_f32_32x32x16_bf16 v[16:31], v[88:91], v[92:95], v[16:31]
	v_mfma_f32_32x32x16_bf16 v[0:15], v[88:91], v[96:99], v[0:15]
	ds_read_b128 v[88:91], v164 offset:55360
	ds_read_b128 v[92:95], v165 offset:36928
	ds_read_b128 v[96:99], v165 offset:41536
	s_waitcnt lgkmcnt(1)
	v_mfma_f32_32x32x16_bf16 v[48:63], v[88:91], v[92:95], v[48:63]
	s_waitcnt lgkmcnt(0)
	v_mfma_f32_32x32x16_bf16 v[32:47], v[88:91], v[96:99], v[32:47]
	ds_read_b128 v[88:91], v164 offset:59968
	s_waitcnt vmcnt(13)
	ds_write_b128 v134, v[120:123] offset:4608
	s_waitcnt vmcnt(12)
	ds_write_b128 v134, v[124:127] offset:23040
	s_waitcnt lgkmcnt(2)
	v_mfma_f32_32x32x16_bf16 v[16:31], v[88:91], v[92:95], v[16:31]
	v_mfma_f32_32x32x16_bf16 v[0:15], v[88:91], v[96:99], v[0:15]
	ds_read_b128 v[88:91], v164 offset:55392
	ds_read_b128 v[92:95], v165 offset:36960
	ds_read_b128 v[96:99], v165 offset:41568
	ds_read_b128 v[100:103], v164 offset:60000
	s_waitcnt lgkmcnt(2)
	v_mfma_f32_32x32x16_bf16 v[48:63], v[88:91], v[92:95], v[48:63]
	s_waitcnt lgkmcnt(1)
	v_mfma_f32_32x32x16_bf16 v[32:47], v[88:91], v[96:99], v[32:47]
	v_lshlrev_b64 v[88:89], 10, v[130:131]
	v_lshlrev_b64 v[90:91], 10, v[132:133]
	v_lshl_add_u64 v[154:155], v[140:141], 0, v[88:89]
	v_lshl_add_u64 v[156:157], v[140:141], 0, v[90:91]
	global_load_dwordx4 v[130:133], v[154:155], off
	global_load_dwordx4 v[120:123], v[156:157], off
	global_load_dwordx4 v[150:153], v[142:143], off offset:1024
	global_load_dwordx4 v[124:127], v[148:149], off offset:1024
	s_waitcnt vmcnt(15)
	ds_write_b128 v134, v[72:75] offset:9216
	s_waitcnt vmcnt(14)
	ds_write_b128 v134, v[76:79] offset:27648
	s_waitcnt vmcnt(13)
	ds_write_b128 v134, v[80:83] offset:13824
	s_waitcnt vmcnt(12)
	ds_write_b128 v134, v[84:87] offset:32256
	s_waitcnt lgkmcnt(4)
	v_mfma_f32_32x32x16_bf16 v[16:31], v[100:103], v[92:95], v[16:31]
	v_mfma_f32_32x32x16_bf16 v[0:15], v[100:103], v[96:99], v[0:15]
	global_load_dwordx4 v[96:99], v[158:159], off
	global_load_dwordx4 v[88:91], v[160:161], off
	global_load_dwordx4 v[100:103], v[144:145], off offset:1024
	global_load_dwordx4 v[92:95], v[146:147], off offset:1024
	s_waitcnt lgkmcnt(0)
	s_barrier
	ds_read_b128 v[72:75], v128 offset:18432
	ds_read_b128 v[76:79], v165
	ds_read_b128 v[80:83], v165 offset:4608
	s_waitcnt lgkmcnt(1)
	v_mfma_f32_32x32x16_bf16 v[48:63], v[72:75], v[76:79], v[48:63]
	s_waitcnt lgkmcnt(0)
	v_mfma_f32_32x32x16_bf16 v[32:47], v[72:75], v[80:83], v[32:47]
	ds_read_b128 v[72:75], v128 offset:23040
	s_waitcnt lgkmcnt(0)
	v_mfma_f32_32x32x16_bf16 v[16:31], v[72:75], v[76:79], v[16:31]
	v_mfma_f32_32x32x16_bf16 v[0:15], v[72:75], v[80:83], v[0:15]
	ds_read_b128 v[72:75], v164 offset:18464
	ds_read_b128 v[76:79], v165 offset:32
	ds_read_b128 v[80:83], v165 offset:4640
	s_waitcnt lgkmcnt(1)
	v_mfma_f32_32x32x16_bf16 v[48:63], v[72:75], v[76:79], v[48:63]
	s_waitcnt lgkmcnt(0)
	v_mfma_f32_32x32x16_bf16 v[32:47], v[72:75], v[80:83], v[32:47]
	ds_read_b128 v[72:75], v164 offset:23072
	s_waitcnt vmcnt(15)
	ds_write_b128 v134, v[204:207] offset:36864
	s_waitcnt vmcnt(14)
	ds_write_b128 v134, v[208:211] offset:55296
	s_waitcnt lgkmcnt(2)
	v_mfma_f32_32x32x16_bf16 v[16:31], v[72:75], v[76:79], v[16:31]
	v_mfma_f32_32x32x16_bf16 v[0:15], v[72:75], v[80:83], v[0:15]
	ds_read_b128 v[72:75], v164 offset:18496
	ds_read_b128 v[76:79], v165 offset:64
	ds_read_b128 v[80:83], v165 offset:4672
	s_waitcnt lgkmcnt(1)
	v_mfma_f32_32x32x16_bf16 v[48:63], v[72:75], v[76:79], v[48:63]
	s_waitcnt lgkmcnt(0)
	v_mfma_f32_32x32x16_bf16 v[32:47], v[72:75], v[80:83], v[32:47]
	ds_read_b128 v[72:75], v164 offset:23104
	s_waitcnt vmcnt(13)
	ds_write_b128 v134, v[108:111] offset:41472
	s_waitcnt vmcnt(12)
	ds_write_b128 v134, v[116:119] offset:59904
	s_waitcnt lgkmcnt(2)
	v_mfma_f32_32x32x16_bf16 v[16:31], v[72:75], v[76:79], v[16:31]
	v_mfma_f32_32x32x16_bf16 v[0:15], v[72:75], v[80:83], v[0:15]
	ds_read_b128 v[72:75], v164 offset:18528
	ds_read_b128 v[76:79], v165 offset:96
	ds_read_b128 v[194:197], v165 offset:4704
	s_waitcnt lgkmcnt(1)
	v_mfma_f32_32x32x16_bf16 v[48:63], v[72:75], v[76:79], v[48:63]
	s_waitcnt lgkmcnt(0)
	v_mfma_f32_32x32x16_bf16 v[32:47], v[72:75], v[194:197], v[32:47]
	ds_read_b128 v[72:75], v164 offset:23136
	global_load_dwordx4 v[108:111], v[154:155], off offset:128
	global_load_dwordx4 v[80:83], v[156:157], off offset:128
	global_load_dwordx4 v[116:119], v[142:143], off offset:1152
	global_load_dwordx4 v[84:87], v[148:149], off offset:1152
	s_waitcnt vmcnt(15)
	ds_write_b128 v134, v[64:67] offset:46080
	s_waitcnt vmcnt(14)
	ds_write_b128 v134, v[68:71] offset:64512
	s_waitcnt vmcnt(13)
	ds_write_b128 v134, v[104:107] offset:50688
	s_waitcnt vmcnt(12)
	ds_write_b128 v135, v[112:115] offset:13824
	s_waitcnt lgkmcnt(4)
	v_mfma_f32_32x32x16_bf16 v[16:31], v[72:75], v[76:79], v[16:31]
	v_mfma_f32_32x32x16_bf16 v[0:15], v[72:75], v[194:197], v[0:15]
	global_load_dwordx4 v[72:75], v[158:159], off offset:128
	global_load_dwordx4 v[64:67], v[160:161], off offset:128
	global_load_dwordx4 v[76:79], v[144:145], off offset:1152
	global_load_dwordx4 v[68:71], v[146:147], off offset:1152
	s_waitcnt lgkmcnt(0)
	s_barrier
; #define GLOADQ(RA, RB, KT, q) do { const int k0_ = (KT) << 6; \
;     RA[q] = ldg16(ap.ptr(m0 + lrow + 32 * (q), k0_) + lkc); RB[q] = ldg16(W + (size_t)(n0 + lrow + 32 * (q)) * ldw + k0_ + lkc); } while (0)
; #define SSTOREQ(RA, RB, ST, q) do { \
;     *(u32x4*)(sA + (ST) * SBUF + (lrow + 32 * (q)) * GP + lkc) = RA[q]; *(u32x4*)(sB + (ST) * SBUF + (lrow + 32 * (q)) * GP + lkc) = RB[q]; } while (0)
; template <bool MIDK, class AP, class EPI>
; DI void gemm_tile(const AP& ap, const u16* __restrict__ W, int ldw, int K, int m0, int n0, const EPI& epi, char* smem, float r0, float r1, int tid, bool dry) {
;     ...
;   for (int kt = 0; kt < nk; kt += 2) {
;     const bool l3 = kt + 3 < nk, s2 = kt + 2 < nk, l4 = kt + 4 < nk;
;     FLOAD(f0, 0, 0); FLOAD(f1, 0, 1);
;     FMMA(f0); SSTOREQ(ra1, rb1, 1, 0); if (l3) GLOADQ(ra1, rb1, kt + 3, 0);
;     FLOAD(f0, 0, 2);
;     FMMA(f1); SSTOREQ(ra1, rb1, 1, 1); if (l3) GLOADQ(ra1, rb1, kt + 3, 1);
;     FLOAD(f1, 0, 3);
;     FMMA(f0); SSTOREQ(ra1, rb1, 1, 2); if (l3) GLOADQ(ra1, rb1, kt + 3, 2);
;     FMMA(f1); SSTOREQ(ra1, rb1, 1, 3); if (l3) GLOADQ(ra1, rb1, kt + 3, 3);
;     __syncthreads();
;     FLOAD(f0, 1, 0); FLOAD(f1, 1, 1);
;     FMMA(f0); if (s2) SSTOREQ(ra0, rb0, 0, 0); if (l4) GLOADQ(ra0, rb0, kt + 4, 0);
;     FLOAD(f0, 1, 2);
;     FMMA(f1); if (s2) SSTOREQ(ra0, rb0, 0, 1); if (l4) GLOADQ(ra0, rb0, kt + 4, 1);
;     FLOAD(f1, 1, 3);
;     FMMA(f0); if (s2) SSTOREQ(ra0, rb0, 0, 2); if (l4) GLOADQ(ra0, rb0, kt + 4, 2);
;     FMMA(f1); if (s2) SSTOREQ(ra0, rb0, 0, 3); if (l4) GLOADQ(ra0, rb0, kt + 4, 3);
; __global__ void __launch_bounds__(256, 2) mega(Params pin) {
;     ...
;         const int g0 = mt * 128 + (wave >> 1) * 64 + r;
;         const float ra0 = rsqrtf(ldgf(ssq + 2 * (size_t)MPAD + g0) * (1.0f / 512.0f) + EPS), rg0 = rsqrtf(ldgf(ssq + 3 * (size_t)MPAD + g0) * (1.0f / 512.0f) + EPS);
;         const float ra1 = rsqrtf(ldgf(ssq + 2 * (size_t)MPAD + g0 + 32) * (1.0f / 512.0f) + EPS), rg1 = rsqrtf(ldgf(ssq + 3 * (size_t)MPAD + g0 + 32) * (1.0f / 512.0f) + EPS);
;         EpiRes e; res_bases(p, mt, layer == 0, e.sb, e.db, e.minrow); e.fin0 = rg0; e.fin1 = rg1;
;         gemm_tile<true>(ap, Wl + WO_OUT, 1024, 1024, mt * 128, nt * 128, e, smem, ra0 / rg0, ra1 / rg1, tid, dry);
	ds_read_b128 v[104:107], v128 offset:55296
	ds_read_b128 v[112:115], v165 offset:36864
	ds_read_b128 v[194:197], v165 offset:41472
	s_waitcnt lgkmcnt(1)
	v_mfma_f32_32x32x16_bf16 v[48:63], v[104:107], v[112:115], v[48:63]
	s_waitcnt lgkmcnt(0)
	v_mfma_f32_32x32x16_bf16 v[32:47], v[104:107], v[194:197], v[32:47]
	ds_read_b128 v[104:107], v128 offset:59904
	s_waitcnt lgkmcnt(0)
	v_mfma_f32_32x32x16_bf16 v[16:31], v[104:107], v[112:115], v[16:31]
	v_mfma_f32_32x32x16_bf16 v[0:15], v[104:107], v[194:197], v[0:15]
	ds_read_b128 v[104:107], v164 offset:55328
	ds_read_b128 v[112:115], v165 offset:36896
	ds_read_b128 v[194:197], v165 offset:41504
	ds_read_b128 v[200:203], v164 offset:59936
	s_waitcnt vmcnt(15)
	ds_write_b128 v134, v[130:133]
	s_waitcnt vmcnt(13)
	ds_write_b128 v134, v[150:153] offset:18432
	v_mul_f32_e32 v130, 0x4b800000, v187
	v_cndmask_b32_e64 v130, v187, v130, s[2:3]
	v_rsq_f32_e32 v150, v130
	v_cndmask_b32_e32 v151, v192, v198, vcc
	s_waitcnt lgkmcnt(4)
	v_mfma_f32_32x32x16_bf16 v[48:63], v[104:107], v[112:115], v[48:63]
	v_mul_f32_e32 v153, 0x45800000, v150
	v_cndmask_b32_e64 v153, v150, v153, s[2:3]
	v_fmamk_f32 v150, v186, 0x3b000000, v224
	v_mul_f32_e32 v186, 0x4b800000, v150
	v_cmp_gt_f32_e32 vcc, s5, v150
	s_waitcnt lgkmcnt(3)
	v_mfma_f32_32x32x16_bf16 v[32:47], v[104:107], v[194:197], v[32:47]
	v_fmamk_f32 v104, v188, 0x3b000000, v224
	v_mul_f32_e32 v105, 0x4b800000, v104
	v_cmp_gt_f32_e64 s[0:1], s5, v104
	s_nop 1
	v_cndmask_b32_e64 v104, v104, v105, s[0:1]
	v_rsq_f32_e32 v204, v104
	ds_read_b128 v[104:107], v164 offset:55360
	s_waitcnt lgkmcnt(3)
	v_mfma_f32_32x32x16_bf16 v[16:31], v[200:203], v[112:115], v[16:31]
	ds_read_b128 v[112:115], v165 offset:36928
	ds_read_b128 v[130:133], v164 offset:59968
	ds_read_b128 v[188:191], v165 offset:41536
	v_mul_f32_e32 v152, 0x45800000, v204
	v_cndmask_b32_e64 v152, v204, v152, s[0:1]
	ds_write_b128 v134, v[120:123] offset:4608
	s_waitcnt vmcnt(12)
	ds_write_b128 v134, v[124:127] offset:23040
	s_waitcnt lgkmcnt(4)
	v_mfma_f32_32x32x16_bf16 v[48:63], v[104:107], v[112:115], v[48:63]
	s_waitcnt lgkmcnt(2)
	v_mfma_f32_32x32x16_bf16 v[32:47], v[104:107], v[188:191], v[32:47]
	v_cndmask_b32_e32 v104, v150, v186, vcc
	v_rsq_f32_e32 v104, v104
	v_div_scale_f32 v186, s[0:1], v152, v152, v151
	v_rcp_f32_e32 v192, v186
	v_mul_f32_e32 v105, 0x45800000, v104
	v_cndmask_b32_e32 v150, v104, v105, vcc
	v_mfma_f32_32x32x16_bf16 v[0:15], v[200:203], v[194:197], v[0:15]
	v_fma_f32 v104, -v186, v192, 1.0
	v_fmac_f32_e32 v192, v104, v192
	v_div_scale_f32 v187, vcc, v151, v152, v151
	ds_read_b128 v[104:107], v164 offset:55392
	v_mul_f32_e32 v120, v187, v192
	v_fma_f32 v121, -v186, v120, v187
	v_fmac_f32_e32 v120, v121, v192
	v_div_scale_f32 v122, s[0:1], v150, v150, v153
	v_mfma_f32_32x32x16_bf16 v[16:31], v[130:133], v[112:115], v[16:31]
	ds_read_b128 v[112:115], v165 offset:36960
	v_fma_f32 v121, -v186, v120, v187
	v_rcp_f32_e32 v123, v122
	v_div_fmas_f32 v120, v121, v192, v120
	v_mfma_f32_32x32x16_bf16 v[0:15], v[130:133], v[188:191], v[0:15]
	ds_read_b128 v[130:133], v164 offset:60000
	ds_read_b128 v[186:189], v165 offset:41568
	v_div_fixup_f32 v190, v120, v152, v151
	v_fma_f32 v120, -v122, v123, 1.0
	v_fmac_f32_e32 v123, v120, v123
	s_waitcnt lgkmcnt(2)
	v_mfma_f32_32x32x16_bf16 v[48:63], v[104:107], v[112:115], v[48:63]
	s_waitcnt lgkmcnt(0)
	v_mfma_f32_32x32x16_bf16 v[32:47], v[104:107], v[186:189], v[32:47]
	v_div_scale_f32 v104, vcc, v153, v150, v153
	v_mul_f32_e32 v105, v104, v123
	v_fma_f32 v106, -v122, v105, v104
	v_fmac_f32_e32 v105, v106, v123
	v_fma_f32 v104, -v122, v105, v104
	v_div_fmas_f32 v104, v104, v123, v105
	v_mfma_f32_32x32x16_bf16 v[16:31], v[130:133], v[112:115], v[16:31]
	v_div_fixup_f32 v192, v104, v150, v153
	global_load_dwordx4 v[120:123], v[154:155], off offset:256
	global_load_dwordx4 v[104:107], v[156:157], off offset:256
	global_load_dwordx4 v[124:127], v[142:143], off offset:1280
	global_load_dwordx4 v[112:115], v[148:149], off offset:1280
	s_waitcnt vmcnt(15)
	ds_write_b128 v134, v[96:99] offset:9216
	s_waitcnt vmcnt(13)
	ds_write_b128 v134, v[100:103] offset:27648
	ds_write_b128 v134, v[88:91] offset:13824
	s_waitcnt vmcnt(12)
	ds_write_b128 v134, v[92:95] offset:32256
	global_load_dwordx4 v[96:99], v[158:159], off offset:256
	global_load_dwordx4 v[88:91], v[160:161], off offset:256
	global_load_dwordx4 v[100:103], v[144:145], off offset:1280
	global_load_dwordx4 v[92:95], v[146:147], off offset:1280
	s_waitcnt lgkmcnt(0)
	s_barrier
; #define GLOADQ(RA, RB, KT, q) do { const int k0_ = (KT) << 6; \
;     RA[q] = ldg16(ap.ptr(m0 + lrow + 32 * (q), k0_) + lkc); RB[q] = ldg16(W + (size_t)(n0 + lrow + 32 * (q)) * ldw + k0_ + lkc); } while (0)
; #define SSTOREQ(RA, RB, ST, q) do { \
;     *(u32x4*)(sA + (ST) * SBUF + (lrow + 32 * (q)) * GP + lkc) = RA[q]; *(u32x4*)(sB + (ST) * SBUF + (lrow + 32 * (q)) * GP + lkc) = RB[q]; } while (0)
; #define FLOAD(F, ST, ks) do { _Pragma("unroll") for (int a = 0; a < 2; ++a) { \
;     F[a] = *(const bf16x8*)(sB + (ST) * SBUF + (wn * 64 + a * 32 + r) * GP + (ks) * 16 + h * 8); \
;     F[2 + a] = *(const bf16x8*)(sA + (ST) * SBUF + (wm * 64 + a * 32 + r) * GP + (ks) * 16 + h * 8); } } while (0)
; #define FMMA(F) do { _Pragma("unroll") for (int a = 0; a < 2; ++a) _Pragma("unroll") for (int b = 0; b < 2; ++b) acc[a][b] = MFMA(F[a], F[2 + b], acc[a][b]); } while (0)
; template <bool MIDK, class AP, class EPI>
; DI void gemm_tile(const AP& ap, const u16* __restrict__ W, int ldw, int K, int m0, int n0, const EPI& epi, char* smem, float r0, float r1, int tid, bool dry) {
;     ...
;   for (int kt = 0; kt < nk; kt += 2) {
;     const bool l3 = kt + 3 < nk, s2 = kt + 2 < nk, l4 = kt + 4 < nk;
;     FLOAD(f0, 0, 0); FLOAD(f1, 0, 1);
;     FMMA(f0); SSTOREQ(ra1, rb1, 1, 0); if (l3) GLOADQ(ra1, rb1, kt + 3, 0);
;     FLOAD(f0, 0, 2);
;     FMMA(f1); SSTOREQ(ra1, rb1, 1, 1); if (l3) GLOADQ(ra1, rb1, kt + 3, 1);
;     FLOAD(f1, 0, 3);
;     FMMA(f0); SSTOREQ(ra1, rb1, 1, 2); if (l3) GLOADQ(ra1, rb1, kt + 3, 2);
;     FMMA(f1); SSTOREQ(ra1, rb1, 1, 3); if (l3) GLOADQ(ra1, rb1, kt + 3, 3);
;     __syncthreads();
;     FLOAD(f0, 1, 0); FLOAD(f1, 1, 1);
;     FMMA(f0); if (s2) SSTOREQ(ra0, rb0, 0, 0); if (l4) GLOADQ(ra0, rb0, kt + 4, 0);
;     FLOAD(f0, 1, 2);
;     FMMA(f1); if (s2) SSTOREQ(ra0, rb0, 0, 1); if (l4) GLOADQ(ra0, rb0, kt + 4, 1);
;     FLOAD(f1, 1, 3);
;     FMMA(f0); if (s2) SSTOREQ(ra0, rb0, 0, 2); if (l4) GLOADQ(ra0, rb0, kt + 4, 2);
;     FMMA(f1); if (s2) SSTOREQ(ra0, rb0, 0, 3); if (l4) GLOADQ(ra0, rb0, kt + 4, 3);
;     if (MIDK && kt == 6) {
; #pragma unroll
;       for (int a = 0; a < 2; ++a)
; #pragma unroll
;         for (int i = 0; i < 16; ++i) { acc[a][0][i] *= r0; acc[a][1][i] *= r1; }
;     }
	v_mfma_f32_32x32x16_bf16 v[0:15], v[130:133], v[186:189], v[0:15]
	ds_read_b128 v[130:133], v128 offset:18432
	ds_read_b128 v[194:197], v128 offset:23040
	ds_read_b128 v[186:189], v165
	ds_read_b128 v[200:203], v165 offset:4608
	v_mul_f32_e64 v32, v192, v32
	v_mul_f32_e64 v33, v192, v33
	v_pk_mul_f32 v[46:47], v[192:193], v[46:47] op_sel_hi:[0,1]
	v_pk_mul_f32 v[44:45], v[192:193], v[44:45] op_sel_hi:[0,1]
	v_pk_mul_f32 v[48:49], v[190:191], v[48:49] op_sel_hi:[0,1]
	v_pk_mul_f32 v[62:63], v[190:191], v[62:63] op_sel_hi:[0,1]
	v_pk_mul_f32 v[60:61], v[190:191], v[60:61] op_sel_hi:[0,1]
	v_pk_mul_f32 v[58:59], v[190:191], v[58:59] op_sel_hi:[0,1]
	v_pk_mul_f32 v[56:57], v[190:191], v[56:57] op_sel_hi:[0,1]
	v_pk_mul_f32 v[54:55], v[190:191], v[54:55] op_sel_hi:[0,1]
	v_pk_mul_f32 v[52:53], v[190:191], v[52:53] op_sel_hi:[0,1]
	v_pk_mul_f32 v[50:51], v[190:191], v[50:51] op_sel_hi:[0,1]
	v_pk_mul_f32 v[42:43], v[192:193], v[42:43] op_sel_hi:[0,1]
	v_pk_mul_f32 v[40:41], v[192:193], v[40:41] op_sel_hi:[0,1]
	v_pk_mul_f32 v[38:39], v[192:193], v[38:39] op_sel_hi:[0,1]
	v_pk_mul_f32 v[36:37], v[192:193], v[36:37] op_sel_hi:[0,1]
	v_pk_mul_f32 v[34:35], v[192:193], v[34:35] op_sel_hi:[0,1]
	s_waitcnt lgkmcnt(1)
	v_mfma_f32_32x32x16_bf16 v[48:63], v[130:133], v[186:189], v[48:63]
	v_mul_f32_e64 v0, v192, v0
	v_mul_f32_e64 v1, v192, v1
	v_mul_f32_e64 v16, v190, v16
	v_mul_f32_e64 v17, v190, v17
	v_mul_f32_e64 v30, v190, v30
	v_mul_f32_e64 v31, v190, v31
	v_pk_mul_f32 v[28:29], v[190:191], v[28:29] op_sel_hi:[0,1]
	v_pk_mul_f32 v[26:27], v[190:191], v[26:27] op_sel_hi:[0,1]
	v_pk_mul_f32 v[24:25], v[190:191], v[24:25] op_sel_hi:[0,1]
	v_pk_mul_f32 v[22:23], v[190:191], v[22:23] op_sel_hi:[0,1]
	s_waitcnt lgkmcnt(0)
	v_mfma_f32_32x32x16_bf16 v[32:47], v[130:133], v[200:203], v[32:47]
	v_mul_f32_e64 v20, v190, v20
	v_mul_f32_e64 v21, v190, v21
	v_mul_f32_e64 v18, v190, v18
	v_mul_f32_e64 v19, v190, v19
	v_mul_f32_e64 v14, v192, v14
	v_mul_f32_e64 v15, v192, v15
	v_pk_mul_f32 v[12:13], v[192:193], v[12:13] op_sel_hi:[0,1]
	v_pk_mul_f32 v[10:11], v[192:193], v[10:11] op_sel_hi:[0,1]
	v_pk_mul_f32 v[8:9], v[192:193], v[8:9] op_sel_hi:[0,1]
	v_pk_mul_f32 v[6:7], v[192:193], v[6:7] op_sel_hi:[0,1]
	v_pk_mul_f32 v[4:5], v[192:193], v[4:5] op_sel_hi:[0,1]
	v_pk_mul_f32 v[2:3], v[192:193], v[2:3] op_sel_hi:[0,1]
	v_mfma_f32_32x32x16_bf16 v[16:31], v[194:197], v[186:189], v[16:31]
	ds_read_b128 v[130:133], v164 offset:18464
	ds_read_b128 v[186:189], v165 offset:32
	s_andn2_b64 vcc, exec, s[38:39]
	v_mfma_f32_32x32x16_bf16 v[0:15], v[194:197], v[200:203], v[0:15]
	ds_read_b128 v[194:197], v165 offset:4640
	s_waitcnt lgkmcnt(1)
	v_mfma_f32_32x32x16_bf16 v[48:63], v[130:133], v[186:189], v[48:63]
	s_waitcnt lgkmcnt(0)
	v_mfma_f32_32x32x16_bf16 v[32:47], v[130:133], v[194:197], v[32:47]
	ds_read_b128 v[130:133], v164 offset:23072
	s_waitcnt vmcnt(15)
	ds_write_b128 v134, v[108:111] offset:36864
	s_waitcnt vmcnt(13)
	ds_write_b128 v134, v[116:119] offset:55296
	ds_read_b128 v[108:111], v164 offset:18496
	ds_read_b128 v[116:119], v165 offset:64
	s_waitcnt lgkmcnt(4)
	v_mfma_f32_32x32x16_bf16 v[16:31], v[130:133], v[186:189], v[16:31]
	v_mfma_f32_32x32x16_bf16 v[0:15], v[130:133], v[194:197], v[0:15]
	ds_read_b128 v[130:133], v165 offset:4672
	s_waitcnt lgkmcnt(1)
	v_mfma_f32_32x32x16_bf16 v[48:63], v[108:111], v[116:119], v[48:63]
	s_waitcnt lgkmcnt(0)
	v_mfma_f32_32x32x16_bf16 v[32:47], v[108:111], v[130:133], v[32:47]
	ds_read_b128 v[108:111], v164 offset:23104
	ds_write_b128 v134, v[80:83] offset:41472
	s_waitcnt vmcnt(12)
	ds_write_b128 v134, v[84:87] offset:59904
	ds_read_b128 v[80:83], v164 offset:18528
	ds_read_b128 v[84:87], v165 offset:96
	s_waitcnt lgkmcnt(4)
	v_mfma_f32_32x32x16_bf16 v[16:31], v[108:111], v[116:119], v[16:31]
	v_mfma_f32_32x32x16_bf16 v[0:15], v[108:111], v[130:133], v[0:15]
	ds_read_b128 v[108:111], v165 offset:4704
	s_waitcnt lgkmcnt(1)
	v_mfma_f32_32x32x16_bf16 v[48:63], v[80:83], v[84:87], v[48:63]
	s_waitcnt lgkmcnt(0)
	v_mfma_f32_32x32x16_bf16 v[32:47], v[80:83], v[108:111], v[32:47]
	ds_read_b128 v[80:83], v164 offset:23136
	global_load_dwordx4 v[186:189], v[154:155], off offset:384
	global_load_dwordx4 v[116:119], v[156:157], off offset:384
	global_load_dwordx4 v[194:197], v[142:143], off offset:1408
	global_load_dwordx4 v[130:133], v[148:149], off offset:1408
	s_waitcnt vmcnt(15)
	ds_write_b128 v134, v[72:75] offset:46080
	s_waitcnt vmcnt(13)
	ds_write_b128 v134, v[76:79] offset:64512
	ds_write_b128 v134, v[64:67] offset:50688
	s_waitcnt vmcnt(12)
	ds_write_b128 v135, v[68:71] offset:13824
	s_waitcnt lgkmcnt(4)
	v_mfma_f32_32x32x16_bf16 v[16:31], v[80:83], v[84:87], v[16:31]
	v_mfma_f32_32x32x16_bf16 v[0:15], v[80:83], v[108:111], v[0:15]
	global_load_dwordx4 v[80:83], v[158:159], off offset:384
	global_load_dwordx4 v[64:67], v[160:161], off offset:384
	global_load_dwordx4 v[108:111], v[144:145], off offset:1408
	global_load_dwordx4 v[72:75], v[146:147], off offset:1408
	s_waitcnt lgkmcnt(0)
	s_barrier
; #define GLOADQ(RA, RB, KT, q) do { const int k0_ = (KT) << 6; \
;     RA[q] = ldg16(ap.ptr(m0 + lrow + 32 * (q), k0_) + lkc); RB[q] = ldg16(W + (size_t)(n0 + lrow + 32 * (q)) * ldw + k0_ + lkc); } while (0)
; #define SSTOREQ(RA, RB, ST, q) do { \
;     *(u32x4*)(sA + (ST) * SBUF + (lrow + 32 * (q)) * GP + lkc) = RA[q]; *(u32x4*)(sB + (ST) * SBUF + (lrow + 32 * (q)) * GP + lkc) = RB[q]; } while (0)
; #define FLOAD(F, ST, ks) do { _Pragma("unroll") for (int a = 0; a < 2; ++a) { \
;     F[a] = *(const bf16x8*)(sB + (ST) * SBUF + (wn * 64 + a * 32 + r) * GP + (ks) * 16 + h * 8); \
;     F[2 + a] = *(const bf16x8*)(sA + (ST) * SBUF + (wm * 64 + a * 32 + r) * GP + (ks) * 16 + h * 8); } } while (0)
; #define FMMA(F) do { _Pragma("unroll") for (int a = 0; a < 2; ++a) _Pragma("unroll") for (int b = 0; b < 2; ++b) acc[a][b] = MFMA(F[a], F[2 + b], acc[a][b]); } while (0)
; template <bool MIDK, class AP, class EPI>
; DI void gemm_tile(const AP& ap, const u16* __restrict__ W, int ldw, int K, int m0, int n0, const EPI& epi, char* smem, float r0, float r1, int tid, bool dry) {
;     ...
;   for (int kt = 0; kt < nk; kt += 2) {
;     const bool l3 = kt + 3 < nk, s2 = kt + 2 < nk, l4 = kt + 4 < nk;
;     FLOAD(f0, 0, 0); FLOAD(f1, 0, 1);
;     FMMA(f0); SSTOREQ(ra1, rb1, 1, 0); if (l3) GLOADQ(ra1, rb1, kt + 3, 0);
;     FLOAD(f0, 0, 2);
;     FMMA(f1); SSTOREQ(ra1, rb1, 1, 1); if (l3) GLOADQ(ra1, rb1, kt + 3, 1);
;     FLOAD(f1, 0, 3);
;     FMMA(f0); SSTOREQ(ra1, rb1, 1, 2); if (l3) GLOADQ(ra1, rb1, kt + 3, 2);
;     FMMA(f1); SSTOREQ(ra1, rb1, 1, 3); if (l3) GLOADQ(ra1, rb1, kt + 3, 3);
;     __syncthreads();
;     FLOAD(f0, 1, 0); FLOAD(f1, 1, 1);
;     FMMA(f0); if (s2) SSTOREQ(ra0, rb0, 0, 0); if (l4) GLOADQ(ra0, rb0, kt + 4, 0);
;     FLOAD(f0, 1, 2);
;     FMMA(f1); if (s2) SSTOREQ(ra0, rb0, 0, 1); if (l4) GLOADQ(ra0, rb0, kt + 4, 1);
;     FLOAD(f1, 1, 3);
;     FMMA(f0); if (s2) SSTOREQ(ra0, rb0, 0, 2); if (l4) GLOADQ(ra0, rb0, kt + 4, 2);
;     FMMA(f1); if (s2) SSTOREQ(ra0, rb0, 0, 3); if (l4) GLOADQ(ra0, rb0, kt + 4, 3);
	ds_read_b128 v[68:71], v128 offset:55296
	ds_read_b128 v[76:79], v165 offset:36864
	ds_read_b128 v[84:87], v165 offset:41472
	s_waitcnt lgkmcnt(1)
	v_mfma_f32_32x32x16_bf16 v[48:63], v[68:71], v[76:79], v[48:63]
	s_waitcnt lgkmcnt(0)
	v_mfma_f32_32x32x16_bf16 v[32:47], v[68:71], v[84:87], v[32:47]
	ds_read_b128 v[68:71], v128 offset:59904
	s_waitcnt lgkmcnt(0)
	v_mfma_f32_32x32x16_bf16 v[16:31], v[68:71], v[76:79], v[16:31]
	v_mfma_f32_32x32x16_bf16 v[0:15], v[68:71], v[84:87], v[0:15]
	ds_read_b128 v[68:71], v164 offset:55328
	ds_read_b128 v[76:79], v165 offset:36896
	ds_read_b128 v[84:87], v165 offset:41504
	s_waitcnt lgkmcnt(1)
	v_mfma_f32_32x32x16_bf16 v[48:63], v[68:71], v[76:79], v[48:63]
	s_waitcnt lgkmcnt(0)
	v_mfma_f32_32x32x16_bf16 v[32:47], v[68:71], v[84:87], v[32:47]
	ds_read_b128 v[68:71], v164 offset:59936
	s_waitcnt vmcnt(15)
	ds_write_b128 v134, v[120:123]
	s_waitcnt vmcnt(13)
	ds_write_b128 v134, v[124:127] offset:18432
	s_waitcnt lgkmcnt(2)
	v_mfma_f32_32x32x16_bf16 v[16:31], v[68:71], v[76:79], v[16:31]
	v_mfma_f32_32x32x16_bf16 v[0:15], v[68:71], v[84:87], v[0:15]
	ds_read_b128 v[68:71], v164 offset:55360
	ds_read_b128 v[76:79], v165 offset:36928
	ds_read_b128 v[84:87], v165 offset:41536
	s_waitcnt lgkmcnt(1)
	v_mfma_f32_32x32x16_bf16 v[48:63], v[68:71], v[76:79], v[48:63]
	s_waitcnt lgkmcnt(0)
	v_mfma_f32_32x32x16_bf16 v[32:47], v[68:71], v[84:87], v[32:47]
	ds_read_b128 v[68:71], v164 offset:59968
	ds_write_b128 v134, v[104:107] offset:4608
	s_waitcnt vmcnt(12)
	ds_write_b128 v134, v[112:115] offset:23040
	s_waitcnt lgkmcnt(2)
	v_mfma_f32_32x32x16_bf16 v[16:31], v[68:71], v[76:79], v[16:31]
	v_mfma_f32_32x32x16_bf16 v[0:15], v[68:71], v[84:87], v[0:15]
	ds_read_b128 v[68:71], v164 offset:55392
	ds_read_b128 v[76:79], v165 offset:36960
	ds_read_b128 v[84:87], v165 offset:41568
	s_waitcnt lgkmcnt(1)
	v_mfma_f32_32x32x16_bf16 v[48:63], v[68:71], v[76:79], v[48:63]
	s_waitcnt lgkmcnt(0)
	v_mfma_f32_32x32x16_bf16 v[32:47], v[68:71], v[84:87], v[32:47]
	ds_read_b128 v[68:71], v164 offset:60000
	global_load_dwordx4 v[120:123], v[154:155], off offset:512
	global_load_dwordx4 v[104:107], v[156:157], off offset:512
	global_load_dwordx4 v[124:127], v[142:143], off offset:1536
	global_load_dwordx4 v[112:115], v[148:149], off offset:1536
	s_waitcnt vmcnt(15)
	ds_write_b128 v134, v[96:99] offset:9216
	s_waitcnt vmcnt(13)
	ds_write_b128 v134, v[100:103] offset:27648
	ds_write_b128 v134, v[88:91] offset:13824
	s_waitcnt vmcnt(12)
	ds_write_b128 v134, v[92:95] offset:32256
	s_waitcnt lgkmcnt(4)
	v_mfma_f32_32x32x16_bf16 v[16:31], v[68:71], v[76:79], v[16:31]
	v_mfma_f32_32x32x16_bf16 v[0:15], v[68:71], v[84:87], v[0:15]
	global_load_dwordx4 v[84:87], v[158:159], off offset:512
	global_load_dwordx4 v[68:71], v[160:161], off offset:512
	global_load_dwordx4 v[88:91], v[144:145], off offset:1536
	global_load_dwordx4 v[76:79], v[146:147], off offset:1536
	s_waitcnt lgkmcnt(0)
	s_barrier
	ds_read_b128 v[92:95], v128 offset:18432
	ds_read_b128 v[96:99], v165
	ds_read_b128 v[100:103], v165 offset:4608
	s_waitcnt lgkmcnt(1)
	v_mfma_f32_32x32x16_bf16 v[48:63], v[92:95], v[96:99], v[48:63]
	s_waitcnt lgkmcnt(0)
	v_mfma_f32_32x32x16_bf16 v[32:47], v[92:95], v[100:103], v[32:47]
	ds_read_b128 v[92:95], v128 offset:23040
	s_waitcnt lgkmcnt(0)
	v_mfma_f32_32x32x16_bf16 v[16:31], v[92:95], v[96:99], v[16:31]
	v_mfma_f32_32x32x16_bf16 v[0:15], v[92:95], v[100:103], v[0:15]
	ds_read_b128 v[92:95], v164 offset:18464
	ds_read_b128 v[96:99], v165 offset:32
	ds_read_b128 v[100:103], v165 offset:4640
	s_waitcnt lgkmcnt(1)
	v_mfma_f32_32x32x16_bf16 v[48:63], v[92:95], v[96:99], v[48:63]
	s_waitcnt lgkmcnt(0)
	v_mfma_f32_32x32x16_bf16 v[32:47], v[92:95], v[100:103], v[32:47]
	ds_read_b128 v[92:95], v164 offset:23072
	s_waitcnt vmcnt(15)
	ds_write_b128 v134, v[186:189] offset:36864
	s_waitcnt vmcnt(13)
	ds_write_b128 v134, v[194:197] offset:55296
	s_waitcnt lgkmcnt(2)
	v_mfma_f32_32x32x16_bf16 v[16:31], v[92:95], v[96:99], v[16:31]
	v_mfma_f32_32x32x16_bf16 v[0:15], v[92:95], v[100:103], v[0:15]
	ds_read_b128 v[92:95], v164 offset:18496
	ds_read_b128 v[96:99], v165 offset:64
	ds_read_b128 v[100:103], v165 offset:4672
	s_waitcnt lgkmcnt(1)
	v_mfma_f32_32x32x16_bf16 v[48:63], v[92:95], v[96:99], v[48:63]
	s_waitcnt lgkmcnt(0)
	v_mfma_f32_32x32x16_bf16 v[32:47], v[92:95], v[100:103], v[32:47]
	ds_read_b128 v[92:95], v164 offset:23104
	ds_write_b128 v134, v[116:119] offset:41472
	s_waitcnt vmcnt(12)
	ds_write_b128 v134, v[130:133] offset:59904
	s_waitcnt lgkmcnt(2)
	v_mfma_f32_32x32x16_bf16 v[16:31], v[92:95], v[96:99], v[16:31]
	v_mfma_f32_32x32x16_bf16 v[0:15], v[92:95], v[100:103], v[0:15]
	ds_read_b128 v[92:95], v164 offset:18528
	ds_read_b128 v[96:99], v165 offset:96
	ds_read_b128 v[116:119], v165 offset:4704
	s_waitcnt lgkmcnt(1)
	v_mfma_f32_32x32x16_bf16 v[48:63], v[92:95], v[96:99], v[48:63]
	s_waitcnt lgkmcnt(0)
	v_mfma_f32_32x32x16_bf16 v[32:47], v[92:95], v[116:119], v[32:47]
	ds_read_b128 v[92:95], v164 offset:23136
	s_waitcnt lgkmcnt(0)
	v_mfma_f32_32x32x16_bf16 v[16:31], v[92:95], v[96:99], v[16:31]
	global_load_dwordx4 v[130:133], v[154:155], off offset:640
	global_load_dwordx4 v[96:99], v[156:157], off offset:640
	global_load_dwordx4 v[186:189], v[142:143], off offset:1664
	global_load_dwordx4 v[100:103], v[148:149], off offset:1664
	s_waitcnt vmcnt(15)
	ds_write_b128 v134, v[80:83] offset:46080
	s_waitcnt vmcnt(13)
	ds_write_b128 v134, v[108:111] offset:64512
	ds_write_b128 v134, v[64:67] offset:50688
	s_waitcnt vmcnt(12)
	ds_write_b128 v135, v[72:75] offset:13824
	v_mfma_f32_32x32x16_bf16 v[0:15], v[92:95], v[116:119], v[0:15]
	global_load_dwordx4 v[80:83], v[158:159], off offset:640
	global_load_dwordx4 v[64:67], v[160:161], off offset:640
	global_load_dwordx4 v[92:95], v[144:145], off offset:1664
	global_load_dwordx4 v[72:75], v[146:147], off offset:1664
	s_waitcnt lgkmcnt(0)
	s_barrier
; #define GLOADQ(RA, RB, KT, q) do { const int k0_ = (KT) << 6; \
;     RA[q] = ldg16(ap.ptr(m0 + lrow + 32 * (q), k0_) + lkc); RB[q] = ldg16(W + (size_t)(n0 + lrow + 32 * (q)) * ldw + k0_ + lkc); } while (0)
; #define SSTOREQ(RA, RB, ST, q) do { \
;     *(u32x4*)(sA + (ST) * SBUF + (lrow + 32 * (q)) * GP + lkc) = RA[q]; *(u32x4*)(sB + (ST) * SBUF + (lrow + 32 * (q)) * GP + lkc) = RB[q]; } while (0)
; #define FLOAD(F, ST, ks) do { _Pragma("unroll") for (int a = 0; a < 2; ++a) { \
;     F[a] = *(const bf16x8*)(sB + (ST) * SBUF + (wn * 64 + a * 32 + r) * GP + (ks) * 16 + h * 8); \
;     F[2 + a] = *(const bf16x8*)(sA + (ST) * SBUF + (wm * 64 + a * 32 + r) * GP + (ks) * 16 + h * 8); } } while (0)
; #define FMMA(F) do { _Pragma("unroll") for (int a = 0; a < 2; ++a) _Pragma("unroll") for (int b = 0; b < 2; ++b) acc[a][b] = MFMA(F[a], F[2 + b], acc[a][b]); } while (0)
; template <bool MIDK, class AP, class EPI>
; DI void gemm_tile(const AP& ap, const u16* __restrict__ W, int ldw, int K, int m0, int n0, const EPI& epi, char* smem, float r0, float r1, int tid, bool dry) {
;     ...
;   for (int kt = 0; kt < nk; kt += 2) {
;     const bool l3 = kt + 3 < nk, s2 = kt + 2 < nk, l4 = kt + 4 < nk;
;     FLOAD(f0, 0, 0); FLOAD(f1, 0, 1);
;     FMMA(f0); SSTOREQ(ra1, rb1, 1, 0); if (l3) GLOADQ(ra1, rb1, kt + 3, 0);
;     FLOAD(f0, 0, 2);
;     FMMA(f1); SSTOREQ(ra1, rb1, 1, 1); if (l3) GLOADQ(ra1, rb1, kt + 3, 1);
;     FLOAD(f1, 0, 3);
;     FMMA(f0); SSTOREQ(ra1, rb1, 1, 2); if (l3) GLOADQ(ra1, rb1, kt + 3, 2);
;     FMMA(f1); SSTOREQ(ra1, rb1, 1, 3); if (l3) GLOADQ(ra1, rb1, kt + 3, 3);
;     __syncthreads();
;     FLOAD(f0, 1, 0); FLOAD(f1, 1, 1);
;     FMMA(f0); if (s2) SSTOREQ(ra0, rb0, 0, 0); if (l4) GLOADQ(ra0, rb0, kt + 4, 0);
;     FLOAD(f0, 1, 2);
;     FMMA(f1); if (s2) SSTOREQ(ra0, rb0, 0, 1); if (l4) GLOADQ(ra0, rb0, kt + 4, 1);
;     FLOAD(f1, 1, 3);
;     FMMA(f0); if (s2) SSTOREQ(ra0, rb0, 0, 2); if (l4) GLOADQ(ra0, rb0, kt + 4, 2);
;     FMMA(f1); if (s2) SSTOREQ(ra0, rb0, 0, 3); if (l4) GLOADQ(ra0, rb0, kt + 4, 3);
	ds_read_b128 v[108:111], v128 offset:55296
	ds_read_b128 v[116:119], v165 offset:36864
	ds_read_b128 v[194:197], v165 offset:41472
	s_waitcnt lgkmcnt(1)
	v_mfma_f32_32x32x16_bf16 v[48:63], v[108:111], v[116:119], v[48:63]
	s_waitcnt lgkmcnt(0)
	v_mfma_f32_32x32x16_bf16 v[32:47], v[108:111], v[194:197], v[32:47]
	ds_read_b128 v[108:111], v128 offset:59904
	s_waitcnt lgkmcnt(0)
	v_mfma_f32_32x32x16_bf16 v[16:31], v[108:111], v[116:119], v[16:31]
	v_mfma_f32_32x32x16_bf16 v[0:15], v[108:111], v[194:197], v[0:15]
	ds_read_b128 v[108:111], v164 offset:55328
	ds_read_b128 v[116:119], v165 offset:36896
	ds_read_b128 v[194:197], v165 offset:41504
	s_waitcnt lgkmcnt(1)
	v_mfma_f32_32x32x16_bf16 v[48:63], v[108:111], v[116:119], v[48:63]
	s_waitcnt lgkmcnt(0)
	v_mfma_f32_32x32x16_bf16 v[32:47], v[108:111], v[194:197], v[32:47]
	ds_read_b128 v[108:111], v164 offset:59936
	s_waitcnt vmcnt(15)
	ds_write_b128 v134, v[120:123]
	s_waitcnt vmcnt(13)
	ds_write_b128 v134, v[124:127] offset:18432
	s_waitcnt lgkmcnt(2)
	v_mfma_f32_32x32x16_bf16 v[16:31], v[108:111], v[116:119], v[16:31]
	v_mfma_f32_32x32x16_bf16 v[0:15], v[108:111], v[194:197], v[0:15]
	ds_read_b128 v[108:111], v164 offset:55360
	ds_read_b128 v[116:119], v165 offset:36928
	ds_read_b128 v[120:123], v165 offset:41536
	s_waitcnt lgkmcnt(1)
	v_mfma_f32_32x32x16_bf16 v[48:63], v[108:111], v[116:119], v[48:63]
	s_waitcnt lgkmcnt(0)
	v_mfma_f32_32x32x16_bf16 v[32:47], v[108:111], v[120:123], v[32:47]
	ds_read_b128 v[108:111], v164 offset:59968
	ds_write_b128 v134, v[104:107] offset:4608
	s_waitcnt vmcnt(12)
	ds_write_b128 v134, v[112:115] offset:23040
	s_waitcnt lgkmcnt(2)
	v_mfma_f32_32x32x16_bf16 v[16:31], v[108:111], v[116:119], v[16:31]
	v_mfma_f32_32x32x16_bf16 v[0:15], v[108:111], v[120:123], v[0:15]
	ds_read_b128 v[104:107], v164 offset:55392
	ds_read_b128 v[108:111], v165 offset:36960
	ds_read_b128 v[112:115], v165 offset:41568
	ds_read_b128 v[116:119], v164 offset:60000
	s_waitcnt lgkmcnt(2)
	v_mfma_f32_32x32x16_bf16 v[48:63], v[104:107], v[108:111], v[48:63]
	s_waitcnt lgkmcnt(1)
	v_mfma_f32_32x32x16_bf16 v[32:47], v[104:107], v[112:115], v[32:47]
	s_waitcnt lgkmcnt(0)
	v_mfma_f32_32x32x16_bf16 v[16:31], v[116:119], v[108:111], v[16:31]
	global_load_dwordx4 v[120:123], v[154:155], off offset:768
	global_load_dwordx4 v[104:107], v[156:157], off offset:768
	global_load_dwordx4 v[124:127], v[142:143], off offset:1792
	global_load_dwordx4 v[108:111], v[148:149], off offset:1792
	s_waitcnt vmcnt(15)
	ds_write_b128 v134, v[84:87] offset:9216
	s_waitcnt vmcnt(13)
	ds_write_b128 v134, v[88:91] offset:27648
	ds_write_b128 v134, v[68:71] offset:13824
	s_waitcnt vmcnt(12)
	ds_write_b128 v134, v[76:79] offset:32256
	global_load_dwordx4 v[84:87], v[158:159], off offset:768
	global_load_dwordx4 v[68:71], v[160:161], off offset:768
	global_load_dwordx4 v[88:91], v[144:145], off offset:1792
	global_load_dwordx4 v[76:79], v[146:147], off offset:1792
	s_waitcnt lgkmcnt(0)
	s_barrier
	v_mfma_f32_32x32x16_bf16 v[0:15], v[116:119], v[112:115], v[0:15]
	ds_read_b128 v[112:115], v128 offset:18432
	ds_read_b128 v[116:119], v165
	ds_read_b128 v[194:197], v165 offset:4608
	s_waitcnt lgkmcnt(1)
	v_mfma_f32_32x32x16_bf16 v[48:63], v[112:115], v[116:119], v[48:63]
	s_waitcnt lgkmcnt(0)
	v_mfma_f32_32x32x16_bf16 v[32:47], v[112:115], v[194:197], v[32:47]
	ds_read_b128 v[112:115], v128 offset:23040
	s_waitcnt lgkmcnt(0)
	v_mfma_f32_32x32x16_bf16 v[16:31], v[112:115], v[116:119], v[16:31]
	v_mfma_f32_32x32x16_bf16 v[0:15], v[112:115], v[194:197], v[0:15]
	ds_read_b128 v[112:115], v164 offset:18464
	ds_read_b128 v[116:119], v165 offset:32
	ds_read_b128 v[194:197], v165 offset:4640
	s_waitcnt lgkmcnt(1)
	v_mfma_f32_32x32x16_bf16 v[48:63], v[112:115], v[116:119], v[48:63]
	s_waitcnt lgkmcnt(0)
	v_mfma_f32_32x32x16_bf16 v[32:47], v[112:115], v[194:197], v[32:47]
	ds_read_b128 v[112:115], v164 offset:23072
	s_waitcnt vmcnt(15)
	ds_write_b128 v134, v[130:133] offset:36864
	s_waitcnt vmcnt(13)
	ds_write_b128 v134, v[186:189] offset:55296
	s_waitcnt lgkmcnt(2)
	v_mfma_f32_32x32x16_bf16 v[16:31], v[112:115], v[116:119], v[16:31]
	v_mfma_f32_32x32x16_bf16 v[0:15], v[112:115], v[194:197], v[0:15]
	ds_read_b128 v[112:115], v164 offset:18496
	ds_read_b128 v[116:119], v165 offset:64
	ds_read_b128 v[130:133], v165 offset:4672
	s_waitcnt lgkmcnt(1)
	v_mfma_f32_32x32x16_bf16 v[48:63], v[112:115], v[116:119], v[48:63]
	s_waitcnt lgkmcnt(0)
	v_mfma_f32_32x32x16_bf16 v[32:47], v[112:115], v[130:133], v[32:47]
	ds_read_b128 v[112:115], v164 offset:23104
	ds_write_b128 v134, v[96:99] offset:41472
	s_waitcnt vmcnt(12)
	ds_write_b128 v134, v[100:103] offset:59904
	ds_read_b128 v[96:99], v164 offset:18528
	ds_read_b128 v[100:103], v165 offset:96
	s_waitcnt lgkmcnt(4)
	v_mfma_f32_32x32x16_bf16 v[16:31], v[112:115], v[116:119], v[16:31]
	v_mfma_f32_32x32x16_bf16 v[0:15], v[112:115], v[130:133], v[0:15]
	ds_read_b128 v[112:115], v165 offset:4704
	s_waitcnt lgkmcnt(1)
	v_mfma_f32_32x32x16_bf16 v[48:63], v[96:99], v[100:103], v[48:63]
	s_waitcnt lgkmcnt(0)
	v_mfma_f32_32x32x16_bf16 v[32:47], v[96:99], v[112:115], v[32:47]
	ds_read_b128 v[96:99], v164 offset:23136
	s_waitcnt lgkmcnt(0)
	v_mfma_f32_32x32x16_bf16 v[16:31], v[96:99], v[100:103], v[16:31]
	global_load_dwordx4 v[100:103], v[154:155], off offset:896
	global_load_dwordx4 v[116:119], v[156:157], off offset:896
	global_load_dwordx4 v[130:133], v[142:143], off offset:1920
	s_nop 0
	global_load_dwordx4 v[154:157], v[148:149], off offset:1920
	s_waitcnt vmcnt(15)
	ds_write_b128 v134, v[80:83] offset:46080
	s_waitcnt vmcnt(13)
	ds_write_b128 v134, v[92:95] offset:64512
	ds_write_b128 v134, v[64:67] offset:50688
	s_waitcnt vmcnt(12)
	ds_write_b128 v135, v[72:75] offset:13824
	global_load_dwordx4 v[80:83], v[158:159], off offset:896
	global_load_dwordx4 v[64:67], v[160:161], off offset:896
	global_load_dwordx4 v[92:95], v[144:145], off offset:1920
	global_load_dwordx4 v[72:75], v[146:147], off offset:1920
	s_waitcnt lgkmcnt(0)
	s_barrier
; #define GLOADQ(RA, RB, KT, q) do { const int k0_ = (KT) << 6; \
;     RA[q] = ldg16(ap.ptr(m0 + lrow + 32 * (q), k0_) + lkc); RB[q] = ldg16(W + (size_t)(n0 + lrow + 32 * (q)) * ldw + k0_ + lkc); } while (0)
; #define SSTOREQ(RA, RB, ST, q) do { \
;     *(u32x4*)(sA + (ST) * SBUF + (lrow + 32 * (q)) * GP + lkc) = RA[q]; *(u32x4*)(sB + (ST) * SBUF + (lrow + 32 * (q)) * GP + lkc) = RB[q]; } while (0)
; #define FLOAD(F, ST, ks) do { _Pragma("unroll") for (int a = 0; a < 2; ++a) { \
;     F[a] = *(const bf16x8*)(sB + (ST) * SBUF + (wn * 64 + a * 32 + r) * GP + (ks) * 16 + h * 8); \
;     F[2 + a] = *(const bf16x8*)(sA + (ST) * SBUF + (wm * 64 + a * 32 + r) * GP + (ks) * 16 + h * 8); } } while (0)
; #define FMMA(F) do { _Pragma("unroll") for (int a = 0; a < 2; ++a) _Pragma("unroll") for (int b = 0; b < 2; ++b) acc[a][b] = MFMA(F[a], F[2 + b], acc[a][b]); } while (0)
; template <bool MIDK, class AP, class EPI>
; DI void gemm_tile(const AP& ap, const u16* __restrict__ W, int ldw, int K, int m0, int n0, const EPI& epi, char* smem, float r0, float r1, int tid, bool dry) {
;     ...
;   for (int kt = 0; kt < nk; kt += 2) {
;     const bool l3 = kt + 3 < nk, s2 = kt + 2 < nk, l4 = kt + 4 < nk;
;     FLOAD(f0, 0, 0); FLOAD(f1, 0, 1);
;     FMMA(f0); SSTOREQ(ra1, rb1, 1, 0); if (l3) GLOADQ(ra1, rb1, kt + 3, 0);
;     FLOAD(f0, 0, 2);
;     FMMA(f1); SSTOREQ(ra1, rb1, 1, 1); if (l3) GLOADQ(ra1, rb1, kt + 3, 1);
;     FLOAD(f1, 0, 3);
;     FMMA(f0); SSTOREQ(ra1, rb1, 1, 2); if (l3) GLOADQ(ra1, rb1, kt + 3, 2);
;     FMMA(f1); SSTOREQ(ra1, rb1, 1, 3); if (l3) GLOADQ(ra1, rb1, kt + 3, 3);
;     __syncthreads();
;     FLOAD(f0, 1, 0); FLOAD(f1, 1, 1);
;     FMMA(f0); if (s2) SSTOREQ(ra0, rb0, 0, 0); if (l4) GLOADQ(ra0, rb0, kt + 4, 0);
;     FLOAD(f0, 1, 2);
;     FMMA(f1); if (s2) SSTOREQ(ra0, rb0, 0, 1); if (l4) GLOADQ(ra0, rb0, kt + 4, 1);
;     FLOAD(f1, 1, 3);
;     FMMA(f0); if (s2) SSTOREQ(ra0, rb0, 0, 2); if (l4) GLOADQ(ra0, rb0, kt + 4, 2);
;     FMMA(f1); if (s2) SSTOREQ(ra0, rb0, 0, 3); if (l4) GLOADQ(ra0, rb0, kt + 4, 3);
;     if (MIDK && kt == 6) {
; #pragma unroll
;       for (int a = 0; a < 2; ++a)
; #pragma unroll
;         for (int i = 0; i < 16; ++i) { acc[a][0][i] *= r0; acc[a][1][i] *= r1; }
;     }
;     __syncthreads();
	v_mfma_f32_32x32x16_bf16 v[0:15], v[96:99], v[112:115], v[0:15]
	ds_read_b128 v[96:99], v128 offset:55296
	ds_read_b128 v[112:115], v165 offset:36864
	ds_read_b128 v[142:145], v165 offset:41472
	s_waitcnt lgkmcnt(1)
	v_mfma_f32_32x32x16_bf16 v[48:63], v[96:99], v[112:115], v[48:63]
	s_waitcnt lgkmcnt(0)
	v_mfma_f32_32x32x16_bf16 v[32:47], v[96:99], v[142:145], v[32:47]
	ds_read_b128 v[96:99], v128 offset:59904
	s_waitcnt lgkmcnt(0)
	v_mfma_f32_32x32x16_bf16 v[16:31], v[96:99], v[112:115], v[16:31]
	v_mfma_f32_32x32x16_bf16 v[0:15], v[96:99], v[142:145], v[0:15]
	ds_read_b128 v[96:99], v164 offset:55328
	ds_read_b128 v[112:115], v165 offset:36896
	ds_read_b128 v[142:145], v165 offset:41504
	s_waitcnt lgkmcnt(1)
	v_mfma_f32_32x32x16_bf16 v[48:63], v[96:99], v[112:115], v[48:63]
	s_waitcnt lgkmcnt(0)
	v_mfma_f32_32x32x16_bf16 v[32:47], v[96:99], v[142:145], v[32:47]
	ds_read_b128 v[96:99], v164 offset:59936
	s_waitcnt vmcnt(15)
	ds_write_b128 v134, v[120:123]
	s_waitcnt vmcnt(13)
	ds_write_b128 v134, v[124:127] offset:18432
	s_waitcnt lgkmcnt(2)
	v_mfma_f32_32x32x16_bf16 v[16:31], v[96:99], v[112:115], v[16:31]
	v_mfma_f32_32x32x16_bf16 v[0:15], v[96:99], v[142:145], v[0:15]
	ds_read_b128 v[96:99], v164 offset:55360
	ds_read_b128 v[112:115], v165 offset:36928
	ds_read_b128 v[120:123], v165 offset:41536
	s_waitcnt lgkmcnt(1)
	v_mfma_f32_32x32x16_bf16 v[48:63], v[96:99], v[112:115], v[48:63]
	s_waitcnt lgkmcnt(0)
	v_mfma_f32_32x32x16_bf16 v[32:47], v[96:99], v[120:123], v[32:47]
	ds_read_b128 v[96:99], v164 offset:59968
	ds_write_b128 v134, v[104:107] offset:4608
	s_waitcnt vmcnt(12)
	ds_write_b128 v134, v[108:111] offset:23040
	s_waitcnt lgkmcnt(2)
	v_mfma_f32_32x32x16_bf16 v[16:31], v[96:99], v[112:115], v[16:31]
	v_mfma_f32_32x32x16_bf16 v[0:15], v[96:99], v[120:123], v[0:15]
	ds_read_b128 v[96:99], v164 offset:55392
	ds_read_b128 v[104:107], v165 offset:36960
	ds_read_b128 v[108:111], v165 offset:41568
	s_waitcnt lgkmcnt(1)
	v_mfma_f32_32x32x16_bf16 v[48:63], v[96:99], v[104:107], v[48:63]
	s_waitcnt lgkmcnt(0)
	v_mfma_f32_32x32x16_bf16 v[32:47], v[96:99], v[108:111], v[32:47]
	ds_read_b128 v[96:99], v164 offset:60000
	s_waitcnt vmcnt(11)
	ds_write_b128 v134, v[84:87] offset:9216
	s_waitcnt vmcnt(9)
	ds_write_b128 v134, v[88:91] offset:27648
	ds_write_b128 v134, v[68:71] offset:13824
	s_waitcnt vmcnt(8)
	ds_write_b128 v134, v[76:79] offset:32256
	s_waitcnt lgkmcnt(0)
	s_barrier
	ds_read_b128 v[68:71], v128 offset:18432
	ds_read_b128 v[76:79], v165
	ds_read_b128 v[84:87], v165 offset:4608
	s_waitcnt lgkmcnt(1)
	v_mfma_f32_32x32x16_bf16 v[48:63], v[68:71], v[76:79], v[48:63]
	s_waitcnt lgkmcnt(0)
	v_mfma_f32_32x32x16_bf16 v[32:47], v[68:71], v[84:87], v[32:47]
	ds_read_b128 v[68:71], v128 offset:23040
	v_mfma_f32_32x32x16_bf16 v[16:31], v[96:99], v[104:107], v[16:31]
	v_mfma_f32_32x32x16_bf16 v[0:15], v[96:99], v[108:111], v[0:15]
	s_waitcnt lgkmcnt(0)
	v_mfma_f32_32x32x16_bf16 v[16:31], v[68:71], v[76:79], v[16:31]
	v_mfma_f32_32x32x16_bf16 v[0:15], v[68:71], v[84:87], v[0:15]
	ds_read_b128 v[68:71], v164 offset:18464
	ds_read_b128 v[76:79], v165 offset:32
	ds_read_b128 v[84:87], v165 offset:4640
	s_waitcnt lgkmcnt(1)
	v_mfma_f32_32x32x16_bf16 v[48:63], v[68:71], v[76:79], v[48:63]
	s_waitcnt lgkmcnt(0)
	v_mfma_f32_32x32x16_bf16 v[32:47], v[68:71], v[84:87], v[32:47]
	ds_read_b128 v[68:71], v164 offset:23072
	s_waitcnt vmcnt(7)
	ds_write_b128 v134, v[100:103] offset:36864
	s_waitcnt vmcnt(5)
	ds_write_b128 v134, v[130:133] offset:55296
	s_waitcnt lgkmcnt(2)
	v_mfma_f32_32x32x16_bf16 v[16:31], v[68:71], v[76:79], v[16:31]
	v_mfma_f32_32x32x16_bf16 v[0:15], v[68:71], v[84:87], v[0:15]
	ds_read_b128 v[68:71], v164 offset:18496
	ds_read_b128 v[76:79], v165 offset:64
	ds_read_b128 v[84:87], v165 offset:4672
	s_waitcnt lgkmcnt(1)
	v_mfma_f32_32x32x16_bf16 v[48:63], v[68:71], v[76:79], v[48:63]
	s_waitcnt lgkmcnt(0)
	v_mfma_f32_32x32x16_bf16 v[32:47], v[68:71], v[84:87], v[32:47]
	ds_read_b128 v[68:71], v164 offset:23104
	ds_write_b128 v134, v[116:119] offset:41472
	s_waitcnt vmcnt(4)
	ds_write_b128 v134, v[154:157] offset:59904
	s_waitcnt lgkmcnt(2)
	v_mfma_f32_32x32x16_bf16 v[16:31], v[68:71], v[76:79], v[16:31]
	v_mfma_f32_32x32x16_bf16 v[0:15], v[68:71], v[84:87], v[0:15]
	ds_read_b128 v[68:71], v164 offset:18528
	ds_read_b128 v[76:79], v165 offset:96
	ds_read_b128 v[84:87], v165 offset:4704
	s_waitcnt lgkmcnt(1)
	v_mfma_f32_32x32x16_bf16 v[48:63], v[68:71], v[76:79], v[48:63]
	s_waitcnt lgkmcnt(0)
	v_mfma_f32_32x32x16_bf16 v[32:47], v[68:71], v[84:87], v[32:47]
	ds_read_b128 v[68:71], v164 offset:23136
	s_waitcnt vmcnt(3)
	ds_write_b128 v134, v[80:83] offset:46080
	s_waitcnt vmcnt(1)
	ds_write_b128 v134, v[92:95] offset:64512
	ds_write_b128 v134, v[64:67] offset:50688
	s_waitcnt vmcnt(0)
	ds_write_b128 v135, v[72:75] offset:13824
	s_waitcnt lgkmcnt(0)
	s_barrier
; template <bool MIDK, class AP, class EPI>
; DI void gemm_tile(const AP& ap, const u16* __restrict__ W, int ldw, int K, int m0, int n0, const EPI& epi, char* smem, float r0, float r1, int tid, bool dry) {
;     ...
;   for (int kt = 0; kt < nk; kt += 2) {
;     const bool l3 = kt + 3 < nk, s2 = kt + 2 < nk, l4 = kt + 4 < nk;
;     FLOAD(f0, 0, 0); FLOAD(f1, 0, 1);
;     FMMA(f0); SSTOREQ(ra1, rb1, 1, 0); if (l3) GLOADQ(ra1, rb1, kt + 3, 0);
;     FLOAD(f0, 0, 2);
;     FMMA(f1); SSTOREQ(ra1, rb1, 1, 1); if (l3) GLOADQ(ra1, rb1, kt + 3, 1);
;     FLOAD(f1, 0, 3);
;     FMMA(f0); SSTOREQ(ra1, rb1, 1, 2); if (l3) GLOADQ(ra1, rb1, kt + 3, 2);
;     FMMA(f1); SSTOREQ(ra1, rb1, 1, 3); if (l3) GLOADQ(ra1, rb1, kt + 3, 3);
;     __syncthreads();
;     FLOAD(f0, 1, 0); FLOAD(f1, 1, 1);
;     FMMA(f0); if (s2) SSTOREQ(ra0, rb0, 0, 0); if (l4) GLOADQ(ra0, rb0, kt + 4, 0);
;     FLOAD(f0, 1, 2);
;     FMMA(f1); if (s2) SSTOREQ(ra0, rb0, 0, 1); if (l4) GLOADQ(ra0, rb0, kt + 4, 1);
;     FLOAD(f1, 1, 3);
;     FMMA(f0); if (s2) SSTOREQ(ra0, rb0, 0, 2); if (l4) GLOADQ(ra0, rb0, kt + 4, 2);
;     FMMA(f1); if (s2) SSTOREQ(ra0, rb0, 0, 3); if (l4) GLOADQ(ra0, rb0, kt + 4, 3);
;     if (MIDK && kt == 6) {
;   DI void operator()(f32x16 (&acc)[2][2], int nb, int mb, int lane, u16* wl) const {
;     const int r = lane & 31, h = lane >> 5, mbl = mb & 127;
;     float* wf = (float*)wl;
; #pragma unroll
;     for (int fi = 0; fi < 2; ++fi) {
; #pragma unroll
;       for (int ti = 0; ti < 2; ++ti) {
;         const float sc = ti == 0 ? fin0 : fin1;
; #pragma unroll
;         for (int g4 = 0; g4 < 4; ++g4) {
;           float4 o = make_float4(acc[fi][ti][4 * g4] * sc, acc[fi][ti][4 * g4 + 1] * sc, acc[fi][ti][4 * g4 + 2] * sc, acc[fi][ti][4 * g4 + 3] * sc);
;           *(float4*)(wf + (ti * 32 + r) * 36 + 8 * g4 + 4 * h) = o;
;         }
;       }
;       WAVE_LDS_FENCE();
; #pragma unroll
;       for (int it = 0; it < 8; ++it) {
;         const int row = it * 8 + (lane >> 3), ch = lane & 7;
;         const float4 a = *(const float4*)(wf + row * 36 + ch * 4);
;         const int trow = mbl + row;
;         if (trow >= minrow) {
;           const size_t off = (size_t)trow * 1024 + nb + fi * 32 + ch * 4;
;           float4 x = ldgf4(sb + off);
;           x.x += a.x; x.y += a.y; x.z += a.z; x.w += a.w;
;           stgf4(db + off, x);
;         }
;       }
;       WAVE_LDS_FENCE();
;     }
	v_mfma_f32_32x32x16_bf16 v[16:31], v[68:71], v[76:79], v[16:31]
	v_mfma_f32_32x32x16_bf16 v[0:15], v[68:71], v[84:87], v[0:15]
	ds_read_b128 v[64:67], v128 offset:55296
	ds_read_b128 v[68:71], v165 offset:36864
	ds_read_b128 v[72:75], v165 offset:41472
	s_waitcnt lgkmcnt(1)
	v_mfma_f32_32x32x16_bf16 v[48:63], v[64:67], v[68:71], v[48:63]
	s_waitcnt lgkmcnt(0)
	v_mfma_f32_32x32x16_bf16 v[32:47], v[64:67], v[72:75], v[32:47]
	ds_read_b128 v[64:67], v128 offset:59904
	s_waitcnt lgkmcnt(0)
	v_mfma_f32_32x32x16_bf16 v[16:31], v[64:67], v[68:71], v[16:31]
	v_mfma_f32_32x32x16_bf16 v[0:15], v[64:67], v[72:75], v[0:15]
	ds_read_b128 v[64:67], v164 offset:55328
	ds_read_b128 v[68:71], v165 offset:36896
	ds_read_b128 v[72:75], v165 offset:41504
	s_waitcnt lgkmcnt(1)
	v_mfma_f32_32x32x16_bf16 v[48:63], v[64:67], v[68:71], v[48:63]
	s_waitcnt lgkmcnt(0)
	v_mfma_f32_32x32x16_bf16 v[32:47], v[64:67], v[72:75], v[32:47]
	ds_read_b128 v[64:67], v164 offset:59936
	s_waitcnt lgkmcnt(0)
	v_mfma_f32_32x32x16_bf16 v[16:31], v[64:67], v[68:71], v[16:31]
	v_mfma_f32_32x32x16_bf16 v[0:15], v[64:67], v[72:75], v[0:15]
	ds_read_b128 v[64:67], v164 offset:55360
	ds_read_b128 v[68:71], v165 offset:36928
	ds_read_b128 v[72:75], v165 offset:41536
	s_waitcnt lgkmcnt(1)
	v_mfma_f32_32x32x16_bf16 v[48:63], v[64:67], v[68:71], v[48:63]
	s_waitcnt lgkmcnt(0)
	v_mfma_f32_32x32x16_bf16 v[32:47], v[64:67], v[72:75], v[32:47]
	ds_read_b128 v[64:67], v164 offset:59968
	s_waitcnt lgkmcnt(0)
	v_mfma_f32_32x32x16_bf16 v[16:31], v[64:67], v[68:71], v[16:31]
	v_mfma_f32_32x32x16_bf16 v[0:15], v[64:67], v[72:75], v[0:15]
	ds_read_b128 v[64:67], v164 offset:55392
	ds_read_b128 v[68:71], v165 offset:36960
	ds_read_b128 v[72:75], v165 offset:41568
	s_waitcnt lgkmcnt(1)
	v_mfma_f32_32x32x16_bf16 v[48:63], v[64:67], v[68:71], v[48:63]
	s_waitcnt lgkmcnt(0)
	v_mfma_f32_32x32x16_bf16 v[32:47], v[64:67], v[72:75], v[32:47]
	ds_read_b128 v[64:67], v164 offset:60000
	s_waitcnt lgkmcnt(0)
	s_barrier
	v_mfma_f32_32x32x16_bf16 v[16:31], v[64:67], v[68:71], v[16:31]
	v_mfma_f32_32x32x16_bf16 v[0:15], v[64:67], v[72:75], v[0:15]
	s_cbranch_vccnz .LBB0_156
	s_nop 3
	s_cmp_lg_u32 s16, 0
	s_cbranch_scc1 .Lepi_out_orig
	v_pk_mul_f32 v[48:49], v[152:153], v[48:49] op_sel_hi:[0,1]
	v_pk_mul_f32 v[50:51], v[152:153], v[50:51] op_sel_hi:[0,1]
	ds_write_b128 v183, v[48:51]
	v_pk_mul_f32 v[48:49], v[152:153], v[52:53] op_sel_hi:[0,1]
	v_pk_mul_f32 v[50:51], v[152:153], v[54:55] op_sel_hi:[0,1]
	ds_write_b128 v183, v[48:51] offset:32
	v_pk_mul_f32 v[48:49], v[152:153], v[56:57] op_sel_hi:[0,1]
	v_pk_mul_f32 v[50:51], v[152:153], v[58:59] op_sel_hi:[0,1]
	ds_write_b128 v183, v[48:51] offset:64
	v_pk_mul_f32 v[48:49], v[152:153], v[60:61] op_sel_hi:[0,1]
	v_pk_mul_f32 v[50:51], v[152:153], v[62:63] op_sel_hi:[0,1]
	v_pk_mul_f32 v[32:33], v[150:151], v[32:33] op_sel_hi:[0,1]
	v_pk_mul_f32 v[34:35], v[150:151], v[34:35] op_sel_hi:[0,1]
	ds_write_b128 v183, v[48:51] offset:96
	ds_write_b128 v184, v[32:35]
	v_pk_mul_f32 v[32:33], v[150:151], v[36:37] op_sel_hi:[0,1]
	v_pk_mul_f32 v[34:35], v[150:151], v[38:39] op_sel_hi:[0,1]
	ds_write_b128 v184, v[32:35] offset:32
	v_pk_mul_f32 v[32:33], v[150:151], v[40:41] op_sel_hi:[0,1]
	v_pk_mul_f32 v[34:35], v[150:151], v[42:43] op_sel_hi:[0,1]
	ds_write_b128 v184, v[32:35] offset:64
	v_pk_mul_f32 v[32:33], v[150:151], v[44:45] op_sel_hi:[0,1]
	v_pk_mul_f32 v[34:35], v[150:151], v[46:47] op_sel_hi:[0,1]
	ds_write_b128 v184, v[32:35] offset:96
	s_waitcnt lgkmcnt(0)
	v_or_b32_e32 v64, s4, v166
	v_add_lshl_u32 v36, v64, v168, 2
	global_load_dwordx4 v[68:71], v36, s[74:75]
	ds_read_b128 v[100:103], v185
	v_add_lshl_u32 v37, v64, v170, 2
	global_load_dwordx4 v[72:75], v37, s[74:75]
	ds_read_b128 v[104:107], v185 offset:1152
	v_add_lshl_u32 v38, v64, v172, 2
	global_load_dwordx4 v[76:79], v38, s[74:75]
	ds_read_b128 v[108:111], v185 offset:2304
	v_add_lshl_u32 v39, v64, v174, 2
	global_load_dwordx4 v[80:83], v39, s[74:75]
	ds_read_b128 v[112:115], v185 offset:3456
	v_add_lshl_u32 v40, v64, v176, 2
	global_load_dwordx4 v[84:87], v40, s[74:75]
	ds_read_b128 v[116:119], v185 offset:4608
	v_add_lshl_u32 v41, v64, v178, 2
	global_load_dwordx4 v[88:91], v41, s[74:75]
	ds_read_b128 v[120:123], v185 offset:5760
	v_add_lshl_u32 v42, v64, v180, 2
	global_load_dwordx4 v[92:95], v42, s[74:75]
	ds_read_b128 v[124:127], v185 offset:6912
	v_add_lshl_u32 v43, v64, v182, 2
	global_load_dwordx4 v[96:99], v43, s[74:75]
	ds_read_b128 v[44:47], v185 offset:8064
	s_waitcnt vmcnt(0) lgkmcnt(0)
	v_pk_add_f32 v[68:69], v[100:101], v[68:69]
	v_pk_add_f32 v[70:71], v[102:103], v[70:71]
	global_store_dwordx4 v36, v[68:71], s[50:51]
	v_pk_add_f32 v[72:73], v[104:105], v[72:73]
	v_pk_add_f32 v[74:75], v[106:107], v[74:75]
	global_store_dwordx4 v37, v[72:75], s[50:51]
	v_pk_add_f32 v[76:77], v[108:109], v[76:77]
	v_pk_add_f32 v[78:79], v[110:111], v[78:79]
	global_store_dwordx4 v38, v[76:79], s[50:51]
	v_pk_add_f32 v[80:81], v[112:113], v[80:81]
	v_pk_add_f32 v[82:83], v[114:115], v[82:83]
	global_store_dwordx4 v39, v[80:83], s[50:51]
	v_pk_add_f32 v[84:85], v[116:117], v[84:85]
	v_pk_add_f32 v[86:87], v[118:119], v[86:87]
	global_store_dwordx4 v40, v[84:87], s[50:51]
	v_pk_add_f32 v[88:89], v[120:121], v[88:89]
	v_pk_add_f32 v[90:91], v[122:123], v[90:91]
	global_store_dwordx4 v41, v[88:91], s[50:51]
	v_pk_add_f32 v[92:93], v[124:125], v[92:93]
	v_pk_add_f32 v[94:95], v[126:127], v[94:95]
	global_store_dwordx4 v42, v[92:95], s[50:51]
	v_pk_add_f32 v[96:97], v[44:45], v[96:97]
	v_pk_add_f32 v[98:99], v[46:47], v[98:99]
	global_store_dwordx4 v43, v[96:99], s[50:51]
	v_mov_b32_e32 v153, v152
	v_pk_mul_f32 v[16:17], v[152:153], v[16:17]
	v_pk_mul_f32 v[18:19], v[152:153], v[18:19]
	s_waitcnt lgkmcnt(0)
; #define WAVE_LDS_FENCE() asm volatile("s_waitcnt lgkmcnt(0)" ::: "memory")
; DI float4 ldgf4(const void* p) { const f32x4v v = *(const GAS f32x4v*)p; return make_float4(v.x, v.y, v.z, v.w); }
;   DI void operator()(f32x16 (&acc)[2][2], int nb, int mb, int lane, u16* wl) const {
;     const int r = lane & 31, h = lane >> 5, mbl = mb & 127;
;     float* wf = (float*)wl;
; #pragma unroll
;     for (int fi = 0; fi < 2; ++fi) {
; #pragma unroll
;       for (int ti = 0; ti < 2; ++ti) {
;         const float sc = ti == 0 ? fin0 : fin1;
; #pragma unroll
;         for (int g4 = 0; g4 < 4; ++g4) {
;           float4 o = make_float4(acc[fi][ti][4 * g4] * sc, acc[fi][ti][4 * g4 + 1] * sc, acc[fi][ti][4 * g4 + 2] * sc, acc[fi][ti][4 * g4 + 3] * sc);
;           *(float4*)(wf + (ti * 32 + r) * 36 + 8 * g4 + 4 * h) = o;
;         }
;       }
;       WAVE_LDS_FENCE();
; #pragma unroll
;       for (int it = 0; it < 8; ++it) {
;         const int row = it * 8 + (lane >> 3), ch = lane & 7;
;         const float4 a = *(const float4*)(wf + row * 36 + ch * 4);
;         const int trow = mbl + row;
;         if (trow >= minrow) {
;           const size_t off = (size_t)trow * 1024 + nb + fi * 32 + ch * 4;
;           float4 x = ldgf4(sb + off);
;           x.x += a.x; x.y += a.y; x.z += a.z; x.w += a.w;
;           stgf4(db + off, x);
;         }
;       }
;       WAVE_LDS_FENCE();
;     }
	ds_write_b128 v183, v[16:19]
	v_pk_mul_f32 v[16:17], v[152:153], v[20:21]
	v_pk_mul_f32 v[18:19], v[152:153], v[22:23]
	v_mov_b32_e32 v151, v150
	ds_write_b128 v183, v[16:19] offset:32
	v_pk_mul_f32 v[16:17], v[152:153], v[24:25]
	v_pk_mul_f32 v[18:19], v[152:153], v[26:27]
	ds_write_b128 v183, v[16:19] offset:64
	v_pk_mul_f32 v[16:17], v[152:153], v[28:29]
	v_pk_mul_f32 v[18:19], v[152:153], v[30:31]
	v_pk_mul_f32 v[0:1], v[150:151], v[0:1]
	v_pk_mul_f32 v[2:3], v[150:151], v[2:3]
	ds_write_b128 v183, v[16:19] offset:96
	ds_write_b128 v184, v[0:3]
	v_pk_mul_f32 v[0:1], v[150:151], v[4:5]
	v_pk_mul_f32 v[2:3], v[150:151], v[6:7]
	ds_write_b128 v184, v[0:3] offset:32
	v_pk_mul_f32 v[0:1], v[150:151], v[8:9]
	v_pk_mul_f32 v[2:3], v[150:151], v[10:11]
	ds_write_b128 v184, v[0:3] offset:64
	v_pk_mul_f32 v[0:1], v[150:151], v[12:13]
	v_pk_mul_f32 v[2:3], v[150:151], v[14:15]
	ds_write_b128 v184, v[0:3] offset:96
	s_waitcnt lgkmcnt(0)
	global_load_dwordx4 v[68:71], v36, s[74:75] offset:128
	ds_read_b128 v[100:103], v185
	global_load_dwordx4 v[72:75], v37, s[74:75] offset:128
	ds_read_b128 v[104:107], v185 offset:1152
	global_load_dwordx4 v[76:79], v38, s[74:75] offset:128
	ds_read_b128 v[108:111], v185 offset:2304
	global_load_dwordx4 v[80:83], v39, s[74:75] offset:128
	ds_read_b128 v[112:115], v185 offset:3456
	global_load_dwordx4 v[84:87], v40, s[74:75] offset:128
	ds_read_b128 v[116:119], v185 offset:4608
	global_load_dwordx4 v[88:91], v41, s[74:75] offset:128
	ds_read_b128 v[120:123], v185 offset:5760
	global_load_dwordx4 v[92:95], v42, s[74:75] offset:128
	ds_read_b128 v[124:127], v185 offset:6912
	global_load_dwordx4 v[96:99], v43, s[74:75] offset:128
	ds_read_b128 v[44:47], v185 offset:8064
	s_waitcnt vmcnt(0) lgkmcnt(0)
	v_pk_add_f32 v[68:69], v[100:101], v[68:69]
	v_pk_add_f32 v[70:71], v[102:103], v[70:71]
	global_store_dwordx4 v36, v[68:71], s[50:51] offset:128
	v_pk_add_f32 v[72:73], v[104:105], v[72:73]
	v_pk_add_f32 v[74:75], v[106:107], v[74:75]
	global_store_dwordx4 v37, v[72:75], s[50:51] offset:128
	v_pk_add_f32 v[76:77], v[108:109], v[76:77]
	v_pk_add_f32 v[78:79], v[110:111], v[78:79]
	global_store_dwordx4 v38, v[76:79], s[50:51] offset:128
	v_pk_add_f32 v[80:81], v[112:113], v[80:81]
	v_pk_add_f32 v[82:83], v[114:115], v[82:83]
	global_store_dwordx4 v39, v[80:83], s[50:51] offset:128
	v_pk_add_f32 v[84:85], v[116:117], v[84:85]
	v_pk_add_f32 v[86:87], v[118:119], v[86:87]
	global_store_dwordx4 v40, v[84:87], s[50:51] offset:128
	v_pk_add_f32 v[88:89], v[120:121], v[88:89]
	v_pk_add_f32 v[90:91], v[122:123], v[90:91]
	global_store_dwordx4 v41, v[88:91], s[50:51] offset:128
	v_pk_add_f32 v[92:93], v[124:125], v[92:93]
	v_pk_add_f32 v[94:95], v[126:127], v[94:95]
	global_store_dwordx4 v42, v[92:95], s[50:51] offset:128
	v_pk_add_f32 v[96:97], v[44:45], v[96:97]
	v_pk_add_f32 v[98:99], v[46:47], v[98:99]
	global_store_dwordx4 v43, v[96:99], s[50:51] offset:128
	s_branch .LBB0_156
.Lepi_out_orig:
	v_pk_mul_f32 v[48:49], v[152:153], v[48:49] op_sel_hi:[0,1]
	v_pk_mul_f32 v[50:51], v[152:153], v[50:51] op_sel_hi:[0,1]
	ds_write_b128 v183, v[48:51]
	v_pk_mul_f32 v[48:49], v[152:153], v[52:53] op_sel_hi:[0,1]
	v_pk_mul_f32 v[50:51], v[152:153], v[54:55] op_sel_hi:[0,1]
	ds_write_b128 v183, v[48:51] offset:32
	v_pk_mul_f32 v[48:49], v[152:153], v[56:57] op_sel_hi:[0,1]
	v_pk_mul_f32 v[50:51], v[152:153], v[58:59] op_sel_hi:[0,1]
	ds_write_b128 v183, v[48:51] offset:64
	v_pk_mul_f32 v[48:49], v[152:153], v[60:61] op_sel_hi:[0,1]
	v_pk_mul_f32 v[50:51], v[152:153], v[62:63] op_sel_hi:[0,1]
	v_pk_mul_f32 v[32:33], v[150:151], v[32:33] op_sel_hi:[0,1]
	v_pk_mul_f32 v[34:35], v[150:151], v[34:35] op_sel_hi:[0,1]
	ds_write_b128 v183, v[48:51] offset:96
	ds_write_b128 v184, v[32:35]
	v_pk_mul_f32 v[32:33], v[150:151], v[36:37] op_sel_hi:[0,1]
	v_pk_mul_f32 v[34:35], v[150:151], v[38:39] op_sel_hi:[0,1]
	ds_write_b128 v184, v[32:35] offset:32
	v_pk_mul_f32 v[32:33], v[150:151], v[40:41] op_sel_hi:[0,1]
	v_pk_mul_f32 v[34:35], v[150:151], v[42:43] op_sel_hi:[0,1]
	ds_write_b128 v184, v[32:35] offset:64
	v_pk_mul_f32 v[32:33], v[150:151], v[44:45] op_sel_hi:[0,1]
	v_pk_mul_f32 v[34:35], v[150:151], v[46:47] op_sel_hi:[0,1]
	ds_write_b128 v184, v[32:35] offset:96
	s_waitcnt lgkmcnt(0)
	v_or_b32_e32 v64, s4, v166
	v_cmp_le_u32_e32 vcc, s16, v167
	s_and_saveexec_b64 s[0:1], vcc
	s_cbranch_execz .LBB0_183
	v_or_b32_e32 v32, v64, v168
	v_lshlrev_b32_e32 v40, 2, v32
	global_load_dwordx4 v[32:35], v40, s[74:75]
	ds_read_b128 v[36:39], v185
	s_waitcnt vmcnt(0) lgkmcnt(0)
	v_pk_add_f32 v[34:35], v[38:39], v[34:35]
	v_pk_add_f32 v[32:33], v[36:37], v[32:33]
	global_store_dwordx4 v40, v[32:35], s[50:51]
	s_or_b64 exec, exec, s[0:1]
	v_cmp_le_u32_e64 s[4:5], s16, v169
	s_and_saveexec_b64 s[0:1], s[4:5]
	s_cbranch_execnz .LBB0_184

; #define GLOADQ(RA, RB, KT, q) do { const int k0_ = (KT) << 6; \
;     RA[q] = ldg16(ap.ptr(m0 + lrow + 32 * (q), k0_) + lkc); RB[q] = ldg16(W + (size_t)(n0 + lrow + 32 * (q)) * ldw + k0_ + lkc); } while (0)
; #define GLOAD(RA, RB, KT) do { GLOADQ(RA, RB, KT, 0); GLOADQ(RA, RB, KT, 1); GLOADQ(RA, RB, KT, 2); GLOADQ(RA, RB, KT, 3); } while (0)
; #define SSTOREQ(RA, RB, ST, q) do { \
;     *(u32x4*)(sA + (ST) * SBUF + (lrow + 32 * (q)) * GP + lkc) = RA[q]; *(u32x4*)(sB + (ST) * SBUF + (lrow + 32 * (q)) * GP + lkc) = RB[q]; } while (0)
; #define SSTORE(RA, RB, ST) do { SSTOREQ(RA, RB, ST, 0); SSTOREQ(RA, RB, ST, 1); SSTOREQ(RA, RB, ST, 2); SSTOREQ(RA, RB, ST, 3); } while (0)
; #define FLOAD(F, ST, ks) do { _Pragma("unroll") for (int a = 0; a < 2; ++a) { \
;     F[a] = *(const bf16x8*)(sB + (ST) * SBUF + (wn * 64 + a * 32 + r) * GP + (ks) * 16 + h * 8); \
;     F[2 + a] = *(const bf16x8*)(sA + (ST) * SBUF + (wm * 64 + a * 32 + r) * GP + (ks) * 16 + h * 8); } } while (0)
; template <bool MIDK, class AP, class EPI>
; DI void gemm_tile(const AP& ap, const u16* __restrict__ W, int ldw, int K, int m0, int n0, const EPI& epi, char* smem, float r0, float r1, int tid, bool dry) {
;     ...
;   const int nk = K >> 6;
;     ...
;   bf16x8 f0[4], f1[4];
;   GLOAD(ra0, rb0, 0);
;   GLOAD(ra1, rb1, 1);
;   __syncthreads();
;   SSTORE(ra0, rb0, 0);
;   if (nk > 2) GLOAD(ra0, rb0, 2);
;   __syncthreads();
;   for (int kt = 0; kt < nk; kt += 2) {
;     const bool l3 = kt + 3 < nk, s2 = kt + 2 < nk, l4 = kt + 4 < nk;
;     FLOAD(f0, 0, 0); FLOAD(f1, 0, 1);
;     FMMA(f0); SSTOREQ(ra1, rb1, 1, 0); if (l3) GLOADQ(ra1, rb1, kt + 3, 0);
;     FLOAD(f0, 0, 2);
;     FMMA(f1); SSTOREQ(ra1, rb1, 1, 1); if (l3) GLOADQ(ra1, rb1, kt + 3, 1);
;     FLOAD(f1, 0, 3);
;     FMMA(f0); SSTOREQ(ra1, rb1, 1, 2); if (l3) GLOADQ(ra1, rb1, kt + 3, 2);
;     FMMA(f1); SSTOREQ(ra1, rb1, 1, 3); if (l3) GLOADQ(ra1, rb1, kt + 3, 3);
;     __syncthreads();
;     FLOAD(f0, 1, 0); FLOAD(f1, 1, 1);
;     FMMA(f0); if (s2) SSTOREQ(ra0, rb0, 0, 0); if (l4) GLOADQ(ra0, rb0, kt + 4, 0);
;     FLOAD(f0, 1, 2);
;     FMMA(f1); if (s2) SSTOREQ(ra0, rb0, 0, 1); if (l4) GLOADQ(ra0, rb0, kt + 4, 1);
;     FLOAD(f1, 1, 3);
;     FMMA(f0); if (s2) SSTOREQ(ra0, rb0, 0, 2); if (l4) GLOADQ(ra0, rb0, kt + 4, 2);
;     FMMA(f1); if (s2) SSTOREQ(ra0, rb0, 0, 3); if (l4) GLOADQ(ra0, rb0, kt + 4, 3);
.LBB0_396:
	v_lshl_add_u32 v0, s10, 7, v166
	s_and_b32 s4, s19, 0x380
	v_ashrrev_i32_e32 v1, 31, v0
	v_lshlrev_b64 v[0:1], 13, v[0:1]
	v_add_u32_e32 v4, s4, v166
	v_lshl_add_u64 v[150:151], v[134:135], 0, v[0:1]
	v_ashrrev_i32_e32 v5, 31, v4
	s_mov_b32 s5, 0x41000
	v_lshlrev_b64 v[4:5], 13, v[4:5]
	v_add_co_u32_e32 v138, vcc, s5, v150
	v_lshl_add_u64 v[152:153], v[136:137], 0, v[4:5]
	s_nop 0
	v_addc_co_u32_e32 v139, vcc, 0, v151, vcc
	v_add_co_u32_e32 v140, vcc, s5, v152
	s_mov_b32 s5, 0x81000
	s_nop 0
	v_addc_co_u32_e32 v141, vcc, 0, v153, vcc
	v_add_co_u32_e32 v142, vcc, s5, v150
	global_load_dwordx4 v[0:3], v[150:151], off
	s_nop 0
	v_addc_co_u32_e32 v143, vcc, 0, v151, vcc
	v_add_co_u32_e32 v144, vcc, s5, v152
	s_mov_b32 s5, 0xc1000
	s_nop 0
	v_addc_co_u32_e32 v145, vcc, 0, v153, vcc
	v_add_co_u32_e32 v146, vcc, s5, v150
	global_load_dwordx4 v[4:7], v[152:153], off
	s_nop 0
	v_addc_co_u32_e32 v147, vcc, 0, v151, vcc
	v_add_co_u32_e32 v148, vcc, s5, v152
	global_load_dwordx4 v[8:11], v[138:139], off offset:-4096
	global_load_dwordx4 v[12:15], v[140:141], off offset:-4096
	global_load_dwordx4 v[16:19], v[142:143], off offset:-4096
	global_load_dwordx4 v[20:23], v[144:145], off offset:-4096
	v_addc_co_u32_e32 v149, vcc, 0, v153, vcc
	global_load_dwordx4 v[24:27], v[146:147], off offset:-4096
	global_load_dwordx4 v[28:31], v[148:149], off offset:-4096
	global_load_dwordx4 v[80:83], v[150:151], off offset:128
	s_mov_b64 s[6:7], 0x40000
	s_mov_b64 s[8:9], 0x80000
	s_mov_b64 s[10:11], 0xc0000
	v_lshl_add_u64 v[158:159], v[150:151], 0, s[6:7]
	v_lshl_add_u64 v[156:157], v[150:151], 0, s[8:9]
	v_lshl_add_u64 v[154:155], v[150:151], 0, s[10:11]
	v_lshl_add_u64 v[164:165], v[152:153], 0, s[6:7]
	v_lshl_add_u64 v[162:163], v[152:153], 0, s[8:9]
	v_lshl_add_u64 v[160:161], v[152:153], 0, s[10:11]
	global_load_dwordx4 v[84:87], v[152:153], off offset:128
	global_load_dwordx4 v[88:91], v[158:159], off offset:128
	global_load_dwordx4 v[92:95], v[156:157], off offset:128
	global_load_dwordx4 v[112:115], v[154:155], off offset:128
	global_load_dwordx4 v[104:107], v[164:165], off offset:128
	global_load_dwordx4 v[116:119], v[162:163], off offset:128
	global_load_dwordx4 v[120:123], v[160:161], off offset:128
	s_waitcnt lgkmcnt(0)
	s_barrier
	global_load_dwordx4 v[124:127], v[150:151], off offset:256
	global_load_dwordx4 v[186:189], v[152:153], off offset:256
	global_load_dwordx4 v[96:99], v[158:159], off offset:256
	global_load_dwordx4 v[100:103], v[164:165], off offset:256
	global_load_dwordx4 v[72:75], v[156:157], off offset:256
	global_load_dwordx4 v[76:79], v[162:163], off offset:256
	global_load_dwordx4 v[64:67], v[154:155], off offset:256
	global_load_dwordx4 v[68:71], v[160:161], off offset:256
	s_movk_i32 s5, 0x1000
	s_waitcnt vmcnt(23)
	ds_write_b128 v130, v[0:3]
	s_waitcnt vmcnt(22)
	ds_write_b128 v130, v[4:7] offset:18432
	s_waitcnt vmcnt(21)
	ds_write_b128 v130, v[8:11] offset:4608
	s_waitcnt vmcnt(20)
	ds_write_b128 v130, v[12:15] offset:23040
	s_waitcnt vmcnt(19)
	ds_write_b128 v130, v[16:19] offset:9216
	s_waitcnt vmcnt(18)
	ds_write_b128 v130, v[20:23] offset:27648
	s_waitcnt vmcnt(17)
	ds_write_b128 v130, v[24:27] offset:13824
	s_waitcnt vmcnt(16)
	ds_write_b128 v130, v[28:31] offset:32256
	s_waitcnt lgkmcnt(0)
	s_barrier
	ds_read_b128 v[0:3], v167 offset:18432
	ds_read_b128 v[4:7], v132
	ds_read_b128 v[8:11], v132 offset:4608
	s_waitcnt lgkmcnt(1)
	v_mfma_f32_32x32x16_bf16 v[48:63], v[0:3], v[4:7], 0
	s_waitcnt lgkmcnt(0)
	v_mfma_f32_32x32x16_bf16 v[32:47], v[0:3], v[8:11], 0
	ds_read_b128 v[0:3], v167 offset:23040
	ds_read_b128 v[108:111], v167 offset:18464
	ds_read_b128 v[194:197], v132 offset:32
	ds_read_b128 v[200:203], v132 offset:4640
	s_waitcnt lgkmcnt(1)
	v_mfma_f32_32x32x16_bf16 v[48:63], v[108:111], v[194:197], v[48:63]
	s_waitcnt lgkmcnt(0)
	v_mfma_f32_32x32x16_bf16 v[32:47], v[108:111], v[200:203], v[32:47]
	ds_read_b128 v[108:111], v167 offset:23072
	s_waitcnt vmcnt(15)
	ds_write_b128 v130, v[80:83] offset:36864
	s_waitcnt vmcnt(14)
	ds_write_b128 v130, v[84:87] offset:55296
	ds_read_b128 v[80:83], v167 offset:18496
	ds_read_b128 v[84:87], v132 offset:64
	v_mfma_f32_32x32x16_bf16 v[16:31], v[0:3], v[4:7], 0
	v_mfma_f32_32x32x16_bf16 v[0:15], v[0:3], v[8:11], 0
	s_waitcnt lgkmcnt(4)
	v_mfma_f32_32x32x16_bf16 v[16:31], v[108:111], v[194:197], v[16:31]
	v_mfma_f32_32x32x16_bf16 v[0:15], v[108:111], v[200:203], v[0:15]
	ds_read_b128 v[108:111], v132 offset:4672
	s_waitcnt lgkmcnt(1)
	v_mfma_f32_32x32x16_bf16 v[48:63], v[80:83], v[84:87], v[48:63]
	s_waitcnt lgkmcnt(0)
	v_mfma_f32_32x32x16_bf16 v[32:47], v[80:83], v[108:111], v[32:47]
	ds_read_b128 v[80:83], v167 offset:23104
	s_waitcnt vmcnt(13)
	ds_write_b128 v130, v[88:91] offset:41472
	s_waitcnt vmcnt(10)
	ds_write_b128 v130, v[104:107] offset:59904
	s_waitcnt lgkmcnt(2)
	v_mfma_f32_32x32x16_bf16 v[16:31], v[80:83], v[84:87], v[16:31]
	v_mfma_f32_32x32x16_bf16 v[0:15], v[80:83], v[108:111], v[0:15]
	ds_read_b128 v[80:83], v167 offset:18528
	ds_read_b128 v[84:87], v132 offset:96
	ds_read_b128 v[88:91], v132 offset:4704
	ds_read_b128 v[194:197], v167 offset:23136
	global_load_dwordx4 v[200:203], v[150:151], off offset:384
	s_waitcnt lgkmcnt(2)
	v_mfma_f32_32x32x16_bf16 v[48:63], v[80:83], v[84:87], v[48:63]
	s_waitcnt lgkmcnt(1)
	v_mfma_f32_32x32x16_bf16 v[32:47], v[80:83], v[88:91], v[32:47]
	s_waitcnt lgkmcnt(0)
	v_mfma_f32_32x32x16_bf16 v[16:31], v[194:197], v[84:87], v[16:31]
	global_load_dwordx4 v[204:207], v[152:153], off offset:384
	global_load_dwordx4 v[104:107], v[158:159], off offset:384
	global_load_dwordx4 v[108:111], v[164:165], off offset:384
	global_load_dwordx4 v[80:83], v[156:157], off offset:384
	global_load_dwordx4 v[84:87], v[162:163], off offset:384
	ds_write_b128 v130, v[92:95] offset:46080
	s_waitcnt vmcnt(15)
	ds_write_b128 v130, v[116:119] offset:64512
	ds_write_b128 v130, v[112:115] offset:50688
	s_waitcnt vmcnt(14)
	ds_write_b128 v131, v[120:123] offset:13824
	v_mfma_f32_32x32x16_bf16 v[0:15], v[194:197], v[88:91], v[0:15]
	global_load_dwordx4 v[88:91], v[154:155], off offset:384
	global_load_dwordx4 v[92:95], v[160:161], off offset:384
	s_waitcnt lgkmcnt(0)
	s_barrier
; #define GLOADQ(RA, RB, KT, q) do { const int k0_ = (KT) << 6; \
;     RA[q] = ldg16(ap.ptr(m0 + lrow + 32 * (q), k0_) + lkc); RB[q] = ldg16(W + (size_t)(n0 + lrow + 32 * (q)) * ldw + k0_ + lkc); } while (0)
; #define SSTOREQ(RA, RB, ST, q) do { \
;     *(u32x4*)(sA + (ST) * SBUF + (lrow + 32 * (q)) * GP + lkc) = RA[q]; *(u32x4*)(sB + (ST) * SBUF + (lrow + 32 * (q)) * GP + lkc) = RB[q]; } while (0)
; #define FLOAD(F, ST, ks) do { _Pragma("unroll") for (int a = 0; a < 2; ++a) { \
;     F[a] = *(const bf16x8*)(sB + (ST) * SBUF + (wn * 64 + a * 32 + r) * GP + (ks) * 16 + h * 8); \
;     F[2 + a] = *(const bf16x8*)(sA + (ST) * SBUF + (wm * 64 + a * 32 + r) * GP + (ks) * 16 + h * 8); } } while (0)
; #define FMMA(F) do { _Pragma("unroll") for (int a = 0; a < 2; ++a) _Pragma("unroll") for (int b = 0; b < 2; ++b) acc[a][b] = MFMA(F[a], F[2 + b], acc[a][b]); } while (0)
; template <bool MIDK, class AP, class EPI>
; DI void gemm_tile(const AP& ap, const u16* __restrict__ W, int ldw, int K, int m0, int n0, const EPI& epi, char* smem, float r0, float r1, int tid, bool dry) {
;     ...
;   for (int kt = 0; kt < nk; kt += 2) {
;     const bool l3 = kt + 3 < nk, s2 = kt + 2 < nk, l4 = kt + 4 < nk;
;     FLOAD(f0, 0, 0); FLOAD(f1, 0, 1);
;     FMMA(f0); SSTOREQ(ra1, rb1, 1, 0); if (l3) GLOADQ(ra1, rb1, kt + 3, 0);
;     FLOAD(f0, 0, 2);
;     FMMA(f1); SSTOREQ(ra1, rb1, 1, 1); if (l3) GLOADQ(ra1, rb1, kt + 3, 1);
;     FLOAD(f1, 0, 3);
;     FMMA(f0); SSTOREQ(ra1, rb1, 1, 2); if (l3) GLOADQ(ra1, rb1, kt + 3, 2);
;     FMMA(f1); SSTOREQ(ra1, rb1, 1, 3); if (l3) GLOADQ(ra1, rb1, kt + 3, 3);
;     __syncthreads();
;     FLOAD(f0, 1, 0); FLOAD(f1, 1, 1);
;     FMMA(f0); if (s2) SSTOREQ(ra0, rb0, 0, 0); if (l4) GLOADQ(ra0, rb0, kt + 4, 0);
;     FLOAD(f0, 1, 2);
;     FMMA(f1); if (s2) SSTOREQ(ra0, rb0, 0, 1); if (l4) GLOADQ(ra0, rb0, kt + 4, 1);
;     FLOAD(f1, 1, 3);
;     FMMA(f0); if (s2) SSTOREQ(ra0, rb0, 0, 2); if (l4) GLOADQ(ra0, rb0, kt + 4, 2);
;     FMMA(f1); if (s2) SSTOREQ(ra0, rb0, 0, 3); if (l4) GLOADQ(ra0, rb0, kt + 4, 3);
;     if (MIDK && kt == 6) {
; #pragma unroll
;       for (int a = 0; a < 2; ++a)
; #pragma unroll
;         for (int i = 0; i < 16; ++i) { acc[a][0][i] *= r0; acc[a][1][i] *= r1; }
;     }
;     __syncthreads();
	ds_read_b128 v[112:115], v167 offset:55296
	ds_read_b128 v[116:119], v132 offset:36864
	ds_read_b128 v[120:123], v132 offset:41472
	s_waitcnt lgkmcnt(1)
	v_mfma_f32_32x32x16_bf16 v[48:63], v[112:115], v[116:119], v[48:63]
	s_waitcnt lgkmcnt(0)
	v_mfma_f32_32x32x16_bf16 v[32:47], v[112:115], v[120:123], v[32:47]
	ds_read_b128 v[112:115], v167 offset:59904
	s_waitcnt lgkmcnt(0)
	v_mfma_f32_32x32x16_bf16 v[16:31], v[112:115], v[116:119], v[16:31]
	v_mfma_f32_32x32x16_bf16 v[0:15], v[112:115], v[120:123], v[0:15]
	ds_read_b128 v[112:115], v167 offset:55328
	ds_read_b128 v[116:119], v132 offset:36896
	ds_read_b128 v[120:123], v132 offset:41504
	s_waitcnt lgkmcnt(1)
	v_mfma_f32_32x32x16_bf16 v[48:63], v[112:115], v[116:119], v[48:63]
	s_waitcnt lgkmcnt(0)
	v_mfma_f32_32x32x16_bf16 v[32:47], v[112:115], v[120:123], v[32:47]
	ds_read_b128 v[112:115], v167 offset:59936
	s_waitcnt vmcnt(15)
	ds_write_b128 v130, v[124:127]
	s_waitcnt vmcnt(14)
	ds_write_b128 v130, v[186:189] offset:18432
	s_waitcnt lgkmcnt(2)
	v_mfma_f32_32x32x16_bf16 v[16:31], v[112:115], v[116:119], v[16:31]
	v_mfma_f32_32x32x16_bf16 v[0:15], v[112:115], v[120:123], v[0:15]
	ds_read_b128 v[112:115], v167 offset:55360
	ds_read_b128 v[116:119], v132 offset:36928
	ds_read_b128 v[120:123], v132 offset:41536
	s_waitcnt lgkmcnt(1)
	v_mfma_f32_32x32x16_bf16 v[48:63], v[112:115], v[116:119], v[48:63]
	s_waitcnt lgkmcnt(0)
	v_mfma_f32_32x32x16_bf16 v[32:47], v[112:115], v[120:123], v[32:47]
	ds_read_b128 v[112:115], v167 offset:59968
	s_waitcnt vmcnt(13)
	ds_write_b128 v130, v[96:99] offset:4608
	s_waitcnt vmcnt(12)
	ds_write_b128 v130, v[100:103] offset:23040
	ds_read_b128 v[96:99], v167 offset:55392
	ds_read_b128 v[100:103], v132 offset:36960
	s_waitcnt lgkmcnt(4)
	v_mfma_f32_32x32x16_bf16 v[16:31], v[112:115], v[116:119], v[16:31]
	ds_read_b128 v[116:119], v167 offset:60000
	v_mfma_f32_32x32x16_bf16 v[0:15], v[112:115], v[120:123], v[0:15]
	ds_read_b128 v[112:115], v132 offset:41568
	s_waitcnt lgkmcnt(2)
	v_mfma_f32_32x32x16_bf16 v[48:63], v[96:99], v[100:103], v[48:63]
	s_waitcnt lgkmcnt(0)
	v_mfma_f32_32x32x16_bf16 v[32:47], v[96:99], v[112:115], v[32:47]
	v_mfma_f32_32x32x16_bf16 v[16:31], v[116:119], v[100:103], v[16:31]
	global_load_dwordx4 v[120:123], v[150:151], off offset:512
	global_load_dwordx4 v[124:127], v[152:153], off offset:512
	global_load_dwordx4 v[96:99], v[158:159], off offset:512
	global_load_dwordx4 v[100:103], v[164:165], off offset:512
	s_waitcnt vmcnt(15)
	ds_write_b128 v130, v[72:75] offset:9216
	s_waitcnt vmcnt(14)
	ds_write_b128 v130, v[76:79] offset:27648
	global_load_dwordx4 v[72:75], v[156:157], off offset:512
	global_load_dwordx4 v[76:79], v[162:163], off offset:512
	s_waitcnt vmcnt(15)
	ds_write_b128 v130, v[64:67] offset:13824
	s_waitcnt vmcnt(14)
	ds_write_b128 v130, v[68:71] offset:32256
	global_load_dwordx4 v[64:67], v[154:155], off offset:512
	global_load_dwordx4 v[68:71], v[160:161], off offset:512
	s_waitcnt lgkmcnt(0)
	s_barrier
	v_mfma_f32_32x32x16_bf16 v[0:15], v[116:119], v[112:115], v[0:15]
	ds_read_b128 v[112:115], v167 offset:18432
	ds_read_b128 v[116:119], v132
	ds_read_b128 v[186:189], v132 offset:4608
	s_waitcnt lgkmcnt(1)
	v_mfma_f32_32x32x16_bf16 v[48:63], v[112:115], v[116:119], v[48:63]
	s_waitcnt lgkmcnt(0)
	v_mfma_f32_32x32x16_bf16 v[32:47], v[112:115], v[186:189], v[32:47]
	ds_read_b128 v[112:115], v167 offset:23040
	s_waitcnt lgkmcnt(0)
	v_mfma_f32_32x32x16_bf16 v[16:31], v[112:115], v[116:119], v[16:31]
	v_mfma_f32_32x32x16_bf16 v[0:15], v[112:115], v[186:189], v[0:15]
	ds_read_b128 v[112:115], v167 offset:18464
	ds_read_b128 v[116:119], v132 offset:32
	ds_read_b128 v[186:189], v132 offset:4640
	s_waitcnt lgkmcnt(1)
	v_mfma_f32_32x32x16_bf16 v[48:63], v[112:115], v[116:119], v[48:63]
	s_waitcnt lgkmcnt(0)
	v_mfma_f32_32x32x16_bf16 v[32:47], v[112:115], v[186:189], v[32:47]
	ds_read_b128 v[112:115], v167 offset:23072
	s_waitcnt vmcnt(15)
	ds_write_b128 v130, v[200:203] offset:36864
	s_waitcnt vmcnt(14)
	ds_write_b128 v130, v[204:207] offset:55296
	s_waitcnt lgkmcnt(2)
	v_mfma_f32_32x32x16_bf16 v[16:31], v[112:115], v[116:119], v[16:31]
	v_mfma_f32_32x32x16_bf16 v[0:15], v[112:115], v[186:189], v[0:15]
	ds_read_b128 v[112:115], v167 offset:18496
	ds_read_b128 v[116:119], v132 offset:64
	ds_read_b128 v[186:189], v132 offset:4672
	s_waitcnt lgkmcnt(1)
	v_mfma_f32_32x32x16_bf16 v[48:63], v[112:115], v[116:119], v[48:63]
	s_waitcnt lgkmcnt(0)
	v_mfma_f32_32x32x16_bf16 v[32:47], v[112:115], v[186:189], v[32:47]
	ds_read_b128 v[112:115], v167 offset:23104
	s_waitcnt vmcnt(13)
	ds_write_b128 v130, v[104:107] offset:41472
	s_waitcnt vmcnt(12)
	ds_write_b128 v130, v[108:111] offset:59904
	ds_read_b128 v[104:107], v167 offset:18528
	ds_read_b128 v[108:111], v132 offset:96
	s_waitcnt lgkmcnt(4)
	v_mfma_f32_32x32x16_bf16 v[16:31], v[112:115], v[116:119], v[16:31]
	ds_read_b128 v[116:119], v167 offset:23136
	v_mfma_f32_32x32x16_bf16 v[0:15], v[112:115], v[186:189], v[0:15]
	ds_read_b128 v[112:115], v132 offset:4704
	s_waitcnt lgkmcnt(2)
	v_mfma_f32_32x32x16_bf16 v[48:63], v[104:107], v[108:111], v[48:63]
	s_waitcnt lgkmcnt(0)
	v_mfma_f32_32x32x16_bf16 v[32:47], v[104:107], v[112:115], v[32:47]
	v_mfma_f32_32x32x16_bf16 v[16:31], v[116:119], v[108:111], v[16:31]
	global_load_dwordx4 v[186:189], v[150:151], off offset:640
	global_load_dwordx4 v[194:197], v[152:153], off offset:640
	global_load_dwordx4 v[104:107], v[158:159], off offset:640
	global_load_dwordx4 v[108:111], v[164:165], off offset:640
	s_waitcnt vmcnt(15)
	ds_write_b128 v130, v[80:83] offset:46080
	s_waitcnt vmcnt(14)
	ds_write_b128 v130, v[84:87] offset:64512
	global_load_dwordx4 v[80:83], v[156:157], off offset:640
	global_load_dwordx4 v[84:87], v[162:163], off offset:640
	s_waitcnt vmcnt(15)
	ds_write_b128 v130, v[88:91] offset:50688
	s_waitcnt vmcnt(14)
	ds_write_b128 v131, v[92:95] offset:13824
	global_load_dwordx4 v[88:91], v[154:155], off offset:640
	global_load_dwordx4 v[92:95], v[160:161], off offset:640
	s_waitcnt lgkmcnt(0)
	s_barrier
; #define GLOADQ(RA, RB, KT, q) do { const int k0_ = (KT) << 6; \
;     RA[q] = ldg16(ap.ptr(m0 + lrow + 32 * (q), k0_) + lkc); RB[q] = ldg16(W + (size_t)(n0 + lrow + 32 * (q)) * ldw + k0_ + lkc); } while (0)
; #define SSTOREQ(RA, RB, ST, q) do { \
;     *(u32x4*)(sA + (ST) * SBUF + (lrow + 32 * (q)) * GP + lkc) = RA[q]; *(u32x4*)(sB + (ST) * SBUF + (lrow + 32 * (q)) * GP + lkc) = RB[q]; } while (0)
; #define FLOAD(F, ST, ks) do { _Pragma("unroll") for (int a = 0; a < 2; ++a) { \
;     F[a] = *(const bf16x8*)(sB + (ST) * SBUF + (wn * 64 + a * 32 + r) * GP + (ks) * 16 + h * 8); \
;     F[2 + a] = *(const bf16x8*)(sA + (ST) * SBUF + (wm * 64 + a * 32 + r) * GP + (ks) * 16 + h * 8); } } while (0)
; #define FMMA(F) do { _Pragma("unroll") for (int a = 0; a < 2; ++a) _Pragma("unroll") for (int b = 0; b < 2; ++b) acc[a][b] = MFMA(F[a], F[2 + b], acc[a][b]); } while (0)
; template <bool MIDK, class AP, class EPI>
; DI void gemm_tile(const AP& ap, const u16* __restrict__ W, int ldw, int K, int m0, int n0, const EPI& epi, char* smem, float r0, float r1, int tid, bool dry) {
;     ...
;   for (int kt = 0; kt < nk; kt += 2) {
;     const bool l3 = kt + 3 < nk, s2 = kt + 2 < nk, l4 = kt + 4 < nk;
;     FLOAD(f0, 0, 0); FLOAD(f1, 0, 1);
;     FMMA(f0); SSTOREQ(ra1, rb1, 1, 0); if (l3) GLOADQ(ra1, rb1, kt + 3, 0);
;     FLOAD(f0, 0, 2);
;     FMMA(f1); SSTOREQ(ra1, rb1, 1, 1); if (l3) GLOADQ(ra1, rb1, kt + 3, 1);
;     FLOAD(f1, 0, 3);
;     FMMA(f0); SSTOREQ(ra1, rb1, 1, 2); if (l3) GLOADQ(ra1, rb1, kt + 3, 2);
;     FMMA(f1); SSTOREQ(ra1, rb1, 1, 3); if (l3) GLOADQ(ra1, rb1, kt + 3, 3);
;     __syncthreads();
;     FLOAD(f0, 1, 0); FLOAD(f1, 1, 1);
;     FMMA(f0); if (s2) SSTOREQ(ra0, rb0, 0, 0); if (l4) GLOADQ(ra0, rb0, kt + 4, 0);
;     FLOAD(f0, 1, 2);
;     FMMA(f1); if (s2) SSTOREQ(ra0, rb0, 0, 1); if (l4) GLOADQ(ra0, rb0, kt + 4, 1);
;     FLOAD(f1, 1, 3);
;     FMMA(f0); if (s2) SSTOREQ(ra0, rb0, 0, 2); if (l4) GLOADQ(ra0, rb0, kt + 4, 2);
;     FMMA(f1); if (s2) SSTOREQ(ra0, rb0, 0, 3); if (l4) GLOADQ(ra0, rb0, kt + 4, 3);
;     if (MIDK && kt == 6) {
; #pragma unroll
;       for (int a = 0; a < 2; ++a)
; #pragma unroll
;         for (int i = 0; i < 16; ++i) { acc[a][0][i] *= r0; acc[a][1][i] *= r1; }
;     }
;     __syncthreads();
	v_mfma_f32_32x32x16_bf16 v[0:15], v[116:119], v[112:115], v[0:15]
	ds_read_b128 v[112:115], v167 offset:55296
	ds_read_b128 v[116:119], v132 offset:36864
	ds_read_b128 v[200:203], v132 offset:41472
	s_waitcnt lgkmcnt(1)
	v_mfma_f32_32x32x16_bf16 v[48:63], v[112:115], v[116:119], v[48:63]
	s_waitcnt lgkmcnt(0)
	v_mfma_f32_32x32x16_bf16 v[32:47], v[112:115], v[200:203], v[32:47]
	ds_read_b128 v[112:115], v167 offset:59904
	s_waitcnt lgkmcnt(0)
	v_mfma_f32_32x32x16_bf16 v[16:31], v[112:115], v[116:119], v[16:31]
	v_mfma_f32_32x32x16_bf16 v[0:15], v[112:115], v[200:203], v[0:15]
	ds_read_b128 v[112:115], v167 offset:55328
	ds_read_b128 v[116:119], v132 offset:36896
	ds_read_b128 v[200:203], v132 offset:41504
	s_waitcnt lgkmcnt(1)
	v_mfma_f32_32x32x16_bf16 v[48:63], v[112:115], v[116:119], v[48:63]
	s_waitcnt lgkmcnt(0)
	v_mfma_f32_32x32x16_bf16 v[32:47], v[112:115], v[200:203], v[32:47]
	ds_read_b128 v[112:115], v167 offset:59936
	s_waitcnt vmcnt(15)
	ds_write_b128 v130, v[120:123]
	s_waitcnt vmcnt(14)
	ds_write_b128 v130, v[124:127] offset:18432
	s_waitcnt lgkmcnt(2)
	v_mfma_f32_32x32x16_bf16 v[16:31], v[112:115], v[116:119], v[16:31]
	v_mfma_f32_32x32x16_bf16 v[0:15], v[112:115], v[200:203], v[0:15]
	ds_read_b128 v[112:115], v167 offset:55360
	ds_read_b128 v[116:119], v132 offset:36928
	ds_read_b128 v[120:123], v132 offset:41536
	s_waitcnt lgkmcnt(1)
	v_mfma_f32_32x32x16_bf16 v[48:63], v[112:115], v[116:119], v[48:63]
	s_waitcnt lgkmcnt(0)
	v_mfma_f32_32x32x16_bf16 v[32:47], v[112:115], v[120:123], v[32:47]
	ds_read_b128 v[112:115], v167 offset:59968
	s_waitcnt vmcnt(13)
	ds_write_b128 v130, v[96:99] offset:4608
	s_waitcnt vmcnt(12)
	ds_write_b128 v130, v[100:103] offset:23040
	ds_read_b128 v[96:99], v167 offset:55392
	ds_read_b128 v[100:103], v132 offset:36960
	s_waitcnt lgkmcnt(4)
	v_mfma_f32_32x32x16_bf16 v[16:31], v[112:115], v[116:119], v[16:31]
	ds_read_b128 v[116:119], v167 offset:60000
	v_mfma_f32_32x32x16_bf16 v[0:15], v[112:115], v[120:123], v[0:15]
	ds_read_b128 v[112:115], v132 offset:41568
	s_waitcnt lgkmcnt(2)
	v_mfma_f32_32x32x16_bf16 v[48:63], v[96:99], v[100:103], v[48:63]
	s_waitcnt lgkmcnt(0)
	v_mfma_f32_32x32x16_bf16 v[32:47], v[96:99], v[112:115], v[32:47]
	v_mfma_f32_32x32x16_bf16 v[16:31], v[116:119], v[100:103], v[16:31]
	global_load_dwordx4 v[120:123], v[150:151], off offset:768
	global_load_dwordx4 v[124:127], v[152:153], off offset:768
	global_load_dwordx4 v[96:99], v[158:159], off offset:768
	global_load_dwordx4 v[100:103], v[164:165], off offset:768
	s_waitcnt vmcnt(15)
	ds_write_b128 v130, v[72:75] offset:9216
	s_waitcnt vmcnt(14)
	ds_write_b128 v130, v[76:79] offset:27648
	global_load_dwordx4 v[72:75], v[156:157], off offset:768
	global_load_dwordx4 v[76:79], v[162:163], off offset:768
	s_waitcnt vmcnt(15)
	ds_write_b128 v130, v[64:67] offset:13824
	s_waitcnt vmcnt(14)
	ds_write_b128 v130, v[68:71] offset:32256
	global_load_dwordx4 v[64:67], v[154:155], off offset:768
	global_load_dwordx4 v[68:71], v[160:161], off offset:768
	s_waitcnt lgkmcnt(0)
	s_barrier
	v_mfma_f32_32x32x16_bf16 v[0:15], v[116:119], v[112:115], v[0:15]
	ds_read_b128 v[112:115], v167 offset:18432
	ds_read_b128 v[116:119], v132
	ds_read_b128 v[200:203], v132 offset:4608
	s_waitcnt lgkmcnt(1)
	v_mfma_f32_32x32x16_bf16 v[48:63], v[112:115], v[116:119], v[48:63]
	s_waitcnt lgkmcnt(0)
	v_mfma_f32_32x32x16_bf16 v[32:47], v[112:115], v[200:203], v[32:47]
	ds_read_b128 v[112:115], v167 offset:23040
	s_waitcnt lgkmcnt(0)
	v_mfma_f32_32x32x16_bf16 v[16:31], v[112:115], v[116:119], v[16:31]
	v_mfma_f32_32x32x16_bf16 v[0:15], v[112:115], v[200:203], v[0:15]
	ds_read_b128 v[112:115], v167 offset:18464
	ds_read_b128 v[116:119], v132 offset:32
	ds_read_b128 v[200:203], v132 offset:4640
	s_waitcnt lgkmcnt(1)
	v_mfma_f32_32x32x16_bf16 v[48:63], v[112:115], v[116:119], v[48:63]
	s_waitcnt lgkmcnt(0)
	v_mfma_f32_32x32x16_bf16 v[32:47], v[112:115], v[200:203], v[32:47]
	ds_read_b128 v[112:115], v167 offset:23072
	s_waitcnt vmcnt(15)
	ds_write_b128 v130, v[186:189] offset:36864
	s_waitcnt vmcnt(14)
	ds_write_b128 v130, v[194:197] offset:55296
	s_waitcnt lgkmcnt(2)
	v_mfma_f32_32x32x16_bf16 v[16:31], v[112:115], v[116:119], v[16:31]
	v_mfma_f32_32x32x16_bf16 v[0:15], v[112:115], v[200:203], v[0:15]
	ds_read_b128 v[112:115], v167 offset:18496
	ds_read_b128 v[116:119], v132 offset:64
	ds_read_b128 v[186:189], v132 offset:4672
	s_waitcnt lgkmcnt(1)
	v_mfma_f32_32x32x16_bf16 v[48:63], v[112:115], v[116:119], v[48:63]
	s_waitcnt lgkmcnt(0)
	v_mfma_f32_32x32x16_bf16 v[32:47], v[112:115], v[186:189], v[32:47]
	ds_read_b128 v[112:115], v167 offset:23104
	s_waitcnt vmcnt(13)
	ds_write_b128 v130, v[104:107] offset:41472
	s_waitcnt vmcnt(12)
	ds_write_b128 v130, v[108:111] offset:59904
	ds_read_b128 v[104:107], v167 offset:18528
	ds_read_b128 v[108:111], v132 offset:96
	s_waitcnt lgkmcnt(4)
	v_mfma_f32_32x32x16_bf16 v[16:31], v[112:115], v[116:119], v[16:31]
	ds_read_b128 v[116:119], v167 offset:23136
	v_mfma_f32_32x32x16_bf16 v[0:15], v[112:115], v[186:189], v[0:15]
	ds_read_b128 v[112:115], v132 offset:4704
	s_waitcnt lgkmcnt(2)
	v_mfma_f32_32x32x16_bf16 v[48:63], v[104:107], v[108:111], v[48:63]
	s_waitcnt lgkmcnt(0)
	v_mfma_f32_32x32x16_bf16 v[32:47], v[104:107], v[112:115], v[32:47]
	v_mfma_f32_32x32x16_bf16 v[16:31], v[116:119], v[108:111], v[16:31]
	global_load_dwordx4 v[186:189], v[150:151], off offset:896
	global_load_dwordx4 v[194:197], v[152:153], off offset:896
	global_load_dwordx4 v[104:107], v[158:159], off offset:896
	global_load_dwordx4 v[108:111], v[164:165], off offset:896
	s_waitcnt vmcnt(15)
	ds_write_b128 v130, v[80:83] offset:46080
	s_waitcnt vmcnt(14)
	ds_write_b128 v130, v[84:87] offset:64512
	global_load_dwordx4 v[80:83], v[156:157], off offset:896
	global_load_dwordx4 v[84:87], v[162:163], off offset:896
	s_waitcnt vmcnt(15)
	ds_write_b128 v130, v[88:91] offset:50688
	s_waitcnt vmcnt(14)
	ds_write_b128 v131, v[92:95] offset:13824
	global_load_dwordx4 v[88:91], v[154:155], off offset:896
	global_load_dwordx4 v[92:95], v[160:161], off offset:896
	s_waitcnt lgkmcnt(0)
	s_barrier
; #define GLOADQ(RA, RB, KT, q) do { const int k0_ = (KT) << 6; \
;     RA[q] = ldg16(ap.ptr(m0 + lrow + 32 * (q), k0_) + lkc); RB[q] = ldg16(W + (size_t)(n0 + lrow + 32 * (q)) * ldw + k0_ + lkc); } while (0)
; #define SSTOREQ(RA, RB, ST, q) do { \
;     *(u32x4*)(sA + (ST) * SBUF + (lrow + 32 * (q)) * GP + lkc) = RA[q]; *(u32x4*)(sB + (ST) * SBUF + (lrow + 32 * (q)) * GP + lkc) = RB[q]; } while (0)
; #define FLOAD(F, ST, ks) do { _Pragma("unroll") for (int a = 0; a < 2; ++a) { \
;     F[a] = *(const bf16x8*)(sB + (ST) * SBUF + (wn * 64 + a * 32 + r) * GP + (ks) * 16 + h * 8); \
;     F[2 + a] = *(const bf16x8*)(sA + (ST) * SBUF + (wm * 64 + a * 32 + r) * GP + (ks) * 16 + h * 8); } } while (0)
; #define FMMA(F) do { _Pragma("unroll") for (int a = 0; a < 2; ++a) _Pragma("unroll") for (int b = 0; b < 2; ++b) acc[a][b] = MFMA(F[a], F[2 + b], acc[a][b]); } while (0)
; template <bool MIDK, class AP, class EPI>
; DI void gemm_tile(const AP& ap, const u16* __restrict__ W, int ldw, int K, int m0, int n0, const EPI& epi, char* smem, float r0, float r1, int tid, bool dry) {
;     ...
;   for (int kt = 0; kt < nk; kt += 2) {
;     const bool l3 = kt + 3 < nk, s2 = kt + 2 < nk, l4 = kt + 4 < nk;
;     FLOAD(f0, 0, 0); FLOAD(f1, 0, 1);
;     FMMA(f0); SSTOREQ(ra1, rb1, 1, 0); if (l3) GLOADQ(ra1, rb1, kt + 3, 0);
;     FLOAD(f0, 0, 2);
;     FMMA(f1); SSTOREQ(ra1, rb1, 1, 1); if (l3) GLOADQ(ra1, rb1, kt + 3, 1);
;     FLOAD(f1, 0, 3);
;     FMMA(f0); SSTOREQ(ra1, rb1, 1, 2); if (l3) GLOADQ(ra1, rb1, kt + 3, 2);
;     FMMA(f1); SSTOREQ(ra1, rb1, 1, 3); if (l3) GLOADQ(ra1, rb1, kt + 3, 3);
;     __syncthreads();
;     FLOAD(f0, 1, 0); FLOAD(f1, 1, 1);
;     FMMA(f0); if (s2) SSTOREQ(ra0, rb0, 0, 0); if (l4) GLOADQ(ra0, rb0, kt + 4, 0);
;     FLOAD(f0, 1, 2);
;     FMMA(f1); if (s2) SSTOREQ(ra0, rb0, 0, 1); if (l4) GLOADQ(ra0, rb0, kt + 4, 1);
;     FLOAD(f1, 1, 3);
;     FMMA(f0); if (s2) SSTOREQ(ra0, rb0, 0, 2); if (l4) GLOADQ(ra0, rb0, kt + 4, 2);
;     FMMA(f1); if (s2) SSTOREQ(ra0, rb0, 0, 3); if (l4) GLOADQ(ra0, rb0, kt + 4, 3);
;     if (MIDK && kt == 6) {
; #pragma unroll
;       for (int a = 0; a < 2; ++a)
; #pragma unroll
;         for (int i = 0; i < 16; ++i) { acc[a][0][i] *= r0; acc[a][1][i] *= r1; }
;     }
;     __syncthreads();
	v_mfma_f32_32x32x16_bf16 v[0:15], v[116:119], v[112:115], v[0:15]
	ds_read_b128 v[112:115], v167 offset:55296
	ds_read_b128 v[116:119], v132 offset:36864
	ds_read_b128 v[200:203], v132 offset:41472
	s_waitcnt lgkmcnt(1)
	v_mfma_f32_32x32x16_bf16 v[48:63], v[112:115], v[116:119], v[48:63]
	s_waitcnt lgkmcnt(0)
	v_mfma_f32_32x32x16_bf16 v[32:47], v[112:115], v[200:203], v[32:47]
	ds_read_b128 v[112:115], v167 offset:59904
	s_waitcnt lgkmcnt(0)
	v_mfma_f32_32x32x16_bf16 v[16:31], v[112:115], v[116:119], v[16:31]
	v_mfma_f32_32x32x16_bf16 v[0:15], v[112:115], v[200:203], v[0:15]
	ds_read_b128 v[112:115], v167 offset:55328
	ds_read_b128 v[116:119], v132 offset:36896
	ds_read_b128 v[200:203], v132 offset:41504
	s_waitcnt lgkmcnt(1)
	v_mfma_f32_32x32x16_bf16 v[48:63], v[112:115], v[116:119], v[48:63]
	s_waitcnt lgkmcnt(0)
	v_mfma_f32_32x32x16_bf16 v[32:47], v[112:115], v[200:203], v[32:47]
	ds_read_b128 v[112:115], v167 offset:59936
	s_waitcnt vmcnt(15)
	ds_write_b128 v130, v[120:123]
	s_waitcnt vmcnt(14)
	ds_write_b128 v130, v[124:127] offset:18432
	s_waitcnt lgkmcnt(2)
	v_mfma_f32_32x32x16_bf16 v[16:31], v[112:115], v[116:119], v[16:31]
	v_mfma_f32_32x32x16_bf16 v[0:15], v[112:115], v[200:203], v[0:15]
	ds_read_b128 v[112:115], v167 offset:55360
	ds_read_b128 v[116:119], v132 offset:36928
	ds_read_b128 v[120:123], v132 offset:41536
	s_waitcnt lgkmcnt(1)
	v_mfma_f32_32x32x16_bf16 v[48:63], v[112:115], v[116:119], v[48:63]
	s_waitcnt lgkmcnt(0)
	v_mfma_f32_32x32x16_bf16 v[32:47], v[112:115], v[120:123], v[32:47]
	ds_read_b128 v[112:115], v167 offset:59968
	s_waitcnt vmcnt(13)
	ds_write_b128 v130, v[96:99] offset:4608
	s_waitcnt vmcnt(12)
	ds_write_b128 v130, v[100:103] offset:23040
	ds_read_b128 v[96:99], v167 offset:55392
	ds_read_b128 v[100:103], v132 offset:36960
	s_waitcnt lgkmcnt(4)
	v_mfma_f32_32x32x16_bf16 v[16:31], v[112:115], v[116:119], v[16:31]
	ds_read_b128 v[116:119], v167 offset:60000
	v_mfma_f32_32x32x16_bf16 v[0:15], v[112:115], v[120:123], v[0:15]
	ds_read_b128 v[112:115], v132 offset:41568
	s_waitcnt lgkmcnt(2)
	v_mfma_f32_32x32x16_bf16 v[48:63], v[96:99], v[100:103], v[48:63]
	s_waitcnt lgkmcnt(0)
	v_mfma_f32_32x32x16_bf16 v[32:47], v[96:99], v[112:115], v[32:47]
	v_mfma_f32_32x32x16_bf16 v[16:31], v[116:119], v[100:103], v[16:31]
	global_load_dwordx4 v[120:123], v[150:151], off offset:1024
	global_load_dwordx4 v[124:127], v[152:153], off offset:1024
	global_load_dwordx4 v[96:99], v[158:159], off offset:1024
	global_load_dwordx4 v[100:103], v[164:165], off offset:1024
	s_waitcnt vmcnt(15)
	ds_write_b128 v130, v[72:75] offset:9216
	s_waitcnt vmcnt(14)
	ds_write_b128 v130, v[76:79] offset:27648
	global_load_dwordx4 v[72:75], v[156:157], off offset:1024
	global_load_dwordx4 v[76:79], v[162:163], off offset:1024
	s_waitcnt vmcnt(15)
	ds_write_b128 v130, v[64:67] offset:13824
	s_waitcnt vmcnt(14)
	ds_write_b128 v130, v[68:71] offset:32256
	global_load_dwordx4 v[64:67], v[154:155], off offset:1024
	global_load_dwordx4 v[68:71], v[160:161], off offset:1024
	s_waitcnt lgkmcnt(0)
	s_barrier
	v_mfma_f32_32x32x16_bf16 v[0:15], v[116:119], v[112:115], v[0:15]
	ds_read_b128 v[112:115], v167 offset:18432
	ds_read_b128 v[116:119], v132
	ds_read_b128 v[200:203], v132 offset:4608
	s_waitcnt lgkmcnt(1)
	v_mfma_f32_32x32x16_bf16 v[48:63], v[112:115], v[116:119], v[48:63]
	s_waitcnt lgkmcnt(0)
	v_mfma_f32_32x32x16_bf16 v[32:47], v[112:115], v[200:203], v[32:47]
	ds_read_b128 v[112:115], v167 offset:23040
	s_waitcnt lgkmcnt(0)
	v_mfma_f32_32x32x16_bf16 v[16:31], v[112:115], v[116:119], v[16:31]
	v_mfma_f32_32x32x16_bf16 v[0:15], v[112:115], v[200:203], v[0:15]
	ds_read_b128 v[112:115], v167 offset:18464
	ds_read_b128 v[116:119], v132 offset:32
	ds_read_b128 v[200:203], v132 offset:4640
	s_waitcnt lgkmcnt(1)
	v_mfma_f32_32x32x16_bf16 v[48:63], v[112:115], v[116:119], v[48:63]
	s_waitcnt lgkmcnt(0)
	v_mfma_f32_32x32x16_bf16 v[32:47], v[112:115], v[200:203], v[32:47]
	ds_read_b128 v[112:115], v167 offset:23072
	s_waitcnt vmcnt(15)
	ds_write_b128 v130, v[186:189] offset:36864
	s_waitcnt vmcnt(14)
	ds_write_b128 v130, v[194:197] offset:55296
	s_waitcnt lgkmcnt(2)
	v_mfma_f32_32x32x16_bf16 v[16:31], v[112:115], v[116:119], v[16:31]
	v_mfma_f32_32x32x16_bf16 v[0:15], v[112:115], v[200:203], v[0:15]
	ds_read_b128 v[112:115], v167 offset:18496
	ds_read_b128 v[116:119], v132 offset:64
	ds_read_b128 v[186:189], v132 offset:4672
	s_waitcnt lgkmcnt(1)
	v_mfma_f32_32x32x16_bf16 v[48:63], v[112:115], v[116:119], v[48:63]
	s_waitcnt lgkmcnt(0)
	v_mfma_f32_32x32x16_bf16 v[32:47], v[112:115], v[186:189], v[32:47]
	ds_read_b128 v[112:115], v167 offset:23104
	s_waitcnt vmcnt(13)
	ds_write_b128 v130, v[104:107] offset:41472
	s_waitcnt vmcnt(12)
	ds_write_b128 v130, v[108:111] offset:59904
	ds_read_b128 v[104:107], v167 offset:18528
	ds_read_b128 v[108:111], v132 offset:96
	s_waitcnt lgkmcnt(4)
	v_mfma_f32_32x32x16_bf16 v[16:31], v[112:115], v[116:119], v[16:31]
	ds_read_b128 v[116:119], v167 offset:23136
	v_mfma_f32_32x32x16_bf16 v[0:15], v[112:115], v[186:189], v[0:15]
	ds_read_b128 v[112:115], v132 offset:4704
	s_waitcnt lgkmcnt(2)
	v_mfma_f32_32x32x16_bf16 v[48:63], v[104:107], v[108:111], v[48:63]
	s_waitcnt lgkmcnt(0)
	v_mfma_f32_32x32x16_bf16 v[32:47], v[104:107], v[112:115], v[32:47]
	v_mfma_f32_32x32x16_bf16 v[16:31], v[116:119], v[108:111], v[16:31]
	global_load_dwordx4 v[186:189], v[150:151], off offset:1152
	global_load_dwordx4 v[194:197], v[152:153], off offset:1152
	global_load_dwordx4 v[104:107], v[158:159], off offset:1152
	global_load_dwordx4 v[108:111], v[164:165], off offset:1152
	s_waitcnt vmcnt(15)
	ds_write_b128 v130, v[80:83] offset:46080
	s_waitcnt vmcnt(14)
	ds_write_b128 v130, v[84:87] offset:64512
	global_load_dwordx4 v[80:83], v[156:157], off offset:1152
	global_load_dwordx4 v[84:87], v[162:163], off offset:1152
	s_waitcnt vmcnt(15)
	ds_write_b128 v130, v[88:91] offset:50688
	s_waitcnt vmcnt(14)
	ds_write_b128 v131, v[92:95] offset:13824
	global_load_dwordx4 v[88:91], v[154:155], off offset:1152
	global_load_dwordx4 v[92:95], v[160:161], off offset:1152
	s_waitcnt lgkmcnt(0)
	s_barrier
; #define GLOADQ(RA, RB, KT, q) do { const int k0_ = (KT) << 6; \
;     RA[q] = ldg16(ap.ptr(m0 + lrow + 32 * (q), k0_) + lkc); RB[q] = ldg16(W + (size_t)(n0 + lrow + 32 * (q)) * ldw + k0_ + lkc); } while (0)
; #define SSTOREQ(RA, RB, ST, q) do { \
;     *(u32x4*)(sA + (ST) * SBUF + (lrow + 32 * (q)) * GP + lkc) = RA[q]; *(u32x4*)(sB + (ST) * SBUF + (lrow + 32 * (q)) * GP + lkc) = RB[q]; } while (0)
; #define FLOAD(F, ST, ks) do { _Pragma("unroll") for (int a = 0; a < 2; ++a) { \
;     F[a] = *(const bf16x8*)(sB + (ST) * SBUF + (wn * 64 + a * 32 + r) * GP + (ks) * 16 + h * 8); \
;     F[2 + a] = *(const bf16x8*)(sA + (ST) * SBUF + (wm * 64 + a * 32 + r) * GP + (ks) * 16 + h * 8); } } while (0)
; #define FMMA(F) do { _Pragma("unroll") for (int a = 0; a < 2; ++a) _Pragma("unroll") for (int b = 0; b < 2; ++b) acc[a][b] = MFMA(F[a], F[2 + b], acc[a][b]); } while (0)
; template <bool MIDK, class AP, class EPI>
; DI void gemm_tile(const AP& ap, const u16* __restrict__ W, int ldw, int K, int m0, int n0, const EPI& epi, char* smem, float r0, float r1, int tid, bool dry) {
;     ...
;   for (int kt = 0; kt < nk; kt += 2) {
;     const bool l3 = kt + 3 < nk, s2 = kt + 2 < nk, l4 = kt + 4 < nk;
;     FLOAD(f0, 0, 0); FLOAD(f1, 0, 1);
;     FMMA(f0); SSTOREQ(ra1, rb1, 1, 0); if (l3) GLOADQ(ra1, rb1, kt + 3, 0);
;     FLOAD(f0, 0, 2);
;     FMMA(f1); SSTOREQ(ra1, rb1, 1, 1); if (l3) GLOADQ(ra1, rb1, kt + 3, 1);
;     FLOAD(f1, 0, 3);
;     FMMA(f0); SSTOREQ(ra1, rb1, 1, 2); if (l3) GLOADQ(ra1, rb1, kt + 3, 2);
;     FMMA(f1); SSTOREQ(ra1, rb1, 1, 3); if (l3) GLOADQ(ra1, rb1, kt + 3, 3);
;     __syncthreads();
;     FLOAD(f0, 1, 0); FLOAD(f1, 1, 1);
;     FMMA(f0); if (s2) SSTOREQ(ra0, rb0, 0, 0); if (l4) GLOADQ(ra0, rb0, kt + 4, 0);
;     FLOAD(f0, 1, 2);
;     FMMA(f1); if (s2) SSTOREQ(ra0, rb0, 0, 1); if (l4) GLOADQ(ra0, rb0, kt + 4, 1);
;     FLOAD(f1, 1, 3);
;     FMMA(f0); if (s2) SSTOREQ(ra0, rb0, 0, 2); if (l4) GLOADQ(ra0, rb0, kt + 4, 2);
;     FMMA(f1); if (s2) SSTOREQ(ra0, rb0, 0, 3); if (l4) GLOADQ(ra0, rb0, kt + 4, 3);
;     if (MIDK && kt == 6) {
; #pragma unroll
;       for (int a = 0; a < 2; ++a)
; #pragma unroll
;         for (int i = 0; i < 16; ++i) { acc[a][0][i] *= r0; acc[a][1][i] *= r1; }
;     }
;     __syncthreads();
	v_mfma_f32_32x32x16_bf16 v[0:15], v[116:119], v[112:115], v[0:15]
	ds_read_b128 v[112:115], v167 offset:55296
	ds_read_b128 v[116:119], v132 offset:36864
	ds_read_b128 v[200:203], v132 offset:41472
	s_waitcnt lgkmcnt(1)
	v_mfma_f32_32x32x16_bf16 v[48:63], v[112:115], v[116:119], v[48:63]
	s_waitcnt lgkmcnt(0)
	v_mfma_f32_32x32x16_bf16 v[32:47], v[112:115], v[200:203], v[32:47]
	ds_read_b128 v[112:115], v167 offset:59904
	s_waitcnt lgkmcnt(0)
	v_mfma_f32_32x32x16_bf16 v[16:31], v[112:115], v[116:119], v[16:31]
	v_mfma_f32_32x32x16_bf16 v[0:15], v[112:115], v[200:203], v[0:15]
	ds_read_b128 v[112:115], v167 offset:55328
	ds_read_b128 v[116:119], v132 offset:36896
	ds_read_b128 v[200:203], v132 offset:41504
	s_waitcnt lgkmcnt(1)
	v_mfma_f32_32x32x16_bf16 v[48:63], v[112:115], v[116:119], v[48:63]
	s_waitcnt lgkmcnt(0)
	v_mfma_f32_32x32x16_bf16 v[32:47], v[112:115], v[200:203], v[32:47]
	ds_read_b128 v[112:115], v167 offset:59936
	s_waitcnt vmcnt(15)
	ds_write_b128 v130, v[120:123]
	s_waitcnt vmcnt(14)
	ds_write_b128 v130, v[124:127] offset:18432
	s_waitcnt lgkmcnt(2)
	v_mfma_f32_32x32x16_bf16 v[16:31], v[112:115], v[116:119], v[16:31]
	v_mfma_f32_32x32x16_bf16 v[0:15], v[112:115], v[200:203], v[0:15]
	ds_read_b128 v[112:115], v167 offset:55360
	ds_read_b128 v[116:119], v132 offset:36928
	ds_read_b128 v[120:123], v132 offset:41536
	s_waitcnt lgkmcnt(1)
	v_mfma_f32_32x32x16_bf16 v[48:63], v[112:115], v[116:119], v[48:63]
	s_waitcnt lgkmcnt(0)
	v_mfma_f32_32x32x16_bf16 v[32:47], v[112:115], v[120:123], v[32:47]
	ds_read_b128 v[112:115], v167 offset:59968
	s_waitcnt vmcnt(13)
	ds_write_b128 v130, v[96:99] offset:4608
	s_waitcnt vmcnt(12)
	ds_write_b128 v130, v[100:103] offset:23040
	ds_read_b128 v[96:99], v167 offset:55392
	ds_read_b128 v[100:103], v132 offset:36960
	s_waitcnt lgkmcnt(4)
	v_mfma_f32_32x32x16_bf16 v[16:31], v[112:115], v[116:119], v[16:31]
	ds_read_b128 v[116:119], v167 offset:60000
	v_mfma_f32_32x32x16_bf16 v[0:15], v[112:115], v[120:123], v[0:15]
	ds_read_b128 v[112:115], v132 offset:41568
	s_waitcnt lgkmcnt(2)
	v_mfma_f32_32x32x16_bf16 v[48:63], v[96:99], v[100:103], v[48:63]
	s_waitcnt lgkmcnt(0)
	v_mfma_f32_32x32x16_bf16 v[32:47], v[96:99], v[112:115], v[32:47]
	v_mfma_f32_32x32x16_bf16 v[16:31], v[116:119], v[100:103], v[16:31]
	global_load_dwordx4 v[120:123], v[150:151], off offset:1280
	global_load_dwordx4 v[124:127], v[152:153], off offset:1280
	global_load_dwordx4 v[96:99], v[158:159], off offset:1280
	global_load_dwordx4 v[100:103], v[164:165], off offset:1280
	s_waitcnt vmcnt(15)
	ds_write_b128 v130, v[72:75] offset:9216
	s_waitcnt vmcnt(14)
	ds_write_b128 v130, v[76:79] offset:27648
	global_load_dwordx4 v[72:75], v[156:157], off offset:1280
	global_load_dwordx4 v[76:79], v[162:163], off offset:1280
	s_waitcnt vmcnt(15)
	ds_write_b128 v130, v[64:67] offset:13824
	s_waitcnt vmcnt(14)
	ds_write_b128 v130, v[68:71] offset:32256
	global_load_dwordx4 v[64:67], v[154:155], off offset:1280
	global_load_dwordx4 v[68:71], v[160:161], off offset:1280
	s_waitcnt lgkmcnt(0)
	s_barrier
	v_mfma_f32_32x32x16_bf16 v[0:15], v[116:119], v[112:115], v[0:15]
	ds_read_b128 v[112:115], v167 offset:18432
	ds_read_b128 v[116:119], v132
	ds_read_b128 v[200:203], v132 offset:4608
	s_waitcnt lgkmcnt(1)
	v_mfma_f32_32x32x16_bf16 v[48:63], v[112:115], v[116:119], v[48:63]
	s_waitcnt lgkmcnt(0)
	v_mfma_f32_32x32x16_bf16 v[32:47], v[112:115], v[200:203], v[32:47]
	ds_read_b128 v[112:115], v167 offset:23040
	s_waitcnt lgkmcnt(0)
	v_mfma_f32_32x32x16_bf16 v[16:31], v[112:115], v[116:119], v[16:31]
	v_mfma_f32_32x32x16_bf16 v[0:15], v[112:115], v[200:203], v[0:15]
	ds_read_b128 v[112:115], v167 offset:18464
	ds_read_b128 v[116:119], v132 offset:32
	ds_read_b128 v[200:203], v132 offset:4640
	s_waitcnt lgkmcnt(1)
	v_mfma_f32_32x32x16_bf16 v[48:63], v[112:115], v[116:119], v[48:63]
	s_waitcnt lgkmcnt(0)
	v_mfma_f32_32x32x16_bf16 v[32:47], v[112:115], v[200:203], v[32:47]
	ds_read_b128 v[112:115], v167 offset:23072
	s_waitcnt vmcnt(15)
	ds_write_b128 v130, v[186:189] offset:36864
	s_waitcnt vmcnt(14)
	ds_write_b128 v130, v[194:197] offset:55296
	s_waitcnt lgkmcnt(2)
	v_mfma_f32_32x32x16_bf16 v[16:31], v[112:115], v[116:119], v[16:31]
	v_mfma_f32_32x32x16_bf16 v[0:15], v[112:115], v[200:203], v[0:15]
	ds_read_b128 v[112:115], v167 offset:18496
	ds_read_b128 v[116:119], v132 offset:64
	ds_read_b128 v[186:189], v132 offset:4672
	s_waitcnt lgkmcnt(1)
	v_mfma_f32_32x32x16_bf16 v[48:63], v[112:115], v[116:119], v[48:63]
	s_waitcnt lgkmcnt(0)
	v_mfma_f32_32x32x16_bf16 v[32:47], v[112:115], v[186:189], v[32:47]
	ds_read_b128 v[112:115], v167 offset:23104
	s_waitcnt vmcnt(13)
	ds_write_b128 v130, v[104:107] offset:41472
	s_waitcnt vmcnt(12)
	ds_write_b128 v130, v[108:111] offset:59904
	ds_read_b128 v[104:107], v167 offset:18528
	ds_read_b128 v[108:111], v132 offset:96
	s_waitcnt lgkmcnt(4)
	v_mfma_f32_32x32x16_bf16 v[16:31], v[112:115], v[116:119], v[16:31]
	ds_read_b128 v[116:119], v167 offset:23136
	v_mfma_f32_32x32x16_bf16 v[0:15], v[112:115], v[186:189], v[0:15]
	ds_read_b128 v[112:115], v132 offset:4704
	s_waitcnt lgkmcnt(2)
	v_mfma_f32_32x32x16_bf16 v[48:63], v[104:107], v[108:111], v[48:63]
	s_waitcnt lgkmcnt(0)
	v_mfma_f32_32x32x16_bf16 v[32:47], v[104:107], v[112:115], v[32:47]
	v_mfma_f32_32x32x16_bf16 v[16:31], v[116:119], v[108:111], v[16:31]
	global_load_dwordx4 v[186:189], v[150:151], off offset:1408
	global_load_dwordx4 v[194:197], v[152:153], off offset:1408
	global_load_dwordx4 v[104:107], v[158:159], off offset:1408
	global_load_dwordx4 v[108:111], v[164:165], off offset:1408
	s_waitcnt vmcnt(15)
	ds_write_b128 v130, v[80:83] offset:46080
	s_waitcnt vmcnt(14)
	ds_write_b128 v130, v[84:87] offset:64512
	global_load_dwordx4 v[80:83], v[156:157], off offset:1408
	global_load_dwordx4 v[84:87], v[162:163], off offset:1408
	s_waitcnt vmcnt(15)
	ds_write_b128 v130, v[88:91] offset:50688
	s_waitcnt vmcnt(14)
	ds_write_b128 v131, v[92:95] offset:13824
	global_load_dwordx4 v[88:91], v[154:155], off offset:1408
	global_load_dwordx4 v[92:95], v[160:161], off offset:1408
	s_waitcnt lgkmcnt(0)
	s_barrier
; #define GLOADQ(RA, RB, KT, q) do { const int k0_ = (KT) << 6; \
;     RA[q] = ldg16(ap.ptr(m0 + lrow + 32 * (q), k0_) + lkc); RB[q] = ldg16(W + (size_t)(n0 + lrow + 32 * (q)) * ldw + k0_ + lkc); } while (0)
; #define SSTOREQ(RA, RB, ST, q) do { \
;     *(u32x4*)(sA + (ST) * SBUF + (lrow + 32 * (q)) * GP + lkc) = RA[q]; *(u32x4*)(sB + (ST) * SBUF + (lrow + 32 * (q)) * GP + lkc) = RB[q]; } while (0)
; #define FLOAD(F, ST, ks) do { _Pragma("unroll") for (int a = 0; a < 2; ++a) { \
;     F[a] = *(const bf16x8*)(sB + (ST) * SBUF + (wn * 64 + a * 32 + r) * GP + (ks) * 16 + h * 8); \
;     F[2 + a] = *(const bf16x8*)(sA + (ST) * SBUF + (wm * 64 + a * 32 + r) * GP + (ks) * 16 + h * 8); } } while (0)
; #define FMMA(F) do { _Pragma("unroll") for (int a = 0; a < 2; ++a) _Pragma("unroll") for (int b = 0; b < 2; ++b) acc[a][b] = MFMA(F[a], F[2 + b], acc[a][b]); } while (0)
; template <bool MIDK, class AP, class EPI>
; DI void gemm_tile(const AP& ap, const u16* __restrict__ W, int ldw, int K, int m0, int n0, const EPI& epi, char* smem, float r0, float r1, int tid, bool dry) {
;     ...
;   for (int kt = 0; kt < nk; kt += 2) {
;     const bool l3 = kt + 3 < nk, s2 = kt + 2 < nk, l4 = kt + 4 < nk;
;     FLOAD(f0, 0, 0); FLOAD(f1, 0, 1);
;     FMMA(f0); SSTOREQ(ra1, rb1, 1, 0); if (l3) GLOADQ(ra1, rb1, kt + 3, 0);
;     FLOAD(f0, 0, 2);
;     FMMA(f1); SSTOREQ(ra1, rb1, 1, 1); if (l3) GLOADQ(ra1, rb1, kt + 3, 1);
;     FLOAD(f1, 0, 3);
;     FMMA(f0); SSTOREQ(ra1, rb1, 1, 2); if (l3) GLOADQ(ra1, rb1, kt + 3, 2);
;     FMMA(f1); SSTOREQ(ra1, rb1, 1, 3); if (l3) GLOADQ(ra1, rb1, kt + 3, 3);
;     __syncthreads();
;     FLOAD(f0, 1, 0); FLOAD(f1, 1, 1);
;     FMMA(f0); if (s2) SSTOREQ(ra0, rb0, 0, 0); if (l4) GLOADQ(ra0, rb0, kt + 4, 0);
;     FLOAD(f0, 1, 2);
;     FMMA(f1); if (s2) SSTOREQ(ra0, rb0, 0, 1); if (l4) GLOADQ(ra0, rb0, kt + 4, 1);
;     FLOAD(f1, 1, 3);
;     FMMA(f0); if (s2) SSTOREQ(ra0, rb0, 0, 2); if (l4) GLOADQ(ra0, rb0, kt + 4, 2);
;     FMMA(f1); if (s2) SSTOREQ(ra0, rb0, 0, 3); if (l4) GLOADQ(ra0, rb0, kt + 4, 3);
;     if (MIDK && kt == 6) {
; #pragma unroll
;       for (int a = 0; a < 2; ++a)
; #pragma unroll
;         for (int i = 0; i < 16; ++i) { acc[a][0][i] *= r0; acc[a][1][i] *= r1; }
;     }
;     __syncthreads();
	v_mfma_f32_32x32x16_bf16 v[0:15], v[116:119], v[112:115], v[0:15]
	ds_read_b128 v[112:115], v167 offset:55296
	ds_read_b128 v[116:119], v132 offset:36864
	ds_read_b128 v[200:203], v132 offset:41472
	s_waitcnt lgkmcnt(1)
	v_mfma_f32_32x32x16_bf16 v[48:63], v[112:115], v[116:119], v[48:63]
	s_waitcnt lgkmcnt(0)
	v_mfma_f32_32x32x16_bf16 v[32:47], v[112:115], v[200:203], v[32:47]
	ds_read_b128 v[112:115], v167 offset:59904
	s_waitcnt lgkmcnt(0)
	v_mfma_f32_32x32x16_bf16 v[16:31], v[112:115], v[116:119], v[16:31]
	v_mfma_f32_32x32x16_bf16 v[0:15], v[112:115], v[200:203], v[0:15]
	ds_read_b128 v[112:115], v167 offset:55328
	ds_read_b128 v[116:119], v132 offset:36896
	ds_read_b128 v[200:203], v132 offset:41504
	s_waitcnt lgkmcnt(1)
	v_mfma_f32_32x32x16_bf16 v[48:63], v[112:115], v[116:119], v[48:63]
	s_waitcnt lgkmcnt(0)
	v_mfma_f32_32x32x16_bf16 v[32:47], v[112:115], v[200:203], v[32:47]
	ds_read_b128 v[112:115], v167 offset:59936
	s_waitcnt vmcnt(15)
	ds_write_b128 v130, v[120:123]
	s_waitcnt vmcnt(14)
	ds_write_b128 v130, v[124:127] offset:18432
	s_waitcnt lgkmcnt(2)
	v_mfma_f32_32x32x16_bf16 v[16:31], v[112:115], v[116:119], v[16:31]
	v_mfma_f32_32x32x16_bf16 v[0:15], v[112:115], v[200:203], v[0:15]
	ds_read_b128 v[112:115], v167 offset:55360
	ds_read_b128 v[116:119], v132 offset:36928
	ds_read_b128 v[120:123], v132 offset:41536
	s_waitcnt lgkmcnt(1)
	v_mfma_f32_32x32x16_bf16 v[48:63], v[112:115], v[116:119], v[48:63]
	s_waitcnt lgkmcnt(0)
	v_mfma_f32_32x32x16_bf16 v[32:47], v[112:115], v[120:123], v[32:47]
	ds_read_b128 v[112:115], v167 offset:59968
	s_waitcnt vmcnt(13)
	ds_write_b128 v130, v[96:99] offset:4608
	s_waitcnt vmcnt(12)
	ds_write_b128 v130, v[100:103] offset:23040
	ds_read_b128 v[96:99], v167 offset:55392
	ds_read_b128 v[100:103], v132 offset:36960
	s_waitcnt lgkmcnt(4)
	v_mfma_f32_32x32x16_bf16 v[16:31], v[112:115], v[116:119], v[16:31]
	ds_read_b128 v[116:119], v167 offset:60000
	v_mfma_f32_32x32x16_bf16 v[0:15], v[112:115], v[120:123], v[0:15]
	ds_read_b128 v[112:115], v132 offset:41568
	s_waitcnt lgkmcnt(2)
	v_mfma_f32_32x32x16_bf16 v[48:63], v[96:99], v[100:103], v[48:63]
	s_waitcnt lgkmcnt(0)
	v_mfma_f32_32x32x16_bf16 v[32:47], v[96:99], v[112:115], v[32:47]
	v_mfma_f32_32x32x16_bf16 v[16:31], v[116:119], v[100:103], v[16:31]
	global_load_dwordx4 v[120:123], v[150:151], off offset:1536
	global_load_dwordx4 v[124:127], v[152:153], off offset:1536
	global_load_dwordx4 v[96:99], v[158:159], off offset:1536
	global_load_dwordx4 v[100:103], v[164:165], off offset:1536
	s_waitcnt vmcnt(15)
	ds_write_b128 v130, v[72:75] offset:9216
	s_waitcnt vmcnt(14)
	ds_write_b128 v130, v[76:79] offset:27648
	global_load_dwordx4 v[72:75], v[156:157], off offset:1536
	global_load_dwordx4 v[76:79], v[162:163], off offset:1536
	s_waitcnt vmcnt(15)
	ds_write_b128 v130, v[64:67] offset:13824
	s_waitcnt vmcnt(14)
	ds_write_b128 v130, v[68:71] offset:32256
	global_load_dwordx4 v[64:67], v[154:155], off offset:1536
	global_load_dwordx4 v[68:71], v[160:161], off offset:1536
	s_waitcnt lgkmcnt(0)
	s_barrier
	v_mfma_f32_32x32x16_bf16 v[0:15], v[116:119], v[112:115], v[0:15]
	ds_read_b128 v[112:115], v167 offset:18432
	ds_read_b128 v[116:119], v132
	ds_read_b128 v[200:203], v132 offset:4608
	s_waitcnt lgkmcnt(1)
	v_mfma_f32_32x32x16_bf16 v[48:63], v[112:115], v[116:119], v[48:63]
	s_waitcnt lgkmcnt(0)
	v_mfma_f32_32x32x16_bf16 v[32:47], v[112:115], v[200:203], v[32:47]
	ds_read_b128 v[112:115], v167 offset:23040
	s_waitcnt lgkmcnt(0)
	v_mfma_f32_32x32x16_bf16 v[16:31], v[112:115], v[116:119], v[16:31]
	v_mfma_f32_32x32x16_bf16 v[0:15], v[112:115], v[200:203], v[0:15]
	ds_read_b128 v[112:115], v167 offset:18464
	ds_read_b128 v[116:119], v132 offset:32
	ds_read_b128 v[200:203], v132 offset:4640
	s_waitcnt lgkmcnt(1)
	v_mfma_f32_32x32x16_bf16 v[48:63], v[112:115], v[116:119], v[48:63]
	s_waitcnt lgkmcnt(0)
	v_mfma_f32_32x32x16_bf16 v[32:47], v[112:115], v[200:203], v[32:47]
	ds_read_b128 v[112:115], v167 offset:23072
	s_waitcnt vmcnt(15)
	ds_write_b128 v130, v[186:189] offset:36864
	s_waitcnt vmcnt(14)
	ds_write_b128 v130, v[194:197] offset:55296
	s_waitcnt lgkmcnt(2)
	v_mfma_f32_32x32x16_bf16 v[16:31], v[112:115], v[116:119], v[16:31]
	v_mfma_f32_32x32x16_bf16 v[0:15], v[112:115], v[200:203], v[0:15]
	ds_read_b128 v[112:115], v167 offset:18496
	ds_read_b128 v[116:119], v132 offset:64
	ds_read_b128 v[186:189], v132 offset:4672
	s_waitcnt lgkmcnt(1)
	v_mfma_f32_32x32x16_bf16 v[48:63], v[112:115], v[116:119], v[48:63]
	s_waitcnt lgkmcnt(0)
	v_mfma_f32_32x32x16_bf16 v[32:47], v[112:115], v[186:189], v[32:47]
	ds_read_b128 v[112:115], v167 offset:23104
	s_waitcnt vmcnt(13)
	ds_write_b128 v130, v[104:107] offset:41472
	s_waitcnt vmcnt(12)
	ds_write_b128 v130, v[108:111] offset:59904
	ds_read_b128 v[104:107], v167 offset:18528
	ds_read_b128 v[108:111], v132 offset:96
	s_waitcnt lgkmcnt(4)
	v_mfma_f32_32x32x16_bf16 v[16:31], v[112:115], v[116:119], v[16:31]
	ds_read_b128 v[116:119], v167 offset:23136
	v_mfma_f32_32x32x16_bf16 v[0:15], v[112:115], v[186:189], v[0:15]
	ds_read_b128 v[112:115], v132 offset:4704
	s_waitcnt lgkmcnt(2)
	v_mfma_f32_32x32x16_bf16 v[48:63], v[104:107], v[108:111], v[48:63]
	s_waitcnt lgkmcnt(0)
	v_mfma_f32_32x32x16_bf16 v[32:47], v[104:107], v[112:115], v[32:47]
	v_mfma_f32_32x32x16_bf16 v[16:31], v[116:119], v[108:111], v[16:31]
	global_load_dwordx4 v[186:189], v[150:151], off offset:1664
	global_load_dwordx4 v[194:197], v[152:153], off offset:1664
	global_load_dwordx4 v[104:107], v[158:159], off offset:1664
	global_load_dwordx4 v[108:111], v[164:165], off offset:1664
	s_waitcnt vmcnt(15)
	ds_write_b128 v130, v[80:83] offset:46080
	s_waitcnt vmcnt(14)
	ds_write_b128 v130, v[84:87] offset:64512
	global_load_dwordx4 v[80:83], v[156:157], off offset:1664
	global_load_dwordx4 v[84:87], v[162:163], off offset:1664
	s_waitcnt vmcnt(15)
	ds_write_b128 v130, v[88:91] offset:50688
	s_waitcnt vmcnt(14)
	ds_write_b128 v131, v[92:95] offset:13824
	global_load_dwordx4 v[88:91], v[154:155], off offset:1664
	global_load_dwordx4 v[92:95], v[160:161], off offset:1664
	s_waitcnt lgkmcnt(0)
	s_barrier
; #define GLOADQ(RA, RB, KT, q) do { const int k0_ = (KT) << 6; \
;     RA[q] = ldg16(ap.ptr(m0 + lrow + 32 * (q), k0_) + lkc); RB[q] = ldg16(W + (size_t)(n0 + lrow + 32 * (q)) * ldw + k0_ + lkc); } while (0)
; #define SSTOREQ(RA, RB, ST, q) do { \
;     *(u32x4*)(sA + (ST) * SBUF + (lrow + 32 * (q)) * GP + lkc) = RA[q]; *(u32x4*)(sB + (ST) * SBUF + (lrow + 32 * (q)) * GP + lkc) = RB[q]; } while (0)
; #define FLOAD(F, ST, ks) do { _Pragma("unroll") for (int a = 0; a < 2; ++a) { \
;     F[a] = *(const bf16x8*)(sB + (ST) * SBUF + (wn * 64 + a * 32 + r) * GP + (ks) * 16 + h * 8); \
;     F[2 + a] = *(const bf16x8*)(sA + (ST) * SBUF + (wm * 64 + a * 32 + r) * GP + (ks) * 16 + h * 8); } } while (0)
; #define FMMA(F) do { _Pragma("unroll") for (int a = 0; a < 2; ++a) _Pragma("unroll") for (int b = 0; b < 2; ++b) acc[a][b] = MFMA(F[a], F[2 + b], acc[a][b]); } while (0)
; template <bool MIDK, class AP, class EPI>
; DI void gemm_tile(const AP& ap, const u16* __restrict__ W, int ldw, int K, int m0, int n0, const EPI& epi, char* smem, float r0, float r1, int tid, bool dry) {
;     ...
;   for (int kt = 0; kt < nk; kt += 2) {
;     const bool l3 = kt + 3 < nk, s2 = kt + 2 < nk, l4 = kt + 4 < nk;
;     FLOAD(f0, 0, 0); FLOAD(f1, 0, 1);
;     FMMA(f0); SSTOREQ(ra1, rb1, 1, 0); if (l3) GLOADQ(ra1, rb1, kt + 3, 0);
;     FLOAD(f0, 0, 2);
;     FMMA(f1); SSTOREQ(ra1, rb1, 1, 1); if (l3) GLOADQ(ra1, rb1, kt + 3, 1);
;     FLOAD(f1, 0, 3);
;     FMMA(f0); SSTOREQ(ra1, rb1, 1, 2); if (l3) GLOADQ(ra1, rb1, kt + 3, 2);
;     FMMA(f1); SSTOREQ(ra1, rb1, 1, 3); if (l3) GLOADQ(ra1, rb1, kt + 3, 3);
;     __syncthreads();
;     FLOAD(f0, 1, 0); FLOAD(f1, 1, 1);
;     FMMA(f0); if (s2) SSTOREQ(ra0, rb0, 0, 0); if (l4) GLOADQ(ra0, rb0, kt + 4, 0);
;     FLOAD(f0, 1, 2);
;     FMMA(f1); if (s2) SSTOREQ(ra0, rb0, 0, 1); if (l4) GLOADQ(ra0, rb0, kt + 4, 1);
;     FLOAD(f1, 1, 3);
;     FMMA(f0); if (s2) SSTOREQ(ra0, rb0, 0, 2); if (l4) GLOADQ(ra0, rb0, kt + 4, 2);
;     FMMA(f1); if (s2) SSTOREQ(ra0, rb0, 0, 3); if (l4) GLOADQ(ra0, rb0, kt + 4, 3);
;     if (MIDK && kt == 6) {
; #pragma unroll
;       for (int a = 0; a < 2; ++a)
; #pragma unroll
;         for (int i = 0; i < 16; ++i) { acc[a][0][i] *= r0; acc[a][1][i] *= r1; }
;     }
;     __syncthreads();
	v_mfma_f32_32x32x16_bf16 v[0:15], v[116:119], v[112:115], v[0:15]
	ds_read_b128 v[112:115], v167 offset:55296
	ds_read_b128 v[116:119], v132 offset:36864
	ds_read_b128 v[200:203], v132 offset:41472
	s_waitcnt lgkmcnt(1)
	v_mfma_f32_32x32x16_bf16 v[48:63], v[112:115], v[116:119], v[48:63]
	s_waitcnt lgkmcnt(0)
	v_mfma_f32_32x32x16_bf16 v[32:47], v[112:115], v[200:203], v[32:47]
	ds_read_b128 v[112:115], v167 offset:59904
	s_waitcnt lgkmcnt(0)
	v_mfma_f32_32x32x16_bf16 v[16:31], v[112:115], v[116:119], v[16:31]
	v_mfma_f32_32x32x16_bf16 v[0:15], v[112:115], v[200:203], v[0:15]
	ds_read_b128 v[112:115], v167 offset:55328
	ds_read_b128 v[116:119], v132 offset:36896
	ds_read_b128 v[200:203], v132 offset:41504
	s_waitcnt lgkmcnt(1)
	v_mfma_f32_32x32x16_bf16 v[48:63], v[112:115], v[116:119], v[48:63]
	s_waitcnt lgkmcnt(0)
	v_mfma_f32_32x32x16_bf16 v[32:47], v[112:115], v[200:203], v[32:47]
	ds_read_b128 v[112:115], v167 offset:59936
	s_waitcnt vmcnt(15)
	ds_write_b128 v130, v[120:123]
	s_waitcnt vmcnt(14)
	ds_write_b128 v130, v[124:127] offset:18432
	s_waitcnt lgkmcnt(2)
	v_mfma_f32_32x32x16_bf16 v[16:31], v[112:115], v[116:119], v[16:31]
	v_mfma_f32_32x32x16_bf16 v[0:15], v[112:115], v[200:203], v[0:15]
	ds_read_b128 v[112:115], v167 offset:55360
	ds_read_b128 v[116:119], v132 offset:36928
	ds_read_b128 v[120:123], v132 offset:41536
	s_waitcnt lgkmcnt(1)
	v_mfma_f32_32x32x16_bf16 v[48:63], v[112:115], v[116:119], v[48:63]
	s_waitcnt lgkmcnt(0)
	v_mfma_f32_32x32x16_bf16 v[32:47], v[112:115], v[120:123], v[32:47]
	ds_read_b128 v[112:115], v167 offset:59968
	s_waitcnt vmcnt(13)
	ds_write_b128 v130, v[96:99] offset:4608
	s_waitcnt vmcnt(12)
	ds_write_b128 v130, v[100:103] offset:23040
	ds_read_b128 v[96:99], v167 offset:55392
	ds_read_b128 v[100:103], v132 offset:36960
	s_waitcnt lgkmcnt(4)
	v_mfma_f32_32x32x16_bf16 v[16:31], v[112:115], v[116:119], v[16:31]
	ds_read_b128 v[116:119], v167 offset:60000
	v_mfma_f32_32x32x16_bf16 v[0:15], v[112:115], v[120:123], v[0:15]
	ds_read_b128 v[112:115], v132 offset:41568
	s_waitcnt lgkmcnt(2)
	v_mfma_f32_32x32x16_bf16 v[48:63], v[96:99], v[100:103], v[48:63]
	s_waitcnt lgkmcnt(0)
	v_mfma_f32_32x32x16_bf16 v[32:47], v[96:99], v[112:115], v[32:47]
	v_mfma_f32_32x32x16_bf16 v[16:31], v[116:119], v[100:103], v[16:31]
	global_load_dwordx4 v[120:123], v[150:151], off offset:1792
	global_load_dwordx4 v[124:127], v[152:153], off offset:1792
	global_load_dwordx4 v[96:99], v[158:159], off offset:1792
	global_load_dwordx4 v[100:103], v[164:165], off offset:1792
	s_waitcnt vmcnt(15)
	ds_write_b128 v130, v[72:75] offset:9216
	s_waitcnt vmcnt(14)
	ds_write_b128 v130, v[76:79] offset:27648
	global_load_dwordx4 v[72:75], v[156:157], off offset:1792
	global_load_dwordx4 v[76:79], v[162:163], off offset:1792
	s_waitcnt vmcnt(15)
	ds_write_b128 v130, v[64:67] offset:13824
	s_waitcnt vmcnt(14)
	ds_write_b128 v130, v[68:71] offset:32256
	global_load_dwordx4 v[64:67], v[154:155], off offset:1792
	global_load_dwordx4 v[68:71], v[160:161], off offset:1792
	s_waitcnt lgkmcnt(0)
	s_barrier
	v_mfma_f32_32x32x16_bf16 v[0:15], v[116:119], v[112:115], v[0:15]
	ds_read_b128 v[112:115], v167 offset:18432
	ds_read_b128 v[116:119], v132
	ds_read_b128 v[200:203], v132 offset:4608
	s_waitcnt lgkmcnt(1)
	v_mfma_f32_32x32x16_bf16 v[48:63], v[112:115], v[116:119], v[48:63]
	s_waitcnt lgkmcnt(0)
	v_mfma_f32_32x32x16_bf16 v[32:47], v[112:115], v[200:203], v[32:47]
	ds_read_b128 v[112:115], v167 offset:23040
	s_waitcnt lgkmcnt(0)
	v_mfma_f32_32x32x16_bf16 v[16:31], v[112:115], v[116:119], v[16:31]
	v_mfma_f32_32x32x16_bf16 v[0:15], v[112:115], v[200:203], v[0:15]
	ds_read_b128 v[112:115], v167 offset:18464
	ds_read_b128 v[116:119], v132 offset:32
	ds_read_b128 v[200:203], v132 offset:4640
	s_waitcnt lgkmcnt(1)
	v_mfma_f32_32x32x16_bf16 v[48:63], v[112:115], v[116:119], v[48:63]
	s_waitcnt lgkmcnt(0)
	v_mfma_f32_32x32x16_bf16 v[32:47], v[112:115], v[200:203], v[32:47]
	ds_read_b128 v[112:115], v167 offset:23072
	s_waitcnt vmcnt(15)
	ds_write_b128 v130, v[186:189] offset:36864
	s_waitcnt vmcnt(14)
	ds_write_b128 v130, v[194:197] offset:55296
	s_waitcnt lgkmcnt(2)
	v_mfma_f32_32x32x16_bf16 v[16:31], v[112:115], v[116:119], v[16:31]
	v_mfma_f32_32x32x16_bf16 v[0:15], v[112:115], v[200:203], v[0:15]
	ds_read_b128 v[112:115], v167 offset:18496
	ds_read_b128 v[116:119], v132 offset:64
	ds_read_b128 v[186:189], v132 offset:4672
	s_waitcnt lgkmcnt(1)
	v_mfma_f32_32x32x16_bf16 v[48:63], v[112:115], v[116:119], v[48:63]
	s_waitcnt lgkmcnt(0)
	v_mfma_f32_32x32x16_bf16 v[32:47], v[112:115], v[186:189], v[32:47]
	ds_read_b128 v[112:115], v167 offset:23104
	s_waitcnt vmcnt(13)
	ds_write_b128 v130, v[104:107] offset:41472
	s_waitcnt vmcnt(12)
	ds_write_b128 v130, v[108:111] offset:59904
	ds_read_b128 v[104:107], v167 offset:18528
	ds_read_b128 v[108:111], v132 offset:96
	s_waitcnt lgkmcnt(4)
	v_mfma_f32_32x32x16_bf16 v[16:31], v[112:115], v[116:119], v[16:31]
	ds_read_b128 v[116:119], v167 offset:23136
	v_mfma_f32_32x32x16_bf16 v[0:15], v[112:115], v[186:189], v[0:15]
	ds_read_b128 v[112:115], v132 offset:4704
	s_waitcnt lgkmcnt(2)
	v_mfma_f32_32x32x16_bf16 v[48:63], v[104:107], v[108:111], v[48:63]
	s_waitcnt lgkmcnt(0)
	v_mfma_f32_32x32x16_bf16 v[32:47], v[104:107], v[112:115], v[32:47]
	v_mfma_f32_32x32x16_bf16 v[16:31], v[116:119], v[108:111], v[16:31]
	global_load_dwordx4 v[186:189], v[150:151], off offset:1920
	global_load_dwordx4 v[194:197], v[152:153], off offset:1920
	global_load_dwordx4 v[104:107], v[158:159], off offset:1920
	global_load_dwordx4 v[108:111], v[164:165], off offset:1920
	s_waitcnt vmcnt(15)
	ds_write_b128 v130, v[80:83] offset:46080
	s_waitcnt vmcnt(14)
	ds_write_b128 v130, v[84:87] offset:64512
	global_load_dwordx4 v[80:83], v[156:157], off offset:1920
	global_load_dwordx4 v[84:87], v[162:163], off offset:1920
	s_waitcnt vmcnt(15)
	ds_write_b128 v130, v[88:91] offset:50688
	s_waitcnt vmcnt(14)
	ds_write_b128 v131, v[92:95] offset:13824
	global_load_dwordx4 v[88:91], v[154:155], off offset:1920
	global_load_dwordx4 v[92:95], v[160:161], off offset:1920
	s_waitcnt lgkmcnt(0)
	s_barrier
; #define GLOADQ(RA, RB, KT, q) do { const int k0_ = (KT) << 6; \
;     RA[q] = ldg16(ap.ptr(m0 + lrow + 32 * (q), k0_) + lkc); RB[q] = ldg16(W + (size_t)(n0 + lrow + 32 * (q)) * ldw + k0_ + lkc); } while (0)
; #define SSTOREQ(RA, RB, ST, q) do { \
;     *(u32x4*)(sA + (ST) * SBUF + (lrow + 32 * (q)) * GP + lkc) = RA[q]; *(u32x4*)(sB + (ST) * SBUF + (lrow + 32 * (q)) * GP + lkc) = RB[q]; } while (0)
; #define FLOAD(F, ST, ks) do { _Pragma("unroll") for (int a = 0; a < 2; ++a) { \
;     F[a] = *(const bf16x8*)(sB + (ST) * SBUF + (wn * 64 + a * 32 + r) * GP + (ks) * 16 + h * 8); \
;     F[2 + a] = *(const bf16x8*)(sA + (ST) * SBUF + (wm * 64 + a * 32 + r) * GP + (ks) * 16 + h * 8); } } while (0)
; #define FMMA(F) do { _Pragma("unroll") for (int a = 0; a < 2; ++a) _Pragma("unroll") for (int b = 0; b < 2; ++b) acc[a][b] = MFMA(F[a], F[2 + b], acc[a][b]); } while (0)
; template <bool MIDK, class AP, class EPI>
; DI void gemm_tile(const AP& ap, const u16* __restrict__ W, int ldw, int K, int m0, int n0, const EPI& epi, char* smem, float r0, float r1, int tid, bool dry) {
;     ...
;   for (int kt = 0; kt < nk; kt += 2) {
;     const bool l3 = kt + 3 < nk, s2 = kt + 2 < nk, l4 = kt + 4 < nk;
;     FLOAD(f0, 0, 0); FLOAD(f1, 0, 1);
;     FMMA(f0); SSTOREQ(ra1, rb1, 1, 0); if (l3) GLOADQ(ra1, rb1, kt + 3, 0);
;     FLOAD(f0, 0, 2);
;     FMMA(f1); SSTOREQ(ra1, rb1, 1, 1); if (l3) GLOADQ(ra1, rb1, kt + 3, 1);
;     FLOAD(f1, 0, 3);
;     FMMA(f0); SSTOREQ(ra1, rb1, 1, 2); if (l3) GLOADQ(ra1, rb1, kt + 3, 2);
;     FMMA(f1); SSTOREQ(ra1, rb1, 1, 3); if (l3) GLOADQ(ra1, rb1, kt + 3, 3);
;     __syncthreads();
;     FLOAD(f0, 1, 0); FLOAD(f1, 1, 1);
;     FMMA(f0); if (s2) SSTOREQ(ra0, rb0, 0, 0); if (l4) GLOADQ(ra0, rb0, kt + 4, 0);
;     FLOAD(f0, 1, 2);
;     FMMA(f1); if (s2) SSTOREQ(ra0, rb0, 0, 1); if (l4) GLOADQ(ra0, rb0, kt + 4, 1);
;     FLOAD(f1, 1, 3);
;     FMMA(f0); if (s2) SSTOREQ(ra0, rb0, 0, 2); if (l4) GLOADQ(ra0, rb0, kt + 4, 2);
;     FMMA(f1); if (s2) SSTOREQ(ra0, rb0, 0, 3); if (l4) GLOADQ(ra0, rb0, kt + 4, 3);
;     if (MIDK && kt == 6) {
; #pragma unroll
;       for (int a = 0; a < 2; ++a)
; #pragma unroll
;         for (int i = 0; i < 16; ++i) { acc[a][0][i] *= r0; acc[a][1][i] *= r1; }
;     }
;     __syncthreads();
	v_mfma_f32_32x32x16_bf16 v[0:15], v[116:119], v[112:115], v[0:15]
	ds_read_b128 v[112:115], v167 offset:55296
	ds_read_b128 v[116:119], v132 offset:36864
	ds_read_b128 v[200:203], v132 offset:41472
	s_waitcnt lgkmcnt(1)
	v_mfma_f32_32x32x16_bf16 v[48:63], v[112:115], v[116:119], v[48:63]
	s_waitcnt lgkmcnt(0)
	v_mfma_f32_32x32x16_bf16 v[32:47], v[112:115], v[200:203], v[32:47]
	ds_read_b128 v[112:115], v167 offset:59904
	s_waitcnt lgkmcnt(0)
	v_mfma_f32_32x32x16_bf16 v[16:31], v[112:115], v[116:119], v[16:31]
	v_mfma_f32_32x32x16_bf16 v[0:15], v[112:115], v[200:203], v[0:15]
	ds_read_b128 v[112:115], v167 offset:55328
	ds_read_b128 v[116:119], v132 offset:36896
	ds_read_b128 v[200:203], v132 offset:41504
	s_waitcnt lgkmcnt(1)
	v_mfma_f32_32x32x16_bf16 v[48:63], v[112:115], v[116:119], v[48:63]
	s_waitcnt lgkmcnt(0)
	v_mfma_f32_32x32x16_bf16 v[32:47], v[112:115], v[200:203], v[32:47]
	ds_read_b128 v[112:115], v167 offset:59936
	s_waitcnt vmcnt(15)
	ds_write_b128 v130, v[120:123]
	s_waitcnt vmcnt(14)
	ds_write_b128 v130, v[124:127] offset:18432
	s_waitcnt lgkmcnt(2)
	v_mfma_f32_32x32x16_bf16 v[16:31], v[112:115], v[116:119], v[16:31]
	v_mfma_f32_32x32x16_bf16 v[0:15], v[112:115], v[200:203], v[0:15]
	ds_read_b128 v[112:115], v167 offset:55360
	ds_read_b128 v[116:119], v132 offset:36928
	ds_read_b128 v[120:123], v132 offset:41536
	s_waitcnt lgkmcnt(1)
	v_mfma_f32_32x32x16_bf16 v[48:63], v[112:115], v[116:119], v[48:63]
	s_waitcnt lgkmcnt(0)
	v_mfma_f32_32x32x16_bf16 v[32:47], v[112:115], v[120:123], v[32:47]
	ds_read_b128 v[112:115], v167 offset:59968
	s_waitcnt vmcnt(13)
	ds_write_b128 v130, v[96:99] offset:4608
	s_waitcnt vmcnt(12)
	ds_write_b128 v130, v[100:103] offset:23040
	ds_read_b128 v[96:99], v167 offset:55392
	ds_read_b128 v[100:103], v132 offset:36960
	s_waitcnt lgkmcnt(4)
	v_mfma_f32_32x32x16_bf16 v[16:31], v[112:115], v[116:119], v[16:31]
	ds_read_b128 v[116:119], v167 offset:60000
	v_mfma_f32_32x32x16_bf16 v[0:15], v[112:115], v[120:123], v[0:15]
	ds_read_b128 v[112:115], v132 offset:41568
	s_waitcnt lgkmcnt(2)
	v_mfma_f32_32x32x16_bf16 v[48:63], v[96:99], v[100:103], v[48:63]
	s_waitcnt lgkmcnt(0)
	v_mfma_f32_32x32x16_bf16 v[32:47], v[96:99], v[112:115], v[32:47]
	v_mfma_f32_32x32x16_bf16 v[16:31], v[116:119], v[100:103], v[16:31]
	global_load_dwordx4 v[120:123], v[150:151], off offset:2048
	global_load_dwordx4 v[124:127], v[152:153], off offset:2048
	global_load_dwordx4 v[96:99], v[158:159], off offset:2048
	global_load_dwordx4 v[100:103], v[164:165], off offset:2048
	s_waitcnt vmcnt(15)
	ds_write_b128 v130, v[72:75] offset:9216
	s_waitcnt vmcnt(14)
	ds_write_b128 v130, v[76:79] offset:27648
	global_load_dwordx4 v[72:75], v[156:157], off offset:2048
	global_load_dwordx4 v[76:79], v[162:163], off offset:2048
	s_waitcnt vmcnt(15)
	ds_write_b128 v130, v[64:67] offset:13824
	s_waitcnt vmcnt(14)
	ds_write_b128 v130, v[68:71] offset:32256
	global_load_dwordx4 v[64:67], v[154:155], off offset:2048
	global_load_dwordx4 v[68:71], v[160:161], off offset:2048
	s_waitcnt lgkmcnt(0)
	s_barrier
	v_mfma_f32_32x32x16_bf16 v[0:15], v[116:119], v[112:115], v[0:15]
	ds_read_b128 v[112:115], v167 offset:18432
	ds_read_b128 v[116:119], v132
	ds_read_b128 v[200:203], v132 offset:4608
	s_waitcnt lgkmcnt(1)
	v_mfma_f32_32x32x16_bf16 v[48:63], v[112:115], v[116:119], v[48:63]
	s_waitcnt lgkmcnt(0)
	v_mfma_f32_32x32x16_bf16 v[32:47], v[112:115], v[200:203], v[32:47]
	ds_read_b128 v[112:115], v167 offset:23040
	s_waitcnt lgkmcnt(0)
	v_mfma_f32_32x32x16_bf16 v[16:31], v[112:115], v[116:119], v[16:31]
	v_mfma_f32_32x32x16_bf16 v[0:15], v[112:115], v[200:203], v[0:15]
	ds_read_b128 v[112:115], v167 offset:18464
	ds_read_b128 v[116:119], v132 offset:32
	ds_read_b128 v[200:203], v132 offset:4640
	s_waitcnt lgkmcnt(1)
	v_mfma_f32_32x32x16_bf16 v[48:63], v[112:115], v[116:119], v[48:63]
	s_waitcnt lgkmcnt(0)
	v_mfma_f32_32x32x16_bf16 v[32:47], v[112:115], v[200:203], v[32:47]
	ds_read_b128 v[112:115], v167 offset:23072
	s_waitcnt vmcnt(15)
	ds_write_b128 v130, v[186:189] offset:36864
	s_waitcnt vmcnt(14)
	ds_write_b128 v130, v[194:197] offset:55296
	s_waitcnt lgkmcnt(2)
	v_mfma_f32_32x32x16_bf16 v[16:31], v[112:115], v[116:119], v[16:31]
	v_mfma_f32_32x32x16_bf16 v[0:15], v[112:115], v[200:203], v[0:15]
	ds_read_b128 v[112:115], v167 offset:18496
	ds_read_b128 v[116:119], v132 offset:64
	ds_read_b128 v[186:189], v132 offset:4672
	s_waitcnt lgkmcnt(1)
	v_mfma_f32_32x32x16_bf16 v[48:63], v[112:115], v[116:119], v[48:63]
	s_waitcnt lgkmcnt(0)
	v_mfma_f32_32x32x16_bf16 v[32:47], v[112:115], v[186:189], v[32:47]
	ds_read_b128 v[112:115], v167 offset:23104
	s_waitcnt vmcnt(13)
	ds_write_b128 v130, v[104:107] offset:41472
	s_waitcnt vmcnt(12)
	ds_write_b128 v130, v[108:111] offset:59904
	ds_read_b128 v[104:107], v167 offset:18528
	ds_read_b128 v[108:111], v132 offset:96
	s_waitcnt lgkmcnt(4)
	v_mfma_f32_32x32x16_bf16 v[16:31], v[112:115], v[116:119], v[16:31]
	ds_read_b128 v[116:119], v167 offset:23136
	v_mfma_f32_32x32x16_bf16 v[0:15], v[112:115], v[186:189], v[0:15]
	ds_read_b128 v[112:115], v132 offset:4704
	s_waitcnt lgkmcnt(2)
	v_mfma_f32_32x32x16_bf16 v[48:63], v[104:107], v[108:111], v[48:63]
	s_waitcnt lgkmcnt(0)
	v_mfma_f32_32x32x16_bf16 v[32:47], v[104:107], v[112:115], v[32:47]
	v_mfma_f32_32x32x16_bf16 v[16:31], v[116:119], v[108:111], v[16:31]
	global_load_dwordx4 v[186:189], v[150:151], off offset:2176
	global_load_dwordx4 v[194:197], v[152:153], off offset:2176
	global_load_dwordx4 v[104:107], v[158:159], off offset:2176
	global_load_dwordx4 v[108:111], v[164:165], off offset:2176
	s_waitcnt vmcnt(15)
	ds_write_b128 v130, v[80:83] offset:46080
	s_waitcnt vmcnt(14)
	ds_write_b128 v130, v[84:87] offset:64512
	global_load_dwordx4 v[80:83], v[156:157], off offset:2176
	global_load_dwordx4 v[84:87], v[162:163], off offset:2176
	s_waitcnt vmcnt(15)
	ds_write_b128 v130, v[88:91] offset:50688
	s_waitcnt vmcnt(14)
	ds_write_b128 v131, v[92:95] offset:13824
	global_load_dwordx4 v[88:91], v[154:155], off offset:2176
	global_load_dwordx4 v[92:95], v[160:161], off offset:2176
	s_waitcnt lgkmcnt(0)
	s_barrier
; #define GLOADQ(RA, RB, KT, q) do { const int k0_ = (KT) << 6; \
;     RA[q] = ldg16(ap.ptr(m0 + lrow + 32 * (q), k0_) + lkc); RB[q] = ldg16(W + (size_t)(n0 + lrow + 32 * (q)) * ldw + k0_ + lkc); } while (0)
; #define SSTOREQ(RA, RB, ST, q) do { \
;     *(u32x4*)(sA + (ST) * SBUF + (lrow + 32 * (q)) * GP + lkc) = RA[q]; *(u32x4*)(sB + (ST) * SBUF + (lrow + 32 * (q)) * GP + lkc) = RB[q]; } while (0)
; #define FLOAD(F, ST, ks) do { _Pragma("unroll") for (int a = 0; a < 2; ++a) { \
;     F[a] = *(const bf16x8*)(sB + (ST) * SBUF + (wn * 64 + a * 32 + r) * GP + (ks) * 16 + h * 8); \
;     F[2 + a] = *(const bf16x8*)(sA + (ST) * SBUF + (wm * 64 + a * 32 + r) * GP + (ks) * 16 + h * 8); } } while (0)
; #define FMMA(F) do { _Pragma("unroll") for (int a = 0; a < 2; ++a) _Pragma("unroll") for (int b = 0; b < 2; ++b) acc[a][b] = MFMA(F[a], F[2 + b], acc[a][b]); } while (0)
; template <bool MIDK, class AP, class EPI>
; DI void gemm_tile(const AP& ap, const u16* __restrict__ W, int ldw, int K, int m0, int n0, const EPI& epi, char* smem, float r0, float r1, int tid, bool dry) {
;     ...
;   for (int kt = 0; kt < nk; kt += 2) {
;     const bool l3 = kt + 3 < nk, s2 = kt + 2 < nk, l4 = kt + 4 < nk;
;     FLOAD(f0, 0, 0); FLOAD(f1, 0, 1);
;     FMMA(f0); SSTOREQ(ra1, rb1, 1, 0); if (l3) GLOADQ(ra1, rb1, kt + 3, 0);
;     FLOAD(f0, 0, 2);
;     FMMA(f1); SSTOREQ(ra1, rb1, 1, 1); if (l3) GLOADQ(ra1, rb1, kt + 3, 1);
;     FLOAD(f1, 0, 3);
;     FMMA(f0); SSTOREQ(ra1, rb1, 1, 2); if (l3) GLOADQ(ra1, rb1, kt + 3, 2);
;     FMMA(f1); SSTOREQ(ra1, rb1, 1, 3); if (l3) GLOADQ(ra1, rb1, kt + 3, 3);
;     __syncthreads();
;     FLOAD(f0, 1, 0); FLOAD(f1, 1, 1);
;     FMMA(f0); if (s2) SSTOREQ(ra0, rb0, 0, 0); if (l4) GLOADQ(ra0, rb0, kt + 4, 0);
;     FLOAD(f0, 1, 2);
;     FMMA(f1); if (s2) SSTOREQ(ra0, rb0, 0, 1); if (l4) GLOADQ(ra0, rb0, kt + 4, 1);
;     FLOAD(f1, 1, 3);
;     FMMA(f0); if (s2) SSTOREQ(ra0, rb0, 0, 2); if (l4) GLOADQ(ra0, rb0, kt + 4, 2);
;     FMMA(f1); if (s2) SSTOREQ(ra0, rb0, 0, 3); if (l4) GLOADQ(ra0, rb0, kt + 4, 3);
;     if (MIDK && kt == 6) {
; #pragma unroll
;       for (int a = 0; a < 2; ++a)
; #pragma unroll
;         for (int i = 0; i < 16; ++i) { acc[a][0][i] *= r0; acc[a][1][i] *= r1; }
;     }
;     __syncthreads();
	v_mfma_f32_32x32x16_bf16 v[0:15], v[116:119], v[112:115], v[0:15]
	ds_read_b128 v[112:115], v167 offset:55296
	ds_read_b128 v[116:119], v132 offset:36864
	ds_read_b128 v[200:203], v132 offset:41472
	s_waitcnt lgkmcnt(1)
	v_mfma_f32_32x32x16_bf16 v[48:63], v[112:115], v[116:119], v[48:63]
	s_waitcnt lgkmcnt(0)
	v_mfma_f32_32x32x16_bf16 v[32:47], v[112:115], v[200:203], v[32:47]
	ds_read_b128 v[112:115], v167 offset:59904
	s_waitcnt lgkmcnt(0)
	v_mfma_f32_32x32x16_bf16 v[16:31], v[112:115], v[116:119], v[16:31]
	v_mfma_f32_32x32x16_bf16 v[0:15], v[112:115], v[200:203], v[0:15]
	ds_read_b128 v[112:115], v167 offset:55328
	ds_read_b128 v[116:119], v132 offset:36896
	ds_read_b128 v[200:203], v132 offset:41504
	s_waitcnt lgkmcnt(1)
	v_mfma_f32_32x32x16_bf16 v[48:63], v[112:115], v[116:119], v[48:63]
	s_waitcnt lgkmcnt(0)
	v_mfma_f32_32x32x16_bf16 v[32:47], v[112:115], v[200:203], v[32:47]
	ds_read_b128 v[112:115], v167 offset:59936
	s_waitcnt vmcnt(15)
	ds_write_b128 v130, v[120:123]
	s_waitcnt vmcnt(14)
	ds_write_b128 v130, v[124:127] offset:18432
	s_waitcnt lgkmcnt(2)
	v_mfma_f32_32x32x16_bf16 v[16:31], v[112:115], v[116:119], v[16:31]
	v_mfma_f32_32x32x16_bf16 v[0:15], v[112:115], v[200:203], v[0:15]
	ds_read_b128 v[112:115], v167 offset:55360
	ds_read_b128 v[116:119], v132 offset:36928
	ds_read_b128 v[120:123], v132 offset:41536
	s_waitcnt lgkmcnt(1)
	v_mfma_f32_32x32x16_bf16 v[48:63], v[112:115], v[116:119], v[48:63]
	s_waitcnt lgkmcnt(0)
	v_mfma_f32_32x32x16_bf16 v[32:47], v[112:115], v[120:123], v[32:47]
	ds_read_b128 v[112:115], v167 offset:59968
	s_waitcnt vmcnt(13)
	ds_write_b128 v130, v[96:99] offset:4608
	s_waitcnt vmcnt(12)
	ds_write_b128 v130, v[100:103] offset:23040
	ds_read_b128 v[96:99], v167 offset:55392
	ds_read_b128 v[100:103], v132 offset:36960
	s_waitcnt lgkmcnt(4)
	v_mfma_f32_32x32x16_bf16 v[16:31], v[112:115], v[116:119], v[16:31]
	ds_read_b128 v[116:119], v167 offset:60000
	v_mfma_f32_32x32x16_bf16 v[0:15], v[112:115], v[120:123], v[0:15]
	ds_read_b128 v[112:115], v132 offset:41568
	s_waitcnt lgkmcnt(2)
	v_mfma_f32_32x32x16_bf16 v[48:63], v[96:99], v[100:103], v[48:63]
	s_waitcnt lgkmcnt(0)
	v_mfma_f32_32x32x16_bf16 v[32:47], v[96:99], v[112:115], v[32:47]
	v_mfma_f32_32x32x16_bf16 v[16:31], v[116:119], v[100:103], v[16:31]
	global_load_dwordx4 v[120:123], v[150:151], off offset:2304
	global_load_dwordx4 v[124:127], v[152:153], off offset:2304
	global_load_dwordx4 v[96:99], v[158:159], off offset:2304
	global_load_dwordx4 v[100:103], v[164:165], off offset:2304
	s_waitcnt vmcnt(15)
	ds_write_b128 v130, v[72:75] offset:9216
	s_waitcnt vmcnt(14)
	ds_write_b128 v130, v[76:79] offset:27648
	global_load_dwordx4 v[72:75], v[156:157], off offset:2304
	global_load_dwordx4 v[76:79], v[162:163], off offset:2304
	s_waitcnt vmcnt(15)
	ds_write_b128 v130, v[64:67] offset:13824
	s_waitcnt vmcnt(14)
	ds_write_b128 v130, v[68:71] offset:32256
	global_load_dwordx4 v[64:67], v[154:155], off offset:2304
	global_load_dwordx4 v[68:71], v[160:161], off offset:2304
	s_waitcnt lgkmcnt(0)
	s_barrier
	v_mfma_f32_32x32x16_bf16 v[0:15], v[116:119], v[112:115], v[0:15]
	ds_read_b128 v[112:115], v167 offset:18432
	ds_read_b128 v[116:119], v132
	ds_read_b128 v[200:203], v132 offset:4608
	s_waitcnt lgkmcnt(1)
	v_mfma_f32_32x32x16_bf16 v[48:63], v[112:115], v[116:119], v[48:63]
	s_waitcnt lgkmcnt(0)
	v_mfma_f32_32x32x16_bf16 v[32:47], v[112:115], v[200:203], v[32:47]
	ds_read_b128 v[112:115], v167 offset:23040
	s_waitcnt lgkmcnt(0)
	v_mfma_f32_32x32x16_bf16 v[16:31], v[112:115], v[116:119], v[16:31]
	v_mfma_f32_32x32x16_bf16 v[0:15], v[112:115], v[200:203], v[0:15]
	ds_read_b128 v[112:115], v167 offset:18464
	ds_read_b128 v[116:119], v132 offset:32
	ds_read_b128 v[200:203], v132 offset:4640
	s_waitcnt lgkmcnt(1)
	v_mfma_f32_32x32x16_bf16 v[48:63], v[112:115], v[116:119], v[48:63]
	s_waitcnt lgkmcnt(0)
	v_mfma_f32_32x32x16_bf16 v[32:47], v[112:115], v[200:203], v[32:47]
	ds_read_b128 v[112:115], v167 offset:23072
	s_waitcnt vmcnt(15)
	ds_write_b128 v130, v[186:189] offset:36864
	s_waitcnt vmcnt(14)
	ds_write_b128 v130, v[194:197] offset:55296
	s_waitcnt lgkmcnt(2)
	v_mfma_f32_32x32x16_bf16 v[16:31], v[112:115], v[116:119], v[16:31]
	v_mfma_f32_32x32x16_bf16 v[0:15], v[112:115], v[200:203], v[0:15]
	ds_read_b128 v[112:115], v167 offset:18496
	ds_read_b128 v[116:119], v132 offset:64
	ds_read_b128 v[186:189], v132 offset:4672
	s_waitcnt lgkmcnt(1)
	v_mfma_f32_32x32x16_bf16 v[48:63], v[112:115], v[116:119], v[48:63]
	s_waitcnt lgkmcnt(0)
	v_mfma_f32_32x32x16_bf16 v[32:47], v[112:115], v[186:189], v[32:47]
	ds_read_b128 v[112:115], v167 offset:23104
	s_waitcnt vmcnt(13)
	ds_write_b128 v130, v[104:107] offset:41472
	s_waitcnt vmcnt(12)
	ds_write_b128 v130, v[108:111] offset:59904
	ds_read_b128 v[104:107], v167 offset:18528
	ds_read_b128 v[108:111], v132 offset:96
	s_waitcnt lgkmcnt(4)
	v_mfma_f32_32x32x16_bf16 v[16:31], v[112:115], v[116:119], v[16:31]
	ds_read_b128 v[116:119], v167 offset:23136
	v_mfma_f32_32x32x16_bf16 v[0:15], v[112:115], v[186:189], v[0:15]
	ds_read_b128 v[112:115], v132 offset:4704
	s_waitcnt lgkmcnt(2)
	v_mfma_f32_32x32x16_bf16 v[48:63], v[104:107], v[108:111], v[48:63]
	s_waitcnt lgkmcnt(0)
	v_mfma_f32_32x32x16_bf16 v[32:47], v[104:107], v[112:115], v[32:47]
	v_mfma_f32_32x32x16_bf16 v[16:31], v[116:119], v[108:111], v[16:31]
	global_load_dwordx4 v[186:189], v[150:151], off offset:2432
	global_load_dwordx4 v[194:197], v[152:153], off offset:2432
	global_load_dwordx4 v[104:107], v[158:159], off offset:2432
	global_load_dwordx4 v[108:111], v[164:165], off offset:2432
	s_waitcnt vmcnt(15)
	ds_write_b128 v130, v[80:83] offset:46080
	s_waitcnt vmcnt(14)
	ds_write_b128 v130, v[84:87] offset:64512
	global_load_dwordx4 v[80:83], v[156:157], off offset:2432
	global_load_dwordx4 v[84:87], v[162:163], off offset:2432
	s_waitcnt vmcnt(15)
	ds_write_b128 v130, v[88:91] offset:50688
	s_waitcnt vmcnt(14)
	ds_write_b128 v131, v[92:95] offset:13824
	global_load_dwordx4 v[88:91], v[154:155], off offset:2432
	global_load_dwordx4 v[92:95], v[160:161], off offset:2432
	s_waitcnt lgkmcnt(0)
	s_barrier
; #define GLOADQ(RA, RB, KT, q) do { const int k0_ = (KT) << 6; \
;     RA[q] = ldg16(ap.ptr(m0 + lrow + 32 * (q), k0_) + lkc); RB[q] = ldg16(W + (size_t)(n0 + lrow + 32 * (q)) * ldw + k0_ + lkc); } while (0)
; #define SSTOREQ(RA, RB, ST, q) do { \
;     *(u32x4*)(sA + (ST) * SBUF + (lrow + 32 * (q)) * GP + lkc) = RA[q]; *(u32x4*)(sB + (ST) * SBUF + (lrow + 32 * (q)) * GP + lkc) = RB[q]; } while (0)
; #define FLOAD(F, ST, ks) do { _Pragma("unroll") for (int a = 0; a < 2; ++a) { \
;     F[a] = *(const bf16x8*)(sB + (ST) * SBUF + (wn * 64 + a * 32 + r) * GP + (ks) * 16 + h * 8); \
;     F[2 + a] = *(const bf16x8*)(sA + (ST) * SBUF + (wm * 64 + a * 32 + r) * GP + (ks) * 16 + h * 8); } } while (0)
; #define FMMA(F) do { _Pragma("unroll") for (int a = 0; a < 2; ++a) _Pragma("unroll") for (int b = 0; b < 2; ++b) acc[a][b] = MFMA(F[a], F[2 + b], acc[a][b]); } while (0)
; template <bool MIDK, class AP, class EPI>
; DI void gemm_tile(const AP& ap, const u16* __restrict__ W, int ldw, int K, int m0, int n0, const EPI& epi, char* smem, float r0, float r1, int tid, bool dry) {
;     ...
;   for (int kt = 0; kt < nk; kt += 2) {
;     const bool l3 = kt + 3 < nk, s2 = kt + 2 < nk, l4 = kt + 4 < nk;
;     FLOAD(f0, 0, 0); FLOAD(f1, 0, 1);
;     FMMA(f0); SSTOREQ(ra1, rb1, 1, 0); if (l3) GLOADQ(ra1, rb1, kt + 3, 0);
;     FLOAD(f0, 0, 2);
;     FMMA(f1); SSTOREQ(ra1, rb1, 1, 1); if (l3) GLOADQ(ra1, rb1, kt + 3, 1);
;     FLOAD(f1, 0, 3);
;     FMMA(f0); SSTOREQ(ra1, rb1, 1, 2); if (l3) GLOADQ(ra1, rb1, kt + 3, 2);
;     FMMA(f1); SSTOREQ(ra1, rb1, 1, 3); if (l3) GLOADQ(ra1, rb1, kt + 3, 3);
;     __syncthreads();
;     FLOAD(f0, 1, 0); FLOAD(f1, 1, 1);
;     FMMA(f0); if (s2) SSTOREQ(ra0, rb0, 0, 0); if (l4) GLOADQ(ra0, rb0, kt + 4, 0);
;     FLOAD(f0, 1, 2);
;     FMMA(f1); if (s2) SSTOREQ(ra0, rb0, 0, 1); if (l4) GLOADQ(ra0, rb0, kt + 4, 1);
;     FLOAD(f1, 1, 3);
;     FMMA(f0); if (s2) SSTOREQ(ra0, rb0, 0, 2); if (l4) GLOADQ(ra0, rb0, kt + 4, 2);
;     FMMA(f1); if (s2) SSTOREQ(ra0, rb0, 0, 3); if (l4) GLOADQ(ra0, rb0, kt + 4, 3);
;     if (MIDK && kt == 6) {
; #pragma unroll
;       for (int a = 0; a < 2; ++a)
; #pragma unroll
;         for (int i = 0; i < 16; ++i) { acc[a][0][i] *= r0; acc[a][1][i] *= r1; }
;     }
;     __syncthreads();
	v_mfma_f32_32x32x16_bf16 v[0:15], v[116:119], v[112:115], v[0:15]
	ds_read_b128 v[112:115], v167 offset:55296
	ds_read_b128 v[116:119], v132 offset:36864
	ds_read_b128 v[200:203], v132 offset:41472
	s_waitcnt lgkmcnt(1)
	v_mfma_f32_32x32x16_bf16 v[48:63], v[112:115], v[116:119], v[48:63]
	s_waitcnt lgkmcnt(0)
	v_mfma_f32_32x32x16_bf16 v[32:47], v[112:115], v[200:203], v[32:47]
	ds_read_b128 v[112:115], v167 offset:59904
	s_waitcnt lgkmcnt(0)
	v_mfma_f32_32x32x16_bf16 v[16:31], v[112:115], v[116:119], v[16:31]
	v_mfma_f32_32x32x16_bf16 v[0:15], v[112:115], v[200:203], v[0:15]
	ds_read_b128 v[112:115], v167 offset:55328
	ds_read_b128 v[116:119], v132 offset:36896
	ds_read_b128 v[200:203], v132 offset:41504
	s_waitcnt lgkmcnt(1)
	v_mfma_f32_32x32x16_bf16 v[48:63], v[112:115], v[116:119], v[48:63]
	s_waitcnt lgkmcnt(0)
	v_mfma_f32_32x32x16_bf16 v[32:47], v[112:115], v[200:203], v[32:47]
	ds_read_b128 v[112:115], v167 offset:59936
	s_waitcnt vmcnt(15)
	ds_write_b128 v130, v[120:123]
	s_waitcnt vmcnt(14)
	ds_write_b128 v130, v[124:127] offset:18432
	s_waitcnt lgkmcnt(2)
	v_mfma_f32_32x32x16_bf16 v[16:31], v[112:115], v[116:119], v[16:31]
	v_mfma_f32_32x32x16_bf16 v[0:15], v[112:115], v[200:203], v[0:15]
	ds_read_b128 v[112:115], v167 offset:55360
	ds_read_b128 v[116:119], v132 offset:36928
	ds_read_b128 v[120:123], v132 offset:41536
	s_waitcnt lgkmcnt(1)
	v_mfma_f32_32x32x16_bf16 v[48:63], v[112:115], v[116:119], v[48:63]
	s_waitcnt lgkmcnt(0)
	v_mfma_f32_32x32x16_bf16 v[32:47], v[112:115], v[120:123], v[32:47]
	ds_read_b128 v[112:115], v167 offset:59968
	s_waitcnt vmcnt(13)
	ds_write_b128 v130, v[96:99] offset:4608
	s_waitcnt vmcnt(12)
	ds_write_b128 v130, v[100:103] offset:23040
	ds_read_b128 v[96:99], v167 offset:55392
	ds_read_b128 v[100:103], v132 offset:36960
	s_waitcnt lgkmcnt(4)
	v_mfma_f32_32x32x16_bf16 v[16:31], v[112:115], v[116:119], v[16:31]
	ds_read_b128 v[116:119], v167 offset:60000
	v_mfma_f32_32x32x16_bf16 v[0:15], v[112:115], v[120:123], v[0:15]
	ds_read_b128 v[112:115], v132 offset:41568
	s_waitcnt lgkmcnt(2)
	v_mfma_f32_32x32x16_bf16 v[48:63], v[96:99], v[100:103], v[48:63]
	s_waitcnt lgkmcnt(0)
	v_mfma_f32_32x32x16_bf16 v[32:47], v[96:99], v[112:115], v[32:47]
	v_mfma_f32_32x32x16_bf16 v[16:31], v[116:119], v[100:103], v[16:31]
	global_load_dwordx4 v[120:123], v[150:151], off offset:2560
	global_load_dwordx4 v[124:127], v[152:153], off offset:2560
	global_load_dwordx4 v[96:99], v[158:159], off offset:2560
	global_load_dwordx4 v[100:103], v[164:165], off offset:2560
	s_waitcnt vmcnt(15)
	ds_write_b128 v130, v[72:75] offset:9216
	s_waitcnt vmcnt(14)
	ds_write_b128 v130, v[76:79] offset:27648
	global_load_dwordx4 v[72:75], v[156:157], off offset:2560
	global_load_dwordx4 v[76:79], v[162:163], off offset:2560
	s_waitcnt vmcnt(15)
	ds_write_b128 v130, v[64:67] offset:13824
	s_waitcnt vmcnt(14)
	ds_write_b128 v130, v[68:71] offset:32256
	global_load_dwordx4 v[64:67], v[154:155], off offset:2560
	global_load_dwordx4 v[68:71], v[160:161], off offset:2560
	s_waitcnt lgkmcnt(0)
	s_barrier
	v_mfma_f32_32x32x16_bf16 v[0:15], v[116:119], v[112:115], v[0:15]
	ds_read_b128 v[112:115], v167 offset:18432
	ds_read_b128 v[116:119], v132
	ds_read_b128 v[200:203], v132 offset:4608
	s_waitcnt lgkmcnt(1)
	v_mfma_f32_32x32x16_bf16 v[48:63], v[112:115], v[116:119], v[48:63]
	s_waitcnt lgkmcnt(0)
	v_mfma_f32_32x32x16_bf16 v[32:47], v[112:115], v[200:203], v[32:47]
	ds_read_b128 v[112:115], v167 offset:23040
	s_waitcnt lgkmcnt(0)
	v_mfma_f32_32x32x16_bf16 v[16:31], v[112:115], v[116:119], v[16:31]
	v_mfma_f32_32x32x16_bf16 v[0:15], v[112:115], v[200:203], v[0:15]
	ds_read_b128 v[112:115], v167 offset:18464
	ds_read_b128 v[116:119], v132 offset:32
	ds_read_b128 v[200:203], v132 offset:4640
	s_waitcnt lgkmcnt(1)
	v_mfma_f32_32x32x16_bf16 v[48:63], v[112:115], v[116:119], v[48:63]
	s_waitcnt lgkmcnt(0)
	v_mfma_f32_32x32x16_bf16 v[32:47], v[112:115], v[200:203], v[32:47]
	ds_read_b128 v[112:115], v167 offset:23072
	s_waitcnt vmcnt(15)
	ds_write_b128 v130, v[186:189] offset:36864
	s_waitcnt vmcnt(14)
	ds_write_b128 v130, v[194:197] offset:55296
	s_waitcnt lgkmcnt(2)
	v_mfma_f32_32x32x16_bf16 v[16:31], v[112:115], v[116:119], v[16:31]
	v_mfma_f32_32x32x16_bf16 v[0:15], v[112:115], v[200:203], v[0:15]
	ds_read_b128 v[112:115], v167 offset:18496
	ds_read_b128 v[116:119], v132 offset:64
	ds_read_b128 v[186:189], v132 offset:4672
	s_waitcnt lgkmcnt(1)
	v_mfma_f32_32x32x16_bf16 v[48:63], v[112:115], v[116:119], v[48:63]
	s_waitcnt lgkmcnt(0)
	v_mfma_f32_32x32x16_bf16 v[32:47], v[112:115], v[186:189], v[32:47]
	ds_read_b128 v[112:115], v167 offset:23104
	s_waitcnt vmcnt(13)
	ds_write_b128 v130, v[104:107] offset:41472
	s_waitcnt vmcnt(12)
	ds_write_b128 v130, v[108:111] offset:59904
	ds_read_b128 v[104:107], v167 offset:18528
	ds_read_b128 v[108:111], v132 offset:96
	s_waitcnt lgkmcnt(4)
	v_mfma_f32_32x32x16_bf16 v[16:31], v[112:115], v[116:119], v[16:31]
	ds_read_b128 v[116:119], v167 offset:23136
	v_mfma_f32_32x32x16_bf16 v[0:15], v[112:115], v[186:189], v[0:15]
	ds_read_b128 v[112:115], v132 offset:4704
	s_waitcnt lgkmcnt(2)
	v_mfma_f32_32x32x16_bf16 v[48:63], v[104:107], v[108:111], v[48:63]
	s_waitcnt lgkmcnt(0)
	v_mfma_f32_32x32x16_bf16 v[32:47], v[104:107], v[112:115], v[32:47]
	v_mfma_f32_32x32x16_bf16 v[16:31], v[116:119], v[108:111], v[16:31]
	global_load_dwordx4 v[186:189], v[150:151], off offset:2688
	global_load_dwordx4 v[194:197], v[152:153], off offset:2688
	global_load_dwordx4 v[104:107], v[158:159], off offset:2688
	global_load_dwordx4 v[108:111], v[164:165], off offset:2688
	s_waitcnt vmcnt(15)
	ds_write_b128 v130, v[80:83] offset:46080
	s_waitcnt vmcnt(14)
	ds_write_b128 v130, v[84:87] offset:64512
	global_load_dwordx4 v[80:83], v[156:157], off offset:2688
	global_load_dwordx4 v[84:87], v[162:163], off offset:2688
	s_waitcnt vmcnt(15)
	ds_write_b128 v130, v[88:91] offset:50688
	s_waitcnt vmcnt(14)
	ds_write_b128 v131, v[92:95] offset:13824
	global_load_dwordx4 v[88:91], v[154:155], off offset:2688
	global_load_dwordx4 v[92:95], v[160:161], off offset:2688
	s_waitcnt lgkmcnt(0)
	s_barrier
; #define GLOADQ(RA, RB, KT, q) do { const int k0_ = (KT) << 6; \
;     RA[q] = ldg16(ap.ptr(m0 + lrow + 32 * (q), k0_) + lkc); RB[q] = ldg16(W + (size_t)(n0 + lrow + 32 * (q)) * ldw + k0_ + lkc); } while (0)
; #define SSTOREQ(RA, RB, ST, q) do { \
;     *(u32x4*)(sA + (ST) * SBUF + (lrow + 32 * (q)) * GP + lkc) = RA[q]; *(u32x4*)(sB + (ST) * SBUF + (lrow + 32 * (q)) * GP + lkc) = RB[q]; } while (0)
; #define FLOAD(F, ST, ks) do { _Pragma("unroll") for (int a = 0; a < 2; ++a) { \
;     F[a] = *(const bf16x8*)(sB + (ST) * SBUF + (wn * 64 + a * 32 + r) * GP + (ks) * 16 + h * 8); \
;     F[2 + a] = *(const bf16x8*)(sA + (ST) * SBUF + (wm * 64 + a * 32 + r) * GP + (ks) * 16 + h * 8); } } while (0)
; #define FMMA(F) do { _Pragma("unroll") for (int a = 0; a < 2; ++a) _Pragma("unroll") for (int b = 0; b < 2; ++b) acc[a][b] = MFMA(F[a], F[2 + b], acc[a][b]); } while (0)
; template <bool MIDK, class AP, class EPI>
; DI void gemm_tile(const AP& ap, const u16* __restrict__ W, int ldw, int K, int m0, int n0, const EPI& epi, char* smem, float r0, float r1, int tid, bool dry) {
;     ...
;   for (int kt = 0; kt < nk; kt += 2) {
;     const bool l3 = kt + 3 < nk, s2 = kt + 2 < nk, l4 = kt + 4 < nk;
;     FLOAD(f0, 0, 0); FLOAD(f1, 0, 1);
;     FMMA(f0); SSTOREQ(ra1, rb1, 1, 0); if (l3) GLOADQ(ra1, rb1, kt + 3, 0);
;     FLOAD(f0, 0, 2);
;     FMMA(f1); SSTOREQ(ra1, rb1, 1, 1); if (l3) GLOADQ(ra1, rb1, kt + 3, 1);
;     FLOAD(f1, 0, 3);
;     FMMA(f0); SSTOREQ(ra1, rb1, 1, 2); if (l3) GLOADQ(ra1, rb1, kt + 3, 2);
;     FMMA(f1); SSTOREQ(ra1, rb1, 1, 3); if (l3) GLOADQ(ra1, rb1, kt + 3, 3);
;     __syncthreads();
;     FLOAD(f0, 1, 0); FLOAD(f1, 1, 1);
;     FMMA(f0); if (s2) SSTOREQ(ra0, rb0, 0, 0); if (l4) GLOADQ(ra0, rb0, kt + 4, 0);
;     FLOAD(f0, 1, 2);
;     FMMA(f1); if (s2) SSTOREQ(ra0, rb0, 0, 1); if (l4) GLOADQ(ra0, rb0, kt + 4, 1);
;     FLOAD(f1, 1, 3);
;     FMMA(f0); if (s2) SSTOREQ(ra0, rb0, 0, 2); if (l4) GLOADQ(ra0, rb0, kt + 4, 2);
;     FMMA(f1); if (s2) SSTOREQ(ra0, rb0, 0, 3); if (l4) GLOADQ(ra0, rb0, kt + 4, 3);
;     if (MIDK && kt == 6) {
; #pragma unroll
;       for (int a = 0; a < 2; ++a)
; #pragma unroll
;         for (int i = 0; i < 16; ++i) { acc[a][0][i] *= r0; acc[a][1][i] *= r1; }
;     }
;     __syncthreads();
	v_mfma_f32_32x32x16_bf16 v[0:15], v[116:119], v[112:115], v[0:15]
	ds_read_b128 v[112:115], v167 offset:55296
	ds_read_b128 v[116:119], v132 offset:36864
	ds_read_b128 v[200:203], v132 offset:41472
	s_waitcnt lgkmcnt(1)
	v_mfma_f32_32x32x16_bf16 v[48:63], v[112:115], v[116:119], v[48:63]
	s_waitcnt lgkmcnt(0)
	v_mfma_f32_32x32x16_bf16 v[32:47], v[112:115], v[200:203], v[32:47]
	ds_read_b128 v[112:115], v167 offset:59904
	s_waitcnt lgkmcnt(0)
	v_mfma_f32_32x32x16_bf16 v[16:31], v[112:115], v[116:119], v[16:31]
	v_mfma_f32_32x32x16_bf16 v[0:15], v[112:115], v[200:203], v[0:15]
	ds_read_b128 v[112:115], v167 offset:55328
	ds_read_b128 v[116:119], v132 offset:36896
	ds_read_b128 v[200:203], v132 offset:41504
	s_waitcnt lgkmcnt(1)
	v_mfma_f32_32x32x16_bf16 v[48:63], v[112:115], v[116:119], v[48:63]
	s_waitcnt lgkmcnt(0)
	v_mfma_f32_32x32x16_bf16 v[32:47], v[112:115], v[200:203], v[32:47]
	ds_read_b128 v[112:115], v167 offset:59936
	s_waitcnt vmcnt(15)
	ds_write_b128 v130, v[120:123]
	s_waitcnt vmcnt(14)
	ds_write_b128 v130, v[124:127] offset:18432
	s_waitcnt lgkmcnt(2)
	v_mfma_f32_32x32x16_bf16 v[16:31], v[112:115], v[116:119], v[16:31]
	v_mfma_f32_32x32x16_bf16 v[0:15], v[112:115], v[200:203], v[0:15]
	ds_read_b128 v[112:115], v167 offset:55360
	ds_read_b128 v[116:119], v132 offset:36928
	ds_read_b128 v[120:123], v132 offset:41536
	s_waitcnt lgkmcnt(1)
	v_mfma_f32_32x32x16_bf16 v[48:63], v[112:115], v[116:119], v[48:63]
	s_waitcnt lgkmcnt(0)
	v_mfma_f32_32x32x16_bf16 v[32:47], v[112:115], v[120:123], v[32:47]
	ds_read_b128 v[112:115], v167 offset:59968
	s_waitcnt vmcnt(13)
	ds_write_b128 v130, v[96:99] offset:4608
	s_waitcnt vmcnt(12)
	ds_write_b128 v130, v[100:103] offset:23040
	ds_read_b128 v[96:99], v167 offset:55392
	ds_read_b128 v[100:103], v132 offset:36960
	s_waitcnt lgkmcnt(4)
	v_mfma_f32_32x32x16_bf16 v[16:31], v[112:115], v[116:119], v[16:31]
	ds_read_b128 v[116:119], v167 offset:60000
	v_mfma_f32_32x32x16_bf16 v[0:15], v[112:115], v[120:123], v[0:15]
	ds_read_b128 v[112:115], v132 offset:41568
	s_waitcnt lgkmcnt(2)
	v_mfma_f32_32x32x16_bf16 v[48:63], v[96:99], v[100:103], v[48:63]
	s_waitcnt lgkmcnt(0)
	v_mfma_f32_32x32x16_bf16 v[32:47], v[96:99], v[112:115], v[32:47]
	v_mfma_f32_32x32x16_bf16 v[16:31], v[116:119], v[100:103], v[16:31]
	global_load_dwordx4 v[120:123], v[150:151], off offset:2816
	global_load_dwordx4 v[124:127], v[152:153], off offset:2816
	global_load_dwordx4 v[96:99], v[158:159], off offset:2816
	global_load_dwordx4 v[100:103], v[164:165], off offset:2816
	s_waitcnt vmcnt(15)
	ds_write_b128 v130, v[72:75] offset:9216
	s_waitcnt vmcnt(14)
	ds_write_b128 v130, v[76:79] offset:27648
	global_load_dwordx4 v[72:75], v[156:157], off offset:2816
	global_load_dwordx4 v[76:79], v[162:163], off offset:2816
	s_waitcnt vmcnt(15)
	ds_write_b128 v130, v[64:67] offset:13824
	s_waitcnt vmcnt(14)
	ds_write_b128 v130, v[68:71] offset:32256
	global_load_dwordx4 v[64:67], v[154:155], off offset:2816
	global_load_dwordx4 v[68:71], v[160:161], off offset:2816
	s_waitcnt lgkmcnt(0)
	s_barrier
	v_mfma_f32_32x32x16_bf16 v[0:15], v[116:119], v[112:115], v[0:15]
	ds_read_b128 v[112:115], v167 offset:18432
	ds_read_b128 v[116:119], v132
	ds_read_b128 v[200:203], v132 offset:4608
	s_waitcnt lgkmcnt(1)
	v_mfma_f32_32x32x16_bf16 v[48:63], v[112:115], v[116:119], v[48:63]
	s_waitcnt lgkmcnt(0)
	v_mfma_f32_32x32x16_bf16 v[32:47], v[112:115], v[200:203], v[32:47]
	ds_read_b128 v[112:115], v167 offset:23040
	s_waitcnt lgkmcnt(0)
	v_mfma_f32_32x32x16_bf16 v[16:31], v[112:115], v[116:119], v[16:31]
	v_mfma_f32_32x32x16_bf16 v[0:15], v[112:115], v[200:203], v[0:15]
	ds_read_b128 v[112:115], v167 offset:18464
	ds_read_b128 v[116:119], v132 offset:32
	ds_read_b128 v[200:203], v132 offset:4640
	s_waitcnt lgkmcnt(1)
	v_mfma_f32_32x32x16_bf16 v[48:63], v[112:115], v[116:119], v[48:63]
	s_waitcnt lgkmcnt(0)
	v_mfma_f32_32x32x16_bf16 v[32:47], v[112:115], v[200:203], v[32:47]
	ds_read_b128 v[112:115], v167 offset:23072
	s_waitcnt vmcnt(15)
	ds_write_b128 v130, v[186:189] offset:36864
	s_waitcnt vmcnt(14)
	ds_write_b128 v130, v[194:197] offset:55296
	s_waitcnt lgkmcnt(2)
	v_mfma_f32_32x32x16_bf16 v[16:31], v[112:115], v[116:119], v[16:31]
	v_mfma_f32_32x32x16_bf16 v[0:15], v[112:115], v[200:203], v[0:15]
	ds_read_b128 v[112:115], v167 offset:18496
	ds_read_b128 v[116:119], v132 offset:64
	ds_read_b128 v[186:189], v132 offset:4672
	s_waitcnt lgkmcnt(1)
	v_mfma_f32_32x32x16_bf16 v[48:63], v[112:115], v[116:119], v[48:63]
	s_waitcnt lgkmcnt(0)
	v_mfma_f32_32x32x16_bf16 v[32:47], v[112:115], v[186:189], v[32:47]
	ds_read_b128 v[112:115], v167 offset:23104
	s_waitcnt vmcnt(13)
	ds_write_b128 v130, v[104:107] offset:41472
	s_waitcnt vmcnt(12)
	ds_write_b128 v130, v[108:111] offset:59904
	ds_read_b128 v[104:107], v167 offset:18528
	ds_read_b128 v[108:111], v132 offset:96
	s_waitcnt lgkmcnt(4)
	v_mfma_f32_32x32x16_bf16 v[16:31], v[112:115], v[116:119], v[16:31]
	ds_read_b128 v[116:119], v167 offset:23136
	v_mfma_f32_32x32x16_bf16 v[0:15], v[112:115], v[186:189], v[0:15]
	ds_read_b128 v[112:115], v132 offset:4704
	s_waitcnt lgkmcnt(2)
	v_mfma_f32_32x32x16_bf16 v[48:63], v[104:107], v[108:111], v[48:63]
	s_waitcnt lgkmcnt(0)
	v_mfma_f32_32x32x16_bf16 v[32:47], v[104:107], v[112:115], v[32:47]
	v_mfma_f32_32x32x16_bf16 v[16:31], v[116:119], v[108:111], v[16:31]
	global_load_dwordx4 v[186:189], v[150:151], off offset:2944
	global_load_dwordx4 v[194:197], v[152:153], off offset:2944
	global_load_dwordx4 v[104:107], v[158:159], off offset:2944
	global_load_dwordx4 v[108:111], v[164:165], off offset:2944
	s_waitcnt vmcnt(15)
	ds_write_b128 v130, v[80:83] offset:46080
	s_waitcnt vmcnt(14)
	ds_write_b128 v130, v[84:87] offset:64512
	global_load_dwordx4 v[80:83], v[156:157], off offset:2944
	global_load_dwordx4 v[84:87], v[162:163], off offset:2944
	s_waitcnt vmcnt(15)
	ds_write_b128 v130, v[88:91] offset:50688
	s_waitcnt vmcnt(14)
	ds_write_b128 v131, v[92:95] offset:13824
	global_load_dwordx4 v[88:91], v[154:155], off offset:2944
	global_load_dwordx4 v[92:95], v[160:161], off offset:2944
	s_waitcnt lgkmcnt(0)
	s_barrier
; #define GLOADQ(RA, RB, KT, q) do { const int k0_ = (KT) << 6; \
;     RA[q] = ldg16(ap.ptr(m0 + lrow + 32 * (q), k0_) + lkc); RB[q] = ldg16(W + (size_t)(n0 + lrow + 32 * (q)) * ldw + k0_ + lkc); } while (0)
; #define SSTOREQ(RA, RB, ST, q) do { \
;     *(u32x4*)(sA + (ST) * SBUF + (lrow + 32 * (q)) * GP + lkc) = RA[q]; *(u32x4*)(sB + (ST) * SBUF + (lrow + 32 * (q)) * GP + lkc) = RB[q]; } while (0)
; #define FLOAD(F, ST, ks) do { _Pragma("unroll") for (int a = 0; a < 2; ++a) { \
;     F[a] = *(const bf16x8*)(sB + (ST) * SBUF + (wn * 64 + a * 32 + r) * GP + (ks) * 16 + h * 8); \
;     F[2 + a] = *(const bf16x8*)(sA + (ST) * SBUF + (wm * 64 + a * 32 + r) * GP + (ks) * 16 + h * 8); } } while (0)
; #define FMMA(F) do { _Pragma("unroll") for (int a = 0; a < 2; ++a) _Pragma("unroll") for (int b = 0; b < 2; ++b) acc[a][b] = MFMA(F[a], F[2 + b], acc[a][b]); } while (0)
; template <bool MIDK, class AP, class EPI>
; DI void gemm_tile(const AP& ap, const u16* __restrict__ W, int ldw, int K, int m0, int n0, const EPI& epi, char* smem, float r0, float r1, int tid, bool dry) {
;     ...
;   for (int kt = 0; kt < nk; kt += 2) {
;     const bool l3 = kt + 3 < nk, s2 = kt + 2 < nk, l4 = kt + 4 < nk;
;     FLOAD(f0, 0, 0); FLOAD(f1, 0, 1);
;     FMMA(f0); SSTOREQ(ra1, rb1, 1, 0); if (l3) GLOADQ(ra1, rb1, kt + 3, 0);
;     FLOAD(f0, 0, 2);
;     FMMA(f1); SSTOREQ(ra1, rb1, 1, 1); if (l3) GLOADQ(ra1, rb1, kt + 3, 1);
;     FLOAD(f1, 0, 3);
;     FMMA(f0); SSTOREQ(ra1, rb1, 1, 2); if (l3) GLOADQ(ra1, rb1, kt + 3, 2);
;     FMMA(f1); SSTOREQ(ra1, rb1, 1, 3); if (l3) GLOADQ(ra1, rb1, kt + 3, 3);
;     __syncthreads();
;     FLOAD(f0, 1, 0); FLOAD(f1, 1, 1);
;     FMMA(f0); if (s2) SSTOREQ(ra0, rb0, 0, 0); if (l4) GLOADQ(ra0, rb0, kt + 4, 0);
;     FLOAD(f0, 1, 2);
;     FMMA(f1); if (s2) SSTOREQ(ra0, rb0, 0, 1); if (l4) GLOADQ(ra0, rb0, kt + 4, 1);
;     FLOAD(f1, 1, 3);
;     FMMA(f0); if (s2) SSTOREQ(ra0, rb0, 0, 2); if (l4) GLOADQ(ra0, rb0, kt + 4, 2);
;     FMMA(f1); if (s2) SSTOREQ(ra0, rb0, 0, 3); if (l4) GLOADQ(ra0, rb0, kt + 4, 3);
;     if (MIDK && kt == 6) {
; #pragma unroll
;       for (int a = 0; a < 2; ++a)
; #pragma unroll
;         for (int i = 0; i < 16; ++i) { acc[a][0][i] *= r0; acc[a][1][i] *= r1; }
;     }
;     __syncthreads();
	v_mfma_f32_32x32x16_bf16 v[0:15], v[116:119], v[112:115], v[0:15]
	ds_read_b128 v[112:115], v167 offset:55296
	ds_read_b128 v[116:119], v132 offset:36864
	ds_read_b128 v[200:203], v132 offset:41472
	s_waitcnt lgkmcnt(1)
	v_mfma_f32_32x32x16_bf16 v[48:63], v[112:115], v[116:119], v[48:63]
	s_waitcnt lgkmcnt(0)
	v_mfma_f32_32x32x16_bf16 v[32:47], v[112:115], v[200:203], v[32:47]
	ds_read_b128 v[112:115], v167 offset:59904
	s_waitcnt lgkmcnt(0)
	v_mfma_f32_32x32x16_bf16 v[16:31], v[112:115], v[116:119], v[16:31]
	v_mfma_f32_32x32x16_bf16 v[0:15], v[112:115], v[200:203], v[0:15]
	ds_read_b128 v[112:115], v167 offset:55328
	ds_read_b128 v[116:119], v132 offset:36896
	ds_read_b128 v[200:203], v132 offset:41504
	s_waitcnt lgkmcnt(1)
	v_mfma_f32_32x32x16_bf16 v[48:63], v[112:115], v[116:119], v[48:63]
	s_waitcnt lgkmcnt(0)
	v_mfma_f32_32x32x16_bf16 v[32:47], v[112:115], v[200:203], v[32:47]
	ds_read_b128 v[112:115], v167 offset:59936
	s_waitcnt vmcnt(15)
	ds_write_b128 v130, v[120:123]
	s_waitcnt vmcnt(14)
	ds_write_b128 v130, v[124:127] offset:18432
	s_waitcnt lgkmcnt(2)
	v_mfma_f32_32x32x16_bf16 v[16:31], v[112:115], v[116:119], v[16:31]
	v_mfma_f32_32x32x16_bf16 v[0:15], v[112:115], v[200:203], v[0:15]
	ds_read_b128 v[112:115], v167 offset:55360
	ds_read_b128 v[116:119], v132 offset:36928
	ds_read_b128 v[120:123], v132 offset:41536
	s_waitcnt lgkmcnt(1)
	v_mfma_f32_32x32x16_bf16 v[48:63], v[112:115], v[116:119], v[48:63]
	s_waitcnt lgkmcnt(0)
	v_mfma_f32_32x32x16_bf16 v[32:47], v[112:115], v[120:123], v[32:47]
	ds_read_b128 v[112:115], v167 offset:59968
	s_waitcnt vmcnt(13)
	ds_write_b128 v130, v[96:99] offset:4608
	s_waitcnt vmcnt(12)
	ds_write_b128 v130, v[100:103] offset:23040
	ds_read_b128 v[96:99], v167 offset:55392
	ds_read_b128 v[100:103], v132 offset:36960
	s_waitcnt lgkmcnt(4)
	v_mfma_f32_32x32x16_bf16 v[16:31], v[112:115], v[116:119], v[16:31]
	ds_read_b128 v[116:119], v167 offset:60000
	v_mfma_f32_32x32x16_bf16 v[0:15], v[112:115], v[120:123], v[0:15]
	ds_read_b128 v[112:115], v132 offset:41568
	s_waitcnt lgkmcnt(2)
	v_mfma_f32_32x32x16_bf16 v[48:63], v[96:99], v[100:103], v[48:63]
	s_waitcnt lgkmcnt(0)
	v_mfma_f32_32x32x16_bf16 v[32:47], v[96:99], v[112:115], v[32:47]
	v_mfma_f32_32x32x16_bf16 v[16:31], v[116:119], v[100:103], v[16:31]
	global_load_dwordx4 v[120:123], v[150:151], off offset:3072
	global_load_dwordx4 v[124:127], v[152:153], off offset:3072
	global_load_dwordx4 v[96:99], v[158:159], off offset:3072
	global_load_dwordx4 v[100:103], v[164:165], off offset:3072
	s_waitcnt vmcnt(15)
	ds_write_b128 v130, v[72:75] offset:9216
	s_waitcnt vmcnt(14)
	ds_write_b128 v130, v[76:79] offset:27648
	global_load_dwordx4 v[72:75], v[156:157], off offset:3072
	global_load_dwordx4 v[76:79], v[162:163], off offset:3072
	s_waitcnt vmcnt(15)
	ds_write_b128 v130, v[64:67] offset:13824
	s_waitcnt vmcnt(14)
	ds_write_b128 v130, v[68:71] offset:32256
	global_load_dwordx4 v[64:67], v[154:155], off offset:3072
	global_load_dwordx4 v[68:71], v[160:161], off offset:3072
	s_waitcnt lgkmcnt(0)
	s_barrier
	v_mfma_f32_32x32x16_bf16 v[0:15], v[116:119], v[112:115], v[0:15]
	ds_read_b128 v[112:115], v167 offset:18432
	ds_read_b128 v[116:119], v132
	ds_read_b128 v[200:203], v132 offset:4608
	s_waitcnt lgkmcnt(1)
	v_mfma_f32_32x32x16_bf16 v[48:63], v[112:115], v[116:119], v[48:63]
	s_waitcnt lgkmcnt(0)
	v_mfma_f32_32x32x16_bf16 v[32:47], v[112:115], v[200:203], v[32:47]
	ds_read_b128 v[112:115], v167 offset:23040
	s_waitcnt lgkmcnt(0)
	v_mfma_f32_32x32x16_bf16 v[16:31], v[112:115], v[116:119], v[16:31]
	v_mfma_f32_32x32x16_bf16 v[0:15], v[112:115], v[200:203], v[0:15]
	ds_read_b128 v[112:115], v167 offset:18464
	ds_read_b128 v[116:119], v132 offset:32
	ds_read_b128 v[200:203], v132 offset:4640
	s_waitcnt lgkmcnt(1)
	v_mfma_f32_32x32x16_bf16 v[48:63], v[112:115], v[116:119], v[48:63]
	s_waitcnt lgkmcnt(0)
	v_mfma_f32_32x32x16_bf16 v[32:47], v[112:115], v[200:203], v[32:47]
	ds_read_b128 v[112:115], v167 offset:23072
	s_waitcnt vmcnt(15)
	ds_write_b128 v130, v[186:189] offset:36864
	s_waitcnt vmcnt(14)
	ds_write_b128 v130, v[194:197] offset:55296
	s_waitcnt lgkmcnt(2)
	v_mfma_f32_32x32x16_bf16 v[16:31], v[112:115], v[116:119], v[16:31]
	v_mfma_f32_32x32x16_bf16 v[0:15], v[112:115], v[200:203], v[0:15]
	ds_read_b128 v[112:115], v167 offset:18496
	ds_read_b128 v[116:119], v132 offset:64
	ds_read_b128 v[186:189], v132 offset:4672
	s_waitcnt lgkmcnt(1)
	v_mfma_f32_32x32x16_bf16 v[48:63], v[112:115], v[116:119], v[48:63]
	s_waitcnt lgkmcnt(0)
	v_mfma_f32_32x32x16_bf16 v[32:47], v[112:115], v[186:189], v[32:47]
	ds_read_b128 v[112:115], v167 offset:23104
	s_waitcnt vmcnt(13)
	ds_write_b128 v130, v[104:107] offset:41472
	s_waitcnt vmcnt(12)
	ds_write_b128 v130, v[108:111] offset:59904
	ds_read_b128 v[104:107], v167 offset:18528
	ds_read_b128 v[108:111], v132 offset:96
	s_waitcnt lgkmcnt(4)
	v_mfma_f32_32x32x16_bf16 v[16:31], v[112:115], v[116:119], v[16:31]
	ds_read_b128 v[116:119], v167 offset:23136
	v_mfma_f32_32x32x16_bf16 v[0:15], v[112:115], v[186:189], v[0:15]
	ds_read_b128 v[112:115], v132 offset:4704
	s_waitcnt lgkmcnt(2)
	v_mfma_f32_32x32x16_bf16 v[48:63], v[104:107], v[108:111], v[48:63]
	s_waitcnt lgkmcnt(0)
	v_mfma_f32_32x32x16_bf16 v[32:47], v[104:107], v[112:115], v[32:47]
	v_mfma_f32_32x32x16_bf16 v[16:31], v[116:119], v[108:111], v[16:31]
	global_load_dwordx4 v[186:189], v[150:151], off offset:3200
	global_load_dwordx4 v[194:197], v[152:153], off offset:3200
	global_load_dwordx4 v[104:107], v[158:159], off offset:3200
	global_load_dwordx4 v[108:111], v[164:165], off offset:3200
	s_waitcnt vmcnt(15)
	ds_write_b128 v130, v[80:83] offset:46080
	s_waitcnt vmcnt(14)
	ds_write_b128 v130, v[84:87] offset:64512
	global_load_dwordx4 v[80:83], v[156:157], off offset:3200
	global_load_dwordx4 v[84:87], v[162:163], off offset:3200
	s_waitcnt vmcnt(15)
	ds_write_b128 v130, v[88:91] offset:50688
	s_waitcnt vmcnt(14)
	ds_write_b128 v131, v[92:95] offset:13824
	global_load_dwordx4 v[88:91], v[154:155], off offset:3200
	global_load_dwordx4 v[92:95], v[160:161], off offset:3200
	s_waitcnt lgkmcnt(0)
	s_barrier
; #define GLOADQ(RA, RB, KT, q) do { const int k0_ = (KT) << 6; \
;     RA[q] = ldg16(ap.ptr(m0 + lrow + 32 * (q), k0_) + lkc); RB[q] = ldg16(W + (size_t)(n0 + lrow + 32 * (q)) * ldw + k0_ + lkc); } while (0)
; #define SSTOREQ(RA, RB, ST, q) do { \
;     *(u32x4*)(sA + (ST) * SBUF + (lrow + 32 * (q)) * GP + lkc) = RA[q]; *(u32x4*)(sB + (ST) * SBUF + (lrow + 32 * (q)) * GP + lkc) = RB[q]; } while (0)
; #define FLOAD(F, ST, ks) do { _Pragma("unroll") for (int a = 0; a < 2; ++a) { \
;     F[a] = *(const bf16x8*)(sB + (ST) * SBUF + (wn * 64 + a * 32 + r) * GP + (ks) * 16 + h * 8); \
;     F[2 + a] = *(const bf16x8*)(sA + (ST) * SBUF + (wm * 64 + a * 32 + r) * GP + (ks) * 16 + h * 8); } } while (0)
; #define FMMA(F) do { _Pragma("unroll") for (int a = 0; a < 2; ++a) _Pragma("unroll") for (int b = 0; b < 2; ++b) acc[a][b] = MFMA(F[a], F[2 + b], acc[a][b]); } while (0)
; template <bool MIDK, class AP, class EPI>
; DI void gemm_tile(const AP& ap, const u16* __restrict__ W, int ldw, int K, int m0, int n0, const EPI& epi, char* smem, float r0, float r1, int tid, bool dry) {
;     ...
;   for (int kt = 0; kt < nk; kt += 2) {
;     const bool l3 = kt + 3 < nk, s2 = kt + 2 < nk, l4 = kt + 4 < nk;
;     FLOAD(f0, 0, 0); FLOAD(f1, 0, 1);
;     FMMA(f0); SSTOREQ(ra1, rb1, 1, 0); if (l3) GLOADQ(ra1, rb1, kt + 3, 0);
;     FLOAD(f0, 0, 2);
;     FMMA(f1); SSTOREQ(ra1, rb1, 1, 1); if (l3) GLOADQ(ra1, rb1, kt + 3, 1);
;     FLOAD(f1, 0, 3);
;     FMMA(f0); SSTOREQ(ra1, rb1, 1, 2); if (l3) GLOADQ(ra1, rb1, kt + 3, 2);
;     FMMA(f1); SSTOREQ(ra1, rb1, 1, 3); if (l3) GLOADQ(ra1, rb1, kt + 3, 3);
;     __syncthreads();
;     FLOAD(f0, 1, 0); FLOAD(f1, 1, 1);
;     FMMA(f0); if (s2) SSTOREQ(ra0, rb0, 0, 0); if (l4) GLOADQ(ra0, rb0, kt + 4, 0);
;     FLOAD(f0, 1, 2);
;     FMMA(f1); if (s2) SSTOREQ(ra0, rb0, 0, 1); if (l4) GLOADQ(ra0, rb0, kt + 4, 1);
;     FLOAD(f1, 1, 3);
;     FMMA(f0); if (s2) SSTOREQ(ra0, rb0, 0, 2); if (l4) GLOADQ(ra0, rb0, kt + 4, 2);
;     FMMA(f1); if (s2) SSTOREQ(ra0, rb0, 0, 3); if (l4) GLOADQ(ra0, rb0, kt + 4, 3);
;     if (MIDK && kt == 6) {
; #pragma unroll
;       for (int a = 0; a < 2; ++a)
; #pragma unroll
;         for (int i = 0; i < 16; ++i) { acc[a][0][i] *= r0; acc[a][1][i] *= r1; }
;     }
;     __syncthreads();
	v_mfma_f32_32x32x16_bf16 v[0:15], v[116:119], v[112:115], v[0:15]
	ds_read_b128 v[112:115], v167 offset:55296
	ds_read_b128 v[116:119], v132 offset:36864
	ds_read_b128 v[200:203], v132 offset:41472
	s_waitcnt lgkmcnt(1)
	v_mfma_f32_32x32x16_bf16 v[48:63], v[112:115], v[116:119], v[48:63]
	s_waitcnt lgkmcnt(0)
	v_mfma_f32_32x32x16_bf16 v[32:47], v[112:115], v[200:203], v[32:47]
	ds_read_b128 v[112:115], v167 offset:59904
	s_waitcnt lgkmcnt(0)
	v_mfma_f32_32x32x16_bf16 v[16:31], v[112:115], v[116:119], v[16:31]
	v_mfma_f32_32x32x16_bf16 v[0:15], v[112:115], v[200:203], v[0:15]
	ds_read_b128 v[112:115], v167 offset:55328
	ds_read_b128 v[116:119], v132 offset:36896
	ds_read_b128 v[200:203], v132 offset:41504
	s_waitcnt lgkmcnt(1)
	v_mfma_f32_32x32x16_bf16 v[48:63], v[112:115], v[116:119], v[48:63]
	s_waitcnt lgkmcnt(0)
	v_mfma_f32_32x32x16_bf16 v[32:47], v[112:115], v[200:203], v[32:47]
	ds_read_b128 v[112:115], v167 offset:59936
	s_waitcnt vmcnt(15)
	ds_write_b128 v130, v[120:123]
	s_waitcnt vmcnt(14)
	ds_write_b128 v130, v[124:127] offset:18432
	s_waitcnt lgkmcnt(2)
	v_mfma_f32_32x32x16_bf16 v[16:31], v[112:115], v[116:119], v[16:31]
	v_mfma_f32_32x32x16_bf16 v[0:15], v[112:115], v[200:203], v[0:15]
	ds_read_b128 v[112:115], v167 offset:55360
	ds_read_b128 v[116:119], v132 offset:36928
	ds_read_b128 v[120:123], v132 offset:41536
	s_waitcnt lgkmcnt(1)
	v_mfma_f32_32x32x16_bf16 v[48:63], v[112:115], v[116:119], v[48:63]
	s_waitcnt lgkmcnt(0)
	v_mfma_f32_32x32x16_bf16 v[32:47], v[112:115], v[120:123], v[32:47]
	ds_read_b128 v[112:115], v167 offset:59968
	s_waitcnt vmcnt(13)
	ds_write_b128 v130, v[96:99] offset:4608
	s_waitcnt vmcnt(12)
	ds_write_b128 v130, v[100:103] offset:23040
	ds_read_b128 v[96:99], v167 offset:55392
	ds_read_b128 v[100:103], v132 offset:36960
	s_waitcnt lgkmcnt(4)
	v_mfma_f32_32x32x16_bf16 v[16:31], v[112:115], v[116:119], v[16:31]
	ds_read_b128 v[116:119], v167 offset:60000
	v_mfma_f32_32x32x16_bf16 v[0:15], v[112:115], v[120:123], v[0:15]
	ds_read_b128 v[112:115], v132 offset:41568
	s_waitcnt lgkmcnt(2)
	v_mfma_f32_32x32x16_bf16 v[48:63], v[96:99], v[100:103], v[48:63]
	s_waitcnt lgkmcnt(0)
	v_mfma_f32_32x32x16_bf16 v[32:47], v[96:99], v[112:115], v[32:47]
	v_mfma_f32_32x32x16_bf16 v[16:31], v[116:119], v[100:103], v[16:31]
	global_load_dwordx4 v[120:123], v[150:151], off offset:3328
	global_load_dwordx4 v[124:127], v[152:153], off offset:3328
	global_load_dwordx4 v[96:99], v[158:159], off offset:3328
	global_load_dwordx4 v[100:103], v[164:165], off offset:3328
	s_waitcnt vmcnt(15)
	ds_write_b128 v130, v[72:75] offset:9216
	s_waitcnt vmcnt(14)
	ds_write_b128 v130, v[76:79] offset:27648
	global_load_dwordx4 v[72:75], v[156:157], off offset:3328
	global_load_dwordx4 v[76:79], v[162:163], off offset:3328
	s_waitcnt vmcnt(15)
	ds_write_b128 v130, v[64:67] offset:13824
	s_waitcnt vmcnt(14)
	ds_write_b128 v130, v[68:71] offset:32256
	global_load_dwordx4 v[64:67], v[154:155], off offset:3328
	global_load_dwordx4 v[68:71], v[160:161], off offset:3328
	s_waitcnt lgkmcnt(0)
	s_barrier
	v_mfma_f32_32x32x16_bf16 v[0:15], v[116:119], v[112:115], v[0:15]
	ds_read_b128 v[112:115], v167 offset:18432
	ds_read_b128 v[116:119], v132
	ds_read_b128 v[200:203], v132 offset:4608
	s_waitcnt lgkmcnt(1)
	v_mfma_f32_32x32x16_bf16 v[48:63], v[112:115], v[116:119], v[48:63]
	s_waitcnt lgkmcnt(0)
	v_mfma_f32_32x32x16_bf16 v[32:47], v[112:115], v[200:203], v[32:47]
	ds_read_b128 v[112:115], v167 offset:23040
	s_waitcnt lgkmcnt(0)
	v_mfma_f32_32x32x16_bf16 v[16:31], v[112:115], v[116:119], v[16:31]
	v_mfma_f32_32x32x16_bf16 v[0:15], v[112:115], v[200:203], v[0:15]
	ds_read_b128 v[112:115], v167 offset:18464
	ds_read_b128 v[116:119], v132 offset:32
	ds_read_b128 v[200:203], v132 offset:4640
	s_waitcnt lgkmcnt(1)
	v_mfma_f32_32x32x16_bf16 v[48:63], v[112:115], v[116:119], v[48:63]
	s_waitcnt lgkmcnt(0)
	v_mfma_f32_32x32x16_bf16 v[32:47], v[112:115], v[200:203], v[32:47]
	ds_read_b128 v[112:115], v167 offset:23072
	s_waitcnt vmcnt(15)
	ds_write_b128 v130, v[186:189] offset:36864
	s_waitcnt vmcnt(14)
	ds_write_b128 v130, v[194:197] offset:55296
	s_waitcnt lgkmcnt(2)
	v_mfma_f32_32x32x16_bf16 v[16:31], v[112:115], v[116:119], v[16:31]
	v_mfma_f32_32x32x16_bf16 v[0:15], v[112:115], v[200:203], v[0:15]
	ds_read_b128 v[112:115], v167 offset:18496
	ds_read_b128 v[116:119], v132 offset:64
	ds_read_b128 v[186:189], v132 offset:4672
	s_waitcnt lgkmcnt(1)
	v_mfma_f32_32x32x16_bf16 v[48:63], v[112:115], v[116:119], v[48:63]
	s_waitcnt lgkmcnt(0)
	v_mfma_f32_32x32x16_bf16 v[32:47], v[112:115], v[186:189], v[32:47]
	ds_read_b128 v[112:115], v167 offset:23104
	s_waitcnt vmcnt(13)
	ds_write_b128 v130, v[104:107] offset:41472
	s_waitcnt vmcnt(12)
	ds_write_b128 v130, v[108:111] offset:59904
	ds_read_b128 v[104:107], v167 offset:18528
	ds_read_b128 v[108:111], v132 offset:96
	s_waitcnt lgkmcnt(4)
	v_mfma_f32_32x32x16_bf16 v[16:31], v[112:115], v[116:119], v[16:31]
	ds_read_b128 v[116:119], v167 offset:23136
	v_mfma_f32_32x32x16_bf16 v[0:15], v[112:115], v[186:189], v[0:15]
	ds_read_b128 v[112:115], v132 offset:4704
	s_waitcnt lgkmcnt(2)
	v_mfma_f32_32x32x16_bf16 v[48:63], v[104:107], v[108:111], v[48:63]
	s_waitcnt lgkmcnt(0)
	v_mfma_f32_32x32x16_bf16 v[32:47], v[104:107], v[112:115], v[32:47]
	v_mfma_f32_32x32x16_bf16 v[16:31], v[116:119], v[108:111], v[16:31]
	global_load_dwordx4 v[186:189], v[150:151], off offset:3456
	global_load_dwordx4 v[194:197], v[152:153], off offset:3456
	global_load_dwordx4 v[104:107], v[158:159], off offset:3456
	global_load_dwordx4 v[108:111], v[164:165], off offset:3456
	s_waitcnt vmcnt(15)
	ds_write_b128 v130, v[80:83] offset:46080
	s_waitcnt vmcnt(14)
	ds_write_b128 v130, v[84:87] offset:64512
	global_load_dwordx4 v[80:83], v[156:157], off offset:3456
	global_load_dwordx4 v[84:87], v[162:163], off offset:3456
	s_waitcnt vmcnt(15)
	ds_write_b128 v130, v[88:91] offset:50688
	s_waitcnt vmcnt(14)
	ds_write_b128 v131, v[92:95] offset:13824
	global_load_dwordx4 v[88:91], v[154:155], off offset:3456
	global_load_dwordx4 v[92:95], v[160:161], off offset:3456
	s_waitcnt lgkmcnt(0)
	s_barrier
; #define GLOADQ(RA, RB, KT, q) do { const int k0_ = (KT) << 6; \
;     RA[q] = ldg16(ap.ptr(m0 + lrow + 32 * (q), k0_) + lkc); RB[q] = ldg16(W + (size_t)(n0 + lrow + 32 * (q)) * ldw + k0_ + lkc); } while (0)
; #define SSTOREQ(RA, RB, ST, q) do { \
;     *(u32x4*)(sA + (ST) * SBUF + (lrow + 32 * (q)) * GP + lkc) = RA[q]; *(u32x4*)(sB + (ST) * SBUF + (lrow + 32 * (q)) * GP + lkc) = RB[q]; } while (0)
; #define FLOAD(F, ST, ks) do { _Pragma("unroll") for (int a = 0; a < 2; ++a) { \
;     F[a] = *(const bf16x8*)(sB + (ST) * SBUF + (wn * 64 + a * 32 + r) * GP + (ks) * 16 + h * 8); \
;     F[2 + a] = *(const bf16x8*)(sA + (ST) * SBUF + (wm * 64 + a * 32 + r) * GP + (ks) * 16 + h * 8); } } while (0)
; #define FMMA(F) do { _Pragma("unroll") for (int a = 0; a < 2; ++a) _Pragma("unroll") for (int b = 0; b < 2; ++b) acc[a][b] = MFMA(F[a], F[2 + b], acc[a][b]); } while (0)
; template <bool MIDK, class AP, class EPI>
; DI void gemm_tile(const AP& ap, const u16* __restrict__ W, int ldw, int K, int m0, int n0, const EPI& epi, char* smem, float r0, float r1, int tid, bool dry) {
;     ...
;   for (int kt = 0; kt < nk; kt += 2) {
;     const bool l3 = kt + 3 < nk, s2 = kt + 2 < nk, l4 = kt + 4 < nk;
;     FLOAD(f0, 0, 0); FLOAD(f1, 0, 1);
;     FMMA(f0); SSTOREQ(ra1, rb1, 1, 0); if (l3) GLOADQ(ra1, rb1, kt + 3, 0);
;     FLOAD(f0, 0, 2);
;     FMMA(f1); SSTOREQ(ra1, rb1, 1, 1); if (l3) GLOADQ(ra1, rb1, kt + 3, 1);
;     FLOAD(f1, 0, 3);
;     FMMA(f0); SSTOREQ(ra1, rb1, 1, 2); if (l3) GLOADQ(ra1, rb1, kt + 3, 2);
;     FMMA(f1); SSTOREQ(ra1, rb1, 1, 3); if (l3) GLOADQ(ra1, rb1, kt + 3, 3);
;     __syncthreads();
;     FLOAD(f0, 1, 0); FLOAD(f1, 1, 1);
;     FMMA(f0); if (s2) SSTOREQ(ra0, rb0, 0, 0); if (l4) GLOADQ(ra0, rb0, kt + 4, 0);
;     FLOAD(f0, 1, 2);
;     FMMA(f1); if (s2) SSTOREQ(ra0, rb0, 0, 1); if (l4) GLOADQ(ra0, rb0, kt + 4, 1);
;     FLOAD(f1, 1, 3);
;     FMMA(f0); if (s2) SSTOREQ(ra0, rb0, 0, 2); if (l4) GLOADQ(ra0, rb0, kt + 4, 2);
;     FMMA(f1); if (s2) SSTOREQ(ra0, rb0, 0, 3); if (l4) GLOADQ(ra0, rb0, kt + 4, 3);
;     if (MIDK && kt == 6) {
; #pragma unroll
;       for (int a = 0; a < 2; ++a)
; #pragma unroll
;         for (int i = 0; i < 16; ++i) { acc[a][0][i] *= r0; acc[a][1][i] *= r1; }
;     }
;     __syncthreads();
	v_mfma_f32_32x32x16_bf16 v[0:15], v[116:119], v[112:115], v[0:15]
	ds_read_b128 v[112:115], v167 offset:55296
	ds_read_b128 v[116:119], v132 offset:36864
	ds_read_b128 v[200:203], v132 offset:41472
	s_waitcnt lgkmcnt(1)
	v_mfma_f32_32x32x16_bf16 v[48:63], v[112:115], v[116:119], v[48:63]
	s_waitcnt lgkmcnt(0)
	v_mfma_f32_32x32x16_bf16 v[32:47], v[112:115], v[200:203], v[32:47]
	ds_read_b128 v[112:115], v167 offset:59904
	s_waitcnt lgkmcnt(0)
	v_mfma_f32_32x32x16_bf16 v[16:31], v[112:115], v[116:119], v[16:31]
	v_mfma_f32_32x32x16_bf16 v[0:15], v[112:115], v[200:203], v[0:15]
	ds_read_b128 v[112:115], v167 offset:55328
	ds_read_b128 v[116:119], v132 offset:36896
	ds_read_b128 v[200:203], v132 offset:41504
	s_waitcnt lgkmcnt(1)
	v_mfma_f32_32x32x16_bf16 v[48:63], v[112:115], v[116:119], v[48:63]
	s_waitcnt lgkmcnt(0)
	v_mfma_f32_32x32x16_bf16 v[32:47], v[112:115], v[200:203], v[32:47]
	ds_read_b128 v[112:115], v167 offset:59936
	s_waitcnt vmcnt(15)
	ds_write_b128 v130, v[120:123]
	s_waitcnt vmcnt(14)
	ds_write_b128 v130, v[124:127] offset:18432
	s_waitcnt lgkmcnt(2)
	v_mfma_f32_32x32x16_bf16 v[16:31], v[112:115], v[116:119], v[16:31]
	v_mfma_f32_32x32x16_bf16 v[0:15], v[112:115], v[200:203], v[0:15]
	ds_read_b128 v[112:115], v167 offset:55360
	ds_read_b128 v[116:119], v132 offset:36928
	ds_read_b128 v[120:123], v132 offset:41536
	s_waitcnt lgkmcnt(1)
	v_mfma_f32_32x32x16_bf16 v[48:63], v[112:115], v[116:119], v[48:63]
	s_waitcnt lgkmcnt(0)
	v_mfma_f32_32x32x16_bf16 v[32:47], v[112:115], v[120:123], v[32:47]
	ds_read_b128 v[112:115], v167 offset:59968
	s_waitcnt vmcnt(13)
	ds_write_b128 v130, v[96:99] offset:4608
	s_waitcnt vmcnt(12)
	ds_write_b128 v130, v[100:103] offset:23040
	ds_read_b128 v[96:99], v167 offset:55392
	ds_read_b128 v[100:103], v132 offset:36960
	s_waitcnt lgkmcnt(4)
	v_mfma_f32_32x32x16_bf16 v[0:15], v[112:115], v[120:123], v[0:15]
	ds_read_b128 v[120:123], v132 offset:41568
	s_waitcnt lgkmcnt(1)
	v_mfma_f32_32x32x16_bf16 v[48:63], v[96:99], v[100:103], v[48:63]
	s_waitcnt lgkmcnt(0)
	v_mfma_f32_32x32x16_bf16 v[32:47], v[96:99], v[120:123], v[32:47]
	ds_read_b128 v[96:99], v167 offset:60000
	v_mfma_f32_32x32x16_bf16 v[16:31], v[112:115], v[116:119], v[16:31]
	global_load_dwordx4 v[200:203], v[150:151], off offset:3584
	global_load_dwordx4 v[204:207], v[152:153], off offset:3584
	global_load_dwordx4 v[112:115], v[158:159], off offset:3584
	global_load_dwordx4 v[116:119], v[164:165], off offset:3584
	s_waitcnt vmcnt(15)
	ds_write_b128 v130, v[72:75] offset:9216
	s_waitcnt vmcnt(14)
	ds_write_b128 v130, v[76:79] offset:27648
	global_load_dwordx4 v[72:75], v[156:157], off offset:3584
	global_load_dwordx4 v[76:79], v[162:163], off offset:3584
	s_waitcnt vmcnt(15)
	ds_write_b128 v130, v[64:67] offset:13824
	s_waitcnt vmcnt(14)
	ds_write_b128 v130, v[68:71] offset:32256
	s_waitcnt lgkmcnt(4)
	v_mfma_f32_32x32x16_bf16 v[16:31], v[96:99], v[100:103], v[16:31]
	v_mfma_f32_32x32x16_bf16 v[0:15], v[96:99], v[120:123], v[0:15]
	global_load_dwordx4 v[96:99], v[154:155], off offset:3584
	global_load_dwordx4 v[100:103], v[160:161], off offset:3584
	s_waitcnt lgkmcnt(0)
	s_barrier
	ds_read_b128 v[64:67], v167 offset:18432
	ds_read_b128 v[68:71], v132
	ds_read_b128 v[120:123], v132 offset:4608
	s_waitcnt lgkmcnt(1)
	v_mfma_f32_32x32x16_bf16 v[48:63], v[64:67], v[68:71], v[48:63]
	s_waitcnt lgkmcnt(0)
	v_mfma_f32_32x32x16_bf16 v[32:47], v[64:67], v[120:123], v[32:47]
	ds_read_b128 v[64:67], v167 offset:23040
	s_waitcnt lgkmcnt(0)
	v_mfma_f32_32x32x16_bf16 v[16:31], v[64:67], v[68:71], v[16:31]
	v_mfma_f32_32x32x16_bf16 v[0:15], v[64:67], v[120:123], v[0:15]
	ds_read_b128 v[64:67], v167 offset:18464
	ds_read_b128 v[68:71], v132 offset:32
	ds_read_b128 v[120:123], v132 offset:4640
	s_waitcnt lgkmcnt(1)
	v_mfma_f32_32x32x16_bf16 v[48:63], v[64:67], v[68:71], v[48:63]
	s_waitcnt lgkmcnt(0)
	v_mfma_f32_32x32x16_bf16 v[32:47], v[64:67], v[120:123], v[32:47]
	ds_read_b128 v[64:67], v167 offset:23072
	s_waitcnt vmcnt(15)
	ds_write_b128 v130, v[186:189] offset:36864
	s_waitcnt vmcnt(14)
	ds_write_b128 v130, v[194:197] offset:55296
	s_waitcnt lgkmcnt(2)
	v_mfma_f32_32x32x16_bf16 v[16:31], v[64:67], v[68:71], v[16:31]
	v_mfma_f32_32x32x16_bf16 v[0:15], v[64:67], v[120:123], v[0:15]
	ds_read_b128 v[64:67], v167 offset:18496
	ds_read_b128 v[68:71], v132 offset:64
	ds_read_b128 v[120:123], v132 offset:4672
	s_waitcnt lgkmcnt(1)
	v_mfma_f32_32x32x16_bf16 v[48:63], v[64:67], v[68:71], v[48:63]
	s_waitcnt lgkmcnt(0)
	v_mfma_f32_32x32x16_bf16 v[32:47], v[64:67], v[120:123], v[32:47]
	ds_read_b128 v[64:67], v167 offset:23104
	s_waitcnt vmcnt(13)
	ds_write_b128 v130, v[104:107] offset:41472
	s_waitcnt vmcnt(12)
	ds_write_b128 v130, v[108:111] offset:59904
	s_waitcnt lgkmcnt(2)
	v_mfma_f32_32x32x16_bf16 v[16:31], v[64:67], v[68:71], v[16:31]
	v_mfma_f32_32x32x16_bf16 v[0:15], v[64:67], v[120:123], v[0:15]
	ds_read_b128 v[64:67], v167 offset:18528
	ds_read_b128 v[68:71], v132 offset:96
	ds_read_b128 v[104:107], v132 offset:4704
	s_waitcnt lgkmcnt(1)
	v_mfma_f32_32x32x16_bf16 v[48:63], v[64:67], v[68:71], v[48:63]
	s_waitcnt lgkmcnt(0)
	v_mfma_f32_32x32x16_bf16 v[32:47], v[64:67], v[104:107], v[32:47]
	ds_read_b128 v[64:67], v167 offset:23136
	global_load_dwordx4 v[186:189], v[150:151], off offset:3712
	global_load_dwordx4 v[194:197], v[152:153], off offset:3712
	global_load_dwordx4 v[120:123], v[158:159], off offset:3712
	global_load_dwordx4 v[124:127], v[164:165], off offset:3712
	s_waitcnt vmcnt(15)
	ds_write_b128 v130, v[80:83] offset:46080
	s_waitcnt vmcnt(14)
	ds_write_b128 v130, v[84:87] offset:64512
	global_load_dwordx4 v[80:83], v[156:157], off offset:3712
	global_load_dwordx4 v[84:87], v[162:163], off offset:3712
	s_waitcnt vmcnt(15)
	ds_write_b128 v130, v[88:91] offset:50688
	s_waitcnt vmcnt(14)
	ds_write_b128 v131, v[92:95] offset:13824
	global_load_dwordx4 v[88:91], v[154:155], off offset:3712
	global_load_dwordx4 v[92:95], v[160:161], off offset:3712
	s_waitcnt lgkmcnt(0)
	v_mfma_f32_32x32x16_bf16 v[16:31], v[64:67], v[68:71], v[16:31]
	s_barrier
; #define GLOADQ(RA, RB, KT, q) do { const int k0_ = (KT) << 6; \
;     RA[q] = ldg16(ap.ptr(m0 + lrow + 32 * (q), k0_) + lkc); RB[q] = ldg16(W + (size_t)(n0 + lrow + 32 * (q)) * ldw + k0_ + lkc); } while (0)
; #define SSTOREQ(RA, RB, ST, q) do { \
;     *(u32x4*)(sA + (ST) * SBUF + (lrow + 32 * (q)) * GP + lkc) = RA[q]; *(u32x4*)(sB + (ST) * SBUF + (lrow + 32 * (q)) * GP + lkc) = RB[q]; } while (0)
; #define FLOAD(F, ST, ks) do { _Pragma("unroll") for (int a = 0; a < 2; ++a) { \
;     F[a] = *(const bf16x8*)(sB + (ST) * SBUF + (wn * 64 + a * 32 + r) * GP + (ks) * 16 + h * 8); \
;     F[2 + a] = *(const bf16x8*)(sA + (ST) * SBUF + (wm * 64 + a * 32 + r) * GP + (ks) * 16 + h * 8); } } while (0)
; #define FMMA(F) do { _Pragma("unroll") for (int a = 0; a < 2; ++a) _Pragma("unroll") for (int b = 0; b < 2; ++b) acc[a][b] = MFMA(F[a], F[2 + b], acc[a][b]); } while (0)
; template <bool MIDK, class AP, class EPI>
; DI void gemm_tile(const AP& ap, const u16* __restrict__ W, int ldw, int K, int m0, int n0, const EPI& epi, char* smem, float r0, float r1, int tid, bool dry) {
;     ...
;   for (int kt = 0; kt < nk; kt += 2) {
;     const bool l3 = kt + 3 < nk, s2 = kt + 2 < nk, l4 = kt + 4 < nk;
;     FLOAD(f0, 0, 0); FLOAD(f1, 0, 1);
;     FMMA(f0); SSTOREQ(ra1, rb1, 1, 0); if (l3) GLOADQ(ra1, rb1, kt + 3, 0);
;     FLOAD(f0, 0, 2);
;     FMMA(f1); SSTOREQ(ra1, rb1, 1, 1); if (l3) GLOADQ(ra1, rb1, kt + 3, 1);
;     FLOAD(f1, 0, 3);
;     FMMA(f0); SSTOREQ(ra1, rb1, 1, 2); if (l3) GLOADQ(ra1, rb1, kt + 3, 2);
;     FMMA(f1); SSTOREQ(ra1, rb1, 1, 3); if (l3) GLOADQ(ra1, rb1, kt + 3, 3);
;     __syncthreads();
;     FLOAD(f0, 1, 0); FLOAD(f1, 1, 1);
;     FMMA(f0); if (s2) SSTOREQ(ra0, rb0, 0, 0); if (l4) GLOADQ(ra0, rb0, kt + 4, 0);
;     FLOAD(f0, 1, 2);
;     FMMA(f1); if (s2) SSTOREQ(ra0, rb0, 0, 1); if (l4) GLOADQ(ra0, rb0, kt + 4, 1);
;     FLOAD(f1, 1, 3);
;     FMMA(f0); if (s2) SSTOREQ(ra0, rb0, 0, 2); if (l4) GLOADQ(ra0, rb0, kt + 4, 2);
;     FMMA(f1); if (s2) SSTOREQ(ra0, rb0, 0, 3); if (l4) GLOADQ(ra0, rb0, kt + 4, 3);
;     if (MIDK && kt == 6) {
; #pragma unroll
;       for (int a = 0; a < 2; ++a)
; #pragma unroll
;         for (int i = 0; i < 16; ++i) { acc[a][0][i] *= r0; acc[a][1][i] *= r1; }
;     }
;     __syncthreads();
	v_mfma_f32_32x32x16_bf16 v[0:15], v[64:67], v[104:107], v[0:15]
	ds_read_b128 v[64:67], v167 offset:55296
	ds_read_b128 v[68:71], v132 offset:36864
	ds_read_b128 v[104:107], v132 offset:41472
	s_waitcnt lgkmcnt(1)
	v_mfma_f32_32x32x16_bf16 v[48:63], v[64:67], v[68:71], v[48:63]
	s_waitcnt lgkmcnt(0)
	v_mfma_f32_32x32x16_bf16 v[32:47], v[64:67], v[104:107], v[32:47]
	ds_read_b128 v[64:67], v167 offset:59904
	s_waitcnt lgkmcnt(0)
	v_mfma_f32_32x32x16_bf16 v[16:31], v[64:67], v[68:71], v[16:31]
	v_mfma_f32_32x32x16_bf16 v[0:15], v[64:67], v[104:107], v[0:15]
	ds_read_b128 v[64:67], v167 offset:55328
	ds_read_b128 v[68:71], v132 offset:36896
	ds_read_b128 v[104:107], v132 offset:41504
	s_waitcnt lgkmcnt(1)
	v_mfma_f32_32x32x16_bf16 v[48:63], v[64:67], v[68:71], v[48:63]
	s_waitcnt lgkmcnt(0)
	v_mfma_f32_32x32x16_bf16 v[32:47], v[64:67], v[104:107], v[32:47]
	ds_read_b128 v[64:67], v167 offset:59936
	s_waitcnt vmcnt(15)
	ds_write_b128 v130, v[200:203]
	s_waitcnt vmcnt(14)
	ds_write_b128 v130, v[204:207] offset:18432
	s_waitcnt lgkmcnt(2)
	v_mfma_f32_32x32x16_bf16 v[16:31], v[64:67], v[68:71], v[16:31]
	v_mfma_f32_32x32x16_bf16 v[0:15], v[64:67], v[104:107], v[0:15]
	ds_read_b128 v[64:67], v167 offset:55360
	ds_read_b128 v[68:71], v132 offset:36928
	ds_read_b128 v[104:107], v132 offset:41536
	s_waitcnt lgkmcnt(1)
	v_mfma_f32_32x32x16_bf16 v[48:63], v[64:67], v[68:71], v[48:63]
	s_waitcnt lgkmcnt(0)
	v_mfma_f32_32x32x16_bf16 v[32:47], v[64:67], v[104:107], v[32:47]
	ds_read_b128 v[64:67], v167 offset:59968
	s_waitcnt vmcnt(13)
	ds_write_b128 v130, v[112:115] offset:4608
	s_waitcnt vmcnt(12)
	ds_write_b128 v130, v[116:119] offset:23040
	s_waitcnt lgkmcnt(2)
	v_mfma_f32_32x32x16_bf16 v[16:31], v[64:67], v[68:71], v[16:31]
	v_mfma_f32_32x32x16_bf16 v[0:15], v[64:67], v[104:107], v[0:15]
	ds_read_b128 v[64:67], v167 offset:55392
	ds_read_b128 v[68:71], v132 offset:36960
	ds_read_b128 v[112:115], v132 offset:41568
	ds_read_b128 v[116:119], v167 offset:60000
	global_load_dwordx4 v[200:203], v[150:151], off offset:3840
	global_load_dwordx4 v[204:207], v[152:153], off offset:3840
	global_load_dwordx4 v[104:107], v[158:159], off offset:3840
	global_load_dwordx4 v[108:111], v[164:165], off offset:3840
	s_waitcnt vmcnt(15)
	ds_write_b128 v130, v[72:75] offset:9216
	s_waitcnt vmcnt(14)
	ds_write_b128 v130, v[76:79] offset:27648
	s_waitcnt lgkmcnt(4)
	v_mfma_f32_32x32x16_bf16 v[48:63], v[64:67], v[68:71], v[48:63]
	s_waitcnt lgkmcnt(3)
	v_mfma_f32_32x32x16_bf16 v[32:47], v[64:67], v[112:115], v[32:47]
	s_waitcnt lgkmcnt(2)
	v_mfma_f32_32x32x16_bf16 v[16:31], v[116:119], v[68:71], v[16:31]
	global_load_dwordx4 v[64:67], v[156:157], off offset:3840
	global_load_dwordx4 v[68:71], v[162:163], off offset:3840
	s_waitcnt vmcnt(15)
	ds_write_b128 v130, v[96:99] offset:13824
	s_waitcnt vmcnt(14)
	ds_write_b128 v130, v[100:103] offset:32256
	global_load_dwordx4 v[72:75], v[154:155], off offset:3840
	global_load_dwordx4 v[76:79], v[160:161], off offset:3840
	s_waitcnt lgkmcnt(0)
	s_barrier
	ds_read_b128 v[96:99], v167 offset:18432
	ds_read_b128 v[100:103], v132
	v_mfma_f32_32x32x16_bf16 v[0:15], v[116:119], v[112:115], v[0:15]
	ds_read_b128 v[112:115], v132 offset:4608
	s_waitcnt lgkmcnt(1)
	v_mfma_f32_32x32x16_bf16 v[48:63], v[96:99], v[100:103], v[48:63]
	s_waitcnt lgkmcnt(0)
	v_mfma_f32_32x32x16_bf16 v[32:47], v[96:99], v[112:115], v[32:47]
	ds_read_b128 v[96:99], v167 offset:23040
	s_waitcnt lgkmcnt(0)
	v_mfma_f32_32x32x16_bf16 v[16:31], v[96:99], v[100:103], v[16:31]
	v_mfma_f32_32x32x16_bf16 v[0:15], v[96:99], v[112:115], v[0:15]
	ds_read_b128 v[96:99], v167 offset:18464
	ds_read_b128 v[100:103], v132 offset:32
	ds_read_b128 v[112:115], v132 offset:4640
	s_waitcnt lgkmcnt(1)
	v_mfma_f32_32x32x16_bf16 v[48:63], v[96:99], v[100:103], v[48:63]
	s_waitcnt lgkmcnt(0)
	v_mfma_f32_32x32x16_bf16 v[32:47], v[96:99], v[112:115], v[32:47]
	ds_read_b128 v[96:99], v167 offset:23072
	s_waitcnt vmcnt(15)
	ds_write_b128 v130, v[186:189] offset:36864
	s_waitcnt vmcnt(14)
	ds_write_b128 v130, v[194:197] offset:55296
	s_waitcnt lgkmcnt(2)
	v_mfma_f32_32x32x16_bf16 v[16:31], v[96:99], v[100:103], v[16:31]
	v_mfma_f32_32x32x16_bf16 v[0:15], v[96:99], v[112:115], v[0:15]
	ds_read_b128 v[96:99], v167 offset:18496
	ds_read_b128 v[100:103], v132 offset:64
	ds_read_b128 v[112:115], v132 offset:4672
	s_waitcnt lgkmcnt(1)
	v_mfma_f32_32x32x16_bf16 v[48:63], v[96:99], v[100:103], v[48:63]
	s_waitcnt lgkmcnt(0)
	v_mfma_f32_32x32x16_bf16 v[32:47], v[96:99], v[112:115], v[32:47]
	ds_read_b128 v[96:99], v167 offset:23104
	s_waitcnt vmcnt(13)
	ds_write_b128 v130, v[120:123] offset:41472
	s_waitcnt vmcnt(12)
	ds_write_b128 v130, v[124:127] offset:59904
	s_waitcnt lgkmcnt(2)
	v_mfma_f32_32x32x16_bf16 v[16:31], v[96:99], v[100:103], v[16:31]
	v_mfma_f32_32x32x16_bf16 v[0:15], v[96:99], v[112:115], v[0:15]
	ds_read_b128 v[96:99], v167 offset:18528
	ds_read_b128 v[100:103], v132 offset:96
	ds_read_b128 v[112:115], v132 offset:4704
	ds_read_b128 v[116:119], v167 offset:23136
	s_waitcnt lgkmcnt(2)
	v_mfma_f32_32x32x16_bf16 v[48:63], v[96:99], v[100:103], v[48:63]
	s_waitcnt lgkmcnt(1)
	v_mfma_f32_32x32x16_bf16 v[32:47], v[96:99], v[112:115], v[32:47]
	s_waitcnt lgkmcnt(0)
	v_mfma_f32_32x32x16_bf16 v[16:31], v[116:119], v[100:103], v[16:31]
	global_load_dwordx4 v[120:123], v[150:151], off offset:3968
	global_load_dwordx4 v[124:127], v[152:153], off offset:3968
	global_load_dwordx4 v[96:99], v[158:159], off offset:3968
	global_load_dwordx4 v[100:103], v[164:165], off offset:3968
	s_waitcnt vmcnt(15)
	ds_write_b128 v130, v[80:83] offset:46080
	s_waitcnt vmcnt(14)
	ds_write_b128 v130, v[84:87] offset:64512
	global_load_dwordx4 v[80:83], v[156:157], off offset:3968
	global_load_dwordx4 v[84:87], v[162:163], off offset:3968
	s_waitcnt vmcnt(15)
	ds_write_b128 v130, v[88:91] offset:50688
	s_waitcnt vmcnt(14)
	ds_write_b128 v131, v[92:95] offset:13824
	global_load_dwordx4 v[88:91], v[154:155], off offset:3968
	global_load_dwordx4 v[92:95], v[160:161], off offset:3968
	s_waitcnt lgkmcnt(0)
	s_barrier
; #define GLOADQ(RA, RB, KT, q) do { const int k0_ = (KT) << 6; \
;     RA[q] = ldg16(ap.ptr(m0 + lrow + 32 * (q), k0_) + lkc); RB[q] = ldg16(W + (size_t)(n0 + lrow + 32 * (q)) * ldw + k0_ + lkc); } while (0)
; #define SSTOREQ(RA, RB, ST, q) do { \
;     *(u32x4*)(sA + (ST) * SBUF + (lrow + 32 * (q)) * GP + lkc) = RA[q]; *(u32x4*)(sB + (ST) * SBUF + (lrow + 32 * (q)) * GP + lkc) = RB[q]; } while (0)
; #define FLOAD(F, ST, ks) do { _Pragma("unroll") for (int a = 0; a < 2; ++a) { \
;     F[a] = *(const bf16x8*)(sB + (ST) * SBUF + (wn * 64 + a * 32 + r) * GP + (ks) * 16 + h * 8); \
;     F[2 + a] = *(const bf16x8*)(sA + (ST) * SBUF + (wm * 64 + a * 32 + r) * GP + (ks) * 16 + h * 8); } } while (0)
; #define FMMA(F) do { _Pragma("unroll") for (int a = 0; a < 2; ++a) _Pragma("unroll") for (int b = 0; b < 2; ++b) acc[a][b] = MFMA(F[a], F[2 + b], acc[a][b]); } while (0)
; template <bool MIDK, class AP, class EPI>
; DI void gemm_tile(const AP& ap, const u16* __restrict__ W, int ldw, int K, int m0, int n0, const EPI& epi, char* smem, float r0, float r1, int tid, bool dry) {
;     ...
;   for (int kt = 0; kt < nk; kt += 2) {
;     const bool l3 = kt + 3 < nk, s2 = kt + 2 < nk, l4 = kt + 4 < nk;
;     FLOAD(f0, 0, 0); FLOAD(f1, 0, 1);
;     FMMA(f0); SSTOREQ(ra1, rb1, 1, 0); if (l3) GLOADQ(ra1, rb1, kt + 3, 0);
;     FLOAD(f0, 0, 2);
;     FMMA(f1); SSTOREQ(ra1, rb1, 1, 1); if (l3) GLOADQ(ra1, rb1, kt + 3, 1);
;     FLOAD(f1, 0, 3);
;     FMMA(f0); SSTOREQ(ra1, rb1, 1, 2); if (l3) GLOADQ(ra1, rb1, kt + 3, 2);
;     FMMA(f1); SSTOREQ(ra1, rb1, 1, 3); if (l3) GLOADQ(ra1, rb1, kt + 3, 3);
;     __syncthreads();
;     FLOAD(f0, 1, 0); FLOAD(f1, 1, 1);
;     FMMA(f0); if (s2) SSTOREQ(ra0, rb0, 0, 0); if (l4) GLOADQ(ra0, rb0, kt + 4, 0);
;     FLOAD(f0, 1, 2);
;     FMMA(f1); if (s2) SSTOREQ(ra0, rb0, 0, 1); if (l4) GLOADQ(ra0, rb0, kt + 4, 1);
;     FLOAD(f1, 1, 3);
;     FMMA(f0); if (s2) SSTOREQ(ra0, rb0, 0, 2); if (l4) GLOADQ(ra0, rb0, kt + 4, 2);
;     FMMA(f1); if (s2) SSTOREQ(ra0, rb0, 0, 3); if (l4) GLOADQ(ra0, rb0, kt + 4, 3);
;     if (MIDK && kt == 6) {
; #pragma unroll
;       for (int a = 0; a < 2; ++a)
; #pragma unroll
;         for (int i = 0; i < 16; ++i) { acc[a][0][i] *= r0; acc[a][1][i] *= r1; }
;     }
;     __syncthreads();
	v_mfma_f32_32x32x16_bf16 v[0:15], v[116:119], v[112:115], v[0:15]
	ds_read_b128 v[112:115], v167 offset:55296
	ds_read_b128 v[116:119], v132 offset:36864
	ds_read_b128 v[154:157], v132 offset:41472
	s_waitcnt lgkmcnt(1)
	v_mfma_f32_32x32x16_bf16 v[48:63], v[112:115], v[116:119], v[48:63]
	s_waitcnt lgkmcnt(0)
	v_mfma_f32_32x32x16_bf16 v[32:47], v[112:115], v[154:157], v[32:47]
	ds_read_b128 v[112:115], v167 offset:59904
	s_waitcnt lgkmcnt(0)
	v_mfma_f32_32x32x16_bf16 v[16:31], v[112:115], v[116:119], v[16:31]
	v_mfma_f32_32x32x16_bf16 v[0:15], v[112:115], v[154:157], v[0:15]
	ds_read_b128 v[112:115], v167 offset:55328
	ds_read_b128 v[116:119], v132 offset:36896
	ds_read_b128 v[154:157], v132 offset:41504
	s_waitcnt lgkmcnt(1)
	v_mfma_f32_32x32x16_bf16 v[48:63], v[112:115], v[116:119], v[48:63]
	s_waitcnt lgkmcnt(0)
	v_mfma_f32_32x32x16_bf16 v[32:47], v[112:115], v[154:157], v[32:47]
	ds_read_b128 v[112:115], v167 offset:59936
	s_waitcnt vmcnt(15)
	ds_write_b128 v130, v[200:203]
	s_waitcnt vmcnt(14)
	ds_write_b128 v130, v[204:207] offset:18432
	s_waitcnt lgkmcnt(2)
	v_mfma_f32_32x32x16_bf16 v[16:31], v[112:115], v[116:119], v[16:31]
	v_mfma_f32_32x32x16_bf16 v[0:15], v[112:115], v[154:157], v[0:15]
	ds_read_b128 v[112:115], v167 offset:55360
	ds_read_b128 v[116:119], v132 offset:36928
	ds_read_b128 v[154:157], v132 offset:41536
	s_waitcnt lgkmcnt(1)
	v_mfma_f32_32x32x16_bf16 v[48:63], v[112:115], v[116:119], v[48:63]
	s_waitcnt lgkmcnt(0)
	v_mfma_f32_32x32x16_bf16 v[32:47], v[112:115], v[154:157], v[32:47]
	ds_read_b128 v[112:115], v167 offset:59968
	s_waitcnt vmcnt(13)
	ds_write_b128 v130, v[104:107] offset:4608
	s_waitcnt vmcnt(12)
	ds_write_b128 v130, v[108:111] offset:23040
	ds_read_b128 v[104:107], v167 offset:55392
	ds_read_b128 v[108:111], v132 offset:36960
	s_waitcnt lgkmcnt(4)
	v_mfma_f32_32x32x16_bf16 v[16:31], v[112:115], v[116:119], v[16:31]
	v_mfma_f32_32x32x16_bf16 v[0:15], v[112:115], v[154:157], v[0:15]
	ds_read_b128 v[116:119], v132 offset:41568
	ds_read_b128 v[154:157], v167 offset:60000
	v_add_co_u32_e32 v112, vcc, s5, v150
	s_nop 1
	v_addc_co_u32_e32 v113, vcc, 0, v151, vcc
	v_add_co_u32_e32 v114, vcc, s5, v152
	s_waitcnt lgkmcnt(2)
	v_mfma_f32_32x32x16_bf16 v[48:63], v[104:107], v[108:111], v[48:63]
	v_addc_co_u32_e32 v115, vcc, 0, v153, vcc
	s_andn2_b64 vcc, exec, s[38:39]
	s_waitcnt lgkmcnt(1)
	v_mfma_f32_32x32x16_bf16 v[32:47], v[104:107], v[116:119], v[32:47]
	s_waitcnt lgkmcnt(0)
	v_mfma_f32_32x32x16_bf16 v[16:31], v[154:157], v[108:111], v[16:31]
	global_load_dwordx4 v[150:153], v[112:113], off
	global_load_dwordx4 v[158:161], v[114:115], off
	global_load_dwordx4 v[104:107], v[138:139], off
	global_load_dwordx4 v[108:111], v[140:141], off
	s_waitcnt vmcnt(15)
	ds_write_b128 v130, v[64:67] offset:9216
	s_waitcnt vmcnt(14)
	ds_write_b128 v130, v[68:71] offset:27648
	global_load_dwordx4 v[64:67], v[142:143], off
	global_load_dwordx4 v[68:71], v[144:145], off
	s_waitcnt vmcnt(15)
	ds_write_b128 v130, v[72:75] offset:13824
	s_waitcnt vmcnt(14)
	ds_write_b128 v130, v[76:79] offset:32256
	global_load_dwordx4 v[72:75], v[146:147], off
	global_load_dwordx4 v[76:79], v[148:149], off
	s_waitcnt lgkmcnt(0)
	s_barrier
	v_mfma_f32_32x32x16_bf16 v[0:15], v[154:157], v[116:119], v[0:15]
	ds_read_b128 v[116:119], v167 offset:18432
	ds_read_b128 v[154:157], v132
	ds_read_b128 v[162:165], v132 offset:4608
	s_waitcnt lgkmcnt(1)
	v_mfma_f32_32x32x16_bf16 v[48:63], v[116:119], v[154:157], v[48:63]
	s_waitcnt lgkmcnt(0)
	v_mfma_f32_32x32x16_bf16 v[32:47], v[116:119], v[162:165], v[32:47]
	ds_read_b128 v[116:119], v167 offset:23040
	s_waitcnt lgkmcnt(0)
	v_mfma_f32_32x32x16_bf16 v[16:31], v[116:119], v[154:157], v[16:31]
	v_mfma_f32_32x32x16_bf16 v[0:15], v[116:119], v[162:165], v[0:15]
	ds_read_b128 v[116:119], v167 offset:18464
	ds_read_b128 v[154:157], v132 offset:32
	ds_read_b128 v[162:165], v132 offset:4640
	s_waitcnt lgkmcnt(1)
	v_mfma_f32_32x32x16_bf16 v[48:63], v[116:119], v[154:157], v[48:63]
	s_waitcnt lgkmcnt(0)
	v_mfma_f32_32x32x16_bf16 v[32:47], v[116:119], v[162:165], v[32:47]
	ds_read_b128 v[116:119], v167 offset:23072
	s_waitcnt vmcnt(15)
	ds_write_b128 v130, v[120:123] offset:36864
	s_waitcnt vmcnt(14)
	ds_write_b128 v130, v[124:127] offset:55296
	s_waitcnt lgkmcnt(2)
	v_mfma_f32_32x32x16_bf16 v[16:31], v[116:119], v[154:157], v[16:31]
	v_mfma_f32_32x32x16_bf16 v[0:15], v[116:119], v[162:165], v[0:15]
	ds_read_b128 v[116:119], v167 offset:18496
	ds_read_b128 v[120:123], v132 offset:64
	ds_read_b128 v[124:127], v132 offset:4672
	s_waitcnt lgkmcnt(1)
	v_mfma_f32_32x32x16_bf16 v[48:63], v[116:119], v[120:123], v[48:63]
	s_waitcnt lgkmcnt(0)
	v_mfma_f32_32x32x16_bf16 v[32:47], v[116:119], v[124:127], v[32:47]
	ds_read_b128 v[116:119], v167 offset:23104
	s_waitcnt vmcnt(13)
	ds_write_b128 v130, v[96:99] offset:41472
	s_waitcnt vmcnt(12)
	ds_write_b128 v130, v[100:103] offset:59904
	ds_read_b128 v[96:99], v167 offset:18528
	ds_read_b128 v[100:103], v132 offset:96
	s_waitcnt lgkmcnt(4)
	v_mfma_f32_32x32x16_bf16 v[16:31], v[116:119], v[120:123], v[16:31]
	ds_read_b128 v[120:123], v167 offset:23136
	v_mfma_f32_32x32x16_bf16 v[0:15], v[116:119], v[124:127], v[0:15]
	ds_read_b128 v[116:119], v132 offset:4704
	s_waitcnt lgkmcnt(2)
	v_mfma_f32_32x32x16_bf16 v[48:63], v[96:99], v[100:103], v[48:63]
	s_waitcnt lgkmcnt(0)
	v_mfma_f32_32x32x16_bf16 v[32:47], v[96:99], v[116:119], v[32:47]
	v_mfma_f32_32x32x16_bf16 v[16:31], v[120:123], v[100:103], v[16:31]
	global_load_dwordx4 v[124:127], v[112:113], off offset:128
	global_load_dwordx4 v[154:157], v[114:115], off offset:128
	global_load_dwordx4 v[96:99], v[138:139], off offset:128
	global_load_dwordx4 v[100:103], v[140:141], off offset:128
	s_waitcnt vmcnt(15)
	ds_write_b128 v130, v[80:83] offset:46080
	s_waitcnt vmcnt(14)
	ds_write_b128 v130, v[84:87] offset:64512
	global_load_dwordx4 v[80:83], v[142:143], off offset:128
	global_load_dwordx4 v[84:87], v[144:145], off offset:128
	s_waitcnt vmcnt(15)
	ds_write_b128 v130, v[88:91] offset:50688
	s_waitcnt vmcnt(14)
	ds_write_b128 v131, v[92:95] offset:13824
	global_load_dwordx4 v[88:91], v[146:147], off offset:128
	global_load_dwordx4 v[92:95], v[148:149], off offset:128
	s_waitcnt lgkmcnt(0)
	s_barrier
; #define GLOADQ(RA, RB, KT, q) do { const int k0_ = (KT) << 6; \
;     RA[q] = ldg16(ap.ptr(m0 + lrow + 32 * (q), k0_) + lkc); RB[q] = ldg16(W + (size_t)(n0 + lrow + 32 * (q)) * ldw + k0_ + lkc); } while (0)
; #define SSTOREQ(RA, RB, ST, q) do { \
;     *(u32x4*)(sA + (ST) * SBUF + (lrow + 32 * (q)) * GP + lkc) = RA[q]; *(u32x4*)(sB + (ST) * SBUF + (lrow + 32 * (q)) * GP + lkc) = RB[q]; } while (0)
; #define FLOAD(F, ST, ks) do { _Pragma("unroll") for (int a = 0; a < 2; ++a) { \
;     F[a] = *(const bf16x8*)(sB + (ST) * SBUF + (wn * 64 + a * 32 + r) * GP + (ks) * 16 + h * 8); \
;     F[2 + a] = *(const bf16x8*)(sA + (ST) * SBUF + (wm * 64 + a * 32 + r) * GP + (ks) * 16 + h * 8); } } while (0)
; #define FMMA(F) do { _Pragma("unroll") for (int a = 0; a < 2; ++a) _Pragma("unroll") for (int b = 0; b < 2; ++b) acc[a][b] = MFMA(F[a], F[2 + b], acc[a][b]); } while (0)
; template <bool MIDK, class AP, class EPI>
; DI void gemm_tile(const AP& ap, const u16* __restrict__ W, int ldw, int K, int m0, int n0, const EPI& epi, char* smem, float r0, float r1, int tid, bool dry) {
;     ...
;   for (int kt = 0; kt < nk; kt += 2) {
;     const bool l3 = kt + 3 < nk, s2 = kt + 2 < nk, l4 = kt + 4 < nk;
;     FLOAD(f0, 0, 0); FLOAD(f1, 0, 1);
;     FMMA(f0); SSTOREQ(ra1, rb1, 1, 0); if (l3) GLOADQ(ra1, rb1, kt + 3, 0);
;     FLOAD(f0, 0, 2);
;     FMMA(f1); SSTOREQ(ra1, rb1, 1, 1); if (l3) GLOADQ(ra1, rb1, kt + 3, 1);
;     FLOAD(f1, 0, 3);
;     FMMA(f0); SSTOREQ(ra1, rb1, 1, 2); if (l3) GLOADQ(ra1, rb1, kt + 3, 2);
;     FMMA(f1); SSTOREQ(ra1, rb1, 1, 3); if (l3) GLOADQ(ra1, rb1, kt + 3, 3);
;     __syncthreads();
;     FLOAD(f0, 1, 0); FLOAD(f1, 1, 1);
;     FMMA(f0); if (s2) SSTOREQ(ra0, rb0, 0, 0); if (l4) GLOADQ(ra0, rb0, kt + 4, 0);
;     FLOAD(f0, 1, 2);
;     FMMA(f1); if (s2) SSTOREQ(ra0, rb0, 0, 1); if (l4) GLOADQ(ra0, rb0, kt + 4, 1);
;     FLOAD(f1, 1, 3);
;     FMMA(f0); if (s2) SSTOREQ(ra0, rb0, 0, 2); if (l4) GLOADQ(ra0, rb0, kt + 4, 2);
;     FMMA(f1); if (s2) SSTOREQ(ra0, rb0, 0, 3); if (l4) GLOADQ(ra0, rb0, kt + 4, 3);
;     if (MIDK && kt == 6) {
; #pragma unroll
;       for (int a = 0; a < 2; ++a)
; #pragma unroll
;         for (int i = 0; i < 16; ++i) { acc[a][0][i] *= r0; acc[a][1][i] *= r1; }
;     }
;     __syncthreads();
	v_mfma_f32_32x32x16_bf16 v[0:15], v[120:123], v[116:119], v[0:15]
	ds_read_b128 v[116:119], v167 offset:55296
	ds_read_b128 v[120:123], v132 offset:36864
	ds_read_b128 v[162:165], v132 offset:41472
	s_waitcnt lgkmcnt(1)
	v_mfma_f32_32x32x16_bf16 v[48:63], v[116:119], v[120:123], v[48:63]
	s_waitcnt lgkmcnt(0)
	v_mfma_f32_32x32x16_bf16 v[32:47], v[116:119], v[162:165], v[32:47]
	ds_read_b128 v[116:119], v167 offset:59904
	s_waitcnt lgkmcnt(0)
	v_mfma_f32_32x32x16_bf16 v[16:31], v[116:119], v[120:123], v[16:31]
	v_mfma_f32_32x32x16_bf16 v[0:15], v[116:119], v[162:165], v[0:15]
	ds_read_b128 v[116:119], v167 offset:55328
	ds_read_b128 v[120:123], v132 offset:36896
	ds_read_b128 v[162:165], v132 offset:41504
	s_waitcnt lgkmcnt(1)
	v_mfma_f32_32x32x16_bf16 v[48:63], v[116:119], v[120:123], v[48:63]
	s_waitcnt lgkmcnt(0)
	v_mfma_f32_32x32x16_bf16 v[32:47], v[116:119], v[162:165], v[32:47]
	ds_read_b128 v[116:119], v167 offset:59936
	s_waitcnt vmcnt(15)
	ds_write_b128 v130, v[150:153]
	s_waitcnt vmcnt(14)
	ds_write_b128 v130, v[158:161] offset:18432
	s_waitcnt lgkmcnt(2)
	v_mfma_f32_32x32x16_bf16 v[16:31], v[116:119], v[120:123], v[16:31]
	v_mfma_f32_32x32x16_bf16 v[0:15], v[116:119], v[162:165], v[0:15]
	ds_read_b128 v[116:119], v167 offset:55360
	ds_read_b128 v[120:123], v132 offset:36928
	ds_read_b128 v[150:153], v132 offset:41536
	s_waitcnt lgkmcnt(1)
	v_mfma_f32_32x32x16_bf16 v[48:63], v[116:119], v[120:123], v[48:63]
	s_waitcnt lgkmcnt(0)
	v_mfma_f32_32x32x16_bf16 v[32:47], v[116:119], v[150:153], v[32:47]
	ds_read_b128 v[116:119], v167 offset:59968
	s_waitcnt vmcnt(13)
	ds_write_b128 v130, v[104:107] offset:4608
	s_waitcnt vmcnt(12)
	ds_write_b128 v130, v[108:111] offset:23040
	ds_read_b128 v[104:107], v167 offset:55392
	ds_read_b128 v[108:111], v132 offset:36960
	s_waitcnt lgkmcnt(4)
	v_mfma_f32_32x32x16_bf16 v[16:31], v[116:119], v[120:123], v[16:31]
	ds_read_b128 v[120:123], v167 offset:60000
	v_mfma_f32_32x32x16_bf16 v[0:15], v[116:119], v[150:153], v[0:15]
	ds_read_b128 v[116:119], v132 offset:41568
	s_waitcnt lgkmcnt(2)
	v_mfma_f32_32x32x16_bf16 v[48:63], v[104:107], v[108:111], v[48:63]
	s_waitcnt lgkmcnt(0)
	v_mfma_f32_32x32x16_bf16 v[32:47], v[104:107], v[116:119], v[32:47]
	v_mfma_f32_32x32x16_bf16 v[16:31], v[120:123], v[108:111], v[16:31]
	global_load_dwordx4 v[150:153], v[112:113], off offset:256
	global_load_dwordx4 v[158:161], v[114:115], off offset:256
	global_load_dwordx4 v[104:107], v[138:139], off offset:256
	global_load_dwordx4 v[108:111], v[140:141], off offset:256
	s_waitcnt vmcnt(15)
	ds_write_b128 v130, v[64:67] offset:9216
	s_waitcnt vmcnt(14)
	ds_write_b128 v130, v[68:71] offset:27648
	global_load_dwordx4 v[64:67], v[142:143], off offset:256
	global_load_dwordx4 v[68:71], v[144:145], off offset:256
	s_waitcnt vmcnt(15)
	ds_write_b128 v130, v[72:75] offset:13824
	s_waitcnt vmcnt(14)
	ds_write_b128 v130, v[76:79] offset:32256
	global_load_dwordx4 v[72:75], v[146:147], off offset:256
	global_load_dwordx4 v[76:79], v[148:149], off offset:256
	s_waitcnt lgkmcnt(0)
	s_barrier
	v_mfma_f32_32x32x16_bf16 v[0:15], v[120:123], v[116:119], v[0:15]
	ds_read_b128 v[116:119], v167 offset:18432
	ds_read_b128 v[120:123], v132
	ds_read_b128 v[162:165], v132 offset:4608
	s_waitcnt lgkmcnt(1)
	v_mfma_f32_32x32x16_bf16 v[48:63], v[116:119], v[120:123], v[48:63]
	s_waitcnt lgkmcnt(0)
	v_mfma_f32_32x32x16_bf16 v[32:47], v[116:119], v[162:165], v[32:47]
	ds_read_b128 v[116:119], v167 offset:23040
	s_waitcnt lgkmcnt(0)
	v_mfma_f32_32x32x16_bf16 v[16:31], v[116:119], v[120:123], v[16:31]
	v_mfma_f32_32x32x16_bf16 v[0:15], v[116:119], v[162:165], v[0:15]
	ds_read_b128 v[116:119], v167 offset:18464
	ds_read_b128 v[120:123], v132 offset:32
	ds_read_b128 v[162:165], v132 offset:4640
	s_waitcnt lgkmcnt(1)
	v_mfma_f32_32x32x16_bf16 v[48:63], v[116:119], v[120:123], v[48:63]
	s_waitcnt lgkmcnt(0)
	v_mfma_f32_32x32x16_bf16 v[32:47], v[116:119], v[162:165], v[32:47]
	ds_read_b128 v[116:119], v167 offset:23072
	s_waitcnt vmcnt(15)
	ds_write_b128 v130, v[124:127] offset:36864
	s_waitcnt vmcnt(14)
	ds_write_b128 v130, v[154:157] offset:55296
	s_waitcnt lgkmcnt(2)
	v_mfma_f32_32x32x16_bf16 v[16:31], v[116:119], v[120:123], v[16:31]
	v_mfma_f32_32x32x16_bf16 v[0:15], v[116:119], v[162:165], v[0:15]
	ds_read_b128 v[116:119], v167 offset:18496
	ds_read_b128 v[120:123], v132 offset:64
	ds_read_b128 v[124:127], v132 offset:4672
	s_waitcnt lgkmcnt(1)
	v_mfma_f32_32x32x16_bf16 v[48:63], v[116:119], v[120:123], v[48:63]
	s_waitcnt lgkmcnt(0)
	v_mfma_f32_32x32x16_bf16 v[32:47], v[116:119], v[124:127], v[32:47]
	ds_read_b128 v[116:119], v167 offset:23104
	s_waitcnt vmcnt(13)
	ds_write_b128 v130, v[96:99] offset:41472
	s_waitcnt vmcnt(12)
	ds_write_b128 v130, v[100:103] offset:59904
	ds_read_b128 v[96:99], v167 offset:18528
	ds_read_b128 v[100:103], v132 offset:96
	s_waitcnt lgkmcnt(4)
	v_mfma_f32_32x32x16_bf16 v[16:31], v[116:119], v[120:123], v[16:31]
	ds_read_b128 v[120:123], v167 offset:23136
	v_mfma_f32_32x32x16_bf16 v[0:15], v[116:119], v[124:127], v[0:15]
	ds_read_b128 v[116:119], v132 offset:4704
	s_waitcnt lgkmcnt(2)
	v_mfma_f32_32x32x16_bf16 v[48:63], v[96:99], v[100:103], v[48:63]
	s_waitcnt lgkmcnt(0)
	v_mfma_f32_32x32x16_bf16 v[32:47], v[96:99], v[116:119], v[32:47]
	v_mfma_f32_32x32x16_bf16 v[16:31], v[120:123], v[100:103], v[16:31]
	global_load_dwordx4 v[124:127], v[112:113], off offset:384
	global_load_dwordx4 v[154:157], v[114:115], off offset:384
	global_load_dwordx4 v[96:99], v[138:139], off offset:384
	global_load_dwordx4 v[100:103], v[140:141], off offset:384
	s_waitcnt vmcnt(15)
	ds_write_b128 v130, v[80:83] offset:46080
	s_waitcnt vmcnt(14)
	ds_write_b128 v130, v[84:87] offset:64512
	global_load_dwordx4 v[80:83], v[142:143], off offset:384
	global_load_dwordx4 v[84:87], v[144:145], off offset:384
	s_waitcnt vmcnt(15)
	ds_write_b128 v130, v[88:91] offset:50688
	s_waitcnt vmcnt(14)
	ds_write_b128 v131, v[92:95] offset:13824
	global_load_dwordx4 v[88:91], v[146:147], off offset:384
	global_load_dwordx4 v[92:95], v[148:149], off offset:384
	s_waitcnt lgkmcnt(0)
	s_barrier
; #define GLOADQ(RA, RB, KT, q) do { const int k0_ = (KT) << 6; \
;     RA[q] = ldg16(ap.ptr(m0 + lrow + 32 * (q), k0_) + lkc); RB[q] = ldg16(W + (size_t)(n0 + lrow + 32 * (q)) * ldw + k0_ + lkc); } while (0)
; #define SSTOREQ(RA, RB, ST, q) do { \
;     *(u32x4*)(sA + (ST) * SBUF + (lrow + 32 * (q)) * GP + lkc) = RA[q]; *(u32x4*)(sB + (ST) * SBUF + (lrow + 32 * (q)) * GP + lkc) = RB[q]; } while (0)
; #define FLOAD(F, ST, ks) do { _Pragma("unroll") for (int a = 0; a < 2; ++a) { \
;     F[a] = *(const bf16x8*)(sB + (ST) * SBUF + (wn * 64 + a * 32 + r) * GP + (ks) * 16 + h * 8); \
;     F[2 + a] = *(const bf16x8*)(sA + (ST) * SBUF + (wm * 64 + a * 32 + r) * GP + (ks) * 16 + h * 8); } } while (0)
; #define FMMA(F) do { _Pragma("unroll") for (int a = 0; a < 2; ++a) _Pragma("unroll") for (int b = 0; b < 2; ++b) acc[a][b] = MFMA(F[a], F[2 + b], acc[a][b]); } while (0)
; template <bool MIDK, class AP, class EPI>
; DI void gemm_tile(const AP& ap, const u16* __restrict__ W, int ldw, int K, int m0, int n0, const EPI& epi, char* smem, float r0, float r1, int tid, bool dry) {
;     ...
;   for (int kt = 0; kt < nk; kt += 2) {
;     const bool l3 = kt + 3 < nk, s2 = kt + 2 < nk, l4 = kt + 4 < nk;
;     FLOAD(f0, 0, 0); FLOAD(f1, 0, 1);
;     FMMA(f0); SSTOREQ(ra1, rb1, 1, 0); if (l3) GLOADQ(ra1, rb1, kt + 3, 0);
;     FLOAD(f0, 0, 2);
;     FMMA(f1); SSTOREQ(ra1, rb1, 1, 1); if (l3) GLOADQ(ra1, rb1, kt + 3, 1);
;     FLOAD(f1, 0, 3);
;     FMMA(f0); SSTOREQ(ra1, rb1, 1, 2); if (l3) GLOADQ(ra1, rb1, kt + 3, 2);
;     FMMA(f1); SSTOREQ(ra1, rb1, 1, 3); if (l3) GLOADQ(ra1, rb1, kt + 3, 3);
;     __syncthreads();
;     FLOAD(f0, 1, 0); FLOAD(f1, 1, 1);
;     FMMA(f0); if (s2) SSTOREQ(ra0, rb0, 0, 0); if (l4) GLOADQ(ra0, rb0, kt + 4, 0);
;     FLOAD(f0, 1, 2);
;     FMMA(f1); if (s2) SSTOREQ(ra0, rb0, 0, 1); if (l4) GLOADQ(ra0, rb0, kt + 4, 1);
;     FLOAD(f1, 1, 3);
;     FMMA(f0); if (s2) SSTOREQ(ra0, rb0, 0, 2); if (l4) GLOADQ(ra0, rb0, kt + 4, 2);
;     FMMA(f1); if (s2) SSTOREQ(ra0, rb0, 0, 3); if (l4) GLOADQ(ra0, rb0, kt + 4, 3);
;     if (MIDK && kt == 6) {
; #pragma unroll
;       for (int a = 0; a < 2; ++a)
; #pragma unroll
;         for (int i = 0; i < 16; ++i) { acc[a][0][i] *= r0; acc[a][1][i] *= r1; }
;     }
;     __syncthreads();
	v_mfma_f32_32x32x16_bf16 v[0:15], v[120:123], v[116:119], v[0:15]
	ds_read_b128 v[116:119], v167 offset:55296
	ds_read_b128 v[120:123], v132 offset:36864
	ds_read_b128 v[162:165], v132 offset:41472
	s_waitcnt lgkmcnt(1)
	v_mfma_f32_32x32x16_bf16 v[48:63], v[116:119], v[120:123], v[48:63]
	s_waitcnt lgkmcnt(0)
	v_mfma_f32_32x32x16_bf16 v[32:47], v[116:119], v[162:165], v[32:47]
	ds_read_b128 v[116:119], v167 offset:59904
	s_waitcnt lgkmcnt(0)
	v_mfma_f32_32x32x16_bf16 v[16:31], v[116:119], v[120:123], v[16:31]
	v_mfma_f32_32x32x16_bf16 v[0:15], v[116:119], v[162:165], v[0:15]
	ds_read_b128 v[116:119], v167 offset:55328
	ds_read_b128 v[120:123], v132 offset:36896
	ds_read_b128 v[162:165], v132 offset:41504
	s_waitcnt lgkmcnt(1)
	v_mfma_f32_32x32x16_bf16 v[48:63], v[116:119], v[120:123], v[48:63]
	s_waitcnt lgkmcnt(0)
	v_mfma_f32_32x32x16_bf16 v[32:47], v[116:119], v[162:165], v[32:47]
	ds_read_b128 v[116:119], v167 offset:59936
	s_waitcnt vmcnt(15)
	ds_write_b128 v130, v[150:153]
	s_waitcnt vmcnt(14)
	ds_write_b128 v130, v[158:161] offset:18432
	s_waitcnt lgkmcnt(2)
	v_mfma_f32_32x32x16_bf16 v[16:31], v[116:119], v[120:123], v[16:31]
	v_mfma_f32_32x32x16_bf16 v[0:15], v[116:119], v[162:165], v[0:15]
	ds_read_b128 v[116:119], v167 offset:55360
	ds_read_b128 v[120:123], v132 offset:36928
	ds_read_b128 v[150:153], v132 offset:41536
	s_waitcnt lgkmcnt(1)
	v_mfma_f32_32x32x16_bf16 v[48:63], v[116:119], v[120:123], v[48:63]
	s_waitcnt lgkmcnt(0)
	v_mfma_f32_32x32x16_bf16 v[32:47], v[116:119], v[150:153], v[32:47]
	ds_read_b128 v[116:119], v167 offset:59968
	s_waitcnt vmcnt(13)
	ds_write_b128 v130, v[104:107] offset:4608
	s_waitcnt vmcnt(12)
	ds_write_b128 v130, v[108:111] offset:23040
	ds_read_b128 v[104:107], v167 offset:55392
	ds_read_b128 v[108:111], v132 offset:36960
	s_waitcnt lgkmcnt(4)
	v_mfma_f32_32x32x16_bf16 v[16:31], v[116:119], v[120:123], v[16:31]
	ds_read_b128 v[120:123], v167 offset:60000
	v_mfma_f32_32x32x16_bf16 v[0:15], v[116:119], v[150:153], v[0:15]
	ds_read_b128 v[116:119], v132 offset:41568
	s_waitcnt lgkmcnt(2)
	v_mfma_f32_32x32x16_bf16 v[48:63], v[104:107], v[108:111], v[48:63]
	s_waitcnt lgkmcnt(0)
	v_mfma_f32_32x32x16_bf16 v[32:47], v[104:107], v[116:119], v[32:47]
	v_mfma_f32_32x32x16_bf16 v[16:31], v[120:123], v[108:111], v[16:31]
	global_load_dwordx4 v[150:153], v[112:113], off offset:512
	global_load_dwordx4 v[158:161], v[114:115], off offset:512
	global_load_dwordx4 v[104:107], v[138:139], off offset:512
	global_load_dwordx4 v[108:111], v[140:141], off offset:512
	s_waitcnt vmcnt(15)
	ds_write_b128 v130, v[64:67] offset:9216
	s_waitcnt vmcnt(14)
	ds_write_b128 v130, v[68:71] offset:27648
	global_load_dwordx4 v[64:67], v[142:143], off offset:512
	global_load_dwordx4 v[68:71], v[144:145], off offset:512
	s_waitcnt vmcnt(15)
	ds_write_b128 v130, v[72:75] offset:13824
	s_waitcnt vmcnt(14)
	ds_write_b128 v130, v[76:79] offset:32256
	global_load_dwordx4 v[72:75], v[146:147], off offset:512
	global_load_dwordx4 v[76:79], v[148:149], off offset:512
	s_waitcnt lgkmcnt(0)
	s_barrier
	v_mfma_f32_32x32x16_bf16 v[0:15], v[120:123], v[116:119], v[0:15]
	ds_read_b128 v[116:119], v167 offset:18432
	ds_read_b128 v[120:123], v132
	ds_read_b128 v[162:165], v132 offset:4608
	s_waitcnt lgkmcnt(1)
	v_mfma_f32_32x32x16_bf16 v[48:63], v[116:119], v[120:123], v[48:63]
	s_waitcnt lgkmcnt(0)
	v_mfma_f32_32x32x16_bf16 v[32:47], v[116:119], v[162:165], v[32:47]
	ds_read_b128 v[116:119], v167 offset:23040
	s_waitcnt lgkmcnt(0)
	v_mfma_f32_32x32x16_bf16 v[16:31], v[116:119], v[120:123], v[16:31]
	v_mfma_f32_32x32x16_bf16 v[0:15], v[116:119], v[162:165], v[0:15]
	ds_read_b128 v[116:119], v167 offset:18464
	ds_read_b128 v[120:123], v132 offset:32
	ds_read_b128 v[162:165], v132 offset:4640
	s_waitcnt lgkmcnt(1)
	v_mfma_f32_32x32x16_bf16 v[48:63], v[116:119], v[120:123], v[48:63]
	s_waitcnt lgkmcnt(0)
	v_mfma_f32_32x32x16_bf16 v[32:47], v[116:119], v[162:165], v[32:47]
	ds_read_b128 v[116:119], v167 offset:23072
	s_waitcnt vmcnt(15)
	ds_write_b128 v130, v[124:127] offset:36864
	s_waitcnt vmcnt(14)
	ds_write_b128 v130, v[154:157] offset:55296
	s_waitcnt lgkmcnt(2)
	v_mfma_f32_32x32x16_bf16 v[16:31], v[116:119], v[120:123], v[16:31]
	v_mfma_f32_32x32x16_bf16 v[0:15], v[116:119], v[162:165], v[0:15]
	ds_read_b128 v[116:119], v167 offset:18496
	ds_read_b128 v[120:123], v132 offset:64
	ds_read_b128 v[124:127], v132 offset:4672
	s_waitcnt lgkmcnt(1)
	v_mfma_f32_32x32x16_bf16 v[48:63], v[116:119], v[120:123], v[48:63]
	s_waitcnt lgkmcnt(0)
	v_mfma_f32_32x32x16_bf16 v[32:47], v[116:119], v[124:127], v[32:47]
	ds_read_b128 v[116:119], v167 offset:23104
	s_waitcnt vmcnt(13)
	ds_write_b128 v130, v[96:99] offset:41472
	s_waitcnt vmcnt(12)
	ds_write_b128 v130, v[100:103] offset:59904
	ds_read_b128 v[96:99], v167 offset:18528
	ds_read_b128 v[100:103], v132 offset:96
	s_waitcnt lgkmcnt(4)
	v_mfma_f32_32x32x16_bf16 v[16:31], v[116:119], v[120:123], v[16:31]
	ds_read_b128 v[120:123], v167 offset:23136
	v_mfma_f32_32x32x16_bf16 v[0:15], v[116:119], v[124:127], v[0:15]
	ds_read_b128 v[116:119], v132 offset:4704
	s_waitcnt lgkmcnt(2)
	v_mfma_f32_32x32x16_bf16 v[48:63], v[96:99], v[100:103], v[48:63]
	s_waitcnt lgkmcnt(0)
	v_mfma_f32_32x32x16_bf16 v[32:47], v[96:99], v[116:119], v[32:47]
	v_mfma_f32_32x32x16_bf16 v[16:31], v[120:123], v[100:103], v[16:31]
	global_load_dwordx4 v[124:127], v[112:113], off offset:640
	global_load_dwordx4 v[154:157], v[114:115], off offset:640
	global_load_dwordx4 v[96:99], v[138:139], off offset:640
	global_load_dwordx4 v[100:103], v[140:141], off offset:640
	s_waitcnt vmcnt(15)
	ds_write_b128 v130, v[80:83] offset:46080
	s_waitcnt vmcnt(14)
	ds_write_b128 v130, v[84:87] offset:64512
	global_load_dwordx4 v[80:83], v[142:143], off offset:640
	global_load_dwordx4 v[84:87], v[144:145], off offset:640
	s_waitcnt vmcnt(15)
	ds_write_b128 v130, v[88:91] offset:50688
	s_waitcnt vmcnt(14)
	ds_write_b128 v131, v[92:95] offset:13824
	global_load_dwordx4 v[88:91], v[146:147], off offset:640
	global_load_dwordx4 v[92:95], v[148:149], off offset:640
	s_waitcnt lgkmcnt(0)
	s_barrier
; #define GLOADQ(RA, RB, KT, q) do { const int k0_ = (KT) << 6; \
;     RA[q] = ldg16(ap.ptr(m0 + lrow + 32 * (q), k0_) + lkc); RB[q] = ldg16(W + (size_t)(n0 + lrow + 32 * (q)) * ldw + k0_ + lkc); } while (0)
; #define SSTOREQ(RA, RB, ST, q) do { \
;     *(u32x4*)(sA + (ST) * SBUF + (lrow + 32 * (q)) * GP + lkc) = RA[q]; *(u32x4*)(sB + (ST) * SBUF + (lrow + 32 * (q)) * GP + lkc) = RB[q]; } while (0)
; #define FLOAD(F, ST, ks) do { _Pragma("unroll") for (int a = 0; a < 2; ++a) { \
;     F[a] = *(const bf16x8*)(sB + (ST) * SBUF + (wn * 64 + a * 32 + r) * GP + (ks) * 16 + h * 8); \
;     F[2 + a] = *(const bf16x8*)(sA + (ST) * SBUF + (wm * 64 + a * 32 + r) * GP + (ks) * 16 + h * 8); } } while (0)
; #define FMMA(F) do { _Pragma("unroll") for (int a = 0; a < 2; ++a) _Pragma("unroll") for (int b = 0; b < 2; ++b) acc[a][b] = MFMA(F[a], F[2 + b], acc[a][b]); } while (0)
; template <bool MIDK, class AP, class EPI>
; DI void gemm_tile(const AP& ap, const u16* __restrict__ W, int ldw, int K, int m0, int n0, const EPI& epi, char* smem, float r0, float r1, int tid, bool dry) {
;     ...
;   for (int kt = 0; kt < nk; kt += 2) {
;     const bool l3 = kt + 3 < nk, s2 = kt + 2 < nk, l4 = kt + 4 < nk;
;     FLOAD(f0, 0, 0); FLOAD(f1, 0, 1);
;     FMMA(f0); SSTOREQ(ra1, rb1, 1, 0); if (l3) GLOADQ(ra1, rb1, kt + 3, 0);
;     FLOAD(f0, 0, 2);
;     FMMA(f1); SSTOREQ(ra1, rb1, 1, 1); if (l3) GLOADQ(ra1, rb1, kt + 3, 1);
;     FLOAD(f1, 0, 3);
;     FMMA(f0); SSTOREQ(ra1, rb1, 1, 2); if (l3) GLOADQ(ra1, rb1, kt + 3, 2);
;     FMMA(f1); SSTOREQ(ra1, rb1, 1, 3); if (l3) GLOADQ(ra1, rb1, kt + 3, 3);
;     __syncthreads();
;     FLOAD(f0, 1, 0); FLOAD(f1, 1, 1);
;     FMMA(f0); if (s2) SSTOREQ(ra0, rb0, 0, 0); if (l4) GLOADQ(ra0, rb0, kt + 4, 0);
;     FLOAD(f0, 1, 2);
;     FMMA(f1); if (s2) SSTOREQ(ra0, rb0, 0, 1); if (l4) GLOADQ(ra0, rb0, kt + 4, 1);
;     FLOAD(f1, 1, 3);
;     FMMA(f0); if (s2) SSTOREQ(ra0, rb0, 0, 2); if (l4) GLOADQ(ra0, rb0, kt + 4, 2);
;     FMMA(f1); if (s2) SSTOREQ(ra0, rb0, 0, 3); if (l4) GLOADQ(ra0, rb0, kt + 4, 3);
;     if (MIDK && kt == 6) {
; #pragma unroll
;       for (int a = 0; a < 2; ++a)
; #pragma unroll
;         for (int i = 0; i < 16; ++i) { acc[a][0][i] *= r0; acc[a][1][i] *= r1; }
;     }
;     __syncthreads();
	v_mfma_f32_32x32x16_bf16 v[0:15], v[120:123], v[116:119], v[0:15]
	ds_read_b128 v[116:119], v167 offset:55296
	ds_read_b128 v[120:123], v132 offset:36864
	ds_read_b128 v[162:165], v132 offset:41472
	s_waitcnt lgkmcnt(1)
	v_mfma_f32_32x32x16_bf16 v[48:63], v[116:119], v[120:123], v[48:63]
	s_waitcnt lgkmcnt(0)
	v_mfma_f32_32x32x16_bf16 v[32:47], v[116:119], v[162:165], v[32:47]
	ds_read_b128 v[116:119], v167 offset:59904
	s_waitcnt lgkmcnt(0)
	v_mfma_f32_32x32x16_bf16 v[16:31], v[116:119], v[120:123], v[16:31]
	v_mfma_f32_32x32x16_bf16 v[0:15], v[116:119], v[162:165], v[0:15]
	ds_read_b128 v[116:119], v167 offset:55328
	ds_read_b128 v[120:123], v132 offset:36896
	ds_read_b128 v[162:165], v132 offset:41504
	s_waitcnt lgkmcnt(1)
	v_mfma_f32_32x32x16_bf16 v[48:63], v[116:119], v[120:123], v[48:63]
	s_waitcnt lgkmcnt(0)
	v_mfma_f32_32x32x16_bf16 v[32:47], v[116:119], v[162:165], v[32:47]
	ds_read_b128 v[116:119], v167 offset:59936
	s_waitcnt vmcnt(15)
	ds_write_b128 v130, v[150:153]
	s_waitcnt vmcnt(14)
	ds_write_b128 v130, v[158:161] offset:18432
	s_waitcnt lgkmcnt(2)
	v_mfma_f32_32x32x16_bf16 v[16:31], v[116:119], v[120:123], v[16:31]
	v_mfma_f32_32x32x16_bf16 v[0:15], v[116:119], v[162:165], v[0:15]
	ds_read_b128 v[116:119], v167 offset:55360
	ds_read_b128 v[120:123], v132 offset:36928
	ds_read_b128 v[150:153], v132 offset:41536
	s_waitcnt lgkmcnt(1)
	v_mfma_f32_32x32x16_bf16 v[48:63], v[116:119], v[120:123], v[48:63]
	s_waitcnt lgkmcnt(0)
	v_mfma_f32_32x32x16_bf16 v[32:47], v[116:119], v[150:153], v[32:47]
	ds_read_b128 v[116:119], v167 offset:59968
	s_waitcnt vmcnt(13)
	ds_write_b128 v130, v[104:107] offset:4608
	s_waitcnt vmcnt(12)
	ds_write_b128 v130, v[108:111] offset:23040
	ds_read_b128 v[104:107], v167 offset:55392
	ds_read_b128 v[108:111], v132 offset:36960
	s_waitcnt lgkmcnt(4)
	v_mfma_f32_32x32x16_bf16 v[16:31], v[116:119], v[120:123], v[16:31]
	ds_read_b128 v[120:123], v167 offset:60000
	v_mfma_f32_32x32x16_bf16 v[0:15], v[116:119], v[150:153], v[0:15]
	ds_read_b128 v[116:119], v132 offset:41568
	s_waitcnt lgkmcnt(2)
	v_mfma_f32_32x32x16_bf16 v[48:63], v[104:107], v[108:111], v[48:63]
	s_waitcnt lgkmcnt(0)
	v_mfma_f32_32x32x16_bf16 v[32:47], v[104:107], v[116:119], v[32:47]
	v_mfma_f32_32x32x16_bf16 v[16:31], v[120:123], v[108:111], v[16:31]
	global_load_dwordx4 v[150:153], v[112:113], off offset:768
	global_load_dwordx4 v[158:161], v[114:115], off offset:768
	global_load_dwordx4 v[104:107], v[138:139], off offset:768
	global_load_dwordx4 v[108:111], v[140:141], off offset:768
	s_waitcnt vmcnt(15)
	ds_write_b128 v130, v[64:67] offset:9216
	s_waitcnt vmcnt(14)
	ds_write_b128 v130, v[68:71] offset:27648
	global_load_dwordx4 v[64:67], v[142:143], off offset:768
	global_load_dwordx4 v[68:71], v[144:145], off offset:768
	s_waitcnt vmcnt(15)
	ds_write_b128 v130, v[72:75] offset:13824
	s_waitcnt vmcnt(14)
	ds_write_b128 v130, v[76:79] offset:32256
	global_load_dwordx4 v[72:75], v[146:147], off offset:768
	global_load_dwordx4 v[76:79], v[148:149], off offset:768
	s_waitcnt lgkmcnt(0)
	s_barrier
	v_mfma_f32_32x32x16_bf16 v[0:15], v[120:123], v[116:119], v[0:15]
	ds_read_b128 v[116:119], v167 offset:18432
	ds_read_b128 v[120:123], v132
	ds_read_b128 v[162:165], v132 offset:4608
	s_waitcnt lgkmcnt(1)
	v_mfma_f32_32x32x16_bf16 v[48:63], v[116:119], v[120:123], v[48:63]
	s_waitcnt lgkmcnt(0)
	v_mfma_f32_32x32x16_bf16 v[32:47], v[116:119], v[162:165], v[32:47]
	ds_read_b128 v[116:119], v167 offset:23040
	s_waitcnt lgkmcnt(0)
	v_mfma_f32_32x32x16_bf16 v[16:31], v[116:119], v[120:123], v[16:31]
	v_mfma_f32_32x32x16_bf16 v[0:15], v[116:119], v[162:165], v[0:15]
	ds_read_b128 v[116:119], v167 offset:18464
	ds_read_b128 v[120:123], v132 offset:32
	ds_read_b128 v[162:165], v132 offset:4640
	s_waitcnt lgkmcnt(1)
	v_mfma_f32_32x32x16_bf16 v[48:63], v[116:119], v[120:123], v[48:63]
	s_waitcnt lgkmcnt(0)
	v_mfma_f32_32x32x16_bf16 v[32:47], v[116:119], v[162:165], v[32:47]
	ds_read_b128 v[116:119], v167 offset:23072
	s_waitcnt vmcnt(15)
	ds_write_b128 v130, v[124:127] offset:36864
	s_waitcnt vmcnt(14)
	ds_write_b128 v130, v[154:157] offset:55296
	s_waitcnt lgkmcnt(2)
	v_mfma_f32_32x32x16_bf16 v[16:31], v[116:119], v[120:123], v[16:31]
	v_mfma_f32_32x32x16_bf16 v[0:15], v[116:119], v[162:165], v[0:15]
	ds_read_b128 v[116:119], v167 offset:18496
	ds_read_b128 v[120:123], v132 offset:64
	ds_read_b128 v[124:127], v132 offset:4672
	s_waitcnt lgkmcnt(1)
	v_mfma_f32_32x32x16_bf16 v[48:63], v[116:119], v[120:123], v[48:63]
	s_waitcnt lgkmcnt(0)
	v_mfma_f32_32x32x16_bf16 v[32:47], v[116:119], v[124:127], v[32:47]
	ds_read_b128 v[116:119], v167 offset:23104
	s_waitcnt vmcnt(13)
	ds_write_b128 v130, v[96:99] offset:41472
	s_waitcnt vmcnt(12)
	ds_write_b128 v130, v[100:103] offset:59904
	ds_read_b128 v[96:99], v167 offset:18528
	ds_read_b128 v[100:103], v132 offset:96
	s_waitcnt lgkmcnt(4)
	v_mfma_f32_32x32x16_bf16 v[16:31], v[116:119], v[120:123], v[16:31]
	ds_read_b128 v[120:123], v167 offset:23136
	v_mfma_f32_32x32x16_bf16 v[0:15], v[116:119], v[124:127], v[0:15]
	ds_read_b128 v[116:119], v132 offset:4704
	s_waitcnt lgkmcnt(2)
	v_mfma_f32_32x32x16_bf16 v[48:63], v[96:99], v[100:103], v[48:63]
	s_waitcnt lgkmcnt(0)
	v_mfma_f32_32x32x16_bf16 v[32:47], v[96:99], v[116:119], v[32:47]
	v_mfma_f32_32x32x16_bf16 v[16:31], v[120:123], v[100:103], v[16:31]
	global_load_dwordx4 v[124:127], v[112:113], off offset:896
	global_load_dwordx4 v[154:157], v[114:115], off offset:896
	global_load_dwordx4 v[96:99], v[138:139], off offset:896
	global_load_dwordx4 v[100:103], v[140:141], off offset:896
	s_waitcnt vmcnt(15)
	ds_write_b128 v130, v[80:83] offset:46080
	s_waitcnt vmcnt(14)
	ds_write_b128 v130, v[84:87] offset:64512
	global_load_dwordx4 v[80:83], v[142:143], off offset:896
	global_load_dwordx4 v[84:87], v[144:145], off offset:896
	s_waitcnt vmcnt(15)
	ds_write_b128 v130, v[88:91] offset:50688
	s_waitcnt vmcnt(14)
	ds_write_b128 v131, v[92:95] offset:13824
	global_load_dwordx4 v[88:91], v[146:147], off offset:896
	global_load_dwordx4 v[92:95], v[148:149], off offset:896
	s_waitcnt lgkmcnt(0)
	s_barrier
; #define GLOADQ(RA, RB, KT, q) do { const int k0_ = (KT) << 6; \
;     RA[q] = ldg16(ap.ptr(m0 + lrow + 32 * (q), k0_) + lkc); RB[q] = ldg16(W + (size_t)(n0 + lrow + 32 * (q)) * ldw + k0_ + lkc); } while (0)
; #define SSTOREQ(RA, RB, ST, q) do { \
;     *(u32x4*)(sA + (ST) * SBUF + (lrow + 32 * (q)) * GP + lkc) = RA[q]; *(u32x4*)(sB + (ST) * SBUF + (lrow + 32 * (q)) * GP + lkc) = RB[q]; } while (0)
; #define FLOAD(F, ST, ks) do { _Pragma("unroll") for (int a = 0; a < 2; ++a) { \
;     F[a] = *(const bf16x8*)(sB + (ST) * SBUF + (wn * 64 + a * 32 + r) * GP + (ks) * 16 + h * 8); \
;     F[2 + a] = *(const bf16x8*)(sA + (ST) * SBUF + (wm * 64 + a * 32 + r) * GP + (ks) * 16 + h * 8); } } while (0)
; #define FMMA(F) do { _Pragma("unroll") for (int a = 0; a < 2; ++a) _Pragma("unroll") for (int b = 0; b < 2; ++b) acc[a][b] = MFMA(F[a], F[2 + b], acc[a][b]); } while (0)
; template <bool MIDK, class AP, class EPI>
; DI void gemm_tile(const AP& ap, const u16* __restrict__ W, int ldw, int K, int m0, int n0, const EPI& epi, char* smem, float r0, float r1, int tid, bool dry) {
;     ...
;   for (int kt = 0; kt < nk; kt += 2) {
;     const bool l3 = kt + 3 < nk, s2 = kt + 2 < nk, l4 = kt + 4 < nk;
;     FLOAD(f0, 0, 0); FLOAD(f1, 0, 1);
;     FMMA(f0); SSTOREQ(ra1, rb1, 1, 0); if (l3) GLOADQ(ra1, rb1, kt + 3, 0);
;     FLOAD(f0, 0, 2);
;     FMMA(f1); SSTOREQ(ra1, rb1, 1, 1); if (l3) GLOADQ(ra1, rb1, kt + 3, 1);
;     FLOAD(f1, 0, 3);
;     FMMA(f0); SSTOREQ(ra1, rb1, 1, 2); if (l3) GLOADQ(ra1, rb1, kt + 3, 2);
;     FMMA(f1); SSTOREQ(ra1, rb1, 1, 3); if (l3) GLOADQ(ra1, rb1, kt + 3, 3);
;     __syncthreads();
;     FLOAD(f0, 1, 0); FLOAD(f1, 1, 1);
;     FMMA(f0); if (s2) SSTOREQ(ra0, rb0, 0, 0); if (l4) GLOADQ(ra0, rb0, kt + 4, 0);
;     FLOAD(f0, 1, 2);
;     FMMA(f1); if (s2) SSTOREQ(ra0, rb0, 0, 1); if (l4) GLOADQ(ra0, rb0, kt + 4, 1);
;     FLOAD(f1, 1, 3);
;     FMMA(f0); if (s2) SSTOREQ(ra0, rb0, 0, 2); if (l4) GLOADQ(ra0, rb0, kt + 4, 2);
;     FMMA(f1); if (s2) SSTOREQ(ra0, rb0, 0, 3); if (l4) GLOADQ(ra0, rb0, kt + 4, 3);
;     if (MIDK && kt == 6) {
; #pragma unroll
;       for (int a = 0; a < 2; ++a)
; #pragma unroll
;         for (int i = 0; i < 16; ++i) { acc[a][0][i] *= r0; acc[a][1][i] *= r1; }
;     }
;     __syncthreads();
	v_mfma_f32_32x32x16_bf16 v[0:15], v[120:123], v[116:119], v[0:15]
	ds_read_b128 v[116:119], v167 offset:55296
	ds_read_b128 v[120:123], v132 offset:36864
	ds_read_b128 v[162:165], v132 offset:41472
	s_waitcnt lgkmcnt(1)
	v_mfma_f32_32x32x16_bf16 v[48:63], v[116:119], v[120:123], v[48:63]
	s_waitcnt lgkmcnt(0)
	v_mfma_f32_32x32x16_bf16 v[32:47], v[116:119], v[162:165], v[32:47]
	ds_read_b128 v[116:119], v167 offset:59904
	s_waitcnt lgkmcnt(0)
	v_mfma_f32_32x32x16_bf16 v[16:31], v[116:119], v[120:123], v[16:31]
	v_mfma_f32_32x32x16_bf16 v[0:15], v[116:119], v[162:165], v[0:15]
	ds_read_b128 v[116:119], v167 offset:55328
	ds_read_b128 v[120:123], v132 offset:36896
	ds_read_b128 v[162:165], v132 offset:41504
	s_waitcnt lgkmcnt(1)
	v_mfma_f32_32x32x16_bf16 v[48:63], v[116:119], v[120:123], v[48:63]
	s_waitcnt lgkmcnt(0)
	v_mfma_f32_32x32x16_bf16 v[32:47], v[116:119], v[162:165], v[32:47]
	ds_read_b128 v[116:119], v167 offset:59936
	s_waitcnt vmcnt(15)
	ds_write_b128 v130, v[150:153]
	s_waitcnt vmcnt(14)
	ds_write_b128 v130, v[158:161] offset:18432
	s_waitcnt lgkmcnt(2)
	v_mfma_f32_32x32x16_bf16 v[16:31], v[116:119], v[120:123], v[16:31]
	v_mfma_f32_32x32x16_bf16 v[0:15], v[116:119], v[162:165], v[0:15]
	ds_read_b128 v[116:119], v167 offset:55360
	ds_read_b128 v[120:123], v132 offset:36928
	ds_read_b128 v[150:153], v132 offset:41536
	s_waitcnt lgkmcnt(1)
	v_mfma_f32_32x32x16_bf16 v[48:63], v[116:119], v[120:123], v[48:63]
	s_waitcnt lgkmcnt(0)
	v_mfma_f32_32x32x16_bf16 v[32:47], v[116:119], v[150:153], v[32:47]
	ds_read_b128 v[116:119], v167 offset:59968
	s_waitcnt vmcnt(13)
	ds_write_b128 v130, v[104:107] offset:4608
	s_waitcnt vmcnt(12)
	ds_write_b128 v130, v[108:111] offset:23040
	ds_read_b128 v[104:107], v167 offset:55392
	ds_read_b128 v[108:111], v132 offset:36960
	s_waitcnt lgkmcnt(4)
	v_mfma_f32_32x32x16_bf16 v[16:31], v[116:119], v[120:123], v[16:31]
	ds_read_b128 v[120:123], v167 offset:60000
	v_mfma_f32_32x32x16_bf16 v[0:15], v[116:119], v[150:153], v[0:15]
	ds_read_b128 v[116:119], v132 offset:41568
	s_waitcnt lgkmcnt(2)
	v_mfma_f32_32x32x16_bf16 v[48:63], v[104:107], v[108:111], v[48:63]
	s_waitcnt lgkmcnt(0)
	v_mfma_f32_32x32x16_bf16 v[32:47], v[104:107], v[116:119], v[32:47]
	v_mfma_f32_32x32x16_bf16 v[16:31], v[120:123], v[108:111], v[16:31]
	global_load_dwordx4 v[150:153], v[112:113], off offset:1024
	global_load_dwordx4 v[158:161], v[114:115], off offset:1024
	global_load_dwordx4 v[104:107], v[138:139], off offset:1024
	global_load_dwordx4 v[108:111], v[140:141], off offset:1024
	s_waitcnt vmcnt(15)
	ds_write_b128 v130, v[64:67] offset:9216
	s_waitcnt vmcnt(14)
	ds_write_b128 v130, v[68:71] offset:27648
	global_load_dwordx4 v[64:67], v[142:143], off offset:1024
	global_load_dwordx4 v[68:71], v[144:145], off offset:1024
	s_waitcnt vmcnt(15)
	ds_write_b128 v130, v[72:75] offset:13824
	s_waitcnt vmcnt(14)
	ds_write_b128 v130, v[76:79] offset:32256
	global_load_dwordx4 v[72:75], v[146:147], off offset:1024
	global_load_dwordx4 v[76:79], v[148:149], off offset:1024
	s_waitcnt lgkmcnt(0)
	s_barrier
	v_mfma_f32_32x32x16_bf16 v[0:15], v[120:123], v[116:119], v[0:15]
	ds_read_b128 v[116:119], v167 offset:18432
	ds_read_b128 v[120:123], v132
	ds_read_b128 v[162:165], v132 offset:4608
	s_waitcnt lgkmcnt(1)
	v_mfma_f32_32x32x16_bf16 v[48:63], v[116:119], v[120:123], v[48:63]
	s_waitcnt lgkmcnt(0)
	v_mfma_f32_32x32x16_bf16 v[32:47], v[116:119], v[162:165], v[32:47]
	ds_read_b128 v[116:119], v167 offset:23040
	s_waitcnt lgkmcnt(0)
	v_mfma_f32_32x32x16_bf16 v[16:31], v[116:119], v[120:123], v[16:31]
	v_mfma_f32_32x32x16_bf16 v[0:15], v[116:119], v[162:165], v[0:15]
	ds_read_b128 v[116:119], v167 offset:18464
	ds_read_b128 v[120:123], v132 offset:32
	ds_read_b128 v[162:165], v132 offset:4640
	s_waitcnt lgkmcnt(1)
	v_mfma_f32_32x32x16_bf16 v[48:63], v[116:119], v[120:123], v[48:63]
	s_waitcnt lgkmcnt(0)
	v_mfma_f32_32x32x16_bf16 v[32:47], v[116:119], v[162:165], v[32:47]
	ds_read_b128 v[116:119], v167 offset:23072
	s_waitcnt vmcnt(15)
	ds_write_b128 v130, v[124:127] offset:36864
	s_waitcnt vmcnt(14)
	ds_write_b128 v130, v[154:157] offset:55296
	s_waitcnt lgkmcnt(2)
	v_mfma_f32_32x32x16_bf16 v[16:31], v[116:119], v[120:123], v[16:31]
	v_mfma_f32_32x32x16_bf16 v[0:15], v[116:119], v[162:165], v[0:15]
	ds_read_b128 v[116:119], v167 offset:18496
	ds_read_b128 v[120:123], v132 offset:64
	ds_read_b128 v[124:127], v132 offset:4672
	s_waitcnt lgkmcnt(1)
	v_mfma_f32_32x32x16_bf16 v[48:63], v[116:119], v[120:123], v[48:63]
	s_waitcnt lgkmcnt(0)
	v_mfma_f32_32x32x16_bf16 v[32:47], v[116:119], v[124:127], v[32:47]
	ds_read_b128 v[116:119], v167 offset:23104
	s_waitcnt vmcnt(13)
	ds_write_b128 v130, v[96:99] offset:41472
	s_waitcnt vmcnt(12)
	ds_write_b128 v130, v[100:103] offset:59904
	ds_read_b128 v[96:99], v167 offset:18528
	ds_read_b128 v[100:103], v132 offset:96
	s_waitcnt lgkmcnt(4)
	v_mfma_f32_32x32x16_bf16 v[16:31], v[116:119], v[120:123], v[16:31]
	ds_read_b128 v[120:123], v167 offset:23136
	v_mfma_f32_32x32x16_bf16 v[0:15], v[116:119], v[124:127], v[0:15]
	ds_read_b128 v[116:119], v132 offset:4704
	s_waitcnt lgkmcnt(2)
	v_mfma_f32_32x32x16_bf16 v[48:63], v[96:99], v[100:103], v[48:63]
	s_waitcnt lgkmcnt(0)
	v_mfma_f32_32x32x16_bf16 v[32:47], v[96:99], v[116:119], v[32:47]
	v_mfma_f32_32x32x16_bf16 v[16:31], v[120:123], v[100:103], v[16:31]
	global_load_dwordx4 v[124:127], v[112:113], off offset:1152
	global_load_dwordx4 v[154:157], v[114:115], off offset:1152
	global_load_dwordx4 v[96:99], v[138:139], off offset:1152
	global_load_dwordx4 v[100:103], v[140:141], off offset:1152
	s_waitcnt vmcnt(15)
	ds_write_b128 v130, v[80:83] offset:46080
	s_waitcnt vmcnt(14)
	ds_write_b128 v130, v[84:87] offset:64512
	global_load_dwordx4 v[80:83], v[142:143], off offset:1152
	global_load_dwordx4 v[84:87], v[144:145], off offset:1152
	s_waitcnt vmcnt(15)
	ds_write_b128 v130, v[88:91] offset:50688
	s_waitcnt vmcnt(14)
	ds_write_b128 v131, v[92:95] offset:13824
	global_load_dwordx4 v[88:91], v[146:147], off offset:1152
	global_load_dwordx4 v[92:95], v[148:149], off offset:1152
	s_waitcnt lgkmcnt(0)
	s_barrier
; #define GLOADQ(RA, RB, KT, q) do { const int k0_ = (KT) << 6; \
;     RA[q] = ldg16(ap.ptr(m0 + lrow + 32 * (q), k0_) + lkc); RB[q] = ldg16(W + (size_t)(n0 + lrow + 32 * (q)) * ldw + k0_ + lkc); } while (0)
; #define SSTOREQ(RA, RB, ST, q) do { \
;     *(u32x4*)(sA + (ST) * SBUF + (lrow + 32 * (q)) * GP + lkc) = RA[q]; *(u32x4*)(sB + (ST) * SBUF + (lrow + 32 * (q)) * GP + lkc) = RB[q]; } while (0)
; #define FLOAD(F, ST, ks) do { _Pragma("unroll") for (int a = 0; a < 2; ++a) { \
;     F[a] = *(const bf16x8*)(sB + (ST) * SBUF + (wn * 64 + a * 32 + r) * GP + (ks) * 16 + h * 8); \
;     F[2 + a] = *(const bf16x8*)(sA + (ST) * SBUF + (wm * 64 + a * 32 + r) * GP + (ks) * 16 + h * 8); } } while (0)
; #define FMMA(F) do { _Pragma("unroll") for (int a = 0; a < 2; ++a) _Pragma("unroll") for (int b = 0; b < 2; ++b) acc[a][b] = MFMA(F[a], F[2 + b], acc[a][b]); } while (0)
; template <bool MIDK, class AP, class EPI>
; DI void gemm_tile(const AP& ap, const u16* __restrict__ W, int ldw, int K, int m0, int n0, const EPI& epi, char* smem, float r0, float r1, int tid, bool dry) {
;     ...
;   for (int kt = 0; kt < nk; kt += 2) {
;     const bool l3 = kt + 3 < nk, s2 = kt + 2 < nk, l4 = kt + 4 < nk;
;     FLOAD(f0, 0, 0); FLOAD(f1, 0, 1);
;     FMMA(f0); SSTOREQ(ra1, rb1, 1, 0); if (l3) GLOADQ(ra1, rb1, kt + 3, 0);
;     FLOAD(f0, 0, 2);
;     FMMA(f1); SSTOREQ(ra1, rb1, 1, 1); if (l3) GLOADQ(ra1, rb1, kt + 3, 1);
;     FLOAD(f1, 0, 3);
;     FMMA(f0); SSTOREQ(ra1, rb1, 1, 2); if (l3) GLOADQ(ra1, rb1, kt + 3, 2);
;     FMMA(f1); SSTOREQ(ra1, rb1, 1, 3); if (l3) GLOADQ(ra1, rb1, kt + 3, 3);
;     __syncthreads();
;     FLOAD(f0, 1, 0); FLOAD(f1, 1, 1);
;     FMMA(f0); if (s2) SSTOREQ(ra0, rb0, 0, 0); if (l4) GLOADQ(ra0, rb0, kt + 4, 0);
;     FLOAD(f0, 1, 2);
;     FMMA(f1); if (s2) SSTOREQ(ra0, rb0, 0, 1); if (l4) GLOADQ(ra0, rb0, kt + 4, 1);
;     FLOAD(f1, 1, 3);
;     FMMA(f0); if (s2) SSTOREQ(ra0, rb0, 0, 2); if (l4) GLOADQ(ra0, rb0, kt + 4, 2);
;     FMMA(f1); if (s2) SSTOREQ(ra0, rb0, 0, 3); if (l4) GLOADQ(ra0, rb0, kt + 4, 3);
;     if (MIDK && kt == 6) {
; #pragma unroll
;       for (int a = 0; a < 2; ++a)
; #pragma unroll
;         for (int i = 0; i < 16; ++i) { acc[a][0][i] *= r0; acc[a][1][i] *= r1; }
;     }
;     __syncthreads();
;   }
	v_mfma_f32_32x32x16_bf16 v[0:15], v[120:123], v[116:119], v[0:15]
	ds_read_b128 v[116:119], v167 offset:55296
	ds_read_b128 v[120:123], v132 offset:36864
	ds_read_b128 v[162:165], v132 offset:41472
	s_waitcnt lgkmcnt(1)
	v_mfma_f32_32x32x16_bf16 v[48:63], v[116:119], v[120:123], v[48:63]
	s_waitcnt lgkmcnt(0)
	v_mfma_f32_32x32x16_bf16 v[32:47], v[116:119], v[162:165], v[32:47]
	ds_read_b128 v[116:119], v167 offset:59904
	s_waitcnt lgkmcnt(0)
	v_mfma_f32_32x32x16_bf16 v[16:31], v[116:119], v[120:123], v[16:31]
	v_mfma_f32_32x32x16_bf16 v[0:15], v[116:119], v[162:165], v[0:15]
	ds_read_b128 v[116:119], v167 offset:55328
	ds_read_b128 v[120:123], v132 offset:36896
	ds_read_b128 v[162:165], v132 offset:41504
	s_waitcnt lgkmcnt(1)
	v_mfma_f32_32x32x16_bf16 v[48:63], v[116:119], v[120:123], v[48:63]
	s_waitcnt lgkmcnt(0)
	v_mfma_f32_32x32x16_bf16 v[32:47], v[116:119], v[162:165], v[32:47]
	ds_read_b128 v[116:119], v167 offset:59936
	s_waitcnt vmcnt(15)
	ds_write_b128 v130, v[150:153]
	s_waitcnt vmcnt(14)
	ds_write_b128 v130, v[158:161] offset:18432
	s_waitcnt lgkmcnt(2)
	v_mfma_f32_32x32x16_bf16 v[16:31], v[116:119], v[120:123], v[16:31]
	v_mfma_f32_32x32x16_bf16 v[0:15], v[116:119], v[162:165], v[0:15]
	ds_read_b128 v[116:119], v167 offset:55360
	ds_read_b128 v[120:123], v132 offset:36928
	ds_read_b128 v[150:153], v132 offset:41536
	s_waitcnt lgkmcnt(1)
	v_mfma_f32_32x32x16_bf16 v[48:63], v[116:119], v[120:123], v[48:63]
	s_waitcnt lgkmcnt(0)
	v_mfma_f32_32x32x16_bf16 v[32:47], v[116:119], v[150:153], v[32:47]
	ds_read_b128 v[116:119], v167 offset:59968
	s_waitcnt vmcnt(13)
	ds_write_b128 v130, v[104:107] offset:4608
	s_waitcnt vmcnt(12)
	ds_write_b128 v130, v[108:111] offset:23040
	ds_read_b128 v[104:107], v167 offset:55392
	ds_read_b128 v[108:111], v132 offset:36960
	s_waitcnt lgkmcnt(4)
	v_mfma_f32_32x32x16_bf16 v[16:31], v[116:119], v[120:123], v[16:31]
	ds_read_b128 v[120:123], v167 offset:60000
	v_mfma_f32_32x32x16_bf16 v[0:15], v[116:119], v[150:153], v[0:15]
	ds_read_b128 v[116:119], v132 offset:41568
	s_waitcnt lgkmcnt(2)
	v_mfma_f32_32x32x16_bf16 v[48:63], v[104:107], v[108:111], v[48:63]
	s_waitcnt lgkmcnt(0)
	v_mfma_f32_32x32x16_bf16 v[32:47], v[104:107], v[116:119], v[32:47]
	v_mfma_f32_32x32x16_bf16 v[16:31], v[120:123], v[108:111], v[16:31]
	global_load_dwordx4 v[150:153], v[112:113], off offset:1280
	global_load_dwordx4 v[158:161], v[114:115], off offset:1280
	global_load_dwordx4 v[104:107], v[138:139], off offset:1280
	global_load_dwordx4 v[108:111], v[140:141], off offset:1280
	s_waitcnt vmcnt(15)
	ds_write_b128 v130, v[64:67] offset:9216
	s_waitcnt vmcnt(14)
	ds_write_b128 v130, v[68:71] offset:27648
	global_load_dwordx4 v[64:67], v[142:143], off offset:1280
	global_load_dwordx4 v[68:71], v[144:145], off offset:1280
	s_waitcnt vmcnt(15)
	ds_write_b128 v130, v[72:75] offset:13824
	s_waitcnt vmcnt(14)
	ds_write_b128 v130, v[76:79] offset:32256
	global_load_dwordx4 v[72:75], v[146:147], off offset:1280
	global_load_dwordx4 v[76:79], v[148:149], off offset:1280
	s_waitcnt lgkmcnt(0)
	s_barrier
	v_mfma_f32_32x32x16_bf16 v[0:15], v[120:123], v[116:119], v[0:15]
	ds_read_b128 v[116:119], v167 offset:18432
	ds_read_b128 v[120:123], v132
	ds_read_b128 v[162:165], v132 offset:4608
	s_waitcnt lgkmcnt(1)
	v_mfma_f32_32x32x16_bf16 v[48:63], v[116:119], v[120:123], v[48:63]
	s_waitcnt lgkmcnt(0)
	v_mfma_f32_32x32x16_bf16 v[32:47], v[116:119], v[162:165], v[32:47]
	ds_read_b128 v[116:119], v167 offset:23040
	s_waitcnt lgkmcnt(0)
	v_mfma_f32_32x32x16_bf16 v[16:31], v[116:119], v[120:123], v[16:31]
	v_mfma_f32_32x32x16_bf16 v[0:15], v[116:119], v[162:165], v[0:15]
	ds_read_b128 v[116:119], v167 offset:18464
	ds_read_b128 v[120:123], v132 offset:32
	ds_read_b128 v[162:165], v132 offset:4640
	s_waitcnt lgkmcnt(1)
	v_mfma_f32_32x32x16_bf16 v[48:63], v[116:119], v[120:123], v[48:63]
	s_waitcnt lgkmcnt(0)
	v_mfma_f32_32x32x16_bf16 v[32:47], v[116:119], v[162:165], v[32:47]
	ds_read_b128 v[116:119], v167 offset:23072
	s_waitcnt vmcnt(15)
	ds_write_b128 v130, v[124:127] offset:36864
	s_waitcnt vmcnt(14)
	ds_write_b128 v130, v[154:157] offset:55296
	s_waitcnt lgkmcnt(2)
	v_mfma_f32_32x32x16_bf16 v[16:31], v[116:119], v[120:123], v[16:31]
	v_mfma_f32_32x32x16_bf16 v[0:15], v[116:119], v[162:165], v[0:15]
	ds_read_b128 v[116:119], v167 offset:18496
	ds_read_b128 v[120:123], v132 offset:64
	ds_read_b128 v[124:127], v132 offset:4672
	s_waitcnt lgkmcnt(1)
	v_mfma_f32_32x32x16_bf16 v[48:63], v[116:119], v[120:123], v[48:63]
	s_waitcnt lgkmcnt(0)
	v_mfma_f32_32x32x16_bf16 v[32:47], v[116:119], v[124:127], v[32:47]
	ds_read_b128 v[116:119], v167 offset:23104
	s_waitcnt vmcnt(13)
	ds_write_b128 v130, v[96:99] offset:41472
	s_waitcnt vmcnt(12)
	ds_write_b128 v130, v[100:103] offset:59904
	ds_read_b128 v[96:99], v167 offset:18528
	ds_read_b128 v[100:103], v132 offset:96
	s_waitcnt lgkmcnt(4)
	v_mfma_f32_32x32x16_bf16 v[16:31], v[116:119], v[120:123], v[16:31]
	ds_read_b128 v[120:123], v167 offset:23136
	v_mfma_f32_32x32x16_bf16 v[0:15], v[116:119], v[124:127], v[0:15]
	ds_read_b128 v[116:119], v132 offset:4704
	s_waitcnt lgkmcnt(2)
	v_mfma_f32_32x32x16_bf16 v[48:63], v[96:99], v[100:103], v[48:63]
	s_waitcnt lgkmcnt(0)
	v_mfma_f32_32x32x16_bf16 v[32:47], v[96:99], v[116:119], v[32:47]
	v_mfma_f32_32x32x16_bf16 v[16:31], v[120:123], v[100:103], v[16:31]
	global_load_dwordx4 v[124:127], v[112:113], off offset:1408
	global_load_dwordx4 v[154:157], v[114:115], off offset:1408
	global_load_dwordx4 v[96:99], v[138:139], off offset:1408
	global_load_dwordx4 v[100:103], v[140:141], off offset:1408
	s_waitcnt vmcnt(15)
	ds_write_b128 v130, v[80:83] offset:46080
	s_waitcnt vmcnt(14)
	ds_write_b128 v130, v[84:87] offset:64512
	global_load_dwordx4 v[80:83], v[142:143], off offset:1408
	global_load_dwordx4 v[84:87], v[144:145], off offset:1408
	s_waitcnt vmcnt(15)
	ds_write_b128 v130, v[88:91] offset:50688
	s_waitcnt vmcnt(14)
	ds_write_b128 v131, v[92:95] offset:13824
	global_load_dwordx4 v[88:91], v[146:147], off offset:1408
	global_load_dwordx4 v[92:95], v[148:149], off offset:1408
	s_waitcnt lgkmcnt(0)
	s_barrier
; #define GLOADQ(RA, RB, KT, q) do { const int k0_ = (KT) << 6; \
;     RA[q] = ldg16(ap.ptr(m0 + lrow + 32 * (q), k0_) + lkc); RB[q] = ldg16(W + (size_t)(n0 + lrow + 32 * (q)) * ldw + k0_ + lkc); } while (0)
; #define SSTOREQ(RA, RB, ST, q) do { \
;     *(u32x4*)(sA + (ST) * SBUF + (lrow + 32 * (q)) * GP + lkc) = RA[q]; *(u32x4*)(sB + (ST) * SBUF + (lrow + 32 * (q)) * GP + lkc) = RB[q]; } while (0)
; #define FLOAD(F, ST, ks) do { _Pragma("unroll") for (int a = 0; a < 2; ++a) { \
;     F[a] = *(const bf16x8*)(sB + (ST) * SBUF + (wn * 64 + a * 32 + r) * GP + (ks) * 16 + h * 8); \
;     F[2 + a] = *(const bf16x8*)(sA + (ST) * SBUF + (wm * 64 + a * 32 + r) * GP + (ks) * 16 + h * 8); } } while (0)
; #define FMMA(F) do { _Pragma("unroll") for (int a = 0; a < 2; ++a) _Pragma("unroll") for (int b = 0; b < 2; ++b) acc[a][b] = MFMA(F[a], F[2 + b], acc[a][b]); } while (0)
; template <bool MIDK, class AP, class EPI>
; DI void gemm_tile(const AP& ap, const u16* __restrict__ W, int ldw, int K, int m0, int n0, const EPI& epi, char* smem, float r0, float r1, int tid, bool dry) {
;     ...
;   for (int kt = 0; kt < nk; kt += 2) {
;     const bool l3 = kt + 3 < nk, s2 = kt + 2 < nk, l4 = kt + 4 < nk;
;     FLOAD(f0, 0, 0); FLOAD(f1, 0, 1);
;     FMMA(f0); SSTOREQ(ra1, rb1, 1, 0); if (l3) GLOADQ(ra1, rb1, kt + 3, 0);
;     FLOAD(f0, 0, 2);
;     FMMA(f1); SSTOREQ(ra1, rb1, 1, 1); if (l3) GLOADQ(ra1, rb1, kt + 3, 1);
;     FLOAD(f1, 0, 3);
;     FMMA(f0); SSTOREQ(ra1, rb1, 1, 2); if (l3) GLOADQ(ra1, rb1, kt + 3, 2);
;     FMMA(f1); SSTOREQ(ra1, rb1, 1, 3); if (l3) GLOADQ(ra1, rb1, kt + 3, 3);
;     __syncthreads();
;     FLOAD(f0, 1, 0); FLOAD(f1, 1, 1);
;     FMMA(f0); if (s2) SSTOREQ(ra0, rb0, 0, 0); if (l4) GLOADQ(ra0, rb0, kt + 4, 0);
;     FLOAD(f0, 1, 2);
;     FMMA(f1); if (s2) SSTOREQ(ra0, rb0, 0, 1); if (l4) GLOADQ(ra0, rb0, kt + 4, 1);
;     FLOAD(f1, 1, 3);
;     FMMA(f0); if (s2) SSTOREQ(ra0, rb0, 0, 2); if (l4) GLOADQ(ra0, rb0, kt + 4, 2);
;     FMMA(f1); if (s2) SSTOREQ(ra0, rb0, 0, 3); if (l4) GLOADQ(ra0, rb0, kt + 4, 3);
;     if (MIDK && kt == 6) {
; #pragma unroll
;       for (int a = 0; a < 2; ++a)
; #pragma unroll
;         for (int i = 0; i < 16; ++i) { acc[a][0][i] *= r0; acc[a][1][i] *= r1; }
;     }
;     __syncthreads();
;   }
	v_mfma_f32_32x32x16_bf16 v[0:15], v[120:123], v[116:119], v[0:15]
	ds_read_b128 v[116:119], v167 offset:55296
	ds_read_b128 v[120:123], v132 offset:36864
	ds_read_b128 v[162:165], v132 offset:41472
	s_waitcnt lgkmcnt(1)
	v_mfma_f32_32x32x16_bf16 v[48:63], v[116:119], v[120:123], v[48:63]
	s_waitcnt lgkmcnt(0)
	v_mfma_f32_32x32x16_bf16 v[32:47], v[116:119], v[162:165], v[32:47]
	ds_read_b128 v[116:119], v167 offset:59904
	s_waitcnt lgkmcnt(0)
	v_mfma_f32_32x32x16_bf16 v[16:31], v[116:119], v[120:123], v[16:31]
	v_mfma_f32_32x32x16_bf16 v[0:15], v[116:119], v[162:165], v[0:15]
	ds_read_b128 v[116:119], v167 offset:55328
	ds_read_b128 v[120:123], v132 offset:36896
	ds_read_b128 v[162:165], v132 offset:41504
	s_waitcnt lgkmcnt(1)
	v_mfma_f32_32x32x16_bf16 v[48:63], v[116:119], v[120:123], v[48:63]
	s_waitcnt lgkmcnt(0)
	v_mfma_f32_32x32x16_bf16 v[32:47], v[116:119], v[162:165], v[32:47]
	ds_read_b128 v[116:119], v167 offset:59936
	s_waitcnt vmcnt(15)
	ds_write_b128 v130, v[150:153]
	s_waitcnt vmcnt(14)
	ds_write_b128 v130, v[158:161] offset:18432
	s_waitcnt lgkmcnt(2)
	v_mfma_f32_32x32x16_bf16 v[16:31], v[116:119], v[120:123], v[16:31]
	v_mfma_f32_32x32x16_bf16 v[0:15], v[116:119], v[162:165], v[0:15]
	ds_read_b128 v[116:119], v167 offset:55360
	ds_read_b128 v[120:123], v132 offset:36928
	ds_read_b128 v[150:153], v132 offset:41536
	s_waitcnt lgkmcnt(1)
	v_mfma_f32_32x32x16_bf16 v[48:63], v[116:119], v[120:123], v[48:63]
	s_waitcnt lgkmcnt(0)
	v_mfma_f32_32x32x16_bf16 v[32:47], v[116:119], v[150:153], v[32:47]
	ds_read_b128 v[116:119], v167 offset:59968
	s_waitcnt vmcnt(13)
	ds_write_b128 v130, v[104:107] offset:4608
	s_waitcnt vmcnt(12)
	ds_write_b128 v130, v[108:111] offset:23040
	ds_read_b128 v[104:107], v167 offset:55392
	ds_read_b128 v[108:111], v132 offset:36960
	s_waitcnt lgkmcnt(4)
	v_mfma_f32_32x32x16_bf16 v[16:31], v[116:119], v[120:123], v[16:31]
	ds_read_b128 v[120:123], v167 offset:60000
	v_mfma_f32_32x32x16_bf16 v[0:15], v[116:119], v[150:153], v[0:15]
	ds_read_b128 v[116:119], v132 offset:41568
	s_waitcnt lgkmcnt(2)
	v_mfma_f32_32x32x16_bf16 v[48:63], v[104:107], v[108:111], v[48:63]
	s_waitcnt lgkmcnt(0)
	v_mfma_f32_32x32x16_bf16 v[32:47], v[104:107], v[116:119], v[32:47]
	v_mfma_f32_32x32x16_bf16 v[16:31], v[120:123], v[108:111], v[16:31]
	global_load_dwordx4 v[150:153], v[112:113], off offset:1536
	global_load_dwordx4 v[158:161], v[114:115], off offset:1536
	global_load_dwordx4 v[104:107], v[138:139], off offset:1536
	global_load_dwordx4 v[108:111], v[140:141], off offset:1536
	s_waitcnt vmcnt(15)
	ds_write_b128 v130, v[64:67] offset:9216
	s_waitcnt vmcnt(14)
	ds_write_b128 v130, v[68:71] offset:27648
	global_load_dwordx4 v[64:67], v[142:143], off offset:1536
	global_load_dwordx4 v[68:71], v[144:145], off offset:1536
	s_waitcnt vmcnt(15)
	ds_write_b128 v130, v[72:75] offset:13824
	s_waitcnt vmcnt(14)
	ds_write_b128 v130, v[76:79] offset:32256
	global_load_dwordx4 v[72:75], v[146:147], off offset:1536
	global_load_dwordx4 v[76:79], v[148:149], off offset:1536
	s_waitcnt lgkmcnt(0)
	s_barrier
	v_mfma_f32_32x32x16_bf16 v[0:15], v[120:123], v[116:119], v[0:15]
	ds_read_b128 v[116:119], v167 offset:18432
	ds_read_b128 v[120:123], v132
	ds_read_b128 v[162:165], v132 offset:4608
	s_waitcnt lgkmcnt(1)
	v_mfma_f32_32x32x16_bf16 v[48:63], v[116:119], v[120:123], v[48:63]
	s_waitcnt lgkmcnt(0)
	v_mfma_f32_32x32x16_bf16 v[32:47], v[116:119], v[162:165], v[32:47]
	ds_read_b128 v[116:119], v167 offset:23040
	s_waitcnt lgkmcnt(0)
	v_mfma_f32_32x32x16_bf16 v[16:31], v[116:119], v[120:123], v[16:31]
	v_mfma_f32_32x32x16_bf16 v[0:15], v[116:119], v[162:165], v[0:15]
	ds_read_b128 v[116:119], v167 offset:18464
	ds_read_b128 v[120:123], v132 offset:32
	ds_read_b128 v[162:165], v132 offset:4640
	s_waitcnt lgkmcnt(1)
	v_mfma_f32_32x32x16_bf16 v[48:63], v[116:119], v[120:123], v[48:63]
	s_waitcnt lgkmcnt(0)
	v_mfma_f32_32x32x16_bf16 v[32:47], v[116:119], v[162:165], v[32:47]
	ds_read_b128 v[116:119], v167 offset:23072
	s_waitcnt vmcnt(15)
	ds_write_b128 v130, v[124:127] offset:36864
	s_waitcnt vmcnt(14)
	ds_write_b128 v130, v[154:157] offset:55296
	s_waitcnt lgkmcnt(2)
	v_mfma_f32_32x32x16_bf16 v[16:31], v[116:119], v[120:123], v[16:31]
	v_mfma_f32_32x32x16_bf16 v[0:15], v[116:119], v[162:165], v[0:15]
	ds_read_b128 v[116:119], v167 offset:18496
	ds_read_b128 v[120:123], v132 offset:64
	ds_read_b128 v[124:127], v132 offset:4672
	s_waitcnt lgkmcnt(1)
	v_mfma_f32_32x32x16_bf16 v[48:63], v[116:119], v[120:123], v[48:63]
	s_waitcnt lgkmcnt(0)
	v_mfma_f32_32x32x16_bf16 v[32:47], v[116:119], v[124:127], v[32:47]
	ds_read_b128 v[116:119], v167 offset:23104
	s_waitcnt vmcnt(13)
	ds_write_b128 v130, v[96:99] offset:41472
	s_waitcnt vmcnt(12)
	ds_write_b128 v130, v[100:103] offset:59904
	ds_read_b128 v[96:99], v167 offset:18528
	ds_read_b128 v[100:103], v132 offset:96
	s_waitcnt lgkmcnt(4)
	v_mfma_f32_32x32x16_bf16 v[16:31], v[116:119], v[120:123], v[16:31]
	ds_read_b128 v[120:123], v167 offset:23136
	v_mfma_f32_32x32x16_bf16 v[0:15], v[116:119], v[124:127], v[0:15]
	ds_read_b128 v[116:119], v132 offset:4704
	s_waitcnt lgkmcnt(2)
	v_mfma_f32_32x32x16_bf16 v[48:63], v[96:99], v[100:103], v[48:63]
	s_waitcnt lgkmcnt(0)
	v_mfma_f32_32x32x16_bf16 v[32:47], v[96:99], v[116:119], v[32:47]
	v_mfma_f32_32x32x16_bf16 v[16:31], v[120:123], v[100:103], v[16:31]
	global_load_dwordx4 v[124:127], v[112:113], off offset:1664
	global_load_dwordx4 v[154:157], v[114:115], off offset:1664
	global_load_dwordx4 v[96:99], v[138:139], off offset:1664
	global_load_dwordx4 v[100:103], v[140:141], off offset:1664
	s_waitcnt vmcnt(15)
	ds_write_b128 v130, v[80:83] offset:46080
	s_waitcnt vmcnt(14)
	ds_write_b128 v130, v[84:87] offset:64512
	global_load_dwordx4 v[80:83], v[142:143], off offset:1664
	global_load_dwordx4 v[84:87], v[144:145], off offset:1664
	s_waitcnt vmcnt(15)
	ds_write_b128 v130, v[88:91] offset:50688
	s_waitcnt vmcnt(14)
	ds_write_b128 v131, v[92:95] offset:13824
	global_load_dwordx4 v[88:91], v[146:147], off offset:1664
	global_load_dwordx4 v[92:95], v[148:149], off offset:1664
	s_waitcnt lgkmcnt(0)
	s_barrier
; #define GLOADQ(RA, RB, KT, q) do { const int k0_ = (KT) << 6; \
;     RA[q] = ldg16(ap.ptr(m0 + lrow + 32 * (q), k0_) + lkc); RB[q] = ldg16(W + (size_t)(n0 + lrow + 32 * (q)) * ldw + k0_ + lkc); } while (0)
; #define SSTOREQ(RA, RB, ST, q) do { \
;     *(u32x4*)(sA + (ST) * SBUF + (lrow + 32 * (q)) * GP + lkc) = RA[q]; *(u32x4*)(sB + (ST) * SBUF + (lrow + 32 * (q)) * GP + lkc) = RB[q]; } while (0)
; #define FLOAD(F, ST, ks) do { _Pragma("unroll") for (int a = 0; a < 2; ++a) { \
;     F[a] = *(const bf16x8*)(sB + (ST) * SBUF + (wn * 64 + a * 32 + r) * GP + (ks) * 16 + h * 8); \
;     F[2 + a] = *(const bf16x8*)(sA + (ST) * SBUF + (wm * 64 + a * 32 + r) * GP + (ks) * 16 + h * 8); } } while (0)
; #define FMMA(F) do { _Pragma("unroll") for (int a = 0; a < 2; ++a) _Pragma("unroll") for (int b = 0; b < 2; ++b) acc[a][b] = MFMA(F[a], F[2 + b], acc[a][b]); } while (0)
; template <bool MIDK, class AP, class EPI>
; DI void gemm_tile(const AP& ap, const u16* __restrict__ W, int ldw, int K, int m0, int n0, const EPI& epi, char* smem, float r0, float r1, int tid, bool dry) {
;     ...
;   for (int kt = 0; kt < nk; kt += 2) {
;     const bool l3 = kt + 3 < nk, s2 = kt + 2 < nk, l4 = kt + 4 < nk;
;     FLOAD(f0, 0, 0); FLOAD(f1, 0, 1);
;     FMMA(f0); SSTOREQ(ra1, rb1, 1, 0); if (l3) GLOADQ(ra1, rb1, kt + 3, 0);
;     FLOAD(f0, 0, 2);
;     FMMA(f1); SSTOREQ(ra1, rb1, 1, 1); if (l3) GLOADQ(ra1, rb1, kt + 3, 1);
;     FLOAD(f1, 0, 3);
;     FMMA(f0); SSTOREQ(ra1, rb1, 1, 2); if (l3) GLOADQ(ra1, rb1, kt + 3, 2);
;     FMMA(f1); SSTOREQ(ra1, rb1, 1, 3); if (l3) GLOADQ(ra1, rb1, kt + 3, 3);
;     __syncthreads();
;     FLOAD(f0, 1, 0); FLOAD(f1, 1, 1);
;     FMMA(f0); if (s2) SSTOREQ(ra0, rb0, 0, 0); if (l4) GLOADQ(ra0, rb0, kt + 4, 0);
;     FLOAD(f0, 1, 2);
;     FMMA(f1); if (s2) SSTOREQ(ra0, rb0, 0, 1); if (l4) GLOADQ(ra0, rb0, kt + 4, 1);
;     FLOAD(f1, 1, 3);
;     FMMA(f0); if (s2) SSTOREQ(ra0, rb0, 0, 2); if (l4) GLOADQ(ra0, rb0, kt + 4, 2);
;     FMMA(f1); if (s2) SSTOREQ(ra0, rb0, 0, 3); if (l4) GLOADQ(ra0, rb0, kt + 4, 3);
;     if (MIDK && kt == 6) {
; #pragma unroll
;       for (int a = 0; a < 2; ++a)
; #pragma unroll
;         for (int i = 0; i < 16; ++i) { acc[a][0][i] *= r0; acc[a][1][i] *= r1; }
;     }
;     __syncthreads();
;   }
	v_mfma_f32_32x32x16_bf16 v[0:15], v[120:123], v[116:119], v[0:15]
	ds_read_b128 v[116:119], v167 offset:55296
	ds_read_b128 v[120:123], v132 offset:36864
	ds_read_b128 v[162:165], v132 offset:41472
	s_waitcnt lgkmcnt(1)
	v_mfma_f32_32x32x16_bf16 v[48:63], v[116:119], v[120:123], v[48:63]
	s_waitcnt lgkmcnt(0)
	v_mfma_f32_32x32x16_bf16 v[32:47], v[116:119], v[162:165], v[32:47]
	ds_read_b128 v[116:119], v167 offset:59904
	s_waitcnt lgkmcnt(0)
	v_mfma_f32_32x32x16_bf16 v[16:31], v[116:119], v[120:123], v[16:31]
	v_mfma_f32_32x32x16_bf16 v[0:15], v[116:119], v[162:165], v[0:15]
	ds_read_b128 v[116:119], v167 offset:55328
	ds_read_b128 v[120:123], v132 offset:36896
	ds_read_b128 v[162:165], v132 offset:41504
	s_waitcnt lgkmcnt(1)
	v_mfma_f32_32x32x16_bf16 v[48:63], v[116:119], v[120:123], v[48:63]
	s_waitcnt lgkmcnt(0)
	v_mfma_f32_32x32x16_bf16 v[32:47], v[116:119], v[162:165], v[32:47]
	ds_read_b128 v[116:119], v167 offset:59936
	s_waitcnt vmcnt(15)
	ds_write_b128 v130, v[150:153]
	s_waitcnt vmcnt(14)
	ds_write_b128 v130, v[158:161] offset:18432
	s_waitcnt lgkmcnt(2)
	v_mfma_f32_32x32x16_bf16 v[16:31], v[116:119], v[120:123], v[16:31]
	v_mfma_f32_32x32x16_bf16 v[0:15], v[116:119], v[162:165], v[0:15]
	ds_read_b128 v[116:119], v167 offset:55360
	ds_read_b128 v[120:123], v132 offset:36928
	ds_read_b128 v[150:153], v132 offset:41536
	s_waitcnt lgkmcnt(1)
	v_mfma_f32_32x32x16_bf16 v[48:63], v[116:119], v[120:123], v[48:63]
	s_waitcnt lgkmcnt(0)
	v_mfma_f32_32x32x16_bf16 v[32:47], v[116:119], v[150:153], v[32:47]
	ds_read_b128 v[116:119], v167 offset:59968
	s_waitcnt vmcnt(13)
	ds_write_b128 v130, v[104:107] offset:4608
	s_waitcnt vmcnt(12)
	ds_write_b128 v130, v[108:111] offset:23040
	ds_read_b128 v[104:107], v167 offset:55392
	ds_read_b128 v[108:111], v132 offset:36960
	s_waitcnt lgkmcnt(4)
	v_mfma_f32_32x32x16_bf16 v[16:31], v[116:119], v[120:123], v[16:31]
	ds_read_b128 v[120:123], v167 offset:60000
	v_mfma_f32_32x32x16_bf16 v[0:15], v[116:119], v[150:153], v[0:15]
	ds_read_b128 v[116:119], v132 offset:41568
	s_waitcnt lgkmcnt(2)
	v_mfma_f32_32x32x16_bf16 v[48:63], v[104:107], v[108:111], v[48:63]
	s_waitcnt lgkmcnt(0)
	v_mfma_f32_32x32x16_bf16 v[32:47], v[104:107], v[116:119], v[32:47]
	v_mfma_f32_32x32x16_bf16 v[16:31], v[120:123], v[108:111], v[16:31]
	global_load_dwordx4 v[150:153], v[112:113], off offset:1792
	global_load_dwordx4 v[158:161], v[114:115], off offset:1792
	global_load_dwordx4 v[104:107], v[138:139], off offset:1792
	global_load_dwordx4 v[108:111], v[140:141], off offset:1792
	s_waitcnt vmcnt(15)
	ds_write_b128 v130, v[64:67] offset:9216
	s_waitcnt vmcnt(14)
	ds_write_b128 v130, v[68:71] offset:27648
	global_load_dwordx4 v[64:67], v[142:143], off offset:1792
	global_load_dwordx4 v[68:71], v[144:145], off offset:1792
	s_waitcnt vmcnt(15)
	ds_write_b128 v130, v[72:75] offset:13824
	s_waitcnt vmcnt(14)
	ds_write_b128 v130, v[76:79] offset:32256
	global_load_dwordx4 v[72:75], v[146:147], off offset:1792
	global_load_dwordx4 v[76:79], v[148:149], off offset:1792
	s_waitcnt lgkmcnt(0)
	s_barrier
	v_mfma_f32_32x32x16_bf16 v[0:15], v[120:123], v[116:119], v[0:15]
	ds_read_b128 v[116:119], v167 offset:18432
	ds_read_b128 v[120:123], v132
	ds_read_b128 v[162:165], v132 offset:4608
	s_waitcnt lgkmcnt(1)
	v_mfma_f32_32x32x16_bf16 v[48:63], v[116:119], v[120:123], v[48:63]
	s_waitcnt lgkmcnt(0)
	v_mfma_f32_32x32x16_bf16 v[32:47], v[116:119], v[162:165], v[32:47]
	ds_read_b128 v[116:119], v167 offset:23040
	s_waitcnt lgkmcnt(0)
	v_mfma_f32_32x32x16_bf16 v[16:31], v[116:119], v[120:123], v[16:31]
	v_mfma_f32_32x32x16_bf16 v[0:15], v[116:119], v[162:165], v[0:15]
	ds_read_b128 v[116:119], v167 offset:18464
	ds_read_b128 v[120:123], v132 offset:32
	ds_read_b128 v[162:165], v132 offset:4640
	s_waitcnt lgkmcnt(1)
	v_mfma_f32_32x32x16_bf16 v[48:63], v[116:119], v[120:123], v[48:63]
	s_waitcnt lgkmcnt(0)
	v_mfma_f32_32x32x16_bf16 v[32:47], v[116:119], v[162:165], v[32:47]
	ds_read_b128 v[116:119], v167 offset:23072
	s_waitcnt vmcnt(15)
	ds_write_b128 v130, v[124:127] offset:36864
	s_waitcnt vmcnt(14)
	ds_write_b128 v130, v[154:157] offset:55296
	s_waitcnt lgkmcnt(2)
	v_mfma_f32_32x32x16_bf16 v[16:31], v[116:119], v[120:123], v[16:31]
	v_mfma_f32_32x32x16_bf16 v[0:15], v[116:119], v[162:165], v[0:15]
	ds_read_b128 v[116:119], v167 offset:18496
	ds_read_b128 v[120:123], v132 offset:64
	ds_read_b128 v[124:127], v132 offset:4672
	s_waitcnt lgkmcnt(1)
	v_mfma_f32_32x32x16_bf16 v[48:63], v[116:119], v[120:123], v[48:63]
	s_waitcnt lgkmcnt(0)
	v_mfma_f32_32x32x16_bf16 v[32:47], v[116:119], v[124:127], v[32:47]
	ds_read_b128 v[116:119], v167 offset:23104
	s_waitcnt vmcnt(13)
	ds_write_b128 v130, v[96:99] offset:41472
	s_waitcnt vmcnt(12)
	ds_write_b128 v130, v[100:103] offset:59904
	ds_read_b128 v[96:99], v167 offset:18528
	ds_read_b128 v[100:103], v132 offset:96
	s_waitcnt lgkmcnt(4)
	v_mfma_f32_32x32x16_bf16 v[16:31], v[116:119], v[120:123], v[16:31]
	ds_read_b128 v[120:123], v167 offset:23136
	v_mfma_f32_32x32x16_bf16 v[0:15], v[116:119], v[124:127], v[0:15]
	ds_read_b128 v[116:119], v132 offset:4704
	s_waitcnt lgkmcnt(2)
	v_mfma_f32_32x32x16_bf16 v[48:63], v[96:99], v[100:103], v[48:63]
	s_waitcnt lgkmcnt(0)
	v_mfma_f32_32x32x16_bf16 v[32:47], v[96:99], v[116:119], v[32:47]
	v_mfma_f32_32x32x16_bf16 v[16:31], v[120:123], v[100:103], v[16:31]
	global_load_dwordx4 v[124:127], v[112:113], off offset:1920
	global_load_dwordx4 v[154:157], v[114:115], off offset:1920
	global_load_dwordx4 v[96:99], v[138:139], off offset:1920
	global_load_dwordx4 v[100:103], v[140:141], off offset:1920
	s_waitcnt vmcnt(15)
	ds_write_b128 v130, v[80:83] offset:46080
	s_waitcnt vmcnt(14)
	ds_write_b128 v130, v[84:87] offset:64512
	global_load_dwordx4 v[80:83], v[142:143], off offset:1920
	global_load_dwordx4 v[84:87], v[144:145], off offset:1920
	s_waitcnt vmcnt(15)
	ds_write_b128 v130, v[88:91] offset:50688
	s_waitcnt vmcnt(14)
	ds_write_b128 v131, v[92:95] offset:13824
	global_load_dwordx4 v[88:91], v[146:147], off offset:1920
	global_load_dwordx4 v[92:95], v[148:149], off offset:1920
	s_waitcnt lgkmcnt(0)
	s_barrier
; #define GLOADQ(RA, RB, KT, q) do { const int k0_ = (KT) << 6; \
;     RA[q] = ldg16(ap.ptr(m0 + lrow + 32 * (q), k0_) + lkc); RB[q] = ldg16(W + (size_t)(n0 + lrow + 32 * (q)) * ldw + k0_ + lkc); } while (0)
; #define SSTOREQ(RA, RB, ST, q) do { \
;     *(u32x4*)(sA + (ST) * SBUF + (lrow + 32 * (q)) * GP + lkc) = RA[q]; *(u32x4*)(sB + (ST) * SBUF + (lrow + 32 * (q)) * GP + lkc) = RB[q]; } while (0)
; #define FLOAD(F, ST, ks) do { _Pragma("unroll") for (int a = 0; a < 2; ++a) { \
;     F[a] = *(const bf16x8*)(sB + (ST) * SBUF + (wn * 64 + a * 32 + r) * GP + (ks) * 16 + h * 8); \
;     F[2 + a] = *(const bf16x8*)(sA + (ST) * SBUF + (wm * 64 + a * 32 + r) * GP + (ks) * 16 + h * 8); } } while (0)
; #define FMMA(F) do { _Pragma("unroll") for (int a = 0; a < 2; ++a) _Pragma("unroll") for (int b = 0; b < 2; ++b) acc[a][b] = MFMA(F[a], F[2 + b], acc[a][b]); } while (0)
; template <bool MIDK, class AP, class EPI>
; DI void gemm_tile(const AP& ap, const u16* __restrict__ W, int ldw, int K, int m0, int n0, const EPI& epi, char* smem, float r0, float r1, int tid, bool dry) {
;     ...
;   for (int kt = 0; kt < nk; kt += 2) {
;     const bool l3 = kt + 3 < nk, s2 = kt + 2 < nk, l4 = kt + 4 < nk;
;     FLOAD(f0, 0, 0); FLOAD(f1, 0, 1);
;     FMMA(f0); SSTOREQ(ra1, rb1, 1, 0); if (l3) GLOADQ(ra1, rb1, kt + 3, 0);
;     FLOAD(f0, 0, 2);
;     FMMA(f1); SSTOREQ(ra1, rb1, 1, 1); if (l3) GLOADQ(ra1, rb1, kt + 3, 1);
;     FLOAD(f1, 0, 3);
;     FMMA(f0); SSTOREQ(ra1, rb1, 1, 2); if (l3) GLOADQ(ra1, rb1, kt + 3, 2);
;     FMMA(f1); SSTOREQ(ra1, rb1, 1, 3); if (l3) GLOADQ(ra1, rb1, kt + 3, 3);
;     __syncthreads();
;     FLOAD(f0, 1, 0); FLOAD(f1, 1, 1);
;     FMMA(f0); if (s2) SSTOREQ(ra0, rb0, 0, 0); if (l4) GLOADQ(ra0, rb0, kt + 4, 0);
;     FLOAD(f0, 1, 2);
;     FMMA(f1); if (s2) SSTOREQ(ra0, rb0, 0, 1); if (l4) GLOADQ(ra0, rb0, kt + 4, 1);
;     FLOAD(f1, 1, 3);
;     FMMA(f0); if (s2) SSTOREQ(ra0, rb0, 0, 2); if (l4) GLOADQ(ra0, rb0, kt + 4, 2);
;     FMMA(f1); if (s2) SSTOREQ(ra0, rb0, 0, 3); if (l4) GLOADQ(ra0, rb0, kt + 4, 3);
;     if (MIDK && kt == 6) {
; #pragma unroll
;       for (int a = 0; a < 2; ++a)
; #pragma unroll
;         for (int i = 0; i < 16; ++i) { acc[a][0][i] *= r0; acc[a][1][i] *= r1; }
;     }
;     __syncthreads();
;   }
	v_mfma_f32_32x32x16_bf16 v[0:15], v[120:123], v[116:119], v[0:15]
	ds_read_b128 v[116:119], v167 offset:55296
	ds_read_b128 v[120:123], v132 offset:36864
	ds_read_b128 v[162:165], v132 offset:41472
	s_waitcnt lgkmcnt(1)
	v_mfma_f32_32x32x16_bf16 v[48:63], v[116:119], v[120:123], v[48:63]
	s_waitcnt lgkmcnt(0)
	v_mfma_f32_32x32x16_bf16 v[32:47], v[116:119], v[162:165], v[32:47]
	ds_read_b128 v[116:119], v167 offset:59904
	s_waitcnt lgkmcnt(0)
	v_mfma_f32_32x32x16_bf16 v[16:31], v[116:119], v[120:123], v[16:31]
	v_mfma_f32_32x32x16_bf16 v[0:15], v[116:119], v[162:165], v[0:15]
	ds_read_b128 v[116:119], v167 offset:55328
	ds_read_b128 v[120:123], v132 offset:36896
	ds_read_b128 v[162:165], v132 offset:41504
	s_waitcnt lgkmcnt(1)
	v_mfma_f32_32x32x16_bf16 v[48:63], v[116:119], v[120:123], v[48:63]
	s_waitcnt lgkmcnt(0)
	v_mfma_f32_32x32x16_bf16 v[32:47], v[116:119], v[162:165], v[32:47]
	ds_read_b128 v[116:119], v167 offset:59936
	s_waitcnt vmcnt(15)
	ds_write_b128 v130, v[150:153]
	s_waitcnt vmcnt(14)
	ds_write_b128 v130, v[158:161] offset:18432
	s_waitcnt lgkmcnt(2)
	v_mfma_f32_32x32x16_bf16 v[16:31], v[116:119], v[120:123], v[16:31]
	v_mfma_f32_32x32x16_bf16 v[0:15], v[116:119], v[162:165], v[0:15]
	ds_read_b128 v[116:119], v167 offset:55360
	ds_read_b128 v[120:123], v132 offset:36928
	ds_read_b128 v[150:153], v132 offset:41536
	s_waitcnt lgkmcnt(1)
	v_mfma_f32_32x32x16_bf16 v[48:63], v[116:119], v[120:123], v[48:63]
	s_waitcnt lgkmcnt(0)
	v_mfma_f32_32x32x16_bf16 v[32:47], v[116:119], v[150:153], v[32:47]
	ds_read_b128 v[116:119], v167 offset:59968
	s_waitcnt vmcnt(13)
	ds_write_b128 v130, v[104:107] offset:4608
	s_waitcnt vmcnt(12)
	ds_write_b128 v130, v[108:111] offset:23040
	ds_read_b128 v[104:107], v167 offset:55392
	ds_read_b128 v[108:111], v132 offset:36960
	s_waitcnt lgkmcnt(4)
	v_mfma_f32_32x32x16_bf16 v[16:31], v[116:119], v[120:123], v[16:31]
	ds_read_b128 v[120:123], v167 offset:60000
	v_mfma_f32_32x32x16_bf16 v[0:15], v[116:119], v[150:153], v[0:15]
	ds_read_b128 v[116:119], v132 offset:41568
	s_waitcnt lgkmcnt(2)
	v_mfma_f32_32x32x16_bf16 v[48:63], v[104:107], v[108:111], v[48:63]
	s_waitcnt lgkmcnt(0)
	v_mfma_f32_32x32x16_bf16 v[32:47], v[104:107], v[116:119], v[32:47]
	v_mfma_f32_32x32x16_bf16 v[16:31], v[120:123], v[108:111], v[16:31]
	global_load_dwordx4 v[150:153], v[112:113], off offset:2048
	global_load_dwordx4 v[158:161], v[114:115], off offset:2048
	global_load_dwordx4 v[104:107], v[138:139], off offset:2048
	global_load_dwordx4 v[108:111], v[140:141], off offset:2048
	s_waitcnt vmcnt(15)
	ds_write_b128 v130, v[64:67] offset:9216
	s_waitcnt vmcnt(14)
	ds_write_b128 v130, v[68:71] offset:27648
	global_load_dwordx4 v[64:67], v[142:143], off offset:2048
	global_load_dwordx4 v[68:71], v[144:145], off offset:2048
	s_waitcnt vmcnt(15)
	ds_write_b128 v130, v[72:75] offset:13824
	s_waitcnt vmcnt(14)
	ds_write_b128 v130, v[76:79] offset:32256
	global_load_dwordx4 v[72:75], v[146:147], off offset:2048
	global_load_dwordx4 v[76:79], v[148:149], off offset:2048
	s_waitcnt lgkmcnt(0)
	s_barrier
	v_mfma_f32_32x32x16_bf16 v[0:15], v[120:123], v[116:119], v[0:15]
	ds_read_b128 v[116:119], v167 offset:18432
	ds_read_b128 v[120:123], v132
	ds_read_b128 v[162:165], v132 offset:4608
	s_waitcnt lgkmcnt(1)
	v_mfma_f32_32x32x16_bf16 v[48:63], v[116:119], v[120:123], v[48:63]
	s_waitcnt lgkmcnt(0)
	v_mfma_f32_32x32x16_bf16 v[32:47], v[116:119], v[162:165], v[32:47]
	ds_read_b128 v[116:119], v167 offset:23040
	s_waitcnt lgkmcnt(0)
	v_mfma_f32_32x32x16_bf16 v[16:31], v[116:119], v[120:123], v[16:31]
	v_mfma_f32_32x32x16_bf16 v[0:15], v[116:119], v[162:165], v[0:15]
	ds_read_b128 v[116:119], v167 offset:18464
	ds_read_b128 v[120:123], v132 offset:32
	ds_read_b128 v[162:165], v132 offset:4640
	s_waitcnt lgkmcnt(1)
	v_mfma_f32_32x32x16_bf16 v[48:63], v[116:119], v[120:123], v[48:63]
	s_waitcnt lgkmcnt(0)
	v_mfma_f32_32x32x16_bf16 v[32:47], v[116:119], v[162:165], v[32:47]
	ds_read_b128 v[116:119], v167 offset:23072
	s_waitcnt vmcnt(15)
	ds_write_b128 v130, v[124:127] offset:36864
	s_waitcnt vmcnt(14)
	ds_write_b128 v130, v[154:157] offset:55296
	s_waitcnt lgkmcnt(2)
	v_mfma_f32_32x32x16_bf16 v[16:31], v[116:119], v[120:123], v[16:31]
	v_mfma_f32_32x32x16_bf16 v[0:15], v[116:119], v[162:165], v[0:15]
	ds_read_b128 v[116:119], v167 offset:18496
	ds_read_b128 v[120:123], v132 offset:64
	ds_read_b128 v[124:127], v132 offset:4672
	s_waitcnt lgkmcnt(1)
	v_mfma_f32_32x32x16_bf16 v[48:63], v[116:119], v[120:123], v[48:63]
	s_waitcnt lgkmcnt(0)
	v_mfma_f32_32x32x16_bf16 v[32:47], v[116:119], v[124:127], v[32:47]
	ds_read_b128 v[116:119], v167 offset:23104
	s_waitcnt vmcnt(13)
	ds_write_b128 v130, v[96:99] offset:41472
	s_waitcnt vmcnt(12)
	ds_write_b128 v130, v[100:103] offset:59904
	ds_read_b128 v[96:99], v167 offset:18528
	ds_read_b128 v[100:103], v132 offset:96
	s_waitcnt lgkmcnt(4)
	v_mfma_f32_32x32x16_bf16 v[16:31], v[116:119], v[120:123], v[16:31]
	ds_read_b128 v[120:123], v167 offset:23136
	v_mfma_f32_32x32x16_bf16 v[0:15], v[116:119], v[124:127], v[0:15]
	ds_read_b128 v[116:119], v132 offset:4704
	s_waitcnt lgkmcnt(2)
	v_mfma_f32_32x32x16_bf16 v[48:63], v[96:99], v[100:103], v[48:63]
	s_waitcnt lgkmcnt(0)
	v_mfma_f32_32x32x16_bf16 v[32:47], v[96:99], v[116:119], v[32:47]
	v_mfma_f32_32x32x16_bf16 v[16:31], v[120:123], v[100:103], v[16:31]
	global_load_dwordx4 v[124:127], v[112:113], off offset:2176
	global_load_dwordx4 v[154:157], v[114:115], off offset:2176
	global_load_dwordx4 v[96:99], v[138:139], off offset:2176
	global_load_dwordx4 v[100:103], v[140:141], off offset:2176
	s_waitcnt vmcnt(15)
	ds_write_b128 v130, v[80:83] offset:46080
	s_waitcnt vmcnt(14)
	ds_write_b128 v130, v[84:87] offset:64512
	global_load_dwordx4 v[80:83], v[142:143], off offset:2176
	global_load_dwordx4 v[84:87], v[144:145], off offset:2176
	s_waitcnt vmcnt(15)
	ds_write_b128 v130, v[88:91] offset:50688
	s_waitcnt vmcnt(14)
	ds_write_b128 v131, v[92:95] offset:13824
	global_load_dwordx4 v[88:91], v[146:147], off offset:2176
	global_load_dwordx4 v[92:95], v[148:149], off offset:2176
	s_waitcnt lgkmcnt(0)
	s_barrier
; #define GLOADQ(RA, RB, KT, q) do { const int k0_ = (KT) << 6; \
;     RA[q] = ldg16(ap.ptr(m0 + lrow + 32 * (q), k0_) + lkc); RB[q] = ldg16(W + (size_t)(n0 + lrow + 32 * (q)) * ldw + k0_ + lkc); } while (0)
; #define SSTOREQ(RA, RB, ST, q) do { \
;     *(u32x4*)(sA + (ST) * SBUF + (lrow + 32 * (q)) * GP + lkc) = RA[q]; *(u32x4*)(sB + (ST) * SBUF + (lrow + 32 * (q)) * GP + lkc) = RB[q]; } while (0)
; #define FLOAD(F, ST, ks) do { _Pragma("unroll") for (int a = 0; a < 2; ++a) { \
;     F[a] = *(const bf16x8*)(sB + (ST) * SBUF + (wn * 64 + a * 32 + r) * GP + (ks) * 16 + h * 8); \
;     F[2 + a] = *(const bf16x8*)(sA + (ST) * SBUF + (wm * 64 + a * 32 + r) * GP + (ks) * 16 + h * 8); } } while (0)
; #define FMMA(F) do { _Pragma("unroll") for (int a = 0; a < 2; ++a) _Pragma("unroll") for (int b = 0; b < 2; ++b) acc[a][b] = MFMA(F[a], F[2 + b], acc[a][b]); } while (0)
; template <bool MIDK, class AP, class EPI>
; DI void gemm_tile(const AP& ap, const u16* __restrict__ W, int ldw, int K, int m0, int n0, const EPI& epi, char* smem, float r0, float r1, int tid, bool dry) {
;     ...
;   for (int kt = 0; kt < nk; kt += 2) {
;     const bool l3 = kt + 3 < nk, s2 = kt + 2 < nk, l4 = kt + 4 < nk;
;     FLOAD(f0, 0, 0); FLOAD(f1, 0, 1);
;     FMMA(f0); SSTOREQ(ra1, rb1, 1, 0); if (l3) GLOADQ(ra1, rb1, kt + 3, 0);
;     FLOAD(f0, 0, 2);
;     FMMA(f1); SSTOREQ(ra1, rb1, 1, 1); if (l3) GLOADQ(ra1, rb1, kt + 3, 1);
;     FLOAD(f1, 0, 3);
;     FMMA(f0); SSTOREQ(ra1, rb1, 1, 2); if (l3) GLOADQ(ra1, rb1, kt + 3, 2);
;     FMMA(f1); SSTOREQ(ra1, rb1, 1, 3); if (l3) GLOADQ(ra1, rb1, kt + 3, 3);
;     __syncthreads();
;     FLOAD(f0, 1, 0); FLOAD(f1, 1, 1);
;     FMMA(f0); if (s2) SSTOREQ(ra0, rb0, 0, 0); if (l4) GLOADQ(ra0, rb0, kt + 4, 0);
;     FLOAD(f0, 1, 2);
;     FMMA(f1); if (s2) SSTOREQ(ra0, rb0, 0, 1); if (l4) GLOADQ(ra0, rb0, kt + 4, 1);
;     FLOAD(f1, 1, 3);
;     FMMA(f0); if (s2) SSTOREQ(ra0, rb0, 0, 2); if (l4) GLOADQ(ra0, rb0, kt + 4, 2);
;     FMMA(f1); if (s2) SSTOREQ(ra0, rb0, 0, 3); if (l4) GLOADQ(ra0, rb0, kt + 4, 3);
;     if (MIDK && kt == 6) {
; #pragma unroll
;       for (int a = 0; a < 2; ++a)
; #pragma unroll
;         for (int i = 0; i < 16; ++i) { acc[a][0][i] *= r0; acc[a][1][i] *= r1; }
;     }
;     __syncthreads();
;   }
	v_mfma_f32_32x32x16_bf16 v[0:15], v[120:123], v[116:119], v[0:15]
	ds_read_b128 v[116:119], v167 offset:55296
	ds_read_b128 v[120:123], v132 offset:36864
	ds_read_b128 v[162:165], v132 offset:41472
	s_waitcnt lgkmcnt(1)
	v_mfma_f32_32x32x16_bf16 v[48:63], v[116:119], v[120:123], v[48:63]
	s_waitcnt lgkmcnt(0)
	v_mfma_f32_32x32x16_bf16 v[32:47], v[116:119], v[162:165], v[32:47]
	ds_read_b128 v[116:119], v167 offset:59904
	s_waitcnt lgkmcnt(0)
	v_mfma_f32_32x32x16_bf16 v[16:31], v[116:119], v[120:123], v[16:31]
	v_mfma_f32_32x32x16_bf16 v[0:15], v[116:119], v[162:165], v[0:15]
	ds_read_b128 v[116:119], v167 offset:55328
	ds_read_b128 v[120:123], v132 offset:36896
	ds_read_b128 v[162:165], v132 offset:41504
	s_waitcnt lgkmcnt(1)
	v_mfma_f32_32x32x16_bf16 v[48:63], v[116:119], v[120:123], v[48:63]
	s_waitcnt lgkmcnt(0)
	v_mfma_f32_32x32x16_bf16 v[32:47], v[116:119], v[162:165], v[32:47]
	ds_read_b128 v[116:119], v167 offset:59936
	s_waitcnt vmcnt(15)
	ds_write_b128 v130, v[150:153]
	s_waitcnt vmcnt(14)
	ds_write_b128 v130, v[158:161] offset:18432
	s_waitcnt lgkmcnt(2)
	v_mfma_f32_32x32x16_bf16 v[16:31], v[116:119], v[120:123], v[16:31]
	v_mfma_f32_32x32x16_bf16 v[0:15], v[116:119], v[162:165], v[0:15]
	ds_read_b128 v[116:119], v167 offset:55360
	ds_read_b128 v[120:123], v132 offset:36928
	ds_read_b128 v[150:153], v132 offset:41536
	s_waitcnt lgkmcnt(1)
	v_mfma_f32_32x32x16_bf16 v[48:63], v[116:119], v[120:123], v[48:63]
	s_waitcnt lgkmcnt(0)
	v_mfma_f32_32x32x16_bf16 v[32:47], v[116:119], v[150:153], v[32:47]
	ds_read_b128 v[116:119], v167 offset:59968
	s_waitcnt vmcnt(13)
	ds_write_b128 v130, v[104:107] offset:4608
	s_waitcnt vmcnt(12)
	ds_write_b128 v130, v[108:111] offset:23040
	ds_read_b128 v[104:107], v167 offset:55392
	ds_read_b128 v[108:111], v132 offset:36960
	s_waitcnt lgkmcnt(4)
	v_mfma_f32_32x32x16_bf16 v[16:31], v[116:119], v[120:123], v[16:31]
	ds_read_b128 v[120:123], v167 offset:60000
	v_mfma_f32_32x32x16_bf16 v[0:15], v[116:119], v[150:153], v[0:15]
	ds_read_b128 v[116:119], v132 offset:41568
	s_waitcnt lgkmcnt(2)
	v_mfma_f32_32x32x16_bf16 v[48:63], v[104:107], v[108:111], v[48:63]
	s_waitcnt lgkmcnt(0)
	v_mfma_f32_32x32x16_bf16 v[32:47], v[104:107], v[116:119], v[32:47]
	v_mfma_f32_32x32x16_bf16 v[16:31], v[120:123], v[108:111], v[16:31]
	global_load_dwordx4 v[150:153], v[112:113], off offset:2304
	global_load_dwordx4 v[158:161], v[114:115], off offset:2304
	global_load_dwordx4 v[104:107], v[138:139], off offset:2304
	global_load_dwordx4 v[108:111], v[140:141], off offset:2304
	s_waitcnt vmcnt(15)
	ds_write_b128 v130, v[64:67] offset:9216
	s_waitcnt vmcnt(14)
	ds_write_b128 v130, v[68:71] offset:27648
	global_load_dwordx4 v[64:67], v[142:143], off offset:2304
	global_load_dwordx4 v[68:71], v[144:145], off offset:2304
	s_waitcnt vmcnt(15)
	ds_write_b128 v130, v[72:75] offset:13824
	s_waitcnt vmcnt(14)
	ds_write_b128 v130, v[76:79] offset:32256
	global_load_dwordx4 v[72:75], v[146:147], off offset:2304
	global_load_dwordx4 v[76:79], v[148:149], off offset:2304
	s_waitcnt lgkmcnt(0)
	s_barrier
	v_mfma_f32_32x32x16_bf16 v[0:15], v[120:123], v[116:119], v[0:15]
	ds_read_b128 v[116:119], v167 offset:18432
	ds_read_b128 v[120:123], v132
	ds_read_b128 v[162:165], v132 offset:4608
	s_waitcnt lgkmcnt(1)
	v_mfma_f32_32x32x16_bf16 v[48:63], v[116:119], v[120:123], v[48:63]
	s_waitcnt lgkmcnt(0)
	v_mfma_f32_32x32x16_bf16 v[32:47], v[116:119], v[162:165], v[32:47]
	ds_read_b128 v[116:119], v167 offset:23040
	s_waitcnt lgkmcnt(0)
	v_mfma_f32_32x32x16_bf16 v[16:31], v[116:119], v[120:123], v[16:31]
	v_mfma_f32_32x32x16_bf16 v[0:15], v[116:119], v[162:165], v[0:15]
	ds_read_b128 v[116:119], v167 offset:18464
	ds_read_b128 v[120:123], v132 offset:32
	ds_read_b128 v[162:165], v132 offset:4640
	s_waitcnt lgkmcnt(1)
	v_mfma_f32_32x32x16_bf16 v[48:63], v[116:119], v[120:123], v[48:63]
	s_waitcnt lgkmcnt(0)
	v_mfma_f32_32x32x16_bf16 v[32:47], v[116:119], v[162:165], v[32:47]
	ds_read_b128 v[116:119], v167 offset:23072
	s_waitcnt vmcnt(15)
	ds_write_b128 v130, v[124:127] offset:36864
	s_waitcnt vmcnt(14)
	ds_write_b128 v130, v[154:157] offset:55296
	s_waitcnt lgkmcnt(2)
	v_mfma_f32_32x32x16_bf16 v[16:31], v[116:119], v[120:123], v[16:31]
	v_mfma_f32_32x32x16_bf16 v[0:15], v[116:119], v[162:165], v[0:15]
	ds_read_b128 v[116:119], v167 offset:18496
	ds_read_b128 v[120:123], v132 offset:64
	ds_read_b128 v[124:127], v132 offset:4672
	s_waitcnt lgkmcnt(1)
	v_mfma_f32_32x32x16_bf16 v[48:63], v[116:119], v[120:123], v[48:63]
	s_waitcnt lgkmcnt(0)
	v_mfma_f32_32x32x16_bf16 v[32:47], v[116:119], v[124:127], v[32:47]
	ds_read_b128 v[116:119], v167 offset:23104
	s_waitcnt vmcnt(13)
	ds_write_b128 v130, v[96:99] offset:41472
	s_waitcnt vmcnt(12)
	ds_write_b128 v130, v[100:103] offset:59904
	ds_read_b128 v[96:99], v167 offset:18528
	ds_read_b128 v[100:103], v132 offset:96
	s_waitcnt lgkmcnt(4)
	v_mfma_f32_32x32x16_bf16 v[16:31], v[116:119], v[120:123], v[16:31]
	ds_read_b128 v[120:123], v167 offset:23136
	v_mfma_f32_32x32x16_bf16 v[0:15], v[116:119], v[124:127], v[0:15]
	ds_read_b128 v[116:119], v132 offset:4704
	s_waitcnt lgkmcnt(2)
	v_mfma_f32_32x32x16_bf16 v[48:63], v[96:99], v[100:103], v[48:63]
	s_waitcnt lgkmcnt(0)
	v_mfma_f32_32x32x16_bf16 v[32:47], v[96:99], v[116:119], v[32:47]
	v_mfma_f32_32x32x16_bf16 v[16:31], v[120:123], v[100:103], v[16:31]
	global_load_dwordx4 v[124:127], v[112:113], off offset:2432
	global_load_dwordx4 v[154:157], v[114:115], off offset:2432
	global_load_dwordx4 v[96:99], v[138:139], off offset:2432
	global_load_dwordx4 v[100:103], v[140:141], off offset:2432
	s_waitcnt vmcnt(15)
	ds_write_b128 v130, v[80:83] offset:46080
	s_waitcnt vmcnt(14)
	ds_write_b128 v130, v[84:87] offset:64512
	global_load_dwordx4 v[80:83], v[142:143], off offset:2432
	global_load_dwordx4 v[84:87], v[144:145], off offset:2432
	s_waitcnt vmcnt(15)
	ds_write_b128 v130, v[88:91] offset:50688
	s_waitcnt vmcnt(14)
	ds_write_b128 v131, v[92:95] offset:13824
	global_load_dwordx4 v[88:91], v[146:147], off offset:2432
	global_load_dwordx4 v[92:95], v[148:149], off offset:2432
	s_waitcnt lgkmcnt(0)
	s_barrier
; #define GLOADQ(RA, RB, KT, q) do { const int k0_ = (KT) << 6; \
;     RA[q] = ldg16(ap.ptr(m0 + lrow + 32 * (q), k0_) + lkc); RB[q] = ldg16(W + (size_t)(n0 + lrow + 32 * (q)) * ldw + k0_ + lkc); } while (0)
; #define SSTOREQ(RA, RB, ST, q) do { \
;     *(u32x4*)(sA + (ST) * SBUF + (lrow + 32 * (q)) * GP + lkc) = RA[q]; *(u32x4*)(sB + (ST) * SBUF + (lrow + 32 * (q)) * GP + lkc) = RB[q]; } while (0)
; #define FLOAD(F, ST, ks) do { _Pragma("unroll") for (int a = 0; a < 2; ++a) { \
;     F[a] = *(const bf16x8*)(sB + (ST) * SBUF + (wn * 64 + a * 32 + r) * GP + (ks) * 16 + h * 8); \
;     F[2 + a] = *(const bf16x8*)(sA + (ST) * SBUF + (wm * 64 + a * 32 + r) * GP + (ks) * 16 + h * 8); } } while (0)
; #define FMMA(F) do { _Pragma("unroll") for (int a = 0; a < 2; ++a) _Pragma("unroll") for (int b = 0; b < 2; ++b) acc[a][b] = MFMA(F[a], F[2 + b], acc[a][b]); } while (0)
; template <bool MIDK, class AP, class EPI>
; DI void gemm_tile(const AP& ap, const u16* __restrict__ W, int ldw, int K, int m0, int n0, const EPI& epi, char* smem, float r0, float r1, int tid, bool dry) {
;     ...
;   for (int kt = 0; kt < nk; kt += 2) {
;     const bool l3 = kt + 3 < nk, s2 = kt + 2 < nk, l4 = kt + 4 < nk;
;     FLOAD(f0, 0, 0); FLOAD(f1, 0, 1);
;     FMMA(f0); SSTOREQ(ra1, rb1, 1, 0); if (l3) GLOADQ(ra1, rb1, kt + 3, 0);
;     FLOAD(f0, 0, 2);
;     FMMA(f1); SSTOREQ(ra1, rb1, 1, 1); if (l3) GLOADQ(ra1, rb1, kt + 3, 1);
;     FLOAD(f1, 0, 3);
;     FMMA(f0); SSTOREQ(ra1, rb1, 1, 2); if (l3) GLOADQ(ra1, rb1, kt + 3, 2);
;     FMMA(f1); SSTOREQ(ra1, rb1, 1, 3); if (l3) GLOADQ(ra1, rb1, kt + 3, 3);
;     __syncthreads();
;     FLOAD(f0, 1, 0); FLOAD(f1, 1, 1);
;     FMMA(f0); if (s2) SSTOREQ(ra0, rb0, 0, 0); if (l4) GLOADQ(ra0, rb0, kt + 4, 0);
;     FLOAD(f0, 1, 2);
;     FMMA(f1); if (s2) SSTOREQ(ra0, rb0, 0, 1); if (l4) GLOADQ(ra0, rb0, kt + 4, 1);
;     FLOAD(f1, 1, 3);
;     FMMA(f0); if (s2) SSTOREQ(ra0, rb0, 0, 2); if (l4) GLOADQ(ra0, rb0, kt + 4, 2);
;     FMMA(f1); if (s2) SSTOREQ(ra0, rb0, 0, 3); if (l4) GLOADQ(ra0, rb0, kt + 4, 3);
;     if (MIDK && kt == 6) {
; #pragma unroll
;       for (int a = 0; a < 2; ++a)
; #pragma unroll
;         for (int i = 0; i < 16; ++i) { acc[a][0][i] *= r0; acc[a][1][i] *= r1; }
;     }
;     __syncthreads();
;   }
	v_mfma_f32_32x32x16_bf16 v[0:15], v[120:123], v[116:119], v[0:15]
	ds_read_b128 v[116:119], v167 offset:55296
	ds_read_b128 v[120:123], v132 offset:36864
	ds_read_b128 v[162:165], v132 offset:41472
	s_waitcnt lgkmcnt(1)
	v_mfma_f32_32x32x16_bf16 v[48:63], v[116:119], v[120:123], v[48:63]
	s_waitcnt lgkmcnt(0)
	v_mfma_f32_32x32x16_bf16 v[32:47], v[116:119], v[162:165], v[32:47]
	ds_read_b128 v[116:119], v167 offset:59904
	s_waitcnt lgkmcnt(0)
	v_mfma_f32_32x32x16_bf16 v[16:31], v[116:119], v[120:123], v[16:31]
	v_mfma_f32_32x32x16_bf16 v[0:15], v[116:119], v[162:165], v[0:15]
	ds_read_b128 v[116:119], v167 offset:55328
	ds_read_b128 v[120:123], v132 offset:36896
	ds_read_b128 v[162:165], v132 offset:41504
	s_waitcnt lgkmcnt(1)
	v_mfma_f32_32x32x16_bf16 v[48:63], v[116:119], v[120:123], v[48:63]
	s_waitcnt lgkmcnt(0)
	v_mfma_f32_32x32x16_bf16 v[32:47], v[116:119], v[162:165], v[32:47]
	ds_read_b128 v[116:119], v167 offset:59936
	s_waitcnt vmcnt(15)
	ds_write_b128 v130, v[150:153]
	s_waitcnt vmcnt(14)
	ds_write_b128 v130, v[158:161] offset:18432
	s_waitcnt lgkmcnt(2)
	v_mfma_f32_32x32x16_bf16 v[16:31], v[116:119], v[120:123], v[16:31]
	v_mfma_f32_32x32x16_bf16 v[0:15], v[116:119], v[162:165], v[0:15]
	ds_read_b128 v[116:119], v167 offset:55360
	ds_read_b128 v[120:123], v132 offset:36928
	ds_read_b128 v[150:153], v132 offset:41536
	s_waitcnt lgkmcnt(1)
	v_mfma_f32_32x32x16_bf16 v[48:63], v[116:119], v[120:123], v[48:63]
	s_waitcnt lgkmcnt(0)
	v_mfma_f32_32x32x16_bf16 v[32:47], v[116:119], v[150:153], v[32:47]
	ds_read_b128 v[116:119], v167 offset:59968
	s_waitcnt vmcnt(13)
	ds_write_b128 v130, v[104:107] offset:4608
	s_waitcnt vmcnt(12)
	ds_write_b128 v130, v[108:111] offset:23040
	ds_read_b128 v[104:107], v167 offset:55392
	ds_read_b128 v[108:111], v132 offset:36960
	s_waitcnt lgkmcnt(4)
	v_mfma_f32_32x32x16_bf16 v[16:31], v[116:119], v[120:123], v[16:31]
	ds_read_b128 v[120:123], v167 offset:60000
	v_mfma_f32_32x32x16_bf16 v[0:15], v[116:119], v[150:153], v[0:15]
	ds_read_b128 v[116:119], v132 offset:41568
	s_waitcnt lgkmcnt(2)
	v_mfma_f32_32x32x16_bf16 v[48:63], v[104:107], v[108:111], v[48:63]
	s_waitcnt lgkmcnt(0)
	v_mfma_f32_32x32x16_bf16 v[32:47], v[104:107], v[116:119], v[32:47]
	v_mfma_f32_32x32x16_bf16 v[16:31], v[120:123], v[108:111], v[16:31]
	global_load_dwordx4 v[150:153], v[112:113], off offset:2560
	global_load_dwordx4 v[158:161], v[114:115], off offset:2560
	global_load_dwordx4 v[104:107], v[138:139], off offset:2560
	global_load_dwordx4 v[108:111], v[140:141], off offset:2560
	s_waitcnt vmcnt(15)
	ds_write_b128 v130, v[64:67] offset:9216
	s_waitcnt vmcnt(14)
	ds_write_b128 v130, v[68:71] offset:27648
	global_load_dwordx4 v[64:67], v[142:143], off offset:2560
	global_load_dwordx4 v[68:71], v[144:145], off offset:2560
	s_waitcnt vmcnt(15)
	ds_write_b128 v130, v[72:75] offset:13824
	s_waitcnt vmcnt(14)
	ds_write_b128 v130, v[76:79] offset:32256
	global_load_dwordx4 v[72:75], v[146:147], off offset:2560
	global_load_dwordx4 v[76:79], v[148:149], off offset:2560
	s_waitcnt lgkmcnt(0)
	s_barrier
	v_mfma_f32_32x32x16_bf16 v[0:15], v[120:123], v[116:119], v[0:15]
	ds_read_b128 v[116:119], v167 offset:18432
	ds_read_b128 v[120:123], v132
	ds_read_b128 v[162:165], v132 offset:4608
	s_waitcnt lgkmcnt(1)
	v_mfma_f32_32x32x16_bf16 v[48:63], v[116:119], v[120:123], v[48:63]
	s_waitcnt lgkmcnt(0)
	v_mfma_f32_32x32x16_bf16 v[32:47], v[116:119], v[162:165], v[32:47]
	ds_read_b128 v[116:119], v167 offset:23040
	s_waitcnt lgkmcnt(0)
	v_mfma_f32_32x32x16_bf16 v[16:31], v[116:119], v[120:123], v[16:31]
	v_mfma_f32_32x32x16_bf16 v[0:15], v[116:119], v[162:165], v[0:15]
	ds_read_b128 v[116:119], v167 offset:18464
	ds_read_b128 v[120:123], v132 offset:32
	ds_read_b128 v[162:165], v132 offset:4640
	s_waitcnt lgkmcnt(1)
	v_mfma_f32_32x32x16_bf16 v[48:63], v[116:119], v[120:123], v[48:63]
	s_waitcnt lgkmcnt(0)
	v_mfma_f32_32x32x16_bf16 v[32:47], v[116:119], v[162:165], v[32:47]
	ds_read_b128 v[116:119], v167 offset:23072
	s_waitcnt vmcnt(15)
	ds_write_b128 v130, v[124:127] offset:36864
	s_waitcnt vmcnt(14)
	ds_write_b128 v130, v[154:157] offset:55296
	s_waitcnt lgkmcnt(2)
	v_mfma_f32_32x32x16_bf16 v[16:31], v[116:119], v[120:123], v[16:31]
	v_mfma_f32_32x32x16_bf16 v[0:15], v[116:119], v[162:165], v[0:15]
	ds_read_b128 v[116:119], v167 offset:18496
	ds_read_b128 v[120:123], v132 offset:64
	ds_read_b128 v[124:127], v132 offset:4672
	s_waitcnt lgkmcnt(1)
	v_mfma_f32_32x32x16_bf16 v[48:63], v[116:119], v[120:123], v[48:63]
	s_waitcnt lgkmcnt(0)
	v_mfma_f32_32x32x16_bf16 v[32:47], v[116:119], v[124:127], v[32:47]
	ds_read_b128 v[116:119], v167 offset:23104
	s_waitcnt vmcnt(13)
	ds_write_b128 v130, v[96:99] offset:41472
	s_waitcnt vmcnt(12)
	ds_write_b128 v130, v[100:103] offset:59904
	ds_read_b128 v[96:99], v167 offset:18528
	ds_read_b128 v[100:103], v132 offset:96
	s_waitcnt lgkmcnt(4)
	v_mfma_f32_32x32x16_bf16 v[16:31], v[116:119], v[120:123], v[16:31]
	ds_read_b128 v[120:123], v167 offset:23136
	v_mfma_f32_32x32x16_bf16 v[0:15], v[116:119], v[124:127], v[0:15]
	ds_read_b128 v[116:119], v132 offset:4704
	s_waitcnt lgkmcnt(2)
	v_mfma_f32_32x32x16_bf16 v[48:63], v[96:99], v[100:103], v[48:63]
	s_waitcnt lgkmcnt(0)
	v_mfma_f32_32x32x16_bf16 v[32:47], v[96:99], v[116:119], v[32:47]
	v_mfma_f32_32x32x16_bf16 v[16:31], v[120:123], v[100:103], v[16:31]
	global_load_dwordx4 v[124:127], v[112:113], off offset:2688
	global_load_dwordx4 v[154:157], v[114:115], off offset:2688
	global_load_dwordx4 v[96:99], v[138:139], off offset:2688
	global_load_dwordx4 v[100:103], v[140:141], off offset:2688
	s_waitcnt vmcnt(15)
	ds_write_b128 v130, v[80:83] offset:46080
	s_waitcnt vmcnt(14)
	ds_write_b128 v130, v[84:87] offset:64512
	global_load_dwordx4 v[80:83], v[142:143], off offset:2688
	global_load_dwordx4 v[84:87], v[144:145], off offset:2688
	s_waitcnt vmcnt(15)
	ds_write_b128 v130, v[88:91] offset:50688
	s_waitcnt vmcnt(14)
	ds_write_b128 v131, v[92:95] offset:13824
	global_load_dwordx4 v[88:91], v[146:147], off offset:2688
	global_load_dwordx4 v[92:95], v[148:149], off offset:2688
	s_waitcnt lgkmcnt(0)
	s_barrier
; #define GLOADQ(RA, RB, KT, q) do { const int k0_ = (KT) << 6; \
;     RA[q] = ldg16(ap.ptr(m0 + lrow + 32 * (q), k0_) + lkc); RB[q] = ldg16(W + (size_t)(n0 + lrow + 32 * (q)) * ldw + k0_ + lkc); } while (0)
; #define SSTOREQ(RA, RB, ST, q) do { \
;     *(u32x4*)(sA + (ST) * SBUF + (lrow + 32 * (q)) * GP + lkc) = RA[q]; *(u32x4*)(sB + (ST) * SBUF + (lrow + 32 * (q)) * GP + lkc) = RB[q]; } while (0)
; #define FLOAD(F, ST, ks) do { _Pragma("unroll") for (int a = 0; a < 2; ++a) { \
;     F[a] = *(const bf16x8*)(sB + (ST) * SBUF + (wn * 64 + a * 32 + r) * GP + (ks) * 16 + h * 8); \
;     F[2 + a] = *(const bf16x8*)(sA + (ST) * SBUF + (wm * 64 + a * 32 + r) * GP + (ks) * 16 + h * 8); } } while (0)
; #define FMMA(F) do { _Pragma("unroll") for (int a = 0; a < 2; ++a) _Pragma("unroll") for (int b = 0; b < 2; ++b) acc[a][b] = MFMA(F[a], F[2 + b], acc[a][b]); } while (0)
; template <bool MIDK, class AP, class EPI>
; DI void gemm_tile(const AP& ap, const u16* __restrict__ W, int ldw, int K, int m0, int n0, const EPI& epi, char* smem, float r0, float r1, int tid, bool dry) {
;     ...
;   for (int kt = 0; kt < nk; kt += 2) {
;     const bool l3 = kt + 3 < nk, s2 = kt + 2 < nk, l4 = kt + 4 < nk;
;     FLOAD(f0, 0, 0); FLOAD(f1, 0, 1);
;     FMMA(f0); SSTOREQ(ra1, rb1, 1, 0); if (l3) GLOADQ(ra1, rb1, kt + 3, 0);
;     FLOAD(f0, 0, 2);
;     FMMA(f1); SSTOREQ(ra1, rb1, 1, 1); if (l3) GLOADQ(ra1, rb1, kt + 3, 1);
;     FLOAD(f1, 0, 3);
;     FMMA(f0); SSTOREQ(ra1, rb1, 1, 2); if (l3) GLOADQ(ra1, rb1, kt + 3, 2);
;     FMMA(f1); SSTOREQ(ra1, rb1, 1, 3); if (l3) GLOADQ(ra1, rb1, kt + 3, 3);
;     __syncthreads();
;     FLOAD(f0, 1, 0); FLOAD(f1, 1, 1);
;     FMMA(f0); if (s2) SSTOREQ(ra0, rb0, 0, 0); if (l4) GLOADQ(ra0, rb0, kt + 4, 0);
;     FLOAD(f0, 1, 2);
;     FMMA(f1); if (s2) SSTOREQ(ra0, rb0, 0, 1); if (l4) GLOADQ(ra0, rb0, kt + 4, 1);
;     FLOAD(f1, 1, 3);
;     FMMA(f0); if (s2) SSTOREQ(ra0, rb0, 0, 2); if (l4) GLOADQ(ra0, rb0, kt + 4, 2);
;     FMMA(f1); if (s2) SSTOREQ(ra0, rb0, 0, 3); if (l4) GLOADQ(ra0, rb0, kt + 4, 3);
;     if (MIDK && kt == 6) {
; #pragma unroll
;       for (int a = 0; a < 2; ++a)
; #pragma unroll
;         for (int i = 0; i < 16; ++i) { acc[a][0][i] *= r0; acc[a][1][i] *= r1; }
;     }
;     __syncthreads();
;   }
	v_mfma_f32_32x32x16_bf16 v[0:15], v[120:123], v[116:119], v[0:15]
	ds_read_b128 v[116:119], v167 offset:55296
	ds_read_b128 v[120:123], v132 offset:36864
	ds_read_b128 v[162:165], v132 offset:41472
	s_waitcnt lgkmcnt(1)
	v_mfma_f32_32x32x16_bf16 v[48:63], v[116:119], v[120:123], v[48:63]
	s_waitcnt lgkmcnt(0)
	v_mfma_f32_32x32x16_bf16 v[32:47], v[116:119], v[162:165], v[32:47]
	ds_read_b128 v[116:119], v167 offset:59904
	s_waitcnt lgkmcnt(0)
	v_mfma_f32_32x32x16_bf16 v[16:31], v[116:119], v[120:123], v[16:31]
	v_mfma_f32_32x32x16_bf16 v[0:15], v[116:119], v[162:165], v[0:15]
	ds_read_b128 v[116:119], v167 offset:55328
	ds_read_b128 v[120:123], v132 offset:36896
	ds_read_b128 v[162:165], v132 offset:41504
	s_waitcnt lgkmcnt(1)
	v_mfma_f32_32x32x16_bf16 v[48:63], v[116:119], v[120:123], v[48:63]
	s_waitcnt lgkmcnt(0)
	v_mfma_f32_32x32x16_bf16 v[32:47], v[116:119], v[162:165], v[32:47]
	ds_read_b128 v[116:119], v167 offset:59936
	s_waitcnt vmcnt(15)
	ds_write_b128 v130, v[150:153]
	s_waitcnt vmcnt(14)
	ds_write_b128 v130, v[158:161] offset:18432
	s_waitcnt lgkmcnt(2)
	v_mfma_f32_32x32x16_bf16 v[16:31], v[116:119], v[120:123], v[16:31]
	v_mfma_f32_32x32x16_bf16 v[0:15], v[116:119], v[162:165], v[0:15]
	ds_read_b128 v[116:119], v167 offset:55360
	ds_read_b128 v[120:123], v132 offset:36928
	ds_read_b128 v[150:153], v132 offset:41536
	s_waitcnt lgkmcnt(1)
	v_mfma_f32_32x32x16_bf16 v[48:63], v[116:119], v[120:123], v[48:63]
	s_waitcnt lgkmcnt(0)
	v_mfma_f32_32x32x16_bf16 v[32:47], v[116:119], v[150:153], v[32:47]
	ds_read_b128 v[116:119], v167 offset:59968
	s_waitcnt vmcnt(13)
	ds_write_b128 v130, v[104:107] offset:4608
	s_waitcnt vmcnt(12)
	ds_write_b128 v130, v[108:111] offset:23040
	ds_read_b128 v[104:107], v167 offset:55392
	ds_read_b128 v[108:111], v132 offset:36960
	s_waitcnt lgkmcnt(4)
	v_mfma_f32_32x32x16_bf16 v[16:31], v[116:119], v[120:123], v[16:31]
	ds_read_b128 v[120:123], v167 offset:60000
	v_mfma_f32_32x32x16_bf16 v[0:15], v[116:119], v[150:153], v[0:15]
	ds_read_b128 v[116:119], v132 offset:41568
	s_waitcnt lgkmcnt(2)
	v_mfma_f32_32x32x16_bf16 v[48:63], v[104:107], v[108:111], v[48:63]
	s_waitcnt lgkmcnt(0)
	v_mfma_f32_32x32x16_bf16 v[32:47], v[104:107], v[116:119], v[32:47]
	v_mfma_f32_32x32x16_bf16 v[16:31], v[120:123], v[108:111], v[16:31]
	global_load_dwordx4 v[150:153], v[112:113], off offset:2816
	global_load_dwordx4 v[158:161], v[114:115], off offset:2816
	global_load_dwordx4 v[104:107], v[138:139], off offset:2816
	global_load_dwordx4 v[108:111], v[140:141], off offset:2816
	s_waitcnt vmcnt(15)
	ds_write_b128 v130, v[64:67] offset:9216
	s_waitcnt vmcnt(14)
	ds_write_b128 v130, v[68:71] offset:27648
	global_load_dwordx4 v[64:67], v[142:143], off offset:2816
	global_load_dwordx4 v[68:71], v[144:145], off offset:2816
	s_waitcnt vmcnt(15)
	ds_write_b128 v130, v[72:75] offset:13824
	s_waitcnt vmcnt(14)
	ds_write_b128 v130, v[76:79] offset:32256
	global_load_dwordx4 v[72:75], v[146:147], off offset:2816
	global_load_dwordx4 v[76:79], v[148:149], off offset:2816
	s_waitcnt lgkmcnt(0)
	s_barrier
	v_mfma_f32_32x32x16_bf16 v[0:15], v[120:123], v[116:119], v[0:15]
	ds_read_b128 v[116:119], v167 offset:18432
	ds_read_b128 v[120:123], v132
	ds_read_b128 v[162:165], v132 offset:4608
	s_waitcnt lgkmcnt(1)
	v_mfma_f32_32x32x16_bf16 v[48:63], v[116:119], v[120:123], v[48:63]
	s_waitcnt lgkmcnt(0)
	v_mfma_f32_32x32x16_bf16 v[32:47], v[116:119], v[162:165], v[32:47]
	ds_read_b128 v[116:119], v167 offset:23040
	s_waitcnt lgkmcnt(0)
	v_mfma_f32_32x32x16_bf16 v[16:31], v[116:119], v[120:123], v[16:31]
	v_mfma_f32_32x32x16_bf16 v[0:15], v[116:119], v[162:165], v[0:15]
	ds_read_b128 v[116:119], v167 offset:18464
	ds_read_b128 v[120:123], v132 offset:32
	ds_read_b128 v[162:165], v132 offset:4640
	s_waitcnt lgkmcnt(1)
	v_mfma_f32_32x32x16_bf16 v[48:63], v[116:119], v[120:123], v[48:63]
	s_waitcnt lgkmcnt(0)
	v_mfma_f32_32x32x16_bf16 v[32:47], v[116:119], v[162:165], v[32:47]
	ds_read_b128 v[116:119], v167 offset:23072
	s_waitcnt vmcnt(15)
	ds_write_b128 v130, v[124:127] offset:36864
	s_waitcnt vmcnt(14)
	ds_write_b128 v130, v[154:157] offset:55296
	s_waitcnt lgkmcnt(2)
	v_mfma_f32_32x32x16_bf16 v[16:31], v[116:119], v[120:123], v[16:31]
	v_mfma_f32_32x32x16_bf16 v[0:15], v[116:119], v[162:165], v[0:15]
	ds_read_b128 v[116:119], v167 offset:18496
	ds_read_b128 v[120:123], v132 offset:64
	ds_read_b128 v[124:127], v132 offset:4672
	s_waitcnt lgkmcnt(1)
	v_mfma_f32_32x32x16_bf16 v[48:63], v[116:119], v[120:123], v[48:63]
	s_waitcnt lgkmcnt(0)
	v_mfma_f32_32x32x16_bf16 v[32:47], v[116:119], v[124:127], v[32:47]
	ds_read_b128 v[116:119], v167 offset:23104
	s_waitcnt vmcnt(13)
	ds_write_b128 v130, v[96:99] offset:41472
	s_waitcnt vmcnt(12)
	ds_write_b128 v130, v[100:103] offset:59904
	ds_read_b128 v[96:99], v167 offset:18528
	ds_read_b128 v[100:103], v132 offset:96
	s_waitcnt lgkmcnt(4)
	v_mfma_f32_32x32x16_bf16 v[16:31], v[116:119], v[120:123], v[16:31]
	ds_read_b128 v[120:123], v167 offset:23136
	v_mfma_f32_32x32x16_bf16 v[0:15], v[116:119], v[124:127], v[0:15]
	ds_read_b128 v[116:119], v132 offset:4704
	s_waitcnt lgkmcnt(2)
	v_mfma_f32_32x32x16_bf16 v[48:63], v[96:99], v[100:103], v[48:63]
	s_waitcnt lgkmcnt(0)
	v_mfma_f32_32x32x16_bf16 v[32:47], v[96:99], v[116:119], v[32:47]
	v_mfma_f32_32x32x16_bf16 v[16:31], v[120:123], v[100:103], v[16:31]
	global_load_dwordx4 v[124:127], v[112:113], off offset:2944
	global_load_dwordx4 v[154:157], v[114:115], off offset:2944
	global_load_dwordx4 v[96:99], v[138:139], off offset:2944
	global_load_dwordx4 v[100:103], v[140:141], off offset:2944
	s_waitcnt vmcnt(15)
	ds_write_b128 v130, v[80:83] offset:46080
	s_waitcnt vmcnt(14)
	ds_write_b128 v130, v[84:87] offset:64512
	global_load_dwordx4 v[80:83], v[142:143], off offset:2944
	global_load_dwordx4 v[84:87], v[144:145], off offset:2944
	s_waitcnt vmcnt(15)
	ds_write_b128 v130, v[88:91] offset:50688
	s_waitcnt vmcnt(14)
	ds_write_b128 v131, v[92:95] offset:13824
	global_load_dwordx4 v[88:91], v[146:147], off offset:2944
	global_load_dwordx4 v[92:95], v[148:149], off offset:2944
	s_waitcnt lgkmcnt(0)
	s_barrier
; #define GLOADQ(RA, RB, KT, q) do { const int k0_ = (KT) << 6; \
;     RA[q] = ldg16(ap.ptr(m0 + lrow + 32 * (q), k0_) + lkc); RB[q] = ldg16(W + (size_t)(n0 + lrow + 32 * (q)) * ldw + k0_ + lkc); } while (0)
; #define SSTOREQ(RA, RB, ST, q) do { \
;     *(u32x4*)(sA + (ST) * SBUF + (lrow + 32 * (q)) * GP + lkc) = RA[q]; *(u32x4*)(sB + (ST) * SBUF + (lrow + 32 * (q)) * GP + lkc) = RB[q]; } while (0)
; #define FLOAD(F, ST, ks) do { _Pragma("unroll") for (int a = 0; a < 2; ++a) { \
;     F[a] = *(const bf16x8*)(sB + (ST) * SBUF + (wn * 64 + a * 32 + r) * GP + (ks) * 16 + h * 8); \
;     F[2 + a] = *(const bf16x8*)(sA + (ST) * SBUF + (wm * 64 + a * 32 + r) * GP + (ks) * 16 + h * 8); } } while (0)
; #define FMMA(F) do { _Pragma("unroll") for (int a = 0; a < 2; ++a) _Pragma("unroll") for (int b = 0; b < 2; ++b) acc[a][b] = MFMA(F[a], F[2 + b], acc[a][b]); } while (0)
; template <bool MIDK, class AP, class EPI>
; DI void gemm_tile(const AP& ap, const u16* __restrict__ W, int ldw, int K, int m0, int n0, const EPI& epi, char* smem, float r0, float r1, int tid, bool dry) {
;     ...
;   for (int kt = 0; kt < nk; kt += 2) {
;     const bool l3 = kt + 3 < nk, s2 = kt + 2 < nk, l4 = kt + 4 < nk;
;     FLOAD(f0, 0, 0); FLOAD(f1, 0, 1);
;     FMMA(f0); SSTOREQ(ra1, rb1, 1, 0); if (l3) GLOADQ(ra1, rb1, kt + 3, 0);
;     FLOAD(f0, 0, 2);
;     FMMA(f1); SSTOREQ(ra1, rb1, 1, 1); if (l3) GLOADQ(ra1, rb1, kt + 3, 1);
;     FLOAD(f1, 0, 3);
;     FMMA(f0); SSTOREQ(ra1, rb1, 1, 2); if (l3) GLOADQ(ra1, rb1, kt + 3, 2);
;     FMMA(f1); SSTOREQ(ra1, rb1, 1, 3); if (l3) GLOADQ(ra1, rb1, kt + 3, 3);
;     __syncthreads();
;     FLOAD(f0, 1, 0); FLOAD(f1, 1, 1);
;     FMMA(f0); if (s2) SSTOREQ(ra0, rb0, 0, 0); if (l4) GLOADQ(ra0, rb0, kt + 4, 0);
;     FLOAD(f0, 1, 2);
;     FMMA(f1); if (s2) SSTOREQ(ra0, rb0, 0, 1); if (l4) GLOADQ(ra0, rb0, kt + 4, 1);
;     FLOAD(f1, 1, 3);
;     FMMA(f0); if (s2) SSTOREQ(ra0, rb0, 0, 2); if (l4) GLOADQ(ra0, rb0, kt + 4, 2);
;     FMMA(f1); if (s2) SSTOREQ(ra0, rb0, 0, 3); if (l4) GLOADQ(ra0, rb0, kt + 4, 3);
;     if (MIDK && kt == 6) {
; #pragma unroll
;       for (int a = 0; a < 2; ++a)
; #pragma unroll
;         for (int i = 0; i < 16; ++i) { acc[a][0][i] *= r0; acc[a][1][i] *= r1; }
;     }
;     __syncthreads();
;   }
	v_mfma_f32_32x32x16_bf16 v[0:15], v[120:123], v[116:119], v[0:15]
	ds_read_b128 v[116:119], v167 offset:55296
	ds_read_b128 v[120:123], v132 offset:36864
	ds_read_b128 v[162:165], v132 offset:41472
	s_waitcnt lgkmcnt(1)
	v_mfma_f32_32x32x16_bf16 v[48:63], v[116:119], v[120:123], v[48:63]
	s_waitcnt lgkmcnt(0)
	v_mfma_f32_32x32x16_bf16 v[32:47], v[116:119], v[162:165], v[32:47]
	ds_read_b128 v[116:119], v167 offset:59904
	s_waitcnt lgkmcnt(0)
	v_mfma_f32_32x32x16_bf16 v[16:31], v[116:119], v[120:123], v[16:31]
	v_mfma_f32_32x32x16_bf16 v[0:15], v[116:119], v[162:165], v[0:15]
	ds_read_b128 v[116:119], v167 offset:55328
	ds_read_b128 v[120:123], v132 offset:36896
	ds_read_b128 v[162:165], v132 offset:41504
	s_waitcnt lgkmcnt(1)
	v_mfma_f32_32x32x16_bf16 v[48:63], v[116:119], v[120:123], v[48:63]
	s_waitcnt lgkmcnt(0)
	v_mfma_f32_32x32x16_bf16 v[32:47], v[116:119], v[162:165], v[32:47]
	ds_read_b128 v[116:119], v167 offset:59936
	s_waitcnt vmcnt(15)
	ds_write_b128 v130, v[150:153]
	s_waitcnt vmcnt(14)
	ds_write_b128 v130, v[158:161] offset:18432
	s_waitcnt lgkmcnt(2)
	v_mfma_f32_32x32x16_bf16 v[16:31], v[116:119], v[120:123], v[16:31]
	v_mfma_f32_32x32x16_bf16 v[0:15], v[116:119], v[162:165], v[0:15]
	ds_read_b128 v[116:119], v167 offset:55360
	ds_read_b128 v[120:123], v132 offset:36928
	ds_read_b128 v[150:153], v132 offset:41536
	s_waitcnt lgkmcnt(1)
	v_mfma_f32_32x32x16_bf16 v[48:63], v[116:119], v[120:123], v[48:63]
	s_waitcnt lgkmcnt(0)
	v_mfma_f32_32x32x16_bf16 v[32:47], v[116:119], v[150:153], v[32:47]
	ds_read_b128 v[116:119], v167 offset:59968
	s_waitcnt vmcnt(13)
	ds_write_b128 v130, v[104:107] offset:4608
	s_waitcnt vmcnt(12)
	ds_write_b128 v130, v[108:111] offset:23040
	ds_read_b128 v[104:107], v167 offset:55392
	ds_read_b128 v[108:111], v132 offset:36960
	s_waitcnt lgkmcnt(4)
	v_mfma_f32_32x32x16_bf16 v[16:31], v[116:119], v[120:123], v[16:31]
	ds_read_b128 v[120:123], v167 offset:60000
	v_mfma_f32_32x32x16_bf16 v[0:15], v[116:119], v[150:153], v[0:15]
	ds_read_b128 v[116:119], v132 offset:41568
	s_waitcnt lgkmcnt(2)
	v_mfma_f32_32x32x16_bf16 v[48:63], v[104:107], v[108:111], v[48:63]
	s_waitcnt lgkmcnt(0)
	v_mfma_f32_32x32x16_bf16 v[32:47], v[104:107], v[116:119], v[32:47]
	v_mfma_f32_32x32x16_bf16 v[16:31], v[120:123], v[108:111], v[16:31]
	global_load_dwordx4 v[150:153], v[112:113], off offset:3072
	global_load_dwordx4 v[158:161], v[114:115], off offset:3072
	global_load_dwordx4 v[104:107], v[138:139], off offset:3072
	global_load_dwordx4 v[108:111], v[140:141], off offset:3072
	s_waitcnt vmcnt(15)
	ds_write_b128 v130, v[64:67] offset:9216
	s_waitcnt vmcnt(14)
	ds_write_b128 v130, v[68:71] offset:27648
	global_load_dwordx4 v[64:67], v[142:143], off offset:3072
	global_load_dwordx4 v[68:71], v[144:145], off offset:3072
	s_waitcnt vmcnt(15)
	ds_write_b128 v130, v[72:75] offset:13824
	s_waitcnt vmcnt(14)
	ds_write_b128 v130, v[76:79] offset:32256
	global_load_dwordx4 v[72:75], v[146:147], off offset:3072
	global_load_dwordx4 v[76:79], v[148:149], off offset:3072
	s_waitcnt lgkmcnt(0)
	s_barrier
	v_mfma_f32_32x32x16_bf16 v[0:15], v[120:123], v[116:119], v[0:15]
	ds_read_b128 v[116:119], v167 offset:18432
	ds_read_b128 v[120:123], v132
	ds_read_b128 v[162:165], v132 offset:4608
	s_waitcnt lgkmcnt(1)
	v_mfma_f32_32x32x16_bf16 v[48:63], v[116:119], v[120:123], v[48:63]
	s_waitcnt lgkmcnt(0)
	v_mfma_f32_32x32x16_bf16 v[32:47], v[116:119], v[162:165], v[32:47]
	ds_read_b128 v[116:119], v167 offset:23040
	s_waitcnt lgkmcnt(0)
	v_mfma_f32_32x32x16_bf16 v[16:31], v[116:119], v[120:123], v[16:31]
	v_mfma_f32_32x32x16_bf16 v[0:15], v[116:119], v[162:165], v[0:15]
	ds_read_b128 v[116:119], v167 offset:18464
	ds_read_b128 v[120:123], v132 offset:32
	ds_read_b128 v[162:165], v132 offset:4640
	s_waitcnt lgkmcnt(1)
	v_mfma_f32_32x32x16_bf16 v[48:63], v[116:119], v[120:123], v[48:63]
	s_waitcnt lgkmcnt(0)
	v_mfma_f32_32x32x16_bf16 v[32:47], v[116:119], v[162:165], v[32:47]
	ds_read_b128 v[116:119], v167 offset:23072
	s_waitcnt vmcnt(15)
	ds_write_b128 v130, v[124:127] offset:36864
	s_waitcnt vmcnt(14)
	ds_write_b128 v130, v[154:157] offset:55296
	s_waitcnt lgkmcnt(2)
	v_mfma_f32_32x32x16_bf16 v[16:31], v[116:119], v[120:123], v[16:31]
	v_mfma_f32_32x32x16_bf16 v[0:15], v[116:119], v[162:165], v[0:15]
	ds_read_b128 v[116:119], v167 offset:18496
	ds_read_b128 v[120:123], v132 offset:64
	ds_read_b128 v[124:127], v132 offset:4672
	s_waitcnt lgkmcnt(1)
	v_mfma_f32_32x32x16_bf16 v[48:63], v[116:119], v[120:123], v[48:63]
	s_waitcnt lgkmcnt(0)
	v_mfma_f32_32x32x16_bf16 v[32:47], v[116:119], v[124:127], v[32:47]
	ds_read_b128 v[116:119], v167 offset:23104
	s_waitcnt vmcnt(13)
	ds_write_b128 v130, v[96:99] offset:41472
	s_waitcnt vmcnt(12)
	ds_write_b128 v130, v[100:103] offset:59904
	ds_read_b128 v[96:99], v167 offset:18528
	ds_read_b128 v[100:103], v132 offset:96
	s_waitcnt lgkmcnt(4)
	v_mfma_f32_32x32x16_bf16 v[16:31], v[116:119], v[120:123], v[16:31]
	ds_read_b128 v[120:123], v167 offset:23136
	v_mfma_f32_32x32x16_bf16 v[0:15], v[116:119], v[124:127], v[0:15]
	ds_read_b128 v[116:119], v132 offset:4704
	s_waitcnt lgkmcnt(2)
	v_mfma_f32_32x32x16_bf16 v[48:63], v[96:99], v[100:103], v[48:63]
	s_waitcnt lgkmcnt(0)
	v_mfma_f32_32x32x16_bf16 v[32:47], v[96:99], v[116:119], v[32:47]
	v_mfma_f32_32x32x16_bf16 v[16:31], v[120:123], v[100:103], v[16:31]
	global_load_dwordx4 v[124:127], v[112:113], off offset:3200
	global_load_dwordx4 v[154:157], v[114:115], off offset:3200
	global_load_dwordx4 v[96:99], v[138:139], off offset:3200
	global_load_dwordx4 v[100:103], v[140:141], off offset:3200
	s_waitcnt vmcnt(15)
	ds_write_b128 v130, v[80:83] offset:46080
	s_waitcnt vmcnt(14)
	ds_write_b128 v130, v[84:87] offset:64512
	global_load_dwordx4 v[80:83], v[142:143], off offset:3200
	global_load_dwordx4 v[84:87], v[144:145], off offset:3200
	s_waitcnt vmcnt(15)
	ds_write_b128 v130, v[88:91] offset:50688
	s_waitcnt vmcnt(14)
	ds_write_b128 v131, v[92:95] offset:13824
	global_load_dwordx4 v[88:91], v[146:147], off offset:3200
	global_load_dwordx4 v[92:95], v[148:149], off offset:3200
	s_waitcnt lgkmcnt(0)
	s_barrier
; #define GLOADQ(RA, RB, KT, q) do { const int k0_ = (KT) << 6; \
;     RA[q] = ldg16(ap.ptr(m0 + lrow + 32 * (q), k0_) + lkc); RB[q] = ldg16(W + (size_t)(n0 + lrow + 32 * (q)) * ldw + k0_ + lkc); } while (0)
; #define SSTOREQ(RA, RB, ST, q) do { \
;     *(u32x4*)(sA + (ST) * SBUF + (lrow + 32 * (q)) * GP + lkc) = RA[q]; *(u32x4*)(sB + (ST) * SBUF + (lrow + 32 * (q)) * GP + lkc) = RB[q]; } while (0)
; #define FLOAD(F, ST, ks) do { _Pragma("unroll") for (int a = 0; a < 2; ++a) { \
;     F[a] = *(const bf16x8*)(sB + (ST) * SBUF + (wn * 64 + a * 32 + r) * GP + (ks) * 16 + h * 8); \
;     F[2 + a] = *(const bf16x8*)(sA + (ST) * SBUF + (wm * 64 + a * 32 + r) * GP + (ks) * 16 + h * 8); } } while (0)
; #define FMMA(F) do { _Pragma("unroll") for (int a = 0; a < 2; ++a) _Pragma("unroll") for (int b = 0; b < 2; ++b) acc[a][b] = MFMA(F[a], F[2 + b], acc[a][b]); } while (0)
; template <bool MIDK, class AP, class EPI>
; DI void gemm_tile(const AP& ap, const u16* __restrict__ W, int ldw, int K, int m0, int n0, const EPI& epi, char* smem, float r0, float r1, int tid, bool dry) {
;     ...
;   for (int kt = 0; kt < nk; kt += 2) {
;     const bool l3 = kt + 3 < nk, s2 = kt + 2 < nk, l4 = kt + 4 < nk;
;     FLOAD(f0, 0, 0); FLOAD(f1, 0, 1);
;     FMMA(f0); SSTOREQ(ra1, rb1, 1, 0); if (l3) GLOADQ(ra1, rb1, kt + 3, 0);
;     FLOAD(f0, 0, 2);
;     FMMA(f1); SSTOREQ(ra1, rb1, 1, 1); if (l3) GLOADQ(ra1, rb1, kt + 3, 1);
;     FLOAD(f1, 0, 3);
;     FMMA(f0); SSTOREQ(ra1, rb1, 1, 2); if (l3) GLOADQ(ra1, rb1, kt + 3, 2);
;     FMMA(f1); SSTOREQ(ra1, rb1, 1, 3); if (l3) GLOADQ(ra1, rb1, kt + 3, 3);
;     __syncthreads();
;     FLOAD(f0, 1, 0); FLOAD(f1, 1, 1);
;     FMMA(f0); if (s2) SSTOREQ(ra0, rb0, 0, 0); if (l4) GLOADQ(ra0, rb0, kt + 4, 0);
;     FLOAD(f0, 1, 2);
;     FMMA(f1); if (s2) SSTOREQ(ra0, rb0, 0, 1); if (l4) GLOADQ(ra0, rb0, kt + 4, 1);
;     FLOAD(f1, 1, 3);
;     FMMA(f0); if (s2) SSTOREQ(ra0, rb0, 0, 2); if (l4) GLOADQ(ra0, rb0, kt + 4, 2);
;     FMMA(f1); if (s2) SSTOREQ(ra0, rb0, 0, 3); if (l4) GLOADQ(ra0, rb0, kt + 4, 3);
;     if (MIDK && kt == 6) {
; #pragma unroll
;       for (int a = 0; a < 2; ++a)
; #pragma unroll
;         for (int i = 0; i < 16; ++i) { acc[a][0][i] *= r0; acc[a][1][i] *= r1; }
;     }
;     __syncthreads();
;   }
	v_mfma_f32_32x32x16_bf16 v[0:15], v[120:123], v[116:119], v[0:15]
	ds_read_b128 v[116:119], v167 offset:55296
	ds_read_b128 v[120:123], v132 offset:36864
	ds_read_b128 v[162:165], v132 offset:41472
	s_waitcnt lgkmcnt(1)
	v_mfma_f32_32x32x16_bf16 v[48:63], v[116:119], v[120:123], v[48:63]
	s_waitcnt lgkmcnt(0)
	v_mfma_f32_32x32x16_bf16 v[32:47], v[116:119], v[162:165], v[32:47]
	ds_read_b128 v[116:119], v167 offset:59904
	s_waitcnt lgkmcnt(0)
	v_mfma_f32_32x32x16_bf16 v[16:31], v[116:119], v[120:123], v[16:31]
	v_mfma_f32_32x32x16_bf16 v[0:15], v[116:119], v[162:165], v[0:15]
	ds_read_b128 v[116:119], v167 offset:55328
	ds_read_b128 v[120:123], v132 offset:36896
	ds_read_b128 v[162:165], v132 offset:41504
	s_waitcnt lgkmcnt(1)
	v_mfma_f32_32x32x16_bf16 v[48:63], v[116:119], v[120:123], v[48:63]
	s_waitcnt lgkmcnt(0)
	v_mfma_f32_32x32x16_bf16 v[32:47], v[116:119], v[162:165], v[32:47]
	ds_read_b128 v[116:119], v167 offset:59936
	s_waitcnt vmcnt(15)
	ds_write_b128 v130, v[150:153]
	s_waitcnt vmcnt(14)
	ds_write_b128 v130, v[158:161] offset:18432
	s_waitcnt lgkmcnt(2)
	v_mfma_f32_32x32x16_bf16 v[16:31], v[116:119], v[120:123], v[16:31]
	v_mfma_f32_32x32x16_bf16 v[0:15], v[116:119], v[162:165], v[0:15]
	ds_read_b128 v[116:119], v167 offset:55360
	ds_read_b128 v[120:123], v132 offset:36928
	ds_read_b128 v[150:153], v132 offset:41536
	s_waitcnt lgkmcnt(1)
	v_mfma_f32_32x32x16_bf16 v[48:63], v[116:119], v[120:123], v[48:63]
	s_waitcnt lgkmcnt(0)
	v_mfma_f32_32x32x16_bf16 v[32:47], v[116:119], v[150:153], v[32:47]
	ds_read_b128 v[116:119], v167 offset:59968
	s_waitcnt vmcnt(13)
	ds_write_b128 v130, v[104:107] offset:4608
	s_waitcnt vmcnt(12)
	ds_write_b128 v130, v[108:111] offset:23040
	ds_read_b128 v[104:107], v167 offset:55392
	ds_read_b128 v[108:111], v132 offset:36960
	s_waitcnt lgkmcnt(4)
	v_mfma_f32_32x32x16_bf16 v[16:31], v[116:119], v[120:123], v[16:31]
	ds_read_b128 v[120:123], v167 offset:60000
	v_mfma_f32_32x32x16_bf16 v[0:15], v[116:119], v[150:153], v[0:15]
	ds_read_b128 v[116:119], v132 offset:41568
	s_waitcnt lgkmcnt(2)
	v_mfma_f32_32x32x16_bf16 v[48:63], v[104:107], v[108:111], v[48:63]
	s_waitcnt lgkmcnt(0)
	v_mfma_f32_32x32x16_bf16 v[32:47], v[104:107], v[116:119], v[32:47]
	v_mfma_f32_32x32x16_bf16 v[16:31], v[120:123], v[108:111], v[16:31]
	global_load_dwordx4 v[150:153], v[112:113], off offset:3328
	global_load_dwordx4 v[158:161], v[114:115], off offset:3328
	global_load_dwordx4 v[104:107], v[138:139], off offset:3328
	global_load_dwordx4 v[108:111], v[140:141], off offset:3328
	s_waitcnt vmcnt(15)
	ds_write_b128 v130, v[64:67] offset:9216
	s_waitcnt vmcnt(14)
	ds_write_b128 v130, v[68:71] offset:27648
	global_load_dwordx4 v[64:67], v[142:143], off offset:3328
	global_load_dwordx4 v[68:71], v[144:145], off offset:3328
	s_waitcnt vmcnt(15)
	ds_write_b128 v130, v[72:75] offset:13824
	s_waitcnt vmcnt(14)
	ds_write_b128 v130, v[76:79] offset:32256
	global_load_dwordx4 v[72:75], v[146:147], off offset:3328
	global_load_dwordx4 v[76:79], v[148:149], off offset:3328
	s_waitcnt lgkmcnt(0)
	s_barrier
	v_mfma_f32_32x32x16_bf16 v[0:15], v[120:123], v[116:119], v[0:15]
	ds_read_b128 v[116:119], v167 offset:18432
	ds_read_b128 v[120:123], v132
	ds_read_b128 v[162:165], v132 offset:4608
	s_waitcnt lgkmcnt(1)
	v_mfma_f32_32x32x16_bf16 v[48:63], v[116:119], v[120:123], v[48:63]
	s_waitcnt lgkmcnt(0)
	v_mfma_f32_32x32x16_bf16 v[32:47], v[116:119], v[162:165], v[32:47]
	ds_read_b128 v[116:119], v167 offset:23040
	s_waitcnt lgkmcnt(0)
	v_mfma_f32_32x32x16_bf16 v[16:31], v[116:119], v[120:123], v[16:31]
	v_mfma_f32_32x32x16_bf16 v[0:15], v[116:119], v[162:165], v[0:15]
	ds_read_b128 v[116:119], v167 offset:18464
	ds_read_b128 v[120:123], v132 offset:32
	ds_read_b128 v[162:165], v132 offset:4640
	s_waitcnt lgkmcnt(1)
	v_mfma_f32_32x32x16_bf16 v[48:63], v[116:119], v[120:123], v[48:63]
	s_waitcnt lgkmcnt(0)
	v_mfma_f32_32x32x16_bf16 v[32:47], v[116:119], v[162:165], v[32:47]
	ds_read_b128 v[116:119], v167 offset:23072
	s_waitcnt vmcnt(15)
	ds_write_b128 v130, v[124:127] offset:36864
	s_waitcnt vmcnt(14)
	ds_write_b128 v130, v[154:157] offset:55296
	s_waitcnt lgkmcnt(2)
	v_mfma_f32_32x32x16_bf16 v[16:31], v[116:119], v[120:123], v[16:31]
	v_mfma_f32_32x32x16_bf16 v[0:15], v[116:119], v[162:165], v[0:15]
	ds_read_b128 v[116:119], v167 offset:18496
	ds_read_b128 v[120:123], v132 offset:64
	ds_read_b128 v[124:127], v132 offset:4672
	s_waitcnt lgkmcnt(1)
	v_mfma_f32_32x32x16_bf16 v[48:63], v[116:119], v[120:123], v[48:63]
	s_waitcnt lgkmcnt(0)
	v_mfma_f32_32x32x16_bf16 v[32:47], v[116:119], v[124:127], v[32:47]
	ds_read_b128 v[116:119], v167 offset:23104
	s_waitcnt vmcnt(13)
	ds_write_b128 v130, v[96:99] offset:41472
	s_waitcnt vmcnt(12)
	ds_write_b128 v130, v[100:103] offset:59904
	ds_read_b128 v[96:99], v167 offset:18528
	ds_read_b128 v[100:103], v132 offset:96
	s_waitcnt lgkmcnt(4)
	v_mfma_f32_32x32x16_bf16 v[16:31], v[116:119], v[120:123], v[16:31]
	ds_read_b128 v[120:123], v167 offset:23136
	v_mfma_f32_32x32x16_bf16 v[0:15], v[116:119], v[124:127], v[0:15]
	ds_read_b128 v[116:119], v132 offset:4704
	s_waitcnt lgkmcnt(2)
	v_mfma_f32_32x32x16_bf16 v[48:63], v[96:99], v[100:103], v[48:63]
	s_waitcnt lgkmcnt(0)
	v_mfma_f32_32x32x16_bf16 v[32:47], v[96:99], v[116:119], v[32:47]
	v_mfma_f32_32x32x16_bf16 v[16:31], v[120:123], v[100:103], v[16:31]
	global_load_dwordx4 v[124:127], v[112:113], off offset:3456
	global_load_dwordx4 v[154:157], v[114:115], off offset:3456
	global_load_dwordx4 v[96:99], v[138:139], off offset:3456
	global_load_dwordx4 v[100:103], v[140:141], off offset:3456
	s_waitcnt vmcnt(15)
	ds_write_b128 v130, v[80:83] offset:46080
	s_waitcnt vmcnt(14)
	ds_write_b128 v130, v[84:87] offset:64512
	global_load_dwordx4 v[80:83], v[142:143], off offset:3456
	global_load_dwordx4 v[84:87], v[144:145], off offset:3456
	s_waitcnt vmcnt(15)
	ds_write_b128 v130, v[88:91] offset:50688
	s_waitcnt vmcnt(14)
	ds_write_b128 v131, v[92:95] offset:13824
	global_load_dwordx4 v[88:91], v[146:147], off offset:3456
	global_load_dwordx4 v[92:95], v[148:149], off offset:3456
	s_waitcnt lgkmcnt(0)
	s_barrier
; #define GLOADQ(RA, RB, KT, q) do { const int k0_ = (KT) << 6; \
;     RA[q] = ldg16(ap.ptr(m0 + lrow + 32 * (q), k0_) + lkc); RB[q] = ldg16(W + (size_t)(n0 + lrow + 32 * (q)) * ldw + k0_ + lkc); } while (0)
; #define SSTOREQ(RA, RB, ST, q) do { \
;     *(u32x4*)(sA + (ST) * SBUF + (lrow + 32 * (q)) * GP + lkc) = RA[q]; *(u32x4*)(sB + (ST) * SBUF + (lrow + 32 * (q)) * GP + lkc) = RB[q]; } while (0)
; #define FLOAD(F, ST, ks) do { _Pragma("unroll") for (int a = 0; a < 2; ++a) { \
;     F[a] = *(const bf16x8*)(sB + (ST) * SBUF + (wn * 64 + a * 32 + r) * GP + (ks) * 16 + h * 8); \
;     F[2 + a] = *(const bf16x8*)(sA + (ST) * SBUF + (wm * 64 + a * 32 + r) * GP + (ks) * 16 + h * 8); } } while (0)
; #define FMMA(F) do { _Pragma("unroll") for (int a = 0; a < 2; ++a) _Pragma("unroll") for (int b = 0; b < 2; ++b) acc[a][b] = MFMA(F[a], F[2 + b], acc[a][b]); } while (0)
; template <bool MIDK, class AP, class EPI>
; DI void gemm_tile(const AP& ap, const u16* __restrict__ W, int ldw, int K, int m0, int n0, const EPI& epi, char* smem, float r0, float r1, int tid, bool dry) {
;     ...
;   for (int kt = 0; kt < nk; kt += 2) {
;     const bool l3 = kt + 3 < nk, s2 = kt + 2 < nk, l4 = kt + 4 < nk;
;     FLOAD(f0, 0, 0); FLOAD(f1, 0, 1);
;     FMMA(f0); SSTOREQ(ra1, rb1, 1, 0); if (l3) GLOADQ(ra1, rb1, kt + 3, 0);
;     FLOAD(f0, 0, 2);
;     FMMA(f1); SSTOREQ(ra1, rb1, 1, 1); if (l3) GLOADQ(ra1, rb1, kt + 3, 1);
;     FLOAD(f1, 0, 3);
;     FMMA(f0); SSTOREQ(ra1, rb1, 1, 2); if (l3) GLOADQ(ra1, rb1, kt + 3, 2);
;     FMMA(f1); SSTOREQ(ra1, rb1, 1, 3); if (l3) GLOADQ(ra1, rb1, kt + 3, 3);
;     __syncthreads();
;     FLOAD(f0, 1, 0); FLOAD(f1, 1, 1);
;     FMMA(f0); if (s2) SSTOREQ(ra0, rb0, 0, 0); if (l4) GLOADQ(ra0, rb0, kt + 4, 0);
;     FLOAD(f0, 1, 2);
;     FMMA(f1); if (s2) SSTOREQ(ra0, rb0, 0, 1); if (l4) GLOADQ(ra0, rb0, kt + 4, 1);
;     FLOAD(f1, 1, 3);
;     FMMA(f0); if (s2) SSTOREQ(ra0, rb0, 0, 2); if (l4) GLOADQ(ra0, rb0, kt + 4, 2);
;     FMMA(f1); if (s2) SSTOREQ(ra0, rb0, 0, 3); if (l4) GLOADQ(ra0, rb0, kt + 4, 3);
;     if (MIDK && kt == 6) {
; #pragma unroll
;       for (int a = 0; a < 2; ++a)
; #pragma unroll
;         for (int i = 0; i < 16; ++i) { acc[a][0][i] *= r0; acc[a][1][i] *= r1; }
;     }
;     __syncthreads();
;   }
	v_mfma_f32_32x32x16_bf16 v[0:15], v[120:123], v[116:119], v[0:15]
	ds_read_b128 v[116:119], v167 offset:55296
	ds_read_b128 v[120:123], v132 offset:36864
	ds_read_b128 v[162:165], v132 offset:41472
	s_waitcnt lgkmcnt(1)
	v_mfma_f32_32x32x16_bf16 v[48:63], v[116:119], v[120:123], v[48:63]
	s_waitcnt lgkmcnt(0)
	v_mfma_f32_32x32x16_bf16 v[32:47], v[116:119], v[162:165], v[32:47]
	ds_read_b128 v[116:119], v167 offset:59904
	s_waitcnt lgkmcnt(0)
	v_mfma_f32_32x32x16_bf16 v[16:31], v[116:119], v[120:123], v[16:31]
	v_mfma_f32_32x32x16_bf16 v[0:15], v[116:119], v[162:165], v[0:15]
	ds_read_b128 v[116:119], v167 offset:55328
	ds_read_b128 v[120:123], v132 offset:36896
	ds_read_b128 v[162:165], v132 offset:41504
	s_waitcnt lgkmcnt(1)
	v_mfma_f32_32x32x16_bf16 v[48:63], v[116:119], v[120:123], v[48:63]
	s_waitcnt lgkmcnt(0)
	v_mfma_f32_32x32x16_bf16 v[32:47], v[116:119], v[162:165], v[32:47]
	ds_read_b128 v[116:119], v167 offset:59936
	s_waitcnt vmcnt(15)
	ds_write_b128 v130, v[150:153]
	s_waitcnt vmcnt(14)
	ds_write_b128 v130, v[158:161] offset:18432
	s_waitcnt lgkmcnt(2)
	v_mfma_f32_32x32x16_bf16 v[16:31], v[116:119], v[120:123], v[16:31]
	v_mfma_f32_32x32x16_bf16 v[0:15], v[116:119], v[162:165], v[0:15]
	ds_read_b128 v[116:119], v167 offset:55360
	ds_read_b128 v[120:123], v132 offset:36928
	ds_read_b128 v[150:153], v132 offset:41536
	s_waitcnt lgkmcnt(1)
	v_mfma_f32_32x32x16_bf16 v[48:63], v[116:119], v[120:123], v[48:63]
	s_waitcnt lgkmcnt(0)
	v_mfma_f32_32x32x16_bf16 v[32:47], v[116:119], v[150:153], v[32:47]
	ds_read_b128 v[116:119], v167 offset:59968
	s_waitcnt vmcnt(13)
	ds_write_b128 v130, v[104:107] offset:4608
	s_waitcnt vmcnt(12)
	ds_write_b128 v130, v[108:111] offset:23040
	ds_read_b128 v[104:107], v167 offset:55392
	ds_read_b128 v[108:111], v132 offset:36960
	s_waitcnt lgkmcnt(4)
	v_mfma_f32_32x32x16_bf16 v[16:31], v[116:119], v[120:123], v[16:31]
	ds_read_b128 v[120:123], v167 offset:60000
	v_mfma_f32_32x32x16_bf16 v[0:15], v[116:119], v[150:153], v[0:15]
	ds_read_b128 v[116:119], v132 offset:41568
	s_waitcnt lgkmcnt(2)
	v_mfma_f32_32x32x16_bf16 v[48:63], v[104:107], v[108:111], v[48:63]
	s_waitcnt lgkmcnt(0)
	v_mfma_f32_32x32x16_bf16 v[32:47], v[104:107], v[116:119], v[32:47]
	v_mfma_f32_32x32x16_bf16 v[16:31], v[120:123], v[108:111], v[16:31]
	global_load_dwordx4 v[150:153], v[112:113], off offset:3584
	global_load_dwordx4 v[158:161], v[114:115], off offset:3584
	global_load_dwordx4 v[104:107], v[138:139], off offset:3584
	global_load_dwordx4 v[108:111], v[140:141], off offset:3584
	s_waitcnt vmcnt(15)
	ds_write_b128 v130, v[64:67] offset:9216
	s_waitcnt vmcnt(14)
	ds_write_b128 v130, v[68:71] offset:27648
	global_load_dwordx4 v[64:67], v[142:143], off offset:3584
	global_load_dwordx4 v[68:71], v[144:145], off offset:3584
	s_waitcnt vmcnt(15)
	ds_write_b128 v130, v[72:75] offset:13824
	s_waitcnt vmcnt(14)
	ds_write_b128 v130, v[76:79] offset:32256
	global_load_dwordx4 v[72:75], v[146:147], off offset:3584
	global_load_dwordx4 v[76:79], v[148:149], off offset:3584
	s_waitcnt lgkmcnt(0)
	s_barrier
	v_mfma_f32_32x32x16_bf16 v[0:15], v[120:123], v[116:119], v[0:15]
	ds_read_b128 v[116:119], v167 offset:18432
	ds_read_b128 v[120:123], v132
	ds_read_b128 v[162:165], v132 offset:4608
	s_waitcnt lgkmcnt(1)
	v_mfma_f32_32x32x16_bf16 v[48:63], v[116:119], v[120:123], v[48:63]
	s_waitcnt lgkmcnt(0)
	v_mfma_f32_32x32x16_bf16 v[32:47], v[116:119], v[162:165], v[32:47]
	ds_read_b128 v[116:119], v167 offset:23040
	s_waitcnt lgkmcnt(0)
	v_mfma_f32_32x32x16_bf16 v[16:31], v[116:119], v[120:123], v[16:31]
	v_mfma_f32_32x32x16_bf16 v[0:15], v[116:119], v[162:165], v[0:15]
	ds_read_b128 v[116:119], v167 offset:18464
	ds_read_b128 v[120:123], v132 offset:32
	ds_read_b128 v[162:165], v132 offset:4640
	s_waitcnt lgkmcnt(1)
	v_mfma_f32_32x32x16_bf16 v[48:63], v[116:119], v[120:123], v[48:63]
	s_waitcnt lgkmcnt(0)
	v_mfma_f32_32x32x16_bf16 v[32:47], v[116:119], v[162:165], v[32:47]
	ds_read_b128 v[116:119], v167 offset:23072
	s_waitcnt vmcnt(15)
	ds_write_b128 v130, v[124:127] offset:36864
	s_waitcnt vmcnt(14)
	ds_write_b128 v130, v[154:157] offset:55296
	s_waitcnt lgkmcnt(2)
	v_mfma_f32_32x32x16_bf16 v[16:31], v[116:119], v[120:123], v[16:31]
	v_mfma_f32_32x32x16_bf16 v[0:15], v[116:119], v[162:165], v[0:15]
	ds_read_b128 v[116:119], v167 offset:18496
	ds_read_b128 v[120:123], v132 offset:64
	ds_read_b128 v[124:127], v132 offset:4672
	s_waitcnt lgkmcnt(1)
	v_mfma_f32_32x32x16_bf16 v[48:63], v[116:119], v[120:123], v[48:63]
	s_waitcnt lgkmcnt(0)
	v_mfma_f32_32x32x16_bf16 v[32:47], v[116:119], v[124:127], v[32:47]
	ds_read_b128 v[116:119], v167 offset:23104
	s_waitcnt vmcnt(13)
	ds_write_b128 v130, v[96:99] offset:41472
	s_waitcnt vmcnt(12)
	ds_write_b128 v130, v[100:103] offset:59904
	ds_read_b128 v[96:99], v167 offset:18528
	ds_read_b128 v[100:103], v132 offset:96
	s_waitcnt lgkmcnt(4)
	v_mfma_f32_32x32x16_bf16 v[16:31], v[116:119], v[120:123], v[16:31]
	ds_read_b128 v[120:123], v167 offset:23136
	v_mfma_f32_32x32x16_bf16 v[0:15], v[116:119], v[124:127], v[0:15]
	ds_read_b128 v[116:119], v132 offset:4704
	s_waitcnt lgkmcnt(2)
	v_mfma_f32_32x32x16_bf16 v[48:63], v[96:99], v[100:103], v[48:63]
	s_waitcnt lgkmcnt(0)
	v_mfma_f32_32x32x16_bf16 v[32:47], v[96:99], v[116:119], v[32:47]
	v_mfma_f32_32x32x16_bf16 v[16:31], v[120:123], v[100:103], v[16:31]
	global_load_dwordx4 v[124:127], v[112:113], off offset:3712
	global_load_dwordx4 v[154:157], v[114:115], off offset:3712
	global_load_dwordx4 v[96:99], v[138:139], off offset:3712
	global_load_dwordx4 v[100:103], v[140:141], off offset:3712
	s_waitcnt vmcnt(15)
	ds_write_b128 v130, v[80:83] offset:46080
	s_waitcnt vmcnt(14)
	ds_write_b128 v130, v[84:87] offset:64512
	global_load_dwordx4 v[80:83], v[142:143], off offset:3712
	global_load_dwordx4 v[84:87], v[144:145], off offset:3712
	s_waitcnt vmcnt(15)
	ds_write_b128 v130, v[88:91] offset:50688
	s_waitcnt vmcnt(14)
	ds_write_b128 v131, v[92:95] offset:13824
	global_load_dwordx4 v[88:91], v[146:147], off offset:3712
	global_load_dwordx4 v[92:95], v[148:149], off offset:3712
	s_waitcnt lgkmcnt(0)
	s_barrier
; #define GLOADQ(RA, RB, KT, q) do { const int k0_ = (KT) << 6; \
;     RA[q] = ldg16(ap.ptr(m0 + lrow + 32 * (q), k0_) + lkc); RB[q] = ldg16(W + (size_t)(n0 + lrow + 32 * (q)) * ldw + k0_ + lkc); } while (0)
; #define SSTOREQ(RA, RB, ST, q) do { \
;     *(u32x4*)(sA + (ST) * SBUF + (lrow + 32 * (q)) * GP + lkc) = RA[q]; *(u32x4*)(sB + (ST) * SBUF + (lrow + 32 * (q)) * GP + lkc) = RB[q]; } while (0)
; #define FLOAD(F, ST, ks) do { _Pragma("unroll") for (int a = 0; a < 2; ++a) { \
;     F[a] = *(const bf16x8*)(sB + (ST) * SBUF + (wn * 64 + a * 32 + r) * GP + (ks) * 16 + h * 8); \
;     F[2 + a] = *(const bf16x8*)(sA + (ST) * SBUF + (wm * 64 + a * 32 + r) * GP + (ks) * 16 + h * 8); } } while (0)
; #define FMMA(F) do { _Pragma("unroll") for (int a = 0; a < 2; ++a) _Pragma("unroll") for (int b = 0; b < 2; ++b) acc[a][b] = MFMA(F[a], F[2 + b], acc[a][b]); } while (0)
; template <bool MIDK, class AP, class EPI>
; DI void gemm_tile(const AP& ap, const u16* __restrict__ W, int ldw, int K, int m0, int n0, const EPI& epi, char* smem, float r0, float r1, int tid, bool dry) {
;     ...
;   for (int kt = 0; kt < nk; kt += 2) {
;     const bool l3 = kt + 3 < nk, s2 = kt + 2 < nk, l4 = kt + 4 < nk;
;     FLOAD(f0, 0, 0); FLOAD(f1, 0, 1);
;     FMMA(f0); SSTOREQ(ra1, rb1, 1, 0); if (l3) GLOADQ(ra1, rb1, kt + 3, 0);
;     FLOAD(f0, 0, 2);
;     FMMA(f1); SSTOREQ(ra1, rb1, 1, 1); if (l3) GLOADQ(ra1, rb1, kt + 3, 1);
;     FLOAD(f1, 0, 3);
;     FMMA(f0); SSTOREQ(ra1, rb1, 1, 2); if (l3) GLOADQ(ra1, rb1, kt + 3, 2);
;     FMMA(f1); SSTOREQ(ra1, rb1, 1, 3); if (l3) GLOADQ(ra1, rb1, kt + 3, 3);
;     __syncthreads();
;     FLOAD(f0, 1, 0); FLOAD(f1, 1, 1);
;     FMMA(f0); if (s2) SSTOREQ(ra0, rb0, 0, 0); if (l4) GLOADQ(ra0, rb0, kt + 4, 0);
;     FLOAD(f0, 1, 2);
;     FMMA(f1); if (s2) SSTOREQ(ra0, rb0, 0, 1); if (l4) GLOADQ(ra0, rb0, kt + 4, 1);
;     FLOAD(f1, 1, 3);
;     FMMA(f0); if (s2) SSTOREQ(ra0, rb0, 0, 2); if (l4) GLOADQ(ra0, rb0, kt + 4, 2);
;     FMMA(f1); if (s2) SSTOREQ(ra0, rb0, 0, 3); if (l4) GLOADQ(ra0, rb0, kt + 4, 3);
;     if (MIDK && kt == 6) {
; #pragma unroll
;       for (int a = 0; a < 2; ++a)
; #pragma unroll
;         for (int i = 0; i < 16; ++i) { acc[a][0][i] *= r0; acc[a][1][i] *= r1; }
;     }
;     __syncthreads();
;   }
	v_mfma_f32_32x32x16_bf16 v[0:15], v[120:123], v[116:119], v[0:15]
	ds_read_b128 v[116:119], v167 offset:55296
	ds_read_b128 v[120:123], v132 offset:36864
	ds_read_b128 v[162:165], v132 offset:41472
	s_waitcnt lgkmcnt(1)
	v_mfma_f32_32x32x16_bf16 v[48:63], v[116:119], v[120:123], v[48:63]
	s_waitcnt lgkmcnt(0)
	v_mfma_f32_32x32x16_bf16 v[32:47], v[116:119], v[162:165], v[32:47]
	ds_read_b128 v[116:119], v167 offset:59904
	s_waitcnt lgkmcnt(0)
	v_mfma_f32_32x32x16_bf16 v[16:31], v[116:119], v[120:123], v[16:31]
	v_mfma_f32_32x32x16_bf16 v[0:15], v[116:119], v[162:165], v[0:15]
	ds_read_b128 v[116:119], v167 offset:55328
	ds_read_b128 v[120:123], v132 offset:36896
	ds_read_b128 v[162:165], v132 offset:41504
	s_waitcnt lgkmcnt(1)
	v_mfma_f32_32x32x16_bf16 v[48:63], v[116:119], v[120:123], v[48:63]
	s_waitcnt lgkmcnt(0)
	v_mfma_f32_32x32x16_bf16 v[32:47], v[116:119], v[162:165], v[32:47]
	ds_read_b128 v[116:119], v167 offset:59936
	s_waitcnt vmcnt(15)
	ds_write_b128 v130, v[150:153]
	s_waitcnt vmcnt(14)
	ds_write_b128 v130, v[158:161] offset:18432
	s_waitcnt lgkmcnt(2)
	v_mfma_f32_32x32x16_bf16 v[16:31], v[116:119], v[120:123], v[16:31]
	v_mfma_f32_32x32x16_bf16 v[0:15], v[116:119], v[162:165], v[0:15]
	ds_read_b128 v[116:119], v167 offset:55360
	ds_read_b128 v[120:123], v132 offset:36928
	ds_read_b128 v[150:153], v132 offset:41536
	s_waitcnt lgkmcnt(1)
	v_mfma_f32_32x32x16_bf16 v[48:63], v[116:119], v[120:123], v[48:63]
	s_waitcnt lgkmcnt(0)
	v_mfma_f32_32x32x16_bf16 v[32:47], v[116:119], v[150:153], v[32:47]
	ds_read_b128 v[116:119], v167 offset:59968
	s_waitcnt vmcnt(13)
	ds_write_b128 v130, v[104:107] offset:4608
	s_waitcnt vmcnt(12)
	ds_write_b128 v130, v[108:111] offset:23040
	ds_read_b128 v[104:107], v167 offset:55392
	ds_read_b128 v[108:111], v132 offset:36960
	s_waitcnt lgkmcnt(4)
	v_mfma_f32_32x32x16_bf16 v[16:31], v[116:119], v[120:123], v[16:31]
	ds_read_b128 v[120:123], v167 offset:60000
	v_mfma_f32_32x32x16_bf16 v[0:15], v[116:119], v[150:153], v[0:15]
	ds_read_b128 v[116:119], v132 offset:41568
	s_waitcnt lgkmcnt(2)
	v_mfma_f32_32x32x16_bf16 v[48:63], v[104:107], v[108:111], v[48:63]
	s_waitcnt lgkmcnt(0)
	v_mfma_f32_32x32x16_bf16 v[32:47], v[104:107], v[116:119], v[32:47]
	v_mfma_f32_32x32x16_bf16 v[16:31], v[120:123], v[108:111], v[16:31]
	global_load_dwordx4 v[150:153], v[112:113], off offset:3840
	global_load_dwordx4 v[158:161], v[114:115], off offset:3840
	global_load_dwordx4 v[104:107], v[138:139], off offset:3840
	global_load_dwordx4 v[108:111], v[140:141], off offset:3840
	s_waitcnt vmcnt(15)
	ds_write_b128 v130, v[64:67] offset:9216
	s_waitcnt vmcnt(14)
	ds_write_b128 v130, v[68:71] offset:27648
	global_load_dwordx4 v[64:67], v[142:143], off offset:3840
	global_load_dwordx4 v[68:71], v[144:145], off offset:3840
	s_waitcnt vmcnt(15)
	ds_write_b128 v130, v[72:75] offset:13824
	s_waitcnt vmcnt(14)
	ds_write_b128 v130, v[76:79] offset:32256
	global_load_dwordx4 v[72:75], v[146:147], off offset:3840
	global_load_dwordx4 v[76:79], v[148:149], off offset:3840
	s_waitcnt lgkmcnt(0)
	s_barrier
	v_mfma_f32_32x32x16_bf16 v[0:15], v[120:123], v[116:119], v[0:15]
	ds_read_b128 v[116:119], v167 offset:18432
	ds_read_b128 v[120:123], v132
	ds_read_b128 v[162:165], v132 offset:4608
	s_waitcnt lgkmcnt(1)
	v_mfma_f32_32x32x16_bf16 v[48:63], v[116:119], v[120:123], v[48:63]
	s_waitcnt lgkmcnt(0)
	v_mfma_f32_32x32x16_bf16 v[32:47], v[116:119], v[162:165], v[32:47]
	ds_read_b128 v[116:119], v167 offset:23040
	s_waitcnt lgkmcnt(0)
	v_mfma_f32_32x32x16_bf16 v[16:31], v[116:119], v[120:123], v[16:31]
	v_mfma_f32_32x32x16_bf16 v[0:15], v[116:119], v[162:165], v[0:15]
	ds_read_b128 v[116:119], v167 offset:18464
	ds_read_b128 v[120:123], v132 offset:32
	ds_read_b128 v[162:165], v132 offset:4640
	s_waitcnt lgkmcnt(1)
	v_mfma_f32_32x32x16_bf16 v[48:63], v[116:119], v[120:123], v[48:63]
	s_waitcnt lgkmcnt(0)
	v_mfma_f32_32x32x16_bf16 v[32:47], v[116:119], v[162:165], v[32:47]
	ds_read_b128 v[116:119], v167 offset:23072
	s_waitcnt vmcnt(15)
	ds_write_b128 v130, v[124:127] offset:36864
	s_waitcnt vmcnt(14)
	ds_write_b128 v130, v[154:157] offset:55296
	s_waitcnt lgkmcnt(2)
	v_mfma_f32_32x32x16_bf16 v[16:31], v[116:119], v[120:123], v[16:31]
	v_mfma_f32_32x32x16_bf16 v[0:15], v[116:119], v[162:165], v[0:15]
	ds_read_b128 v[116:119], v167 offset:18496
	ds_read_b128 v[120:123], v132 offset:64
	ds_read_b128 v[124:127], v132 offset:4672
	s_waitcnt lgkmcnt(1)
	v_mfma_f32_32x32x16_bf16 v[48:63], v[116:119], v[120:123], v[48:63]
	s_waitcnt lgkmcnt(0)
	v_mfma_f32_32x32x16_bf16 v[32:47], v[116:119], v[124:127], v[32:47]
	ds_read_b128 v[116:119], v167 offset:23104
	s_waitcnt vmcnt(13)
	ds_write_b128 v130, v[96:99] offset:41472
	s_waitcnt vmcnt(12)
	ds_write_b128 v130, v[100:103] offset:59904
	ds_read_b128 v[96:99], v167 offset:18528
	ds_read_b128 v[100:103], v132 offset:96
	s_waitcnt lgkmcnt(4)
	v_mfma_f32_32x32x16_bf16 v[16:31], v[116:119], v[120:123], v[16:31]
	v_mfma_f32_32x32x16_bf16 v[0:15], v[116:119], v[124:127], v[0:15]
	ds_read_b128 v[116:119], v132 offset:4704
	s_waitcnt lgkmcnt(1)
	v_mfma_f32_32x32x16_bf16 v[48:63], v[96:99], v[100:103], v[48:63]
	s_waitcnt lgkmcnt(0)
	v_mfma_f32_32x32x16_bf16 v[32:47], v[96:99], v[116:119], v[32:47]
	ds_read_b128 v[96:99], v167 offset:23136
	s_waitcnt lgkmcnt(0)
	v_mfma_f32_32x32x16_bf16 v[16:31], v[96:99], v[100:103], v[16:31]
	global_load_dwordx4 v[100:103], v[112:113], off offset:3968
	s_nop 0
	global_load_dwordx4 v[112:115], v[114:115], off offset:3968
	s_nop 0
	global_load_dwordx4 v[120:123], v[138:139], off offset:3968
	global_load_dwordx4 v[124:127], v[140:141], off offset:3968
	s_waitcnt vmcnt(15)
	ds_write_b128 v130, v[80:83] offset:46080
	s_waitcnt vmcnt(14)
	ds_write_b128 v130, v[84:87] offset:64512
	global_load_dwordx4 v[80:83], v[142:143], off offset:3968
	global_load_dwordx4 v[84:87], v[144:145], off offset:3968
	s_waitcnt vmcnt(15)
	ds_write_b128 v130, v[88:91] offset:50688
	s_waitcnt vmcnt(14)
	ds_write_b128 v131, v[92:95] offset:13824
	global_load_dwordx4 v[88:91], v[146:147], off offset:3968
	global_load_dwordx4 v[92:95], v[148:149], off offset:3968
	s_waitcnt lgkmcnt(0)
	s_barrier
; #define GLOADQ(RA, RB, KT, q) do { const int k0_ = (KT) << 6; \
;     RA[q] = ldg16(ap.ptr(m0 + lrow + 32 * (q), k0_) + lkc); RB[q] = ldg16(W + (size_t)(n0 + lrow + 32 * (q)) * ldw + k0_ + lkc); } while (0)
; #define SSTOREQ(RA, RB, ST, q) do { \
;     *(u32x4*)(sA + (ST) * SBUF + (lrow + 32 * (q)) * GP + lkc) = RA[q]; *(u32x4*)(sB + (ST) * SBUF + (lrow + 32 * (q)) * GP + lkc) = RB[q]; } while (0)
; #define FLOAD(F, ST, ks) do { _Pragma("unroll") for (int a = 0; a < 2; ++a) { \
;     F[a] = *(const bf16x8*)(sB + (ST) * SBUF + (wn * 64 + a * 32 + r) * GP + (ks) * 16 + h * 8); \
;     F[2 + a] = *(const bf16x8*)(sA + (ST) * SBUF + (wm * 64 + a * 32 + r) * GP + (ks) * 16 + h * 8); } } while (0)
; #define FMMA(F) do { _Pragma("unroll") for (int a = 0; a < 2; ++a) _Pragma("unroll") for (int b = 0; b < 2; ++b) acc[a][b] = MFMA(F[a], F[2 + b], acc[a][b]); } while (0)
; template <bool MIDK, class AP, class EPI>
; DI void gemm_tile(const AP& ap, const u16* __restrict__ W, int ldw, int K, int m0, int n0, const EPI& epi, char* smem, float r0, float r1, int tid, bool dry) {
;     ...
;   for (int kt = 0; kt < nk; kt += 2) {
;     const bool l3 = kt + 3 < nk, s2 = kt + 2 < nk, l4 = kt + 4 < nk;
;     FLOAD(f0, 0, 0); FLOAD(f1, 0, 1);
;     FMMA(f0); SSTOREQ(ra1, rb1, 1, 0); if (l3) GLOADQ(ra1, rb1, kt + 3, 0);
;     FLOAD(f0, 0, 2);
;     FMMA(f1); SSTOREQ(ra1, rb1, 1, 1); if (l3) GLOADQ(ra1, rb1, kt + 3, 1);
;     FLOAD(f1, 0, 3);
;     FMMA(f0); SSTOREQ(ra1, rb1, 1, 2); if (l3) GLOADQ(ra1, rb1, kt + 3, 2);
;     FMMA(f1); SSTOREQ(ra1, rb1, 1, 3); if (l3) GLOADQ(ra1, rb1, kt + 3, 3);
;     __syncthreads();
;     FLOAD(f0, 1, 0); FLOAD(f1, 1, 1);
;     FMMA(f0); if (s2) SSTOREQ(ra0, rb0, 0, 0); if (l4) GLOADQ(ra0, rb0, kt + 4, 0);
;     FLOAD(f0, 1, 2);
;     FMMA(f1); if (s2) SSTOREQ(ra0, rb0, 0, 1); if (l4) GLOADQ(ra0, rb0, kt + 4, 1);
;     FLOAD(f1, 1, 3);
;     FMMA(f0); if (s2) SSTOREQ(ra0, rb0, 0, 2); if (l4) GLOADQ(ra0, rb0, kt + 4, 2);
;     FMMA(f1); if (s2) SSTOREQ(ra0, rb0, 0, 3); if (l4) GLOADQ(ra0, rb0, kt + 4, 3);
;     if (MIDK && kt == 6) {
; #pragma unroll
;       for (int a = 0; a < 2; ++a)
; #pragma unroll
;         for (int i = 0; i < 16; ++i) { acc[a][0][i] *= r0; acc[a][1][i] *= r1; }
;     }
;     __syncthreads();
;   }
	v_mfma_f32_32x32x16_bf16 v[0:15], v[96:99], v[116:119], v[0:15]
	ds_read_b128 v[96:99], v167 offset:55296
	ds_read_b128 v[116:119], v132 offset:36864
	ds_read_b128 v[138:141], v132 offset:41472
	s_waitcnt lgkmcnt(1)
	v_mfma_f32_32x32x16_bf16 v[48:63], v[96:99], v[116:119], v[48:63]
	s_waitcnt lgkmcnt(0)
	v_mfma_f32_32x32x16_bf16 v[32:47], v[96:99], v[138:141], v[32:47]
	ds_read_b128 v[96:99], v167 offset:59904
	s_waitcnt lgkmcnt(0)
	v_mfma_f32_32x32x16_bf16 v[16:31], v[96:99], v[116:119], v[16:31]
	v_mfma_f32_32x32x16_bf16 v[0:15], v[96:99], v[138:141], v[0:15]
	ds_read_b128 v[96:99], v167 offset:55328
	ds_read_b128 v[116:119], v132 offset:36896
	ds_read_b128 v[138:141], v132 offset:41504
	s_waitcnt lgkmcnt(1)
	v_mfma_f32_32x32x16_bf16 v[48:63], v[96:99], v[116:119], v[48:63]
	s_waitcnt lgkmcnt(0)
	v_mfma_f32_32x32x16_bf16 v[32:47], v[96:99], v[138:141], v[32:47]
	ds_read_b128 v[96:99], v167 offset:59936
	s_waitcnt vmcnt(15)
	ds_write_b128 v130, v[150:153]
	s_waitcnt vmcnt(14)
	ds_write_b128 v130, v[158:161] offset:18432
	s_waitcnt lgkmcnt(2)
	v_mfma_f32_32x32x16_bf16 v[16:31], v[96:99], v[116:119], v[16:31]
	v_mfma_f32_32x32x16_bf16 v[0:15], v[96:99], v[138:141], v[0:15]
	ds_read_b128 v[96:99], v167 offset:55360
	ds_read_b128 v[116:119], v132 offset:36928
	ds_read_b128 v[138:141], v132 offset:41536
	s_waitcnt lgkmcnt(1)
	v_mfma_f32_32x32x16_bf16 v[48:63], v[96:99], v[116:119], v[48:63]
	s_waitcnt lgkmcnt(0)
	v_mfma_f32_32x32x16_bf16 v[32:47], v[96:99], v[138:141], v[32:47]
	ds_read_b128 v[96:99], v167 offset:59968
	s_waitcnt vmcnt(13)
	ds_write_b128 v130, v[104:107] offset:4608
	s_waitcnt vmcnt(12)
	ds_write_b128 v130, v[108:111] offset:23040
	s_waitcnt lgkmcnt(2)
	v_mfma_f32_32x32x16_bf16 v[16:31], v[96:99], v[116:119], v[16:31]
	v_mfma_f32_32x32x16_bf16 v[0:15], v[96:99], v[138:141], v[0:15]
	ds_read_b128 v[96:99], v167 offset:55392
	ds_read_b128 v[104:107], v132 offset:36960
	ds_read_b128 v[108:111], v132 offset:41568
	s_waitcnt lgkmcnt(1)
	v_mfma_f32_32x32x16_bf16 v[48:63], v[96:99], v[104:107], v[48:63]
	s_waitcnt lgkmcnt(0)
	v_mfma_f32_32x32x16_bf16 v[32:47], v[96:99], v[108:111], v[32:47]
	ds_read_b128 v[96:99], v167 offset:60000
	s_waitcnt vmcnt(11)
	ds_write_b128 v130, v[64:67] offset:9216
	s_waitcnt vmcnt(10)
	ds_write_b128 v130, v[68:71] offset:27648
	s_waitcnt vmcnt(9)
	ds_write_b128 v130, v[72:75] offset:13824
	s_waitcnt vmcnt(8)
	ds_write_b128 v130, v[76:79] offset:32256
	s_waitcnt lgkmcnt(0)
	s_barrier
	ds_read_b128 v[64:67], v167 offset:18432
	ds_read_b128 v[68:71], v132
	ds_read_b128 v[72:75], v132 offset:4608
	s_waitcnt lgkmcnt(1)
	v_mfma_f32_32x32x16_bf16 v[48:63], v[64:67], v[68:71], v[48:63]
	s_waitcnt lgkmcnt(0)
	v_mfma_f32_32x32x16_bf16 v[32:47], v[64:67], v[72:75], v[32:47]
	ds_read_b128 v[64:67], v167 offset:23040
	v_mfma_f32_32x32x16_bf16 v[16:31], v[96:99], v[104:107], v[16:31]
	v_mfma_f32_32x32x16_bf16 v[0:15], v[96:99], v[108:111], v[0:15]
	s_waitcnt lgkmcnt(0)
	v_mfma_f32_32x32x16_bf16 v[16:31], v[64:67], v[68:71], v[16:31]
	v_mfma_f32_32x32x16_bf16 v[0:15], v[64:67], v[72:75], v[0:15]
	ds_read_b128 v[64:67], v167 offset:18464
	ds_read_b128 v[68:71], v132 offset:32
	ds_read_b128 v[72:75], v132 offset:4640
	s_waitcnt lgkmcnt(1)
	v_mfma_f32_32x32x16_bf16 v[48:63], v[64:67], v[68:71], v[48:63]
	s_waitcnt lgkmcnt(0)
	v_mfma_f32_32x32x16_bf16 v[32:47], v[64:67], v[72:75], v[32:47]
	ds_read_b128 v[64:67], v167 offset:23072
	s_waitcnt vmcnt(7)
	ds_write_b128 v130, v[100:103] offset:36864
	s_waitcnt vmcnt(6)
	ds_write_b128 v130, v[112:115] offset:55296
	s_waitcnt lgkmcnt(2)
	v_mfma_f32_32x32x16_bf16 v[16:31], v[64:67], v[68:71], v[16:31]
	v_mfma_f32_32x32x16_bf16 v[0:15], v[64:67], v[72:75], v[0:15]
	ds_read_b128 v[64:67], v167 offset:18496
	ds_read_b128 v[68:71], v132 offset:64
	ds_read_b128 v[72:75], v132 offset:4672
	s_waitcnt lgkmcnt(1)
	v_mfma_f32_32x32x16_bf16 v[48:63], v[64:67], v[68:71], v[48:63]
	s_waitcnt lgkmcnt(0)
	v_mfma_f32_32x32x16_bf16 v[32:47], v[64:67], v[72:75], v[32:47]
	ds_read_b128 v[64:67], v167 offset:23104
	s_waitcnt vmcnt(5)
	ds_write_b128 v130, v[120:123] offset:41472
	s_waitcnt vmcnt(4)
	ds_write_b128 v130, v[124:127] offset:59904
	s_waitcnt lgkmcnt(2)
	v_mfma_f32_32x32x16_bf16 v[16:31], v[64:67], v[68:71], v[16:31]
	v_mfma_f32_32x32x16_bf16 v[0:15], v[64:67], v[72:75], v[0:15]
	ds_read_b128 v[64:67], v167 offset:18528
	ds_read_b128 v[68:71], v132 offset:96
	ds_read_b128 v[72:75], v132 offset:4704
	s_waitcnt lgkmcnt(1)
	v_mfma_f32_32x32x16_bf16 v[48:63], v[64:67], v[68:71], v[48:63]
	s_waitcnt lgkmcnt(0)
	v_mfma_f32_32x32x16_bf16 v[32:47], v[64:67], v[72:75], v[32:47]
	ds_read_b128 v[64:67], v167 offset:23136
	s_waitcnt vmcnt(3)
	ds_write_b128 v130, v[80:83] offset:46080
	s_waitcnt vmcnt(2)
	ds_write_b128 v130, v[84:87] offset:64512
	s_waitcnt vmcnt(1)
	ds_write_b128 v130, v[88:91] offset:50688
	s_waitcnt vmcnt(0)
	ds_write_b128 v131, v[92:95] offset:13824
	s_waitcnt lgkmcnt(0)
	s_barrier
; #define WAVE_LDS_FENCE() asm volatile("s_waitcnt lgkmcnt(0)" ::: "memory")
; DI float4 ldgf4(const void* p) { const f32x4v v = *(const GAS f32x4v*)p; return make_float4(v.x, v.y, v.z, v.w); }
; template <bool MIDK, class AP, class EPI>
; DI void gemm_tile(const AP& ap, const u16* __restrict__ W, int ldw, int K, int m0, int n0, const EPI& epi, char* smem, float r0, float r1, int tid, bool dry) {
;     ...
;     FMMA(f1); SSTOREQ(ra1, rb1, 1, 3); if (l3) GLOADQ(ra1, rb1, kt + 3, 3);
;     __syncthreads();
;     FLOAD(f0, 1, 0); FLOAD(f1, 1, 1);
;     FMMA(f0); if (s2) SSTOREQ(ra0, rb0, 0, 0); if (l4) GLOADQ(ra0, rb0, kt + 4, 0);
;     FLOAD(f0, 1, 2);
;     FMMA(f1); if (s2) SSTOREQ(ra0, rb0, 0, 1); if (l4) GLOADQ(ra0, rb0, kt + 4, 1);
;     FLOAD(f1, 1, 3);
;     FMMA(f0); if (s2) SSTOREQ(ra0, rb0, 0, 2); if (l4) GLOADQ(ra0, rb0, kt + 4, 2);
;     FMMA(f1); if (s2) SSTOREQ(ra0, rb0, 0, 3); if (l4) GLOADQ(ra0, rb0, kt + 4, 3);
;     if (MIDK && kt == 6) {
; #pragma unroll
;       for (int a = 0; a < 2; ++a)
; #pragma unroll
;         for (int i = 0; i < 16; ++i) { acc[a][0][i] *= r0; acc[a][1][i] *= r1; }
;     }
;     __syncthreads();
;   DI void operator()(f32x16 (&acc)[2][2], int nb, int mb, int lane, u16* wl) const {
;     ...
; #pragma unroll
;     for (int fi = 0; fi < 2; ++fi) {
; #pragma unroll
;       for (int ti = 0; ti < 2; ++ti) {
;         const float sc = ti == 0 ? fin0 : fin1;
; #pragma unroll
;         for (int g4 = 0; g4 < 4; ++g4) {
;           float4 o = make_float4(acc[fi][ti][4 * g4] * sc, acc[fi][ti][4 * g4 + 1] * sc, acc[fi][ti][4 * g4 + 2] * sc, acc[fi][ti][4 * g4 + 3] * sc);
;           *(float4*)(wf + (ti * 32 + r) * 36 + 8 * g4 + 4 * h) = o;
;         }
;       }
;       WAVE_LDS_FENCE();
; #pragma unroll
;       for (int it = 0; it < 8; ++it) {
;         const int row = it * 8 + (lane >> 3), ch = lane & 7;
;         const float4 a = *(const float4*)(wf + row * 36 + ch * 4);
;         const int trow = mbl + row;
;         if (trow >= minrow) {
;           const size_t off = (size_t)trow * 1024 + nb + fi * 32 + ch * 4;
;           float4 x = ldgf4(sb + off);
;           x.x += a.x; x.y += a.y; x.z += a.z; x.w += a.w;
;           stgf4(db + off, x);
;         }
;       }
;       WAVE_LDS_FENCE();
;     }
	v_mfma_f32_32x32x16_bf16 v[16:31], v[64:67], v[68:71], v[16:31]
	v_mfma_f32_32x32x16_bf16 v[0:15], v[64:67], v[72:75], v[0:15]
	ds_read_b128 v[64:67], v167 offset:55296
	ds_read_b128 v[68:71], v132 offset:36864
	ds_read_b128 v[72:75], v132 offset:41472
	s_waitcnt lgkmcnt(1)
	v_mfma_f32_32x32x16_bf16 v[48:63], v[64:67], v[68:71], v[48:63]
	s_waitcnt lgkmcnt(0)
	v_mfma_f32_32x32x16_bf16 v[32:47], v[64:67], v[72:75], v[32:47]
	ds_read_b128 v[64:67], v167 offset:59904
	s_waitcnt lgkmcnt(0)
	v_mfma_f32_32x32x16_bf16 v[16:31], v[64:67], v[68:71], v[16:31]
	v_mfma_f32_32x32x16_bf16 v[0:15], v[64:67], v[72:75], v[0:15]
	ds_read_b128 v[64:67], v167 offset:55328
	ds_read_b128 v[68:71], v132 offset:36896
	ds_read_b128 v[72:75], v132 offset:41504
	s_waitcnt lgkmcnt(1)
	v_mfma_f32_32x32x16_bf16 v[48:63], v[64:67], v[68:71], v[48:63]
	s_waitcnt lgkmcnt(0)
	v_mfma_f32_32x32x16_bf16 v[32:47], v[64:67], v[72:75], v[32:47]
	ds_read_b128 v[64:67], v167 offset:59936
	s_waitcnt lgkmcnt(0)
	v_mfma_f32_32x32x16_bf16 v[16:31], v[64:67], v[68:71], v[16:31]
	v_mfma_f32_32x32x16_bf16 v[0:15], v[64:67], v[72:75], v[0:15]
	ds_read_b128 v[64:67], v167 offset:55360
	ds_read_b128 v[68:71], v132 offset:36928
	ds_read_b128 v[72:75], v132 offset:41536
	s_waitcnt lgkmcnt(1)
	v_mfma_f32_32x32x16_bf16 v[48:63], v[64:67], v[68:71], v[48:63]
	s_waitcnt lgkmcnt(0)
	v_mfma_f32_32x32x16_bf16 v[32:47], v[64:67], v[72:75], v[32:47]
	ds_read_b128 v[64:67], v167 offset:59968
	s_waitcnt lgkmcnt(0)
	v_mfma_f32_32x32x16_bf16 v[16:31], v[64:67], v[68:71], v[16:31]
	v_mfma_f32_32x32x16_bf16 v[0:15], v[64:67], v[72:75], v[0:15]
	ds_read_b128 v[64:67], v167 offset:55392
	ds_read_b128 v[68:71], v132 offset:36960
	ds_read_b128 v[72:75], v132 offset:41568
	s_waitcnt lgkmcnt(1)
	v_mfma_f32_32x32x16_bf16 v[48:63], v[64:67], v[68:71], v[48:63]
	s_waitcnt lgkmcnt(0)
	v_mfma_f32_32x32x16_bf16 v[32:47], v[64:67], v[72:75], v[32:47]
	ds_read_b128 v[64:67], v167 offset:60000
	s_waitcnt lgkmcnt(0)
	s_barrier
	v_mfma_f32_32x32x16_bf16 v[16:31], v[64:67], v[68:71], v[16:31]
	v_mfma_f32_32x32x16_bf16 v[0:15], v[64:67], v[72:75], v[0:15]
	s_cbranch_vccnz .LBB0_386
	s_nop 3
	s_cmp_lg_u32 s23, 0
	s_cbranch_scc1 .Lepi_down_orig
	ds_write_b128 v128, v[48:51]
	ds_write_b128 v128, v[52:55] offset:32
	ds_write_b128 v128, v[56:59] offset:64
	ds_write_b128 v128, v[60:63] offset:96
	ds_write_b128 v184, v[32:35]
	ds_write_b128 v184, v[36:39] offset:32
	ds_write_b128 v184, v[40:43] offset:64
	ds_write_b128 v184, v[44:47] offset:96
	s_waitcnt lgkmcnt(0)
	v_or_b32_e32 v64, s4, v133
	v_add_lshl_u32 v36, v64, v169, 2
	global_load_dwordx4 v[68:71], v36, s[2:3]
	ds_read_b128 v[100:103], v185
	v_add_lshl_u32 v37, v64, v171, 2
	global_load_dwordx4 v[72:75], v37, s[2:3]
	ds_read_b128 v[104:107], v185 offset:1152
	v_add_lshl_u32 v38, v64, v173, 2
	global_load_dwordx4 v[76:79], v38, s[2:3]
	ds_read_b128 v[108:111], v185 offset:2304
	v_add_lshl_u32 v39, v64, v175, 2
	global_load_dwordx4 v[80:83], v39, s[2:3]
	ds_read_b128 v[112:115], v185 offset:3456
	v_add_lshl_u32 v40, v64, v177, 2
	global_load_dwordx4 v[84:87], v40, s[2:3]
	ds_read_b128 v[116:119], v185 offset:4608
	v_add_lshl_u32 v41, v64, v179, 2
	global_load_dwordx4 v[88:91], v41, s[2:3]
	ds_read_b128 v[120:123], v185 offset:5760
	v_add_lshl_u32 v42, v64, v181, 2
	global_load_dwordx4 v[92:95], v42, s[2:3]
	ds_read_b128 v[124:127], v185 offset:6912
	v_add_lshl_u32 v43, v64, v183, 2
	global_load_dwordx4 v[96:99], v43, s[2:3]
	ds_read_b128 v[44:47], v185 offset:8064
	s_waitcnt vmcnt(0) lgkmcnt(0)
	v_pk_add_f32 v[68:69], v[100:101], v[68:69]
	v_pk_add_f32 v[70:71], v[102:103], v[70:71]
	global_store_dwordx4 v36, v[68:71], s[2:3]
	v_pk_add_f32 v[72:73], v[104:105], v[72:73]
	v_pk_add_f32 v[74:75], v[106:107], v[74:75]
	global_store_dwordx4 v37, v[72:75], s[2:3]
	v_pk_add_f32 v[76:77], v[108:109], v[76:77]
	v_pk_add_f32 v[78:79], v[110:111], v[78:79]
	global_store_dwordx4 v38, v[76:79], s[2:3]
	v_pk_add_f32 v[80:81], v[112:113], v[80:81]
	v_pk_add_f32 v[82:83], v[114:115], v[82:83]
	global_store_dwordx4 v39, v[80:83], s[2:3]
	v_pk_add_f32 v[84:85], v[116:117], v[84:85]
	v_pk_add_f32 v[86:87], v[118:119], v[86:87]
	global_store_dwordx4 v40, v[84:87], s[2:3]
	v_pk_add_f32 v[88:89], v[120:121], v[88:89]
	v_pk_add_f32 v[90:91], v[122:123], v[90:91]
	global_store_dwordx4 v41, v[88:91], s[2:3]
	v_pk_add_f32 v[92:93], v[124:125], v[92:93]
	v_pk_add_f32 v[94:95], v[126:127], v[94:95]
	global_store_dwordx4 v42, v[92:95], s[2:3]
	v_pk_add_f32 v[96:97], v[44:45], v[96:97]
	v_pk_add_f32 v[98:99], v[46:47], v[98:99]
	global_store_dwordx4 v43, v[96:99], s[2:3]
	s_waitcnt lgkmcnt(0)
	ds_write_b128 v128, v[16:19]
	ds_write_b128 v128, v[20:23] offset:32
	ds_write_b128 v128, v[24:27] offset:64
	ds_write_b128 v128, v[28:31] offset:96
	ds_write_b128 v184, v[0:3]
	ds_write_b128 v184, v[4:7] offset:32
	ds_write_b128 v184, v[8:11] offset:64
	ds_write_b128 v184, v[12:15] offset:96
	s_waitcnt lgkmcnt(0)
	global_load_dwordx4 v[68:71], v36, s[2:3] offset:128
	ds_read_b128 v[100:103], v185
	global_load_dwordx4 v[72:75], v37, s[2:3] offset:128
	ds_read_b128 v[104:107], v185 offset:1152
	global_load_dwordx4 v[76:79], v38, s[2:3] offset:128
	ds_read_b128 v[108:111], v185 offset:2304
	global_load_dwordx4 v[80:83], v39, s[2:3] offset:128
	ds_read_b128 v[112:115], v185 offset:3456
	global_load_dwordx4 v[84:87], v40, s[2:3] offset:128
	ds_read_b128 v[116:119], v185 offset:4608
	global_load_dwordx4 v[88:91], v41, s[2:3] offset:128
	ds_read_b128 v[120:123], v185 offset:5760
	global_load_dwordx4 v[92:95], v42, s[2:3] offset:128
	ds_read_b128 v[124:127], v185 offset:6912
	global_load_dwordx4 v[96:99], v43, s[2:3] offset:128
	ds_read_b128 v[44:47], v185 offset:8064
	s_waitcnt vmcnt(0) lgkmcnt(0)
	v_pk_add_f32 v[68:69], v[100:101], v[68:69]
	v_pk_add_f32 v[70:71], v[102:103], v[70:71]
	global_store_dwordx4 v36, v[68:71], s[2:3] offset:128
	v_pk_add_f32 v[72:73], v[104:105], v[72:73]
	v_pk_add_f32 v[74:75], v[106:107], v[74:75]
	global_store_dwordx4 v37, v[72:75], s[2:3] offset:128
	v_pk_add_f32 v[76:77], v[108:109], v[76:77]
	v_pk_add_f32 v[78:79], v[110:111], v[78:79]
	global_store_dwordx4 v38, v[76:79], s[2:3] offset:128
	v_pk_add_f32 v[80:81], v[112:113], v[80:81]
	v_pk_add_f32 v[82:83], v[114:115], v[82:83]
	global_store_dwordx4 v39, v[80:83], s[2:3] offset:128
	v_pk_add_f32 v[84:85], v[116:117], v[84:85]
	v_pk_add_f32 v[86:87], v[118:119], v[86:87]
	global_store_dwordx4 v40, v[84:87], s[2:3] offset:128
	v_pk_add_f32 v[88:89], v[120:121], v[88:89]
	v_pk_add_f32 v[90:91], v[122:123], v[90:91]
	global_store_dwordx4 v41, v[88:91], s[2:3] offset:128
	v_pk_add_f32 v[92:93], v[124:125], v[92:93]
	v_pk_add_f32 v[94:95], v[126:127], v[94:95]
	global_store_dwordx4 v42, v[92:95], s[2:3] offset:128
	v_pk_add_f32 v[96:97], v[44:45], v[96:97]
	v_pk_add_f32 v[98:99], v[46:47], v[98:99]
	global_store_dwordx4 v43, v[96:99], s[2:3] offset:128
	s_branch .LBB0_386
; #define WAVE_LDS_FENCE() asm volatile("s_waitcnt lgkmcnt(0)" ::: "memory")
; DI float4 ldgf4(const void* p) { const f32x4v v = *(const GAS f32x4v*)p; return make_float4(v.x, v.y, v.z, v.w); }
;   DI void operator()(f32x16 (&acc)[2][2], int nb, int mb, int lane, u16* wl) const {
;     ...
; #pragma unroll
;     for (int fi = 0; fi < 2; ++fi) {
; #pragma unroll
;       for (int ti = 0; ti < 2; ++ti) {
;         const float sc = ti == 0 ? fin0 : fin1;
; #pragma unroll
;         for (int g4 = 0; g4 < 4; ++g4) {
;           float4 o = make_float4(acc[fi][ti][4 * g4] * sc, acc[fi][ti][4 * g4 + 1] * sc, acc[fi][ti][4 * g4 + 2] * sc, acc[fi][ti][4 * g4 + 3] * sc);
;           *(float4*)(wf + (ti * 32 + r) * 36 + 8 * g4 + 4 * h) = o;
;         }
;       }
;       WAVE_LDS_FENCE();
; #pragma unroll
;       for (int it = 0; it < 8; ++it) {
;         const int row = it * 8 + (lane >> 3), ch = lane & 7;
;         const float4 a = *(const float4*)(wf + row * 36 + ch * 4);
;         const int trow = mbl + row;
;         if (trow >= minrow) {
;           const size_t off = (size_t)trow * 1024 + nb + fi * 32 + ch * 4;
;           float4 x = ldgf4(sb + off);
;           x.x += a.x; x.y += a.y; x.z += a.z; x.w += a.w;
;           stgf4(db + off, x);
;         }
.Lepi_down_orig:
	ds_write_b128 v128, v[48:51]
	ds_write_b128 v128, v[52:55] offset:32
	ds_write_b128 v128, v[56:59] offset:64
	ds_write_b128 v128, v[60:63] offset:96
	ds_write_b128 v184, v[32:35]
	ds_write_b128 v184, v[36:39] offset:32
	ds_write_b128 v184, v[40:43] offset:64
	ds_write_b128 v184, v[44:47] offset:96
	s_waitcnt lgkmcnt(0)
	v_or_b32_e32 v64, s4, v133
	v_cmp_le_u32_e32 vcc, s23, v168
	s_and_saveexec_b64 s[4:5], vcc
	s_cbranch_execz .LBB0_408
	v_or_b32_e32 v32, v64, v169
	v_lshlrev_b32_e32 v40, 2, v32
	global_load_dwordx4 v[32:35], v40, s[2:3]
	ds_read_b128 v[36:39], v185
	s_waitcnt vmcnt(0) lgkmcnt(0)
	v_pk_add_f32 v[34:35], v[38:39], v[34:35]
	v_pk_add_f32 v[32:33], v[36:37], v[32:33]
	global_store_dwordx4 v40, v[32:35], s[2:3]
	s_or_b64 exec, exec, s[4:5]
	v_cmp_le_u32_e64 s[4:5], s23, v170
	s_and_saveexec_b64 s[6:7], s[4:5]
	s_cbranch_execnz .LBB0_409
